# v6 + first K-loop iteration peeled with C=0 MFMAs, accumulator zero-init moves (1513 VALU) deleted
# speedup vs baseline: 1.0053x; 1.0053x over previous
.LBB0_150:
	v_lshrrev_b32_e32 v4, 1, v2
	v_and_b32_e32 v4, 24, v4
	v_and_b32_e32 v3, 15, v2
	v_lshlrev_b32_e32 v5, 1, v4
	v_lshlrev_b32_e32 v2, 2, v2
	s_sext_i32_i16 s86, s2
	v_lshl_or_b32 v135, s8, 6, v3
	v_lshl_or_b32 v3, v3, 6, v5
	s_lshl_b32 s2, s8, 13
	v_and_b32_e32 v2, 32, v2
	v_bitop3_b32 v5, v3, s2, v2 bitop3:0xde
	s_lshl_b32 s2, s9, 5
	s_and_b32 s2, s2, 0x60
	s_lshl_b32 s8, s2, 7
	v_bitop3_b32 v2, v3, s8, v2 bitop3:0xde
	s_add_u32 s8, s0, 0x80
	s_addc_u32 s9, s1, 0
	s_add_i32 s76, s51, 0x18000
	s_waitcnt vmcnt(2)
	s_barrier
	s_mov_b32 s10, m0
	s_mov_b32 m0, s76
	s_nop 4
	global_load_lds_dwordx4 v134, s[8:9]
	s_mov_b32 m0, s10
	s_add_u32 s8, s0, 0x20080
	s_addc_u32 s9, s1, 0
	s_add_i32 s77, s51, 0x1a000
	s_mov_b32 s10, m0
	s_mov_b32 m0, s77
	s_nop 4
	global_load_lds_dwordx4 v134, s[8:9]
	s_mov_b32 m0, s10
	s_add_u32 s8, s52, 0x80
	s_addc_u32 s9, s53, 0
	s_add_i32 s78, s51, 0x8000
	s_mov_b32 s10, m0
	s_mov_b32 m0, s78
	s_nop 4
	global_load_lds_dwordx4 v1, s[8:9]
	s_mov_b32 m0, s10
	s_add_u32 s8, s52, 0x20080
	s_addc_u32 s9, s53, 0
	s_add_i32 s79, s51, 0xa000
	s_mov_b32 s10, m0
	s_mov_b32 m0, s79
	s_nop 4
	global_load_lds_dwordx4 v1, s[8:9]
	s_mov_b32 m0, s10
	s_add_u32 s8, s0, 0x40080
	s_addc_u32 s9, s1, 0
	s_add_i32 s80, s51, 0x1c000
	s_mov_b32 s10, m0
	s_mov_b32 m0, s80
	s_nop 4
	global_load_lds_dwordx4 v134, s[8:9]
	s_mov_b32 m0, s10
	s_add_u32 s8, s0, 0x60080
	s_addc_u32 s9, s1, 0
	s_add_i32 s81, s51, 0x1e000
	s_mov_b32 s10, m0
	s_mov_b32 m0, s81
	s_nop 4
	global_load_lds_dwordx4 v134, s[8:9]
	s_mov_b32 m0, s10
	s_waitcnt vmcnt(6)
	s_add_i32 s83, s51, 0xc000
	s_cmpk_lt_u32 s3, 0x100
	v_mov_b64_e32 v[6:7], 0
	s_cselect_b64 s[8:9], -1, 0
	s_ashr_i32 s84, s72, 31
	v_or_b32_e32 v136, s2, v4
	v_add_u32_e32 v137, 0, v2
	v_add_u32_e32 v138, 0, v5
	s_movk_i32 s85, 0x1600
	s_waitcnt lgkmcnt(0)
	v_mov_b64_e32 v[130:131], 0x16b0
	v_mov_b64_e32 v[132:133], 0x16af
	s_barrier
	s_branch .LBB0_153

.LBB0_155:
	s_ashr_i32 s41, s40, 31
	s_lshl_b64 s[14:15], s[40:41], 19
	s_add_u32 s42, s16, s14
	s_addc_u32 s43, s17, s15
	s_and_b64 s[14:15], s[2:3], exec
	s_cselect_b32 s14, s43, s53
	s_cselect_b32 s15, s42, s52
	s_ashr_i32 s11, s10, 31
	s_lshl_b64 s[34:35], s[10:11], 19
	s_add_u32 s44, s33, s34
	s_addc_u32 s45, s58, s35
	s_and_b64 s[34:35], s[2:3], exec
	s_cselect_b32 s11, s45, s1
	s_cselect_b32 s41, s44, s0
	s_add_u32 s87, s0, 0x100
	s_addc_u32 s88, s1, 0
	s_mov_b32 s89, -2
	v_add_u32_e32 v139, 0x10000, v137
	ds_read_b128 v[140:143], v139
	ds_read_b128 v[144:147], v139 offset:1024
	ds_read_b128 v[148:151], v139 offset:2048
	ds_read_b128 v[152:155], v139 offset:3072
	v_add_u32_e32 v139, 0x14000, v137
	ds_read_b128 v[156:159], v139
	ds_read_b128 v[160:163], v139 offset:1024
	ds_read_b128 v[164:167], v139 offset:2048
	ds_read_b128 v[168:171], v139 offset:3072
	s_add_u32 s0, s52, 0x100
	s_addc_u32 s1, s53, 0
	s_cmp_eq_u32 s89, 12
	s_cselect_b32 s34, s15, s0
	s_cselect_b32 s35, s14, s1
	s_cselect_b32 s56, s41, s87
	s_cselect_b32 s57, s11, s88
	s_add_u32 s54, s34, 0x80
	s_addc_u32 s55, s35, 0
	ds_read_b128 v[172:175], v138
	ds_read_b128 v[176:179], v138 offset:1024
	ds_read_b128 v[180:183], v138 offset:2048
	ds_read_b128 v[184:187], v138 offset:3072
	ds_read_b128 v[188:191], v138 offset:4096
	ds_read_b128 v[192:195], v138 offset:5120
	ds_read_b128 v[196:199], v138 offset:6144
	ds_read_b128 v[200:203], v138 offset:7168
	s_add_u32 s90, s52, 0x40080
	s_addc_u32 s91, s53, 0
	s_mov_b32 s12, m0
	s_mov_b32 m0, s83
	s_nop 4
	global_load_lds_dwordx4 v1, s[90:91]
	s_mov_b32 m0, s12
	s_add_u32 s52, s52, 0x60080
	s_addc_u32 s53, s53, 0
	s_add_i32 s12, s51, 0xe000
	s_mov_b32 s13, m0
	s_mov_b32 m0, s12
	s_nop 4
	global_load_lds_dwordx4 v1, s[52:53]
	s_mov_b32 m0, s13
	s_waitcnt vmcnt(8)
	s_waitcnt lgkmcnt(0)
	s_barrier
	s_waitcnt lgkmcnt(7)
	v_mfma_f32_16x16x32_bf16 v[122:125], v[140:143], v[172:175], 0
	v_mfma_f32_16x16x32_bf16 v[114:117], v[148:151], v[172:175], 0
	s_waitcnt lgkmcnt(5)
	v_mfma_f32_16x16x32_bf16 v[106:109], v[140:143], v[180:183], 0
	v_mfma_f32_16x16x32_bf16 v[98:101], v[148:151], v[180:183], 0
	s_waitcnt lgkmcnt(3)
	v_mfma_f32_16x16x32_bf16 v[90:93], v[140:143], v[188:191], 0
	v_mfma_f32_16x16x32_bf16 v[82:85], v[148:151], v[188:191], 0
	s_waitcnt lgkmcnt(1)
	v_mfma_f32_16x16x32_bf16 v[74:77], v[140:143], v[196:199], 0
	v_mfma_f32_16x16x32_bf16 v[66:69], v[148:151], v[196:199], 0
	v_mfma_f32_16x16x32_bf16 v[122:125], v[144:147], v[176:179], v[122:125]
	v_mfma_f32_16x16x32_bf16 v[114:117], v[152:155], v[176:179], v[114:117]
	v_mfma_f32_16x16x32_bf16 v[106:109], v[144:147], v[184:187], v[106:109]
	v_mfma_f32_16x16x32_bf16 v[98:101], v[152:155], v[184:187], v[98:101]
	v_mfma_f32_16x16x32_bf16 v[90:93], v[144:147], v[192:195], v[90:93]
	v_mfma_f32_16x16x32_bf16 v[82:85], v[152:155], v[192:195], v[82:85]
	s_waitcnt lgkmcnt(0)
	v_mfma_f32_16x16x32_bf16 v[74:77], v[144:147], v[200:203], v[74:77]
	v_mfma_f32_16x16x32_bf16 v[66:69], v[152:155], v[200:203], v[66:69]
	v_mfma_f32_16x16x32_bf16 v[126:129], v[156:159], v[172:175], 0
	v_mfma_f32_16x16x32_bf16 v[118:121], v[164:167], v[172:175], 0
	v_mfma_f32_16x16x32_bf16 v[110:113], v[156:159], v[180:183], 0
	v_mfma_f32_16x16x32_bf16 v[102:105], v[164:167], v[180:183], 0
	v_mfma_f32_16x16x32_bf16 v[94:97], v[156:159], v[188:191], 0
	v_mfma_f32_16x16x32_bf16 v[86:89], v[164:167], v[188:191], 0
	v_mfma_f32_16x16x32_bf16 v[78:81], v[156:159], v[196:199], 0
	v_mfma_f32_16x16x32_bf16 v[70:73], v[164:167], v[196:199], 0
	v_mfma_f32_16x16x32_bf16 v[126:129], v[160:163], v[176:179], v[126:129]
	v_mfma_f32_16x16x32_bf16 v[118:121], v[168:171], v[176:179], v[118:121]
	v_mfma_f32_16x16x32_bf16 v[110:113], v[160:163], v[184:187], v[110:113]
	v_mfma_f32_16x16x32_bf16 v[102:105], v[168:171], v[184:187], v[102:105]
	v_mfma_f32_16x16x32_bf16 v[94:97], v[160:163], v[192:195], v[94:97]
	v_mfma_f32_16x16x32_bf16 v[86:89], v[168:171], v[192:195], v[86:89]
	v_mfma_f32_16x16x32_bf16 v[78:81], v[160:163], v[200:203], v[78:81]
	v_mfma_f32_16x16x32_bf16 v[70:73], v[168:171], v[200:203], v[70:73]
	s_barrier
	s_add_u32 s52, s56, 0x20000
	ds_read_b128 v[172:175], v138 offset:16384
	ds_read_b128 v[176:179], v138 offset:17408
	ds_read_b128 v[180:183], v138 offset:18432
	ds_read_b128 v[184:187], v138 offset:19456
	ds_read_b128 v[188:191], v138 offset:20480
	ds_read_b128 v[192:195], v138 offset:21504
	ds_read_b128 v[196:199], v138 offset:22528
	ds_read_b128 v[200:203], v138 offset:23552
	s_mov_b32 s12, m0
	s_mov_b32 m0, s62
	s_nop 4
	global_load_lds_dwordx4 v134, s[56:57]
	s_mov_b32 m0, s12
	s_addc_u32 s53, s57, 0
	s_mov_b32 s12, m0
	s_mov_b32 m0, s63
	s_nop 4
	global_load_lds_dwordx4 v134, s[52:53]
	s_mov_b32 m0, s12
	s_add_u32 s52, s56, 0x40000
	s_addc_u32 s53, s57, 0
	s_mov_b32 s12, m0
	s_mov_b32 m0, s64
	s_nop 4
	global_load_lds_dwordx4 v134, s[52:53]
	s_mov_b32 m0, s12
	s_add_u32 s52, s56, 0x60000
	s_addc_u32 s53, s57, 0
	s_mov_b32 s12, m0
	s_mov_b32 m0, s65
	s_nop 4
	global_load_lds_dwordx4 v134, s[52:53]
	s_mov_b32 m0, s12
	s_add_u32 s52, s34, 0x20000
	s_mov_b32 s12, m0
	s_mov_b32 m0, s51
	s_nop 4
	global_load_lds_dwordx4 v1, s[34:35]
	s_mov_b32 m0, s12
	s_addc_u32 s53, s35, 0
	s_mov_b32 s12, m0
	s_mov_b32 m0, s73
	s_nop 4
	global_load_lds_dwordx4 v1, s[52:53]
	s_mov_b32 m0, s12
	s_waitcnt vmcnt(8)
	s_waitcnt lgkmcnt(0)
	s_barrier
	s_waitcnt lgkmcnt(7)
	v_mfma_f32_16x16x32_bf16 v[58:61], v[140:143], v[172:175], 0
	v_mfma_f32_16x16x32_bf16 v[50:53], v[148:151], v[172:175], 0
	s_waitcnt lgkmcnt(5)
	v_mfma_f32_16x16x32_bf16 v[42:45], v[140:143], v[180:183], 0
	v_mfma_f32_16x16x32_bf16 v[34:37], v[148:151], v[180:183], 0
	s_waitcnt lgkmcnt(3)
	v_mfma_f32_16x16x32_bf16 v[26:29], v[140:143], v[188:191], 0
	v_mfma_f32_16x16x32_bf16 v[18:21], v[148:151], v[188:191], 0
	s_waitcnt lgkmcnt(1)
	v_mfma_f32_16x16x32_bf16 v[10:13], v[140:143], v[196:199], 0
	v_mfma_f32_16x16x32_bf16 v[2:5], v[148:151], v[196:199], 0
	v_mfma_f32_16x16x32_bf16 v[58:61], v[144:147], v[176:179], v[58:61]
	v_mfma_f32_16x16x32_bf16 v[50:53], v[152:155], v[176:179], v[50:53]
	v_mfma_f32_16x16x32_bf16 v[42:45], v[144:147], v[184:187], v[42:45]
	v_mfma_f32_16x16x32_bf16 v[34:37], v[152:155], v[184:187], v[34:37]
	v_mfma_f32_16x16x32_bf16 v[26:29], v[144:147], v[192:195], v[26:29]
	v_mfma_f32_16x16x32_bf16 v[18:21], v[152:155], v[192:195], v[18:21]
	s_waitcnt lgkmcnt(0)
	v_mfma_f32_16x16x32_bf16 v[10:13], v[144:147], v[200:203], v[10:13]
	v_mfma_f32_16x16x32_bf16 v[2:5], v[152:155], v[200:203], v[2:5]
	v_mfma_f32_16x16x32_bf16 v[62:65], v[156:159], v[172:175], 0
	v_mfma_f32_16x16x32_bf16 v[54:57], v[164:167], v[172:175], 0
	v_mfma_f32_16x16x32_bf16 v[46:49], v[156:159], v[180:183], 0
	v_mfma_f32_16x16x32_bf16 v[38:41], v[164:167], v[180:183], 0
	v_mfma_f32_16x16x32_bf16 v[30:33], v[156:159], v[188:191], 0
	v_mfma_f32_16x16x32_bf16 v[22:25], v[164:167], v[188:191], 0
	v_mfma_f32_16x16x32_bf16 v[14:17], v[156:159], v[196:199], 0
	v_mfma_f32_16x16x32_bf16 v[6:9], v[164:167], v[196:199], 0
	v_mfma_f32_16x16x32_bf16 v[62:65], v[160:163], v[176:179], v[62:65]
	v_mfma_f32_16x16x32_bf16 v[54:57], v[168:171], v[176:179], v[54:57]
	v_mfma_f32_16x16x32_bf16 v[46:49], v[160:163], v[184:187], v[46:49]
	v_mfma_f32_16x16x32_bf16 v[38:41], v[168:171], v[184:187], v[38:41]
	v_mfma_f32_16x16x32_bf16 v[30:33], v[160:163], v[192:195], v[30:33]
	v_mfma_f32_16x16x32_bf16 v[22:25], v[168:171], v[192:195], v[22:25]
	v_mfma_f32_16x16x32_bf16 v[14:17], v[160:163], v[200:203], v[14:17]
	v_mfma_f32_16x16x32_bf16 v[6:9], v[168:171], v[200:203], v[6:9]
	s_barrier
	v_add_u32_e32 v139, 0x18000, v137
	ds_read_b128 v[140:143], v139
	ds_read_b128 v[144:147], v139 offset:1024
	ds_read_b128 v[148:151], v139 offset:2048
	ds_read_b128 v[152:155], v139 offset:3072
	v_add_u32_e32 v139, 0x1c000, v137
	ds_read_b128 v[156:159], v139
	ds_read_b128 v[160:163], v139 offset:1024
	ds_read_b128 v[164:167], v139 offset:2048
	ds_read_b128 v[168:171], v139 offset:3072
	ds_read_b128 v[172:175], v138 offset:32768
	ds_read_b128 v[176:179], v138 offset:33792
	ds_read_b128 v[180:183], v138 offset:34816
	ds_read_b128 v[184:187], v138 offset:35840
	ds_read_b128 v[188:191], v138 offset:36864
	ds_read_b128 v[192:195], v138 offset:37888
	ds_read_b128 v[196:199], v138 offset:38912
	ds_read_b128 v[200:203], v138 offset:39936
	s_add_u32 s52, s34, 0x40000
	s_addc_u32 s53, s35, 0
	s_mov_b32 s12, m0
	s_mov_b32 m0, s74
	s_nop 4
	global_load_lds_dwordx4 v1, s[52:53]
	s_mov_b32 m0, s12
	s_add_u32 s52, s34, 0x60000
	s_addc_u32 s53, s35, 0
	s_mov_b32 s12, m0
	s_mov_b32 m0, s75
	s_nop 4
	global_load_lds_dwordx4 v1, s[52:53]
	s_mov_b32 m0, s12
	s_waitcnt vmcnt(8)
	s_waitcnt lgkmcnt(0)
	s_barrier
	s_waitcnt lgkmcnt(7)
	v_mfma_f32_16x16x32_bf16 v[122:125], v[140:143], v[172:175], v[122:125]
	v_mfma_f32_16x16x32_bf16 v[114:117], v[148:151], v[172:175], v[114:117]
	s_waitcnt lgkmcnt(5)
	v_mfma_f32_16x16x32_bf16 v[106:109], v[140:143], v[180:183], v[106:109]
	v_mfma_f32_16x16x32_bf16 v[98:101], v[148:151], v[180:183], v[98:101]
	s_waitcnt lgkmcnt(3)
	v_mfma_f32_16x16x32_bf16 v[90:93], v[140:143], v[188:191], v[90:93]
	v_mfma_f32_16x16x32_bf16 v[82:85], v[148:151], v[188:191], v[82:85]
	s_waitcnt lgkmcnt(1)
	v_mfma_f32_16x16x32_bf16 v[74:77], v[140:143], v[196:199], v[74:77]
	v_mfma_f32_16x16x32_bf16 v[66:69], v[148:151], v[196:199], v[66:69]
	v_mfma_f32_16x16x32_bf16 v[122:125], v[144:147], v[176:179], v[122:125]
	v_mfma_f32_16x16x32_bf16 v[114:117], v[152:155], v[176:179], v[114:117]
	v_mfma_f32_16x16x32_bf16 v[106:109], v[144:147], v[184:187], v[106:109]
	v_mfma_f32_16x16x32_bf16 v[98:101], v[152:155], v[184:187], v[98:101]
	v_mfma_f32_16x16x32_bf16 v[90:93], v[144:147], v[192:195], v[90:93]
	v_mfma_f32_16x16x32_bf16 v[82:85], v[152:155], v[192:195], v[82:85]
	s_waitcnt lgkmcnt(0)
	v_mfma_f32_16x16x32_bf16 v[74:77], v[144:147], v[200:203], v[74:77]
	v_mfma_f32_16x16x32_bf16 v[66:69], v[152:155], v[200:203], v[66:69]
	v_mfma_f32_16x16x32_bf16 v[126:129], v[156:159], v[172:175], v[126:129]
	v_mfma_f32_16x16x32_bf16 v[118:121], v[164:167], v[172:175], v[118:121]
	v_mfma_f32_16x16x32_bf16 v[110:113], v[156:159], v[180:183], v[110:113]
	v_mfma_f32_16x16x32_bf16 v[102:105], v[164:167], v[180:183], v[102:105]
	v_mfma_f32_16x16x32_bf16 v[94:97], v[156:159], v[188:191], v[94:97]
	v_mfma_f32_16x16x32_bf16 v[86:89], v[164:167], v[188:191], v[86:89]
	v_mfma_f32_16x16x32_bf16 v[78:81], v[156:159], v[196:199], v[78:81]
	v_mfma_f32_16x16x32_bf16 v[70:73], v[164:167], v[196:199], v[70:73]
	v_mfma_f32_16x16x32_bf16 v[126:129], v[160:163], v[176:179], v[126:129]
	v_mfma_f32_16x16x32_bf16 v[118:121], v[168:171], v[176:179], v[118:121]
	v_mfma_f32_16x16x32_bf16 v[110:113], v[160:163], v[184:187], v[110:113]
	v_mfma_f32_16x16x32_bf16 v[102:105], v[168:171], v[184:187], v[102:105]
	v_mfma_f32_16x16x32_bf16 v[94:97], v[160:163], v[192:195], v[94:97]
	v_mfma_f32_16x16x32_bf16 v[86:89], v[168:171], v[192:195], v[86:89]
	v_mfma_f32_16x16x32_bf16 v[78:81], v[160:163], v[200:203], v[78:81]
	v_mfma_f32_16x16x32_bf16 v[70:73], v[168:171], v[200:203], v[70:73]
	s_barrier
	s_add_u32 s52, s56, 0x80
	s_addc_u32 s53, s57, 0
	ds_read_b128 v[172:175], v138 offset:49152
	ds_read_b128 v[176:179], v138 offset:50176
	ds_read_b128 v[180:183], v138 offset:51200
	ds_read_b128 v[184:187], v138 offset:52224
	ds_read_b128 v[188:191], v138 offset:53248
	ds_read_b128 v[192:195], v138 offset:54272
	ds_read_b128 v[196:199], v138 offset:55296
	ds_read_b128 v[200:203], v138 offset:56320
	s_mov_b32 s12, m0
	s_mov_b32 m0, s76
	s_nop 4
	global_load_lds_dwordx4 v134, s[52:53]
	s_mov_b32 m0, s12
	s_add_u32 s52, s56, 0x20080
	s_addc_u32 s53, s57, 0
	s_mov_b32 s12, m0
	s_mov_b32 m0, s77
	s_nop 4
	global_load_lds_dwordx4 v134, s[52:53]
	s_mov_b32 m0, s12
	s_add_u32 s52, s56, 0x40080
	s_addc_u32 s53, s57, 0
	s_mov_b32 s12, m0
	s_mov_b32 m0, s80
	s_nop 4
	global_load_lds_dwordx4 v134, s[52:53]
	s_mov_b32 m0, s12
	s_add_u32 s52, s56, 0x60080
	s_addc_u32 s53, s57, 0
	s_mov_b32 s12, m0
	s_mov_b32 m0, s81
	s_nop 4
	global_load_lds_dwordx4 v134, s[52:53]
	s_mov_b32 m0, s12
	s_add_u32 s34, s34, 0x20080
	s_mov_b32 s12, m0
	s_mov_b32 m0, s78
	s_nop 4
	global_load_lds_dwordx4 v1, s[54:55]
	s_mov_b32 m0, s12
	s_addc_u32 s35, s35, 0
	s_mov_b32 s12, m0
	s_mov_b32 m0, s79
	s_nop 4
	global_load_lds_dwordx4 v1, s[34:35]
	s_mov_b32 m0, s12
	s_waitcnt vmcnt(8)
	s_waitcnt lgkmcnt(0)
	s_barrier
	s_waitcnt lgkmcnt(7)
	v_mfma_f32_16x16x32_bf16 v[58:61], v[140:143], v[172:175], v[58:61]
	v_mfma_f32_16x16x32_bf16 v[50:53], v[148:151], v[172:175], v[50:53]
	s_waitcnt lgkmcnt(5)
	v_mfma_f32_16x16x32_bf16 v[42:45], v[140:143], v[180:183], v[42:45]
	v_mfma_f32_16x16x32_bf16 v[34:37], v[148:151], v[180:183], v[34:37]
	s_waitcnt lgkmcnt(3)
	v_mfma_f32_16x16x32_bf16 v[26:29], v[140:143], v[188:191], v[26:29]
	v_mfma_f32_16x16x32_bf16 v[18:21], v[148:151], v[188:191], v[18:21]
	s_waitcnt lgkmcnt(1)
	v_mfma_f32_16x16x32_bf16 v[10:13], v[140:143], v[196:199], v[10:13]
	v_mfma_f32_16x16x32_bf16 v[2:5], v[148:151], v[196:199], v[2:5]
	v_mfma_f32_16x16x32_bf16 v[58:61], v[144:147], v[176:179], v[58:61]
	v_mfma_f32_16x16x32_bf16 v[50:53], v[152:155], v[176:179], v[50:53]
	v_mfma_f32_16x16x32_bf16 v[42:45], v[144:147], v[184:187], v[42:45]
	v_mfma_f32_16x16x32_bf16 v[34:37], v[152:155], v[184:187], v[34:37]
	v_mfma_f32_16x16x32_bf16 v[26:29], v[144:147], v[192:195], v[26:29]
	v_mfma_f32_16x16x32_bf16 v[18:21], v[152:155], v[192:195], v[18:21]
	s_waitcnt lgkmcnt(0)
	v_mfma_f32_16x16x32_bf16 v[10:13], v[144:147], v[200:203], v[10:13]
	v_mfma_f32_16x16x32_bf16 v[2:5], v[152:155], v[200:203], v[2:5]
	v_mfma_f32_16x16x32_bf16 v[62:65], v[156:159], v[172:175], v[62:65]
	v_mfma_f32_16x16x32_bf16 v[54:57], v[164:167], v[172:175], v[54:57]
	v_mfma_f32_16x16x32_bf16 v[46:49], v[156:159], v[180:183], v[46:49]
	v_mfma_f32_16x16x32_bf16 v[38:41], v[164:167], v[180:183], v[38:41]
	v_mfma_f32_16x16x32_bf16 v[30:33], v[156:159], v[188:191], v[30:33]
	v_mfma_f32_16x16x32_bf16 v[22:25], v[164:167], v[188:191], v[22:25]
	v_mfma_f32_16x16x32_bf16 v[14:17], v[156:159], v[196:199], v[14:17]
	v_mfma_f32_16x16x32_bf16 v[6:9], v[164:167], v[196:199], v[6:9]
	v_mfma_f32_16x16x32_bf16 v[62:65], v[160:163], v[176:179], v[62:65]
	v_mfma_f32_16x16x32_bf16 v[54:57], v[168:171], v[176:179], v[54:57]
	v_mfma_f32_16x16x32_bf16 v[46:49], v[160:163], v[184:187], v[46:49]
	v_mfma_f32_16x16x32_bf16 v[38:41], v[168:171], v[184:187], v[38:41]
	v_mfma_f32_16x16x32_bf16 v[30:33], v[160:163], v[192:195], v[30:33]
	v_mfma_f32_16x16x32_bf16 v[22:25], v[168:171], v[192:195], v[22:25]
	v_mfma_f32_16x16x32_bf16 v[14:17], v[160:163], v[200:203], v[14:17]
	v_mfma_f32_16x16x32_bf16 v[6:9], v[168:171], v[200:203], v[6:9]
	s_barrier
	s_add_i32 s89, s89, 2
	s_add_u32 s87, s87, 0x100
	s_addc_u32 s88, s88, 0
	s_cmp_gt_u32 s89, 13
	s_mov_b64 s[52:53], s[0:1]

.LBB0_159:
	v_exp_f32_e64 v140, -v122
	v_exp_f32_e64 v141, -v123
	v_pk_mul_f32 v[128:129], v[124:125], v[128:129]
	v_exp_f32_e64 v124, -v124
	v_exp_f32_e64 v125, -v125
	v_pk_add_f32 v[140:141], v[140:141], 1.0 op_sel_hi:[1,0]
	v_pk_mul_f32 v[122:123], v[122:123], v[126:127]
	v_rcp_f32_e32 v126, v140
	v_rcp_f32_e32 v127, v141
	v_pk_add_f32 v[124:125], v[124:125], 1.0 op_sel_hi:[1,0]
	v_lshl_or_b32 v142, s86, 7, v136
	v_rcp_f32_e32 v124, v124
	v_rcp_f32_e32 v125, v125
	v_pk_mul_f32 v[122:123], v[126:127], v[122:123]
	v_exp_f32_e64 v126, -v114
	v_exp_f32_e64 v127, -v115
	v_pk_mul_f32 v[124:125], v[124:125], v[128:129]
	v_exp_f32_e64 v128, -v116
	v_exp_f32_e64 v129, -v117
	v_pk_add_f32 v[126:127], v[126:127], 1.0 op_sel_hi:[1,0]
	v_pk_mul_f32 v[114:115], v[114:115], v[118:119]
	v_rcp_f32_e32 v126, v126
	v_rcp_f32_e32 v127, v127
	v_pk_add_f32 v[128:129], v[128:129], 1.0 op_sel_hi:[1,0]
	v_pk_mul_f32 v[116:117], v[116:117], v[120:121]
	v_rcp_f32_e32 v128, v128
	v_rcp_f32_e32 v129, v129
	v_pk_mul_f32 v[114:115], v[126:127], v[114:115]
	v_cvt_pk_bf16_f32 v118, v122, v123
	v_cvt_pk_bf16_f32 v119, v124, v125
	v_exp_f32_e64 v124, -v106
	v_exp_f32_e64 v125, -v107
	v_lshl_add_u32 v139, s50, 8, v135
	v_ashrrev_i32_e32 v143, 31, v142
	v_pk_mul_f32 v[116:117], v[128:129], v[116:117]
	v_cvt_pk_bf16_f32 v120, v114, v115
	v_mov_b64_e32 v[114:115], s[18:19]
	v_pk_mul_f32 v[112:113], v[108:109], v[112:113]
	v_exp_f32_e64 v108, -v108
	v_exp_f32_e64 v109, -v109
	v_cvt_pk_bf16_f32 v121, v116, v117
	v_mad_i64_i32 v[122:123], s[0:1], v139, s85, v[114:115]
	v_lshlrev_b64 v[116:117], 1, v[142:143]
	v_lshl_add_u64 v[122:123], v[122:123], 0, v[116:117]
	global_store_dwordx4 v[122:123], v[118:121], off
	v_pk_mul_f32 v[106:107], v[106:107], v[110:111]
	v_pk_add_f32 v[108:109], v[108:109], 1.0 op_sel_hi:[1,0]
	v_pk_add_f32 v[118:119], v[124:125], 1.0 op_sel_hi:[1,0]
	v_rcp_f32_e32 v108, v108
	v_rcp_f32_e32 v110, v118
	v_rcp_f32_e32 v111, v119
	v_rcp_f32_e32 v109, v109
	v_pk_mul_f32 v[96:97], v[92:93], v[96:97]
	v_exp_f32_e64 v92, -v92
	v_pk_mul_f32 v[106:107], v[110:111], v[106:107]
	v_exp_f32_e64 v110, -v98
	v_exp_f32_e64 v111, -v99
	v_pk_mul_f32 v[108:109], v[108:109], v[112:113]
	v_exp_f32_e64 v112, -v100
	v_exp_f32_e64 v113, -v101
	v_pk_add_f32 v[110:111], v[110:111], 1.0 op_sel_hi:[1,0]
	v_pk_mul_f32 v[98:99], v[98:99], v[102:103]
	v_rcp_f32_e32 v110, v110
	v_rcp_f32_e32 v111, v111
	v_pk_add_f32 v[112:113], v[112:113], 1.0 op_sel_hi:[1,0]
	v_pk_mul_f32 v[100:101], v[100:101], v[104:105]
	v_rcp_f32_e32 v112, v112
	v_rcp_f32_e32 v113, v113
	v_pk_mul_f32 v[102:103], v[110:111], v[98:99]
	v_cvt_pk_bf16_f32 v98, v106, v107
	v_cvt_pk_bf16_f32 v99, v108, v109
	v_pk_mul_f32 v[104:105], v[112:113], v[100:101]
	v_cvt_pk_bf16_f32 v100, v102, v103
	v_exp_f32_e64 v102, -v90
	v_exp_f32_e64 v103, -v91
	v_cvt_pk_bf16_f32 v101, v104, v105
	v_or_b32_e32 v104, 16, v139
	v_exp_f32_e64 v93, -v93
	v_mad_i64_i32 v[104:105], s[0:1], v104, s85, v[114:115]
	v_lshl_add_u64 v[104:105], v[104:105], 0, v[116:117]
	global_store_dwordx4 v[104:105], v[98:101], off
	v_pk_mul_f32 v[90:91], v[90:91], v[94:95]
	v_pk_add_f32 v[92:93], v[92:93], 1.0 op_sel_hi:[1,0]
	v_pk_add_f32 v[98:99], v[102:103], 1.0 op_sel_hi:[1,0]
	v_rcp_f32_e32 v92, v92
	v_rcp_f32_e32 v94, v98
	v_rcp_f32_e32 v95, v99
	v_rcp_f32_e32 v93, v93
	v_pk_mul_f32 v[80:81], v[76:77], v[80:81]
	v_exp_f32_e64 v76, -v76
	v_pk_mul_f32 v[90:91], v[94:95], v[90:91]
	v_exp_f32_e64 v94, -v82
	v_exp_f32_e64 v95, -v83
	v_pk_mul_f32 v[92:93], v[92:93], v[96:97]
	v_exp_f32_e64 v96, -v84
	v_exp_f32_e64 v97, -v85
	v_pk_add_f32 v[94:95], v[94:95], 1.0 op_sel_hi:[1,0]
	v_pk_mul_f32 v[82:83], v[82:83], v[86:87]
	v_rcp_f32_e32 v94, v94
	v_rcp_f32_e32 v95, v95
	v_pk_add_f32 v[96:97], v[96:97], 1.0 op_sel_hi:[1,0]
	v_pk_mul_f32 v[84:85], v[84:85], v[88:89]
	v_rcp_f32_e32 v96, v96
	v_rcp_f32_e32 v97, v97
	v_pk_mul_f32 v[86:87], v[94:95], v[82:83]
	v_exp_f32_e64 v77, -v77
	v_cvt_pk_bf16_f32 v82, v90, v91
	v_pk_mul_f32 v[88:89], v[96:97], v[84:85]
	v_cvt_pk_bf16_f32 v83, v92, v93
	v_cvt_pk_bf16_f32 v84, v86, v87
	v_exp_f32_e64 v86, -v74
	v_exp_f32_e64 v87, -v75
	v_cvt_pk_bf16_f32 v85, v88, v89
	v_or_b32_e32 v88, 32, v139
	v_mad_i64_i32 v[88:89], s[0:1], v88, s85, v[114:115]
	v_lshl_add_u64 v[88:89], v[88:89], 0, v[116:117]
	v_pk_add_f32 v[76:77], v[76:77], 1.0 op_sel_hi:[1,0]
	global_store_dwordx4 v[88:89], v[82:85], off
	v_rcp_f32_e32 v76, v76
	v_rcp_f32_e32 v77, v77
	v_pk_add_f32 v[82:83], v[86:87], 1.0 op_sel_hi:[1,0]
	v_pk_mul_f32 v[74:75], v[74:75], v[78:79]
	v_rcp_f32_e32 v78, v82
	v_rcp_f32_e32 v79, v83
	v_pk_mul_f32 v[76:77], v[76:77], v[80:81]
	v_exp_f32_e64 v80, -v68
	v_exp_f32_e64 v81, -v69
	v_pk_mul_f32 v[74:75], v[78:79], v[74:75]
	v_exp_f32_e64 v78, -v66
	v_exp_f32_e64 v79, -v67
	v_pk_add_f32 v[80:81], v[80:81], 1.0 op_sel_hi:[1,0]
	v_pk_mul_f32 v[68:69], v[68:69], v[72:73]
	v_rcp_f32_e32 v80, v80
	v_pk_add_f32 v[78:79], v[78:79], 1.0 op_sel_hi:[1,0]
	v_rcp_f32_e32 v81, v81
	v_rcp_f32_e32 v78, v78
	v_rcp_f32_e32 v79, v79
	v_pk_mul_f32 v[66:67], v[66:67], v[70:71]
	v_pk_mul_f32 v[72:73], v[80:81], v[68:69]
	v_pk_mul_f32 v[64:65], v[60:61], v[64:65]
	v_pk_mul_f32 v[70:71], v[78:79], v[66:67]
	v_cvt_pk_bf16_f32 v66, v74, v75
	v_cvt_pk_bf16_f32 v67, v76, v77
	v_exp_f32_e64 v60, -v60
	v_cvt_pk_bf16_f32 v68, v70, v71
	v_cvt_pk_bf16_f32 v69, v72, v73
	v_exp_f32_e64 v72, -v58
	v_exp_f32_e64 v73, -v59
	v_or_b32_e32 v70, 48, v139
	v_exp_f32_e64 v61, -v61
	v_mad_i64_i32 v[70:71], s[0:1], v70, s85, v[114:115]
	v_lshl_add_u64 v[70:71], v[70:71], 0, v[116:117]
	global_store_dwordx4 v[70:71], v[66:69], off
	v_pk_mul_f32 v[58:59], v[58:59], v[62:63]
	v_pk_add_f32 v[60:61], v[60:61], 1.0 op_sel_hi:[1,0]
	v_pk_add_f32 v[66:67], v[72:73], 1.0 op_sel_hi:[1,0]
	v_rcp_f32_e32 v60, v60
	v_rcp_f32_e32 v62, v66
	v_rcp_f32_e32 v63, v67
	v_rcp_f32_e32 v61, v61
	v_add_u32_e32 v68, 0x80, v139
	v_pk_mul_f32 v[48:49], v[44:45], v[48:49]
	v_pk_mul_f32 v[58:59], v[62:63], v[58:59]
	v_exp_f32_e64 v62, -v50
	v_exp_f32_e64 v63, -v51
	v_pk_mul_f32 v[60:61], v[60:61], v[64:65]
	v_exp_f32_e64 v64, -v52
	v_exp_f32_e64 v65, -v53
	v_pk_add_f32 v[62:63], v[62:63], 1.0 op_sel_hi:[1,0]
	v_pk_mul_f32 v[50:51], v[50:51], v[54:55]
	v_rcp_f32_e32 v62, v62
	v_rcp_f32_e32 v63, v63
	v_pk_add_f32 v[64:65], v[64:65], 1.0 op_sel_hi:[1,0]
	v_pk_mul_f32 v[52:53], v[52:53], v[56:57]
	v_rcp_f32_e32 v64, v64
	v_rcp_f32_e32 v65, v65
	v_pk_mul_f32 v[54:55], v[62:63], v[50:51]
	v_cvt_pk_bf16_f32 v50, v58, v59
	v_cvt_pk_bf16_f32 v51, v60, v61
	v_pk_mul_f32 v[56:57], v[64:65], v[52:53]
	v_cvt_pk_bf16_f32 v52, v54, v55
	v_exp_f32_e64 v54, -v42
	v_exp_f32_e64 v55, -v43
	v_exp_f32_e64 v44, -v44
	v_exp_f32_e64 v45, -v45
	v_cvt_pk_bf16_f32 v53, v56, v57
	v_mad_i64_i32 v[56:57], s[0:1], v68, s85, v[114:115]
	v_lshl_add_u64 v[56:57], v[56:57], 0, v[116:117]
	global_store_dwordx4 v[56:57], v[50:53], off
	v_pk_mul_f32 v[42:43], v[42:43], v[46:47]
	v_pk_add_f32 v[44:45], v[44:45], 1.0 op_sel_hi:[1,0]
	v_pk_add_f32 v[50:51], v[54:55], 1.0 op_sel_hi:[1,0]
	v_rcp_f32_e32 v44, v44
	v_rcp_f32_e32 v46, v50
	v_rcp_f32_e32 v47, v51
	v_rcp_f32_e32 v45, v45
	v_pk_mul_f32 v[32:33], v[28:29], v[32:33]
	v_exp_f32_e64 v28, -v28
	v_pk_mul_f32 v[42:43], v[46:47], v[42:43]
	v_exp_f32_e64 v46, -v34
	v_exp_f32_e64 v47, -v35
	v_pk_mul_f32 v[44:45], v[44:45], v[48:49]
	v_exp_f32_e64 v48, -v36
	v_exp_f32_e64 v49, -v37
	v_pk_add_f32 v[46:47], v[46:47], 1.0 op_sel_hi:[1,0]
	v_pk_mul_f32 v[34:35], v[34:35], v[38:39]
	v_rcp_f32_e32 v46, v46
	v_rcp_f32_e32 v47, v47
	v_pk_add_f32 v[48:49], v[48:49], 1.0 op_sel_hi:[1,0]
	v_pk_mul_f32 v[36:37], v[36:37], v[40:41]
	v_rcp_f32_e32 v48, v48
	v_rcp_f32_e32 v49, v49
	v_pk_mul_f32 v[38:39], v[46:47], v[34:35]
	v_cvt_pk_bf16_f32 v34, v42, v43
	v_cvt_pk_bf16_f32 v35, v44, v45
	v_pk_mul_f32 v[40:41], v[48:49], v[36:37]
	v_cvt_pk_bf16_f32 v36, v38, v39
	v_exp_f32_e64 v38, -v26
	v_exp_f32_e64 v39, -v27
	v_cvt_pk_bf16_f32 v37, v40, v41
	v_add_u32_e32 v40, 0x90, v139
	v_exp_f32_e64 v29, -v29
	v_mad_i64_i32 v[40:41], s[0:1], v40, s85, v[114:115]
	v_lshl_add_u64 v[40:41], v[40:41], 0, v[116:117]
	global_store_dwordx4 v[40:41], v[34:37], off
	v_pk_mul_f32 v[26:27], v[26:27], v[30:31]
	v_pk_add_f32 v[28:29], v[28:29], 1.0 op_sel_hi:[1,0]
	v_pk_add_f32 v[34:35], v[38:39], 1.0 op_sel_hi:[1,0]
	v_rcp_f32_e32 v28, v28
	v_rcp_f32_e32 v30, v34
	v_rcp_f32_e32 v31, v35
	v_rcp_f32_e32 v29, v29
	v_pk_mul_f32 v[16:17], v[12:13], v[16:17]
	v_exp_f32_e64 v12, -v12
	v_pk_mul_f32 v[26:27], v[30:31], v[26:27]
	v_exp_f32_e64 v30, -v18
	v_exp_f32_e64 v31, -v19
	v_pk_mul_f32 v[28:29], v[28:29], v[32:33]
	v_exp_f32_e64 v32, -v20
	v_exp_f32_e64 v33, -v21
	v_pk_add_f32 v[30:31], v[30:31], 1.0 op_sel_hi:[1,0]
	v_pk_mul_f32 v[18:19], v[18:19], v[22:23]
	v_rcp_f32_e32 v30, v30
	v_rcp_f32_e32 v31, v31
	v_pk_add_f32 v[32:33], v[32:33], 1.0 op_sel_hi:[1,0]
	v_pk_mul_f32 v[20:21], v[20:21], v[24:25]
	v_rcp_f32_e32 v32, v32
	v_rcp_f32_e32 v33, v33
	v_pk_mul_f32 v[22:23], v[30:31], v[18:19]
	v_cvt_pk_bf16_f32 v18, v26, v27
	v_cvt_pk_bf16_f32 v19, v28, v29
	v_pk_mul_f32 v[24:25], v[32:33], v[20:21]
	v_cvt_pk_bf16_f32 v20, v22, v23
	v_exp_f32_e64 v22, -v10
	v_exp_f32_e64 v23, -v11
	v_cvt_pk_bf16_f32 v21, v24, v25
	v_add_u32_e32 v24, 0xa0, v139
	v_exp_f32_e64 v13, -v13
	v_mad_i64_i32 v[24:25], s[0:1], v24, s85, v[114:115]
	v_lshl_add_u64 v[24:25], v[24:25], 0, v[116:117]
	global_store_dwordx4 v[24:25], v[18:21], off
	v_pk_mul_f32 v[10:11], v[10:11], v[14:15]
	v_pk_add_f32 v[12:13], v[12:13], 1.0 op_sel_hi:[1,0]
	v_pk_add_f32 v[18:19], v[22:23], 1.0 op_sel_hi:[1,0]
	v_rcp_f32_e32 v12, v12
	v_rcp_f32_e32 v14, v18
	v_rcp_f32_e32 v15, v19
	v_rcp_f32_e32 v13, v13
	s_andn2_b64 vcc, exec, s[2:3]
	v_pk_mul_f32 v[10:11], v[14:15], v[10:11]
	v_exp_f32_e64 v14, -v2
	v_exp_f32_e64 v15, -v3
	v_pk_mul_f32 v[12:13], v[12:13], v[16:17]
	v_exp_f32_e64 v16, -v4
	v_exp_f32_e64 v17, -v5
	v_pk_add_f32 v[14:15], v[14:15], 1.0 op_sel_hi:[1,0]
	v_pk_mul_f32 v[2:3], v[2:3], v[6:7]
	v_rcp_f32_e32 v14, v14
	v_rcp_f32_e32 v15, v15
	v_pk_add_f32 v[16:17], v[16:17], 1.0 op_sel_hi:[1,0]
	v_pk_mul_f32 v[4:5], v[4:5], v[8:9]
	v_rcp_f32_e32 v16, v16
	v_rcp_f32_e32 v17, v17
	v_pk_mul_f32 v[6:7], v[14:15], v[2:3]
	v_cvt_pk_bf16_f32 v2, v10, v11
	v_cvt_pk_bf16_f32 v3, v12, v13
	v_pk_mul_f32 v[8:9], v[16:17], v[4:5]
	v_cvt_pk_bf16_f32 v4, v6, v7
	v_add_u32_e32 v6, 0xb0, v139
	v_mad_i64_i32 v[6:7], s[0:1], v6, s85, v[114:115]
	v_cvt_pk_bf16_f32 v5, v8, v9
	v_lshl_add_u64 v[6:7], v[6:7], 0, v[116:117]
	s_mov_b64 s[0:1], -1
	global_store_dwordx4 v[6:7], v[2:5], off
	s_cbranch_vccnz .LBB0_152
	s_andn2_b64 vcc, exec, s[6:7]
	v_mov_b64 v[4:5], 0
	s_cbranch_vccnz .LBB0_151
	s_barrier
	s_branch .LBB0_151

.LBB0_235:
	v_and_b32_e32 v3, 48, v2
	v_lshlrev_b32_e32 v4, 6, v2
	s_movk_i32 s3, 0x3c0
	v_lshlrev_b32_e32 v2, 2, v2
	s_and_b32 s64, s15, 3
	s_lshl_b32 s2, s14, 13
	v_and_or_b32 v3, v4, s3, v3
	v_and_b32_e32 v2, 32, v2
	s_lshl_b32 s79, s14, 6
	v_bitop3_b32 v4, v3, s2, v2 bitop3:0xde
	s_lshl_b32 s2, s64, 12
	s_add_u32 s34, s6, 0x80
	s_addc_u32 s35, s7, 0
	s_add_i32 s81, s65, 0x18000
	v_bitop3_b32 v2, v3, s2, v2 bitop3:0xde
	s_waitcnt vmcnt(2)
	s_barrier
	s_mov_b32 s2, m0
	s_mov_b32 m0, s81
	s_nop 4
	global_load_lds_dwordx4 v131, s[34:35]
	s_mov_b32 m0, s2
	s_add_u32 s34, s6, 0x58080
	s_addc_u32 s35, s7, 0
	s_add_i32 s84, s65, 0x1a000
	s_mov_b32 s2, m0
	s_mov_b32 m0, s84
	s_nop 4
	global_load_lds_dwordx4 v131, s[34:35]
	s_mov_b32 m0, s2
	s_add_u32 s34, s10, 0x80
	s_addc_u32 s35, s11, 0
	s_add_i32 s85, s65, 0x8000
	s_mov_b32 s2, m0
	s_mov_b32 m0, s85
	s_nop 4
	global_load_lds_dwordx4 v130, s[34:35]
	s_mov_b32 m0, s2
	s_add_u32 s34, s10, 0x58080
	s_addc_u32 s35, s11, 0
	s_add_i32 s86, s65, 0xa000
	s_mov_b32 s2, m0
	s_mov_b32 m0, s86
	s_nop 4
	global_load_lds_dwordx4 v130, s[34:35]
	s_mov_b32 m0, s2
	s_add_u32 s34, s6, 0xb0080
	s_addc_u32 s35, s7, 0
	s_add_i32 s87, s65, 0x1c000
	s_mov_b32 s2, m0
	s_mov_b32 m0, s87
	s_nop 4
	global_load_lds_dwordx4 v131, s[34:35]
	s_mov_b32 m0, s2
	s_add_u32 s34, s6, 0x108080
	s_addc_u32 s35, s7, 0
	s_add_i32 s88, s65, 0x1e000
	s_mov_b32 s2, m0
	s_mov_b32 m0, s88
	s_nop 4
	global_load_lds_dwordx4 v131, s[34:35]
	s_mov_b32 m0, s2
	s_waitcnt vmcnt(6)
	s_add_i32 s89, s65, 0xc000
	s_add_u32 s90, s70, s1
	v_mov_b32_e32 v106, 0
	v_add_u32_e32 v2, 0, v2
	s_addc_u32 s91, s71, s0
	s_mov_b32 s92, -2
	s_mov_b64 s[52:53], 0x15cb0080
	v_add_u32_e32 v132, 0x10000, v2
	v_add_u32_e32 v133, 0x14000, v2
	v_add_u32_e32 v134, 0, v4
	v_add_u32_e32 v135, 0x18000, v2
	v_add_u32_e32 v136, 0x1c000, v2
	s_waitcnt lgkmcnt(0)
	s_barrier
	ds_read_b128 v[138:141], v132
	ds_read_b128 v[142:145], v132 offset:1024
	ds_read_b128 v[146:149], v132 offset:2048
	ds_read_b128 v[150:153], v132 offset:3072
	ds_read_b128 v[154:157], v133
	ds_read_b128 v[158:161], v133 offset:1024
	ds_read_b128 v[166:169], v133 offset:2048
	ds_read_b128 v[170:173], v133 offset:3072
	s_add_u32 s0, s52, 0xea350080
	s_addc_u32 s1, s53, -1
	s_cmp_lg_u32 s92, 40
	s_cselect_b32 s3, s0, 0
	s_cselect_b32 s2, s1, 0
	s_add_u32 s0, s10, s3
	s_addc_u32 s1, s11, s2
	s_add_u32 s34, s0, 0x80
	s_addc_u32 s35, s1, 0
	s_add_u32 s54, s6, s3
	s_addc_u32 s55, s7, s2
	ds_read_b128 v[174:177], v134
	ds_read_b128 v[184:187], v134 offset:1024
	ds_read_b128 v[188:191], v134 offset:2048
	ds_read_b128 v[192:195], v134 offset:3072
	ds_read_b128 v[196:199], v134 offset:4096
	ds_read_b128 v[200:203], v134 offset:5120
	ds_read_b128 v[204:207], v134 offset:6144
	ds_read_b128 v[208:211], v134 offset:7168
	s_add_u32 s94, s90, s52
	s_addc_u32 s95, s91, s53
	s_mov_b32 s2, m0
	s_mov_b32 m0, s89
	s_nop 4
	global_load_lds_dwordx4 v130, s[94:95]
	s_mov_b32 m0, s2
	s_add_u32 s94, s94, 0x58000
	s_addc_u32 s95, s95, 0
	s_add_i32 s2, s65, 0xe000
	s_mov_b32 s3, m0
	s_mov_b32 m0, s2
	s_nop 4
	global_load_lds_dwordx4 v130, s[94:95]
	s_mov_b32 m0, s3
	s_waitcnt vmcnt(8)
	s_waitcnt lgkmcnt(0)
	s_barrier
	s_waitcnt lgkmcnt(7)
	v_mfma_f32_16x16x32_bf16 v[2:5], v[138:141], v[174:177], 0
	v_mfma_f32_16x16x32_bf16 v[6:9], v[146:149], v[174:177], 0
	s_waitcnt lgkmcnt(5)
	v_mfma_f32_16x16x32_bf16 v[30:33], v[138:141], v[188:191], 0
	v_mfma_f32_16x16x32_bf16 v[34:37], v[146:149], v[188:191], 0
	s_waitcnt lgkmcnt(3)
	v_mfma_f32_16x16x32_bf16 v[54:57], v[138:141], v[196:199], 0
	v_mfma_f32_16x16x32_bf16 v[50:53], v[146:149], v[196:199], 0
	s_waitcnt lgkmcnt(1)
	v_mfma_f32_16x16x32_bf16 v[70:73], v[138:141], v[204:207], 0
	v_mfma_f32_16x16x32_bf16 v[62:65], v[146:149], v[204:207], 0
	v_mfma_f32_16x16x32_bf16 v[2:5], v[142:145], v[184:187], v[2:5]
	v_mfma_f32_16x16x32_bf16 v[6:9], v[150:153], v[184:187], v[6:9]
	v_mfma_f32_16x16x32_bf16 v[30:33], v[142:145], v[192:195], v[30:33]
	v_mfma_f32_16x16x32_bf16 v[34:37], v[150:153], v[192:195], v[34:37]
	v_mfma_f32_16x16x32_bf16 v[54:57], v[142:145], v[200:203], v[54:57]
	v_mfma_f32_16x16x32_bf16 v[50:53], v[150:153], v[200:203], v[50:53]
	s_waitcnt lgkmcnt(0)
	v_mfma_f32_16x16x32_bf16 v[70:73], v[142:145], v[208:211], v[70:73]
	v_mfma_f32_16x16x32_bf16 v[62:65], v[150:153], v[208:211], v[62:65]
	v_mfma_f32_16x16x32_bf16 v[10:13], v[154:157], v[174:177], 0
	v_mfma_f32_16x16x32_bf16 v[14:17], v[166:169], v[174:177], 0
	v_mfma_f32_16x16x32_bf16 v[22:25], v[154:157], v[188:191], 0
	v_mfma_f32_16x16x32_bf16 v[18:21], v[166:169], v[188:191], 0
	v_mfma_f32_16x16x32_bf16 v[38:41], v[154:157], v[196:199], 0
	v_mfma_f32_16x16x32_bf16 v[26:29], v[166:169], v[196:199], 0
	v_mfma_f32_16x16x32_bf16 v[46:49], v[154:157], v[204:207], 0
	v_mfma_f32_16x16x32_bf16 v[42:45], v[166:169], v[204:207], 0
	v_mfma_f32_16x16x32_bf16 v[10:13], v[158:161], v[184:187], v[10:13]
	v_mfma_f32_16x16x32_bf16 v[14:17], v[170:173], v[184:187], v[14:17]
	v_mfma_f32_16x16x32_bf16 v[22:25], v[158:161], v[192:195], v[22:25]
	v_mfma_f32_16x16x32_bf16 v[18:21], v[170:173], v[192:195], v[18:21]
	v_mfma_f32_16x16x32_bf16 v[38:41], v[158:161], v[200:203], v[38:41]
	v_mfma_f32_16x16x32_bf16 v[26:29], v[170:173], v[200:203], v[26:29]
	v_mfma_f32_16x16x32_bf16 v[46:49], v[158:161], v[208:211], v[46:49]
	v_mfma_f32_16x16x32_bf16 v[42:45], v[170:173], v[208:211], v[42:45]
	s_barrier
	s_add_u32 s94, s54, 0x58000
	ds_read_b128 v[174:177], v134 offset:16384
	ds_read_b128 v[184:187], v134 offset:17408
	ds_read_b128 v[188:191], v134 offset:18432
	ds_read_b128 v[192:195], v134 offset:19456
	ds_read_b128 v[196:199], v134 offset:20480
	ds_read_b128 v[200:203], v134 offset:21504
	ds_read_b128 v[204:207], v134 offset:22528
	ds_read_b128 v[208:211], v134 offset:23552
	s_mov_b32 s2, m0
	s_mov_b32 m0, s73
	s_nop 4
	global_load_lds_dwordx4 v131, s[54:55]
	s_mov_b32 m0, s2
	s_addc_u32 s95, s55, 0
	s_mov_b32 s2, m0
	s_mov_b32 m0, s74
	s_nop 4
	global_load_lds_dwordx4 v131, s[94:95]
	s_mov_b32 m0, s2
	s_add_u32 s94, s54, 0xb0000
	s_addc_u32 s95, s55, 0
	s_mov_b32 s2, m0
	s_mov_b32 m0, s75
	s_nop 4
	global_load_lds_dwordx4 v131, s[94:95]
	s_mov_b32 m0, s2
	s_add_u32 s94, s54, 0x108000
	s_addc_u32 s95, s55, 0
	s_mov_b32 s2, m0
	s_mov_b32 m0, s76
	s_nop 4
	global_load_lds_dwordx4 v131, s[94:95]
	s_mov_b32 m0, s2
	s_add_u32 s94, s0, 0x58000
	s_mov_b32 s2, m0
	s_mov_b32 m0, s65
	s_nop 4
	global_load_lds_dwordx4 v130, s[0:1]
	s_mov_b32 m0, s2
	s_addc_u32 s95, s1, 0
	s_mov_b32 s2, m0
	s_mov_b32 m0, s77
	s_nop 4
	global_load_lds_dwordx4 v130, s[94:95]
	s_mov_b32 m0, s2
	s_waitcnt vmcnt(8)
	s_waitcnt lgkmcnt(0)
	s_barrier
	s_waitcnt lgkmcnt(7)
	v_mfma_f32_16x16x32_bf16 v[82:85], v[138:141], v[174:177], 0
	v_mfma_f32_16x16x32_bf16 v[74:77], v[146:149], v[174:177], 0
	s_waitcnt lgkmcnt(5)
	v_mfma_f32_16x16x32_bf16 v[98:101], v[138:141], v[188:191], 0
	v_mfma_f32_16x16x32_bf16 v[90:93], v[146:149], v[188:191], 0
	s_waitcnt lgkmcnt(3)
	v_mfma_f32_16x16x32_bf16 v[114:117], v[138:141], v[196:199], 0
	v_mfma_f32_16x16x32_bf16 v[110:113], v[146:149], v[196:199], 0
	s_waitcnt lgkmcnt(1)
	v_mfma_f32_16x16x32_bf16 v[126:129], v[138:141], v[204:207], 0
	v_mfma_f32_16x16x32_bf16 v[122:125], v[146:149], v[204:207], 0
	v_mfma_f32_16x16x32_bf16 v[82:85], v[142:145], v[184:187], v[82:85]
	v_mfma_f32_16x16x32_bf16 v[74:77], v[150:153], v[184:187], v[74:77]
	v_mfma_f32_16x16x32_bf16 v[98:101], v[142:145], v[192:195], v[98:101]
	v_mfma_f32_16x16x32_bf16 v[90:93], v[150:153], v[192:195], v[90:93]
	v_mfma_f32_16x16x32_bf16 v[114:117], v[142:145], v[200:203], v[114:117]
	v_mfma_f32_16x16x32_bf16 v[110:113], v[150:153], v[200:203], v[110:113]
	s_waitcnt lgkmcnt(0)
	v_mfma_f32_16x16x32_bf16 v[126:129], v[142:145], v[208:211], v[126:129]
	v_mfma_f32_16x16x32_bf16 v[122:125], v[150:153], v[208:211], v[122:125]
	v_mfma_f32_16x16x32_bf16 v[66:69], v[154:157], v[174:177], 0
	v_mfma_f32_16x16x32_bf16 v[58:61], v[166:169], v[174:177], 0
	v_mfma_f32_16x16x32_bf16 v[86:89], v[154:157], v[188:191], 0
	v_mfma_f32_16x16x32_bf16 v[78:81], v[166:169], v[188:191], 0
	v_mfma_f32_16x16x32_bf16 v[102:105], v[154:157], v[196:199], 0
	v_mfma_f32_16x16x32_bf16 v[94:97], v[166:169], v[196:199], 0
	v_mfma_f32_16x16x32_bf16 v[118:121], v[154:157], v[204:207], 0
	v_mfma_f32_16x16x32_bf16 v[106:109], v[166:169], v[204:207], 0
	v_mfma_f32_16x16x32_bf16 v[66:69], v[158:161], v[184:187], v[66:69]
	v_mfma_f32_16x16x32_bf16 v[58:61], v[170:173], v[184:187], v[58:61]
	v_mfma_f32_16x16x32_bf16 v[86:89], v[158:161], v[192:195], v[86:89]
	v_mfma_f32_16x16x32_bf16 v[78:81], v[170:173], v[192:195], v[78:81]
	v_mfma_f32_16x16x32_bf16 v[102:105], v[158:161], v[200:203], v[102:105]
	v_mfma_f32_16x16x32_bf16 v[94:97], v[170:173], v[200:203], v[94:97]
	v_mfma_f32_16x16x32_bf16 v[118:121], v[158:161], v[208:211], v[118:121]
	v_mfma_f32_16x16x32_bf16 v[106:109], v[170:173], v[208:211], v[106:109]
	s_barrier
	ds_read_b128 v[138:141], v135
	ds_read_b128 v[142:145], v135 offset:1024
	ds_read_b128 v[146:149], v135 offset:2048
	ds_read_b128 v[150:153], v135 offset:3072
	ds_read_b128 v[154:157], v136
	ds_read_b128 v[158:161], v136 offset:1024
	ds_read_b128 v[166:169], v136 offset:2048
	ds_read_b128 v[170:173], v136 offset:3072
	ds_read_b128 v[174:177], v134 offset:32768
	ds_read_b128 v[184:187], v134 offset:33792
	ds_read_b128 v[188:191], v134 offset:34816
	ds_read_b128 v[192:195], v134 offset:35840
	ds_read_b128 v[196:199], v134 offset:36864
	ds_read_b128 v[200:203], v134 offset:37888
	ds_read_b128 v[204:207], v134 offset:38912
	ds_read_b128 v[208:211], v134 offset:39936
	s_add_u32 s94, s0, 0xb0000
	s_addc_u32 s95, s1, 0
	s_mov_b32 s2, m0
	s_mov_b32 m0, s78
	s_nop 4
	global_load_lds_dwordx4 v130, s[94:95]
	s_mov_b32 m0, s2
	s_add_u32 s94, s0, 0x108000
	s_addc_u32 s95, s1, 0
	s_mov_b32 s2, m0
	s_mov_b32 m0, s80
	s_nop 4
	global_load_lds_dwordx4 v130, s[94:95]
	s_mov_b32 m0, s2
	s_waitcnt vmcnt(8)
	s_waitcnt lgkmcnt(0)
	s_barrier
	s_waitcnt lgkmcnt(7)
	v_mfma_f32_16x16x32_bf16 v[2:5], v[138:141], v[174:177], v[2:5]
	v_mfma_f32_16x16x32_bf16 v[6:9], v[146:149], v[174:177], v[6:9]
	s_waitcnt lgkmcnt(5)
	v_mfma_f32_16x16x32_bf16 v[30:33], v[138:141], v[188:191], v[30:33]
	v_mfma_f32_16x16x32_bf16 v[34:37], v[146:149], v[188:191], v[34:37]
	s_waitcnt lgkmcnt(3)
	v_mfma_f32_16x16x32_bf16 v[54:57], v[138:141], v[196:199], v[54:57]
	v_mfma_f32_16x16x32_bf16 v[50:53], v[146:149], v[196:199], v[50:53]
	s_waitcnt lgkmcnt(1)
	v_mfma_f32_16x16x32_bf16 v[70:73], v[138:141], v[204:207], v[70:73]
	v_mfma_f32_16x16x32_bf16 v[62:65], v[146:149], v[204:207], v[62:65]
	v_mfma_f32_16x16x32_bf16 v[2:5], v[142:145], v[184:187], v[2:5]
	v_mfma_f32_16x16x32_bf16 v[6:9], v[150:153], v[184:187], v[6:9]
	v_mfma_f32_16x16x32_bf16 v[30:33], v[142:145], v[192:195], v[30:33]
	v_mfma_f32_16x16x32_bf16 v[34:37], v[150:153], v[192:195], v[34:37]
	v_mfma_f32_16x16x32_bf16 v[54:57], v[142:145], v[200:203], v[54:57]
	v_mfma_f32_16x16x32_bf16 v[50:53], v[150:153], v[200:203], v[50:53]
	s_waitcnt lgkmcnt(0)
	v_mfma_f32_16x16x32_bf16 v[70:73], v[142:145], v[208:211], v[70:73]
	v_mfma_f32_16x16x32_bf16 v[62:65], v[150:153], v[208:211], v[62:65]
	v_mfma_f32_16x16x32_bf16 v[10:13], v[154:157], v[174:177], v[10:13]
	v_mfma_f32_16x16x32_bf16 v[14:17], v[166:169], v[174:177], v[14:17]
	v_mfma_f32_16x16x32_bf16 v[22:25], v[154:157], v[188:191], v[22:25]
	v_mfma_f32_16x16x32_bf16 v[18:21], v[166:169], v[188:191], v[18:21]
	v_mfma_f32_16x16x32_bf16 v[38:41], v[154:157], v[196:199], v[38:41]
	v_mfma_f32_16x16x32_bf16 v[26:29], v[166:169], v[196:199], v[26:29]
	v_mfma_f32_16x16x32_bf16 v[46:49], v[154:157], v[204:207], v[46:49]
	v_mfma_f32_16x16x32_bf16 v[42:45], v[166:169], v[204:207], v[42:45]
	v_mfma_f32_16x16x32_bf16 v[10:13], v[158:161], v[184:187], v[10:13]
	v_mfma_f32_16x16x32_bf16 v[14:17], v[170:173], v[184:187], v[14:17]
	v_mfma_f32_16x16x32_bf16 v[22:25], v[158:161], v[192:195], v[22:25]
	v_mfma_f32_16x16x32_bf16 v[18:21], v[170:173], v[192:195], v[18:21]
	v_mfma_f32_16x16x32_bf16 v[38:41], v[158:161], v[200:203], v[38:41]
	v_mfma_f32_16x16x32_bf16 v[26:29], v[170:173], v[200:203], v[26:29]
	v_mfma_f32_16x16x32_bf16 v[46:49], v[158:161], v[208:211], v[46:49]
	v_mfma_f32_16x16x32_bf16 v[42:45], v[170:173], v[208:211], v[42:45]
	s_barrier
	s_add_u32 s94, s54, 0x80
	s_addc_u32 s95, s55, 0
	ds_read_b128 v[174:177], v134 offset:49152
	ds_read_b128 v[184:187], v134 offset:50176
	ds_read_b128 v[188:191], v134 offset:51200
	ds_read_b128 v[192:195], v134 offset:52224
	ds_read_b128 v[196:199], v134 offset:53248
	ds_read_b128 v[200:203], v134 offset:54272
	ds_read_b128 v[204:207], v134 offset:55296
	ds_read_b128 v[208:211], v134 offset:56320
	s_mov_b32 s2, m0
	s_mov_b32 m0, s81
	s_nop 4
	global_load_lds_dwordx4 v131, s[94:95]
	s_mov_b32 m0, s2
	s_add_u32 s94, s54, 0x58080
	s_addc_u32 s95, s55, 0
	s_mov_b32 s2, m0
	s_mov_b32 m0, s84
	s_nop 4
	global_load_lds_dwordx4 v131, s[94:95]
	s_mov_b32 m0, s2
	s_add_u32 s94, s54, 0xb0080
	s_addc_u32 s95, s55, 0
	s_mov_b32 s2, m0
	s_mov_b32 m0, s87
	s_nop 4
	global_load_lds_dwordx4 v131, s[94:95]
	s_mov_b32 m0, s2
	s_add_u32 s54, s54, 0x108080
	s_addc_u32 s55, s55, 0
	s_mov_b32 s2, m0
	s_mov_b32 m0, s88
	s_nop 4
	global_load_lds_dwordx4 v131, s[54:55]
	s_mov_b32 m0, s2
	s_add_u32 s0, s0, 0x58080
	s_mov_b32 s2, m0
	s_mov_b32 m0, s85
	s_nop 4
	global_load_lds_dwordx4 v130, s[34:35]
	s_mov_b32 m0, s2
	s_addc_u32 s1, s1, 0
	s_mov_b32 s2, m0
	s_mov_b32 m0, s86
	s_nop 4
	global_load_lds_dwordx4 v130, s[0:1]
	s_mov_b32 m0, s2
	s_waitcnt vmcnt(8)
	s_waitcnt lgkmcnt(0)
	s_barrier
	s_waitcnt lgkmcnt(7)
	v_mfma_f32_16x16x32_bf16 v[82:85], v[138:141], v[174:177], v[82:85]
	v_mfma_f32_16x16x32_bf16 v[74:77], v[146:149], v[174:177], v[74:77]
	s_waitcnt lgkmcnt(5)
	v_mfma_f32_16x16x32_bf16 v[98:101], v[138:141], v[188:191], v[98:101]
	v_mfma_f32_16x16x32_bf16 v[90:93], v[146:149], v[188:191], v[90:93]
	s_waitcnt lgkmcnt(3)
	v_mfma_f32_16x16x32_bf16 v[114:117], v[138:141], v[196:199], v[114:117]
	v_mfma_f32_16x16x32_bf16 v[110:113], v[146:149], v[196:199], v[110:113]
	s_waitcnt lgkmcnt(1)
	v_mfma_f32_16x16x32_bf16 v[126:129], v[138:141], v[204:207], v[126:129]
	v_mfma_f32_16x16x32_bf16 v[122:125], v[146:149], v[204:207], v[122:125]
	v_mfma_f32_16x16x32_bf16 v[82:85], v[142:145], v[184:187], v[82:85]
	v_mfma_f32_16x16x32_bf16 v[74:77], v[150:153], v[184:187], v[74:77]
	v_mfma_f32_16x16x32_bf16 v[98:101], v[142:145], v[192:195], v[98:101]
	v_mfma_f32_16x16x32_bf16 v[90:93], v[150:153], v[192:195], v[90:93]
	v_mfma_f32_16x16x32_bf16 v[114:117], v[142:145], v[200:203], v[114:117]
	v_mfma_f32_16x16x32_bf16 v[110:113], v[150:153], v[200:203], v[110:113]
	s_waitcnt lgkmcnt(0)
	v_mfma_f32_16x16x32_bf16 v[126:129], v[142:145], v[208:211], v[126:129]
	v_mfma_f32_16x16x32_bf16 v[122:125], v[150:153], v[208:211], v[122:125]
	v_mfma_f32_16x16x32_bf16 v[66:69], v[154:157], v[174:177], v[66:69]
	v_mfma_f32_16x16x32_bf16 v[58:61], v[166:169], v[174:177], v[58:61]
	v_mfma_f32_16x16x32_bf16 v[86:89], v[154:157], v[188:191], v[86:89]
	v_mfma_f32_16x16x32_bf16 v[78:81], v[166:169], v[188:191], v[78:81]
	v_mfma_f32_16x16x32_bf16 v[102:105], v[154:157], v[196:199], v[102:105]
	v_mfma_f32_16x16x32_bf16 v[94:97], v[166:169], v[196:199], v[94:97]
	v_mfma_f32_16x16x32_bf16 v[118:121], v[154:157], v[204:207], v[118:121]
	v_mfma_f32_16x16x32_bf16 v[106:109], v[166:169], v[204:207], v[106:109]
	v_mfma_f32_16x16x32_bf16 v[66:69], v[158:161], v[184:187], v[66:69]
	v_mfma_f32_16x16x32_bf16 v[58:61], v[170:173], v[184:187], v[58:61]
	v_mfma_f32_16x16x32_bf16 v[86:89], v[158:161], v[192:195], v[86:89]
	v_mfma_f32_16x16x32_bf16 v[78:81], v[170:173], v[192:195], v[78:81]
	v_mfma_f32_16x16x32_bf16 v[102:105], v[158:161], v[200:203], v[102:105]
	v_mfma_f32_16x16x32_bf16 v[94:97], v[170:173], v[200:203], v[94:97]
	v_mfma_f32_16x16x32_bf16 v[118:121], v[158:161], v[208:211], v[118:121]
	v_mfma_f32_16x16x32_bf16 v[106:109], v[170:173], v[208:211], v[106:109]
	s_barrier
	s_add_i32 s92, s92, 2
	s_add_u32 s52, s52, 0x100
	s_addc_u32 s53, s53, 0
	s_cmp_lt_u32 s92, 42

.LBB0_413:
	v_lshrrev_b32_e32 v4, 1, v2
	v_and_b32_e32 v4, 24, v4
	v_and_b32_e32 v3, 15, v2
	v_lshlrev_b32_e32 v5, 1, v4
	v_lshlrev_b32_e32 v2, 2, v2
	v_lshl_or_b32 v143, s14, 6, v3
	v_lshl_or_b32 v3, v3, 6, v5
	s_lshl_b32 s2, s14, 13
	v_and_b32_e32 v2, 32, v2
	v_bitop3_b32 v5, v3, s2, v2 bitop3:0xde
	s_lshl_b32 s2, s15, 5
	s_and_b32 s2, s2, 0x60
	s_lshl_b32 s3, s2, 7
	s_add_u32 s14, s0, 0x80
	s_addc_u32 s15, s1, 0
	s_add_i32 s65, s45, 0x18000
	v_bitop3_b32 v2, v3, s3, v2 bitop3:0xde
	s_waitcnt vmcnt(2)
	s_barrier
	s_mov_b32 s3, m0
	s_mov_b32 m0, s65
	s_nop 4
	global_load_lds_dwordx4 v142, s[14:15]
	s_mov_b32 m0, s3
	s_add_u32 s14, s0, 0x20080
	s_addc_u32 s15, s1, 0
	s_add_i32 s66, s45, 0x1a000
	s_mov_b32 s3, m0
	s_mov_b32 m0, s66
	s_nop 4
	global_load_lds_dwordx4 v142, s[14:15]
	s_mov_b32 m0, s3
	s_add_u32 s14, s50, 0x80
	s_addc_u32 s15, s51, 0
	s_add_i32 s67, s45, 0x8000
	s_mov_b32 s3, m0
	s_mov_b32 m0, s67
	s_nop 4
	global_load_lds_dwordx4 v1, s[14:15]
	s_mov_b32 m0, s3
	s_add_u32 s14, s50, 0x20080
	s_addc_u32 s15, s51, 0
	s_add_i32 s73, s45, 0xa000
	s_mov_b32 s3, m0
	s_mov_b32 m0, s73
	s_nop 4
	global_load_lds_dwordx4 v1, s[14:15]
	s_mov_b32 m0, s3
	s_add_u32 s14, s0, 0x40080
	s_addc_u32 s15, s1, 0
	s_add_i32 s74, s45, 0x1c000
	s_mov_b32 s3, m0
	s_mov_b32 m0, s74
	s_nop 4
	global_load_lds_dwordx4 v142, s[14:15]
	s_mov_b32 m0, s3
	s_add_u32 s14, s0, 0x60080
	s_addc_u32 s15, s1, 0
	s_add_i32 s75, s45, 0x1e000
	s_mov_b32 s3, m0
	s_mov_b32 m0, s75
	s_nop 4
	global_load_lds_dwordx4 v142, s[14:15]
	s_mov_b32 m0, s3
	s_waitcnt vmcnt(6)
	s_add_i32 s76, s45, 0xc000
	s_cmpk_lt_u32 s5, 0x100
	v_mov_b64_e32 v[6:7], 0
	s_sext_i32_i8 s78, s4
	s_cselect_b64 s[24:25], -1, 0
	s_ashr_i32 s77, s72, 31
	v_or_b32_e32 v144, s2, v4
	v_mov_b64_e32 v[130:131], 0x840
	v_mov_b64_e32 v[132:133], 0x83f
	v_add_u32_e32 v145, 0, v2
	v_add_u32_e32 v146, 0, v5
	v_mov_b32_e32 v135, 0x3fb504f3
	s_waitcnt lgkmcnt(0)
	s_barrier
	s_branch .LBB0_416

.LBB0_418:
	s_ashr_i32 s37, s36, 31
	s_lshl_b64 s[14:15], s[36:37], 19
	s_add_u32 s38, s18, s14
	s_addc_u32 s39, s19, s15
	s_and_b64 s[14:15], s[4:5], exec
	s_cselect_b32 s14, s39, s51
	s_cselect_b32 s15, s38, s50
	s_ashr_i32 s27, s26, 31
	s_lshl_b64 s[34:35], s[26:27], 19
	s_add_u32 s42, s40, s34
	s_addc_u32 s43, s41, s35
	s_and_b64 s[34:35], s[4:5], exec
	s_cselect_b32 s27, s43, s1
	s_cselect_b32 s37, s42, s0
	s_add_u32 s79, s0, 0x100
	s_addc_u32 s80, s1, 0
	s_mov_b32 s81, -2
	v_add_u32_e32 v134, 0x10000, v145
	ds_read_b128 v[136:139], v134
	ds_read_b128 v[148:151], v134 offset:1024
	ds_read_b128 v[152:155], v134 offset:2048
	ds_read_b128 v[156:159], v134 offset:3072
	v_add_u32_e32 v134, 0x14000, v145
	ds_read_b128 v[160:163], v134
	ds_read_b128 v[164:167], v134 offset:1024
	ds_read_b128 v[168:171], v134 offset:2048
	ds_read_b128 v[172:175], v134 offset:3072
	s_add_u32 s0, s50, 0x100
	s_addc_u32 s1, s51, 0
	s_cmp_eq_u32 s81, 12
	s_cselect_b32 s34, s15, s0
	s_cselect_b32 s35, s14, s1
	s_cselect_b32 s54, s37, s79
	s_cselect_b32 s55, s27, s80
	s_add_u32 s52, s34, 0x80
	s_addc_u32 s53, s35, 0
	ds_read_b128 v[176:179], v146
	ds_read_b128 v[180:183], v146 offset:1024
	ds_read_b128 v[184:187], v146 offset:2048
	ds_read_b128 v[188:191], v146 offset:3072
	ds_read_b128 v[192:195], v146 offset:4096
	ds_read_b128 v[196:199], v146 offset:5120
	ds_read_b128 v[200:203], v146 offset:6144
	ds_read_b128 v[204:207], v146 offset:7168
	s_add_u32 s84, s50, 0x40080
	s_addc_u32 s85, s51, 0
	s_mov_b32 s2, m0
	s_mov_b32 m0, s76
	s_nop 4
	global_load_lds_dwordx4 v1, s[84:85]
	s_mov_b32 m0, s2
	s_add_u32 s50, s50, 0x60080
	s_addc_u32 s51, s51, 0
	s_add_i32 s2, s45, 0xe000
	s_mov_b32 s3, m0
	s_mov_b32 m0, s2
	s_nop 4
	global_load_lds_dwordx4 v1, s[50:51]
	s_mov_b32 m0, s3
	s_waitcnt vmcnt(8)
	s_waitcnt lgkmcnt(0)
	s_barrier
	s_waitcnt lgkmcnt(7)
	v_mfma_f32_16x16x32_bf16 v[122:125], v[136:139], v[176:179], 0
	v_mfma_f32_16x16x32_bf16 v[114:117], v[152:155], v[176:179], 0
	s_waitcnt lgkmcnt(5)
	v_mfma_f32_16x16x32_bf16 v[106:109], v[136:139], v[184:187], 0
	v_mfma_f32_16x16x32_bf16 v[98:101], v[152:155], v[184:187], 0
	s_waitcnt lgkmcnt(3)
	v_mfma_f32_16x16x32_bf16 v[90:93], v[136:139], v[192:195], 0
	v_mfma_f32_16x16x32_bf16 v[82:85], v[152:155], v[192:195], 0
	s_waitcnt lgkmcnt(1)
	v_mfma_f32_16x16x32_bf16 v[74:77], v[136:139], v[200:203], 0
	v_mfma_f32_16x16x32_bf16 v[66:69], v[152:155], v[200:203], 0
	v_mfma_f32_16x16x32_bf16 v[122:125], v[148:151], v[180:183], v[122:125]
	v_mfma_f32_16x16x32_bf16 v[114:117], v[156:159], v[180:183], v[114:117]
	v_mfma_f32_16x16x32_bf16 v[106:109], v[148:151], v[188:191], v[106:109]
	v_mfma_f32_16x16x32_bf16 v[98:101], v[156:159], v[188:191], v[98:101]
	v_mfma_f32_16x16x32_bf16 v[90:93], v[148:151], v[196:199], v[90:93]
	v_mfma_f32_16x16x32_bf16 v[82:85], v[156:159], v[196:199], v[82:85]
	s_waitcnt lgkmcnt(0)
	v_mfma_f32_16x16x32_bf16 v[74:77], v[148:151], v[204:207], v[74:77]
	v_mfma_f32_16x16x32_bf16 v[66:69], v[156:159], v[204:207], v[66:69]
	v_mfma_f32_16x16x32_bf16 v[126:129], v[160:163], v[176:179], 0
	v_mfma_f32_16x16x32_bf16 v[118:121], v[168:171], v[176:179], 0
	v_mfma_f32_16x16x32_bf16 v[110:113], v[160:163], v[184:187], 0
	v_mfma_f32_16x16x32_bf16 v[102:105], v[168:171], v[184:187], 0
	v_mfma_f32_16x16x32_bf16 v[94:97], v[160:163], v[192:195], 0
	v_mfma_f32_16x16x32_bf16 v[86:89], v[168:171], v[192:195], 0
	v_mfma_f32_16x16x32_bf16 v[78:81], v[160:163], v[200:203], 0
	v_mfma_f32_16x16x32_bf16 v[70:73], v[168:171], v[200:203], 0
	v_mfma_f32_16x16x32_bf16 v[126:129], v[164:167], v[180:183], v[126:129]
	v_mfma_f32_16x16x32_bf16 v[118:121], v[172:175], v[180:183], v[118:121]
	v_mfma_f32_16x16x32_bf16 v[110:113], v[164:167], v[188:191], v[110:113]
	v_mfma_f32_16x16x32_bf16 v[102:105], v[172:175], v[188:191], v[102:105]
	v_mfma_f32_16x16x32_bf16 v[94:97], v[164:167], v[196:199], v[94:97]
	v_mfma_f32_16x16x32_bf16 v[86:89], v[172:175], v[196:199], v[86:89]
	v_mfma_f32_16x16x32_bf16 v[78:81], v[164:167], v[204:207], v[78:81]
	v_mfma_f32_16x16x32_bf16 v[70:73], v[172:175], v[204:207], v[70:73]
	s_barrier
	s_add_u32 s50, s54, 0x20000
	ds_read_b128 v[176:179], v146 offset:16384
	ds_read_b128 v[180:183], v146 offset:17408
	ds_read_b128 v[184:187], v146 offset:18432
	ds_read_b128 v[188:191], v146 offset:19456
	ds_read_b128 v[192:195], v146 offset:20480
	ds_read_b128 v[196:199], v146 offset:21504
	ds_read_b128 v[200:203], v146 offset:22528
	ds_read_b128 v[204:207], v146 offset:23552
	s_mov_b32 s2, m0
	s_mov_b32 m0, s58
	s_nop 4
	global_load_lds_dwordx4 v142, s[54:55]
	s_mov_b32 m0, s2
	s_addc_u32 s51, s55, 0
	s_mov_b32 s2, m0
	s_mov_b32 m0, s59
	s_nop 4
	global_load_lds_dwordx4 v142, s[50:51]
	s_mov_b32 m0, s2
	s_add_u32 s50, s54, 0x40000
	s_addc_u32 s51, s55, 0
	s_mov_b32 s2, m0
	s_mov_b32 m0, s60
	s_nop 4
	global_load_lds_dwordx4 v142, s[50:51]
	s_mov_b32 m0, s2
	s_add_u32 s50, s54, 0x60000
	s_addc_u32 s51, s55, 0
	s_mov_b32 s2, m0
	s_mov_b32 m0, s61
	s_nop 4
	global_load_lds_dwordx4 v142, s[50:51]
	s_mov_b32 m0, s2
	s_add_u32 s50, s34, 0x20000
	s_mov_b32 s2, m0
	s_mov_b32 m0, s45
	s_nop 4
	global_load_lds_dwordx4 v1, s[34:35]
	s_mov_b32 m0, s2
	s_addc_u32 s51, s35, 0
	s_mov_b32 s2, m0
	s_mov_b32 m0, s62
	s_nop 4
	global_load_lds_dwordx4 v1, s[50:51]
	s_mov_b32 m0, s2
	s_waitcnt vmcnt(8)
	s_waitcnt lgkmcnt(0)
	s_barrier
	s_waitcnt lgkmcnt(7)
	v_mfma_f32_16x16x32_bf16 v[58:61], v[136:139], v[176:179], 0
	v_mfma_f32_16x16x32_bf16 v[50:53], v[152:155], v[176:179], 0
	s_waitcnt lgkmcnt(5)
	v_mfma_f32_16x16x32_bf16 v[42:45], v[136:139], v[184:187], 0
	v_mfma_f32_16x16x32_bf16 v[34:37], v[152:155], v[184:187], 0
	s_waitcnt lgkmcnt(3)
	v_mfma_f32_16x16x32_bf16 v[26:29], v[136:139], v[192:195], 0
	v_mfma_f32_16x16x32_bf16 v[18:21], v[152:155], v[192:195], 0
	s_waitcnt lgkmcnt(1)
	v_mfma_f32_16x16x32_bf16 v[10:13], v[136:139], v[200:203], 0
	v_mfma_f32_16x16x32_bf16 v[2:5], v[152:155], v[200:203], 0
	v_mfma_f32_16x16x32_bf16 v[58:61], v[148:151], v[180:183], v[58:61]
	v_mfma_f32_16x16x32_bf16 v[50:53], v[156:159], v[180:183], v[50:53]
	v_mfma_f32_16x16x32_bf16 v[42:45], v[148:151], v[188:191], v[42:45]
	v_mfma_f32_16x16x32_bf16 v[34:37], v[156:159], v[188:191], v[34:37]
	v_mfma_f32_16x16x32_bf16 v[26:29], v[148:151], v[196:199], v[26:29]
	v_mfma_f32_16x16x32_bf16 v[18:21], v[156:159], v[196:199], v[18:21]
	s_waitcnt lgkmcnt(0)
	v_mfma_f32_16x16x32_bf16 v[10:13], v[148:151], v[204:207], v[10:13]
	v_mfma_f32_16x16x32_bf16 v[2:5], v[156:159], v[204:207], v[2:5]
	v_mfma_f32_16x16x32_bf16 v[62:65], v[160:163], v[176:179], 0
	v_mfma_f32_16x16x32_bf16 v[54:57], v[168:171], v[176:179], 0
	v_mfma_f32_16x16x32_bf16 v[46:49], v[160:163], v[184:187], 0
	v_mfma_f32_16x16x32_bf16 v[38:41], v[168:171], v[184:187], 0
	v_mfma_f32_16x16x32_bf16 v[30:33], v[160:163], v[192:195], 0
	v_mfma_f32_16x16x32_bf16 v[22:25], v[168:171], v[192:195], 0
	v_mfma_f32_16x16x32_bf16 v[14:17], v[160:163], v[200:203], 0
	v_mfma_f32_16x16x32_bf16 v[6:9], v[168:171], v[200:203], 0
	v_mfma_f32_16x16x32_bf16 v[62:65], v[164:167], v[180:183], v[62:65]
	v_mfma_f32_16x16x32_bf16 v[54:57], v[172:175], v[180:183], v[54:57]
	v_mfma_f32_16x16x32_bf16 v[46:49], v[164:167], v[188:191], v[46:49]
	v_mfma_f32_16x16x32_bf16 v[38:41], v[172:175], v[188:191], v[38:41]
	v_mfma_f32_16x16x32_bf16 v[30:33], v[164:167], v[196:199], v[30:33]
	v_mfma_f32_16x16x32_bf16 v[22:25], v[172:175], v[196:199], v[22:25]
	v_mfma_f32_16x16x32_bf16 v[14:17], v[164:167], v[204:207], v[14:17]
	v_mfma_f32_16x16x32_bf16 v[6:9], v[172:175], v[204:207], v[6:9]
	s_barrier
	v_add_u32_e32 v134, 0x18000, v145
	ds_read_b128 v[136:139], v134
	ds_read_b128 v[148:151], v134 offset:1024
	ds_read_b128 v[152:155], v134 offset:2048
	ds_read_b128 v[156:159], v134 offset:3072
	v_add_u32_e32 v134, 0x1c000, v145
	ds_read_b128 v[160:163], v134
	ds_read_b128 v[164:167], v134 offset:1024
	ds_read_b128 v[168:171], v134 offset:2048
	ds_read_b128 v[172:175], v134 offset:3072
	ds_read_b128 v[176:179], v146 offset:32768
	ds_read_b128 v[180:183], v146 offset:33792
	ds_read_b128 v[184:187], v146 offset:34816
	ds_read_b128 v[188:191], v146 offset:35840
	ds_read_b128 v[192:195], v146 offset:36864
	ds_read_b128 v[196:199], v146 offset:37888
	ds_read_b128 v[200:203], v146 offset:38912
	ds_read_b128 v[204:207], v146 offset:39936
	s_add_u32 s50, s34, 0x40000
	s_addc_u32 s51, s35, 0
	s_mov_b32 s2, m0
	s_mov_b32 m0, s63
	s_nop 4
	global_load_lds_dwordx4 v1, s[50:51]
	s_mov_b32 m0, s2
	s_add_u32 s50, s34, 0x60000
	s_addc_u32 s51, s35, 0
	s_mov_b32 s2, m0
	s_mov_b32 m0, s64
	s_nop 4
	global_load_lds_dwordx4 v1, s[50:51]
	s_mov_b32 m0, s2
	s_waitcnt vmcnt(8)
	s_waitcnt lgkmcnt(0)
	s_barrier
	s_waitcnt lgkmcnt(7)
	v_mfma_f32_16x16x32_bf16 v[122:125], v[136:139], v[176:179], v[122:125]
	v_mfma_f32_16x16x32_bf16 v[114:117], v[152:155], v[176:179], v[114:117]
	s_waitcnt lgkmcnt(5)
	v_mfma_f32_16x16x32_bf16 v[106:109], v[136:139], v[184:187], v[106:109]
	v_mfma_f32_16x16x32_bf16 v[98:101], v[152:155], v[184:187], v[98:101]
	s_waitcnt lgkmcnt(3)
	v_mfma_f32_16x16x32_bf16 v[90:93], v[136:139], v[192:195], v[90:93]
	v_mfma_f32_16x16x32_bf16 v[82:85], v[152:155], v[192:195], v[82:85]
	s_waitcnt lgkmcnt(1)
	v_mfma_f32_16x16x32_bf16 v[74:77], v[136:139], v[200:203], v[74:77]
	v_mfma_f32_16x16x32_bf16 v[66:69], v[152:155], v[200:203], v[66:69]
	v_mfma_f32_16x16x32_bf16 v[122:125], v[148:151], v[180:183], v[122:125]
	v_mfma_f32_16x16x32_bf16 v[114:117], v[156:159], v[180:183], v[114:117]
	v_mfma_f32_16x16x32_bf16 v[106:109], v[148:151], v[188:191], v[106:109]
	v_mfma_f32_16x16x32_bf16 v[98:101], v[156:159], v[188:191], v[98:101]
	v_mfma_f32_16x16x32_bf16 v[90:93], v[148:151], v[196:199], v[90:93]
	v_mfma_f32_16x16x32_bf16 v[82:85], v[156:159], v[196:199], v[82:85]
	s_waitcnt lgkmcnt(0)
	v_mfma_f32_16x16x32_bf16 v[74:77], v[148:151], v[204:207], v[74:77]
	v_mfma_f32_16x16x32_bf16 v[66:69], v[156:159], v[204:207], v[66:69]
	v_mfma_f32_16x16x32_bf16 v[126:129], v[160:163], v[176:179], v[126:129]
	v_mfma_f32_16x16x32_bf16 v[118:121], v[168:171], v[176:179], v[118:121]
	v_mfma_f32_16x16x32_bf16 v[110:113], v[160:163], v[184:187], v[110:113]
	v_mfma_f32_16x16x32_bf16 v[102:105], v[168:171], v[184:187], v[102:105]
	v_mfma_f32_16x16x32_bf16 v[94:97], v[160:163], v[192:195], v[94:97]
	v_mfma_f32_16x16x32_bf16 v[86:89], v[168:171], v[192:195], v[86:89]
	v_mfma_f32_16x16x32_bf16 v[78:81], v[160:163], v[200:203], v[78:81]
	v_mfma_f32_16x16x32_bf16 v[70:73], v[168:171], v[200:203], v[70:73]
	v_mfma_f32_16x16x32_bf16 v[126:129], v[164:167], v[180:183], v[126:129]
	v_mfma_f32_16x16x32_bf16 v[118:121], v[172:175], v[180:183], v[118:121]
	v_mfma_f32_16x16x32_bf16 v[110:113], v[164:167], v[188:191], v[110:113]
	v_mfma_f32_16x16x32_bf16 v[102:105], v[172:175], v[188:191], v[102:105]
	v_mfma_f32_16x16x32_bf16 v[94:97], v[164:167], v[196:199], v[94:97]
	v_mfma_f32_16x16x32_bf16 v[86:89], v[172:175], v[196:199], v[86:89]
	v_mfma_f32_16x16x32_bf16 v[78:81], v[164:167], v[204:207], v[78:81]
	v_mfma_f32_16x16x32_bf16 v[70:73], v[172:175], v[204:207], v[70:73]
	s_barrier
	s_add_u32 s50, s54, 0x80
	s_addc_u32 s51, s55, 0
	ds_read_b128 v[176:179], v146 offset:49152
	ds_read_b128 v[180:183], v146 offset:50176
	ds_read_b128 v[184:187], v146 offset:51200
	ds_read_b128 v[188:191], v146 offset:52224
	ds_read_b128 v[192:195], v146 offset:53248
	ds_read_b128 v[196:199], v146 offset:54272
	ds_read_b128 v[200:203], v146 offset:55296
	ds_read_b128 v[204:207], v146 offset:56320
	s_mov_b32 s2, m0
	s_mov_b32 m0, s65
	s_nop 4
	global_load_lds_dwordx4 v142, s[50:51]
	s_mov_b32 m0, s2
	s_add_u32 s50, s54, 0x20080
	s_addc_u32 s51, s55, 0
	s_mov_b32 s2, m0
	s_mov_b32 m0, s66
	s_nop 4
	global_load_lds_dwordx4 v142, s[50:51]
	s_mov_b32 m0, s2
	s_add_u32 s50, s54, 0x40080
	s_addc_u32 s51, s55, 0
	s_mov_b32 s2, m0
	s_mov_b32 m0, s74
	s_nop 4
	global_load_lds_dwordx4 v142, s[50:51]
	s_mov_b32 m0, s2
	s_add_u32 s50, s54, 0x60080
	s_addc_u32 s51, s55, 0
	s_mov_b32 s2, m0
	s_mov_b32 m0, s75
	s_nop 4
	global_load_lds_dwordx4 v142, s[50:51]
	s_mov_b32 m0, s2
	s_add_u32 s34, s34, 0x20080
	s_mov_b32 s2, m0
	s_mov_b32 m0, s67
	s_nop 4
	global_load_lds_dwordx4 v1, s[52:53]
	s_mov_b32 m0, s2
	s_addc_u32 s35, s35, 0
	s_mov_b32 s2, m0
	s_mov_b32 m0, s73
	s_nop 4
	global_load_lds_dwordx4 v1, s[34:35]
	s_mov_b32 m0, s2
	s_waitcnt vmcnt(8)
	s_waitcnt lgkmcnt(0)
	s_barrier
	s_waitcnt lgkmcnt(7)
	v_mfma_f32_16x16x32_bf16 v[58:61], v[136:139], v[176:179], v[58:61]
	v_mfma_f32_16x16x32_bf16 v[50:53], v[152:155], v[176:179], v[50:53]
	s_waitcnt lgkmcnt(5)
	v_mfma_f32_16x16x32_bf16 v[42:45], v[136:139], v[184:187], v[42:45]
	v_mfma_f32_16x16x32_bf16 v[34:37], v[152:155], v[184:187], v[34:37]
	s_waitcnt lgkmcnt(3)
	v_mfma_f32_16x16x32_bf16 v[26:29], v[136:139], v[192:195], v[26:29]
	v_mfma_f32_16x16x32_bf16 v[18:21], v[152:155], v[192:195], v[18:21]
	s_waitcnt lgkmcnt(1)
	v_mfma_f32_16x16x32_bf16 v[10:13], v[136:139], v[200:203], v[10:13]
	v_mfma_f32_16x16x32_bf16 v[2:5], v[152:155], v[200:203], v[2:5]
	v_mfma_f32_16x16x32_bf16 v[58:61], v[148:151], v[180:183], v[58:61]
	v_mfma_f32_16x16x32_bf16 v[50:53], v[156:159], v[180:183], v[50:53]
	v_mfma_f32_16x16x32_bf16 v[42:45], v[148:151], v[188:191], v[42:45]
	v_mfma_f32_16x16x32_bf16 v[34:37], v[156:159], v[188:191], v[34:37]
	v_mfma_f32_16x16x32_bf16 v[26:29], v[148:151], v[196:199], v[26:29]
	v_mfma_f32_16x16x32_bf16 v[18:21], v[156:159], v[196:199], v[18:21]
	s_waitcnt lgkmcnt(0)
	v_mfma_f32_16x16x32_bf16 v[10:13], v[148:151], v[204:207], v[10:13]
	v_mfma_f32_16x16x32_bf16 v[2:5], v[156:159], v[204:207], v[2:5]
	v_mfma_f32_16x16x32_bf16 v[62:65], v[160:163], v[176:179], v[62:65]
	v_mfma_f32_16x16x32_bf16 v[54:57], v[168:171], v[176:179], v[54:57]
	v_mfma_f32_16x16x32_bf16 v[46:49], v[160:163], v[184:187], v[46:49]
	v_mfma_f32_16x16x32_bf16 v[38:41], v[168:171], v[184:187], v[38:41]
	v_mfma_f32_16x16x32_bf16 v[30:33], v[160:163], v[192:195], v[30:33]
	v_mfma_f32_16x16x32_bf16 v[22:25], v[168:171], v[192:195], v[22:25]
	v_mfma_f32_16x16x32_bf16 v[14:17], v[160:163], v[200:203], v[14:17]
	v_mfma_f32_16x16x32_bf16 v[6:9], v[168:171], v[200:203], v[6:9]
	v_mfma_f32_16x16x32_bf16 v[62:65], v[164:167], v[180:183], v[62:65]
	v_mfma_f32_16x16x32_bf16 v[54:57], v[172:175], v[180:183], v[54:57]
	v_mfma_f32_16x16x32_bf16 v[46:49], v[164:167], v[188:191], v[46:49]
	v_mfma_f32_16x16x32_bf16 v[38:41], v[172:175], v[188:191], v[38:41]
	v_mfma_f32_16x16x32_bf16 v[30:33], v[164:167], v[196:199], v[30:33]
	v_mfma_f32_16x16x32_bf16 v[22:25], v[172:175], v[196:199], v[22:25]
	v_mfma_f32_16x16x32_bf16 v[14:17], v[164:167], v[204:207], v[14:17]
	v_mfma_f32_16x16x32_bf16 v[6:9], v[172:175], v[204:207], v[6:9]
	s_barrier
	s_add_i32 s81, s81, 2
	s_add_u32 s79, s79, 0x100
	s_addc_u32 s80, s80, 0
	s_cmp_gt_u32 s81, 13
	s_mov_b64 s[50:51], s[0:1]

.LBB0_422:
	v_lshl_add_u32 v140, s44, 8, v143
	v_lshl_or_b32 v138, s78, 7, v144
	v_ashrrev_i32_e32 v141, 31, v140
	v_ashrrev_i32_e32 v139, 31, v138
	v_lshlrev_b64 v[136:137], 10, v[140:141]
	v_lshl_add_u64 v[136:137], v[136:137], 0, v[138:139]
	v_lshlrev_b64 v[136:137], 1, v[136:137]
	v_lshl_add_u64 v[148:149], s[16:17], 0, v[136:137]
	global_load_dwordx4 v[148:151], v[148:149], off
	v_mul_f32_e32 v134, 0xbfb8aa3b, v126
	v_mov_b32_e32 v126, v123
	v_mul_f32_e32 v123, 0xbfb8aa3b, v128
	v_mov_b32_e32 v128, v125
	v_mul_f32_e32 v125, 0xbfb8aa3b, v118
	v_mov_b32_e32 v118, v115
	v_mul_f32_e32 v115, 0xbfb8aa3b, v120
	v_mov_b32_e32 v120, v117
	v_exp_f32_e32 v117, v134
	v_mul_f32_e32 v127, 0xbfb8aa3b, v127
	v_exp_f32_e32 v127, v127
	v_exp_f32_e32 v123, v123
	v_add_f32_e32 v117, 1.0, v117
	v_rcp_f32_e32 v134, v117
	v_add_f32_e32 v127, 1.0, v127
	v_add_f32_e32 v141, 1.0, v123
	v_mul_f32_e32 v129, 0xbfb8aa3b, v129
	v_exp_f32_e32 v129, v129
	v_exp_f32_e32 v125, v125
	v_mul_f32_e32 v119, 0xbfb8aa3b, v119
	v_exp_f32_e32 v119, v119
	v_add_f32_e32 v129, 1.0, v129
	v_add_f32_e32 v147, 1.0, v125
	v_exp_f32_e32 v115, v115
	v_add_f32_e32 v158, 1.0, v119
	v_mul_f32_e32 v121, 0xbfb8aa3b, v121
	v_exp_f32_e32 v121, v121
	v_add_f32_e32 v159, 1.0, v115
	v_or_b32_e32 v152, 16, v140
	v_ashrrev_i32_e32 v153, 31, v152
	v_add_f32_e32 v160, 1.0, v121
	v_lshlrev_b64 v[152:153], 10, v[152:153]
	v_lshl_add_u64 v[152:153], v[152:153], 0, v[138:139]
	v_lshl_add_u64 v[154:155], s[6:7], 0, v[136:137]
	v_lshlrev_b64 v[152:153], 1, v[152:153]
	v_lshl_add_u64 v[156:157], s[16:17], 0, v[152:153]
	v_mul_f32_e32 v111, 0xbfb8aa3b, v111
	v_exp_f32_e32 v111, v111
	v_mul_f32_e32 v113, 0xbfb8aa3b, v113
	v_exp_f32_e32 v113, v113
	v_mul_f32_e32 v103, 0xbfb8aa3b, v103
	v_add_f32_e32 v111, 1.0, v111
	v_exp_f32_e32 v103, v103
	v_add_f32_e32 v113, 1.0, v113
	v_mul_f32_e32 v105, 0xbfb8aa3b, v105
	v_exp_f32_e32 v105, v105
	v_mul_f32_e32 v95, 0xbfb8aa3b, v95
	v_exp_f32_e32 v95, v95
	v_mul_f32_e32 v97, 0xbfb8aa3b, v97
	v_exp_f32_e32 v97, v97
	v_mul_f32_e32 v87, 0xbfb8aa3b, v87
	v_add_f32_e32 v95, 1.0, v95
	v_exp_f32_e32 v87, v87
	v_add_f32_e32 v97, 1.0, v97
	v_mul_f32_e32 v89, 0xbfb8aa3b, v89
	v_exp_f32_e32 v89, v89
	v_mul_f32_e32 v79, 0xbfb8aa3b, v79
	v_exp_f32_e32 v79, v79
	v_mul_f32_e32 v81, 0xbfb8aa3b, v81
	v_exp_f32_e32 v81, v81
	v_mul_f32_e32 v71, 0xbfb8aa3b, v71
	v_add_f32_e32 v79, 1.0, v79
	v_exp_f32_e32 v71, v71
	v_add_f32_e32 v81, 1.0, v81
	v_mul_f32_e32 v73, 0xbfb8aa3b, v73
	v_exp_f32_e32 v73, v73
	s_mov_b64 s[0:1], 0x40000
	v_mul_f32_e32 v63, 0xbfb8aa3b, v63
	v_exp_f32_e32 v63, v63
	v_mul_f32_e32 v65, 0xbfb8aa3b, v65
	v_exp_f32_e32 v65, v65
	v_mul_f32_e32 v55, 0xbfb8aa3b, v55
	v_add_f32_e32 v63, 1.0, v63
	v_exp_f32_e32 v55, v55
	v_add_f32_e32 v65, 1.0, v65
	v_mul_f32_e32 v57, 0xbfb8aa3b, v57
	v_exp_f32_e32 v57, v57
	v_mul_f32_e32 v47, 0xbfb8aa3b, v47
	v_exp_f32_e32 v47, v47
	s_waitcnt vmcnt(0)
	v_lshlrev_b32_e32 v123, 16, v148
	v_pk_mul_f32 v[122:123], v[122:123], v[134:135]
	v_rcp_f32_e32 v134, v127
	v_and_b32_e32 v127, 0xffff0000, v148
	v_lshlrev_b32_e32 v125, 16, v149
	v_lshlrev_b32_e32 v115, 16, v150
	v_pk_mul_f32 v[126:127], v[126:127], v[134:135]
	v_rcp_f32_e32 v134, v141
	v_add_f32_e32 v141, v122, v123
	v_and_b32_e32 v119, 0xffff0000, v150
	v_lshlrev_b32_e32 v117, 16, v151
	v_pk_mul_f32 v[124:125], v[124:125], v[134:135]
	v_rcp_f32_e32 v134, v129
	v_and_b32_e32 v129, 0xffff0000, v149
	v_and_b32_e32 v121, 0xffff0000, v151
	v_add_f32_e32 v47, 1.0, v47
	v_pk_mul_f32 v[128:129], v[128:129], v[134:135]
	v_rcp_f32_e32 v134, v147
	v_mul_f32_e32 v49, 0xbfb8aa3b, v49
	v_exp_f32_e32 v49, v49
	v_mul_f32_e32 v39, 0xbfb8aa3b, v39
	v_pk_mul_f32 v[122:123], v[114:115], v[134:135]
	v_rcp_f32_e32 v134, v158
	v_add_f32_e32 v114, v126, v127
	v_add_f32_e32 v115, v124, v125
	v_add_f32_e32 v124, v128, v129
	v_pk_mul_f32 v[118:119], v[118:119], v[134:135]
	v_rcp_f32_e32 v134, v159
	v_cvt_pk_bf16_f32 v114, v141, v114
	v_cvt_pk_bf16_f32 v115, v115, v124
	v_add_f32_e32 v124, v122, v123
	v_pk_mul_f32 v[122:123], v[116:117], v[134:135]
	v_rcp_f32_e32 v134, v160
	v_add_f32_e32 v116, v118, v119
	v_add_f32_e32 v117, v122, v123
	v_cvt_pk_bf16_f32 v116, v124, v116
	v_pk_mul_f32 v[118:119], v[120:121], v[134:135]
	v_add_f32_e32 v125, 1.0, v103
	v_add_f32_e32 v118, v118, v119
	v_cvt_pk_bf16_f32 v117, v117, v118
	global_store_dwordx4 v[154:155], v[114:117], off
	global_load_dwordx4 v[114:117], v[156:157], off
	v_mul_f32_e32 v118, 0xbfb8aa3b, v110
	v_mov_b32_e32 v110, v107
	v_mul_f32_e32 v107, 0xbfb8aa3b, v112
	v_mov_b32_e32 v112, v109
	v_mul_f32_e32 v109, 0xbfb8aa3b, v102
	v_mov_b32_e32 v102, v99
	v_mul_f32_e32 v99, 0xbfb8aa3b, v104
	v_mov_b32_e32 v104, v101
	v_exp_f32_e32 v101, v118
	v_exp_f32_e32 v107, v107
	v_exp_f32_e32 v109, v109
	v_exp_f32_e32 v99, v99
	v_add_f32_e32 v101, 1.0, v101
	v_rcp_f32_e32 v134, v101
	v_add_f32_e32 v120, 1.0, v107
	v_add_f32_e32 v124, 1.0, v109
	v_add_f32_e32 v126, 1.0, v99
	v_add_f32_e32 v127, 1.0, v105
	v_or_b32_e32 v118, 32, v140
	v_ashrrev_i32_e32 v119, 31, v118
	v_lshlrev_b64 v[118:119], 10, v[118:119]
	v_lshl_add_u64 v[118:119], v[118:119], 0, v[138:139]
	v_lshlrev_b64 v[118:119], 1, v[118:119]
	v_lshl_add_u64 v[122:123], s[16:17], 0, v[118:119]
	v_add_f32_e32 v49, 1.0, v49
	v_exp_f32_e32 v39, v39
	v_mul_f32_e32 v41, 0xbfb8aa3b, v41
	v_exp_f32_e32 v41, v41
	v_mul_f32_e32 v31, 0xbfb8aa3b, v31
	v_exp_f32_e32 v31, v31
	v_mul_f32_e32 v33, 0xbfb8aa3b, v33
	v_exp_f32_e32 v33, v33
	v_mul_f32_e32 v23, 0xbfb8aa3b, v23
	v_add_f32_e32 v31, 1.0, v31
	v_exp_f32_e32 v23, v23
	v_add_f32_e32 v33, 1.0, v33
	v_mul_f32_e32 v25, 0xbfb8aa3b, v25
	v_exp_f32_e32 v25, v25
	v_mul_f32_e32 v15, 0xbfb8aa3b, v15
	v_exp_f32_e32 v15, v15
	v_mul_f32_e32 v17, 0xbfb8aa3b, v17
	v_exp_f32_e32 v17, v17
	v_mul_f32_e32 v7, 0xbfb8aa3b, v7
	v_add_f32_e32 v15, 1.0, v15
	v_exp_f32_e32 v7, v7
	v_mul_f32_e32 v9, 0xbfb8aa3b, v9
	v_exp_f32_e32 v9, v9
	s_andn2_b64 vcc, exec, s[4:5]
	s_waitcnt vmcnt(0)
	v_lshlrev_b32_e32 v107, 16, v114
	v_pk_mul_f32 v[106:107], v[106:107], v[134:135]
	v_rcp_f32_e32 v134, v111
	v_and_b32_e32 v111, 0xffff0000, v114
	v_lshlrev_b32_e32 v109, 16, v115
	v_lshlrev_b32_e32 v99, 16, v116
	v_pk_mul_f32 v[110:111], v[110:111], v[134:135]
	v_rcp_f32_e32 v134, v120
	v_add_f32_e32 v114, v106, v107
	v_and_b32_e32 v103, 0xffff0000, v116
	v_lshlrev_b32_e32 v101, 16, v117
	v_pk_mul_f32 v[108:109], v[108:109], v[134:135]
	v_rcp_f32_e32 v134, v113
	v_and_b32_e32 v113, 0xffff0000, v115
	v_and_b32_e32 v105, 0xffff0000, v117
	v_lshl_add_u64 v[120:121], s[6:7], 0, v[152:153]
	v_pk_mul_f32 v[112:113], v[112:113], v[134:135]
	v_rcp_f32_e32 v134, v124
	s_nop 0
	v_pk_mul_f32 v[106:107], v[98:99], v[134:135]
	v_rcp_f32_e32 v134, v125
	v_add_f32_e32 v98, v110, v111
	v_add_f32_e32 v99, v108, v109
	v_add_f32_e32 v108, v112, v113
	v_pk_mul_f32 v[102:103], v[102:103], v[134:135]
	v_rcp_f32_e32 v134, v126
	v_cvt_pk_bf16_f32 v98, v114, v98
	v_cvt_pk_bf16_f32 v99, v99, v108
	v_add_f32_e32 v108, v106, v107
	v_pk_mul_f32 v[106:107], v[100:101], v[134:135]
	v_rcp_f32_e32 v134, v127
	v_add_f32_e32 v100, v102, v103
	v_add_f32_e32 v101, v106, v107
	v_cvt_pk_bf16_f32 v100, v108, v100
	v_pk_mul_f32 v[102:103], v[104:105], v[134:135]
	v_add_f32_e32 v109, 1.0, v87
	v_add_f32_e32 v102, v102, v103
	v_cvt_pk_bf16_f32 v101, v101, v102
	global_store_dwordx4 v[120:121], v[98:101], off
	global_load_dwordx4 v[98:101], v[122:123], off
	v_mul_f32_e32 v102, 0xbfb8aa3b, v94
	v_mov_b32_e32 v94, v91
	v_mul_f32_e32 v91, 0xbfb8aa3b, v96
	v_mov_b32_e32 v96, v93
	v_mul_f32_e32 v93, 0xbfb8aa3b, v86
	v_mov_b32_e32 v86, v83
	v_mul_f32_e32 v83, 0xbfb8aa3b, v88
	v_mov_b32_e32 v88, v85
	v_exp_f32_e32 v85, v102
	v_exp_f32_e32 v91, v91
	v_exp_f32_e32 v93, v93
	v_exp_f32_e32 v83, v83
	v_add_f32_e32 v85, 1.0, v85
	v_rcp_f32_e32 v134, v85
	v_add_f32_e32 v104, 1.0, v91
	v_add_f32_e32 v108, 1.0, v93
	v_add_f32_e32 v110, 1.0, v83
	v_add_f32_e32 v111, 1.0, v89
	v_or_b32_e32 v102, 48, v140
	v_ashrrev_i32_e32 v103, 31, v102
	v_lshlrev_b64 v[102:103], 10, v[102:103]
	v_lshl_add_u64 v[102:103], v[102:103], 0, v[138:139]
	v_lshlrev_b64 v[102:103], 1, v[102:103]
	v_lshl_add_u64 v[106:107], s[16:17], 0, v[102:103]
	s_waitcnt vmcnt(0)
	v_lshlrev_b32_e32 v91, 16, v98
	v_pk_mul_f32 v[90:91], v[90:91], v[134:135]
	v_rcp_f32_e32 v134, v95
	v_and_b32_e32 v95, 0xffff0000, v98
	v_lshlrev_b32_e32 v93, 16, v99
	v_lshlrev_b32_e32 v83, 16, v100
	v_pk_mul_f32 v[94:95], v[94:95], v[134:135]
	v_rcp_f32_e32 v134, v104
	v_add_f32_e32 v98, v90, v91
	v_and_b32_e32 v87, 0xffff0000, v100
	v_lshlrev_b32_e32 v85, 16, v101
	v_pk_mul_f32 v[92:93], v[92:93], v[134:135]
	v_rcp_f32_e32 v134, v97
	v_and_b32_e32 v97, 0xffff0000, v99
	v_and_b32_e32 v89, 0xffff0000, v101
	v_lshl_add_u64 v[104:105], s[6:7], 0, v[118:119]
	v_pk_mul_f32 v[96:97], v[96:97], v[134:135]
	v_rcp_f32_e32 v134, v108
	s_nop 0
	v_pk_mul_f32 v[90:91], v[82:83], v[134:135]
	v_rcp_f32_e32 v134, v109
	v_add_f32_e32 v82, v94, v95
	v_add_f32_e32 v83, v92, v93
	v_add_f32_e32 v92, v96, v97
	v_pk_mul_f32 v[86:87], v[86:87], v[134:135]
	v_rcp_f32_e32 v134, v110
	v_cvt_pk_bf16_f32 v82, v98, v82
	v_cvt_pk_bf16_f32 v83, v83, v92
	v_add_f32_e32 v92, v90, v91
	v_pk_mul_f32 v[90:91], v[84:85], v[134:135]
	v_rcp_f32_e32 v134, v111
	v_add_f32_e32 v84, v86, v87
	v_add_f32_e32 v85, v90, v91
	v_cvt_pk_bf16_f32 v84, v92, v84
	v_pk_mul_f32 v[86:87], v[88:89], v[134:135]
	v_add_f32_e32 v93, 1.0, v71
	v_add_f32_e32 v86, v86, v87
	v_cvt_pk_bf16_f32 v85, v85, v86
	global_store_dwordx4 v[104:105], v[82:85], off
	global_load_dwordx4 v[82:85], v[106:107], off
	v_mul_f32_e32 v86, 0xbfb8aa3b, v78
	v_mov_b32_e32 v78, v75
	v_mul_f32_e32 v75, 0xbfb8aa3b, v80
	v_mov_b32_e32 v80, v77
	v_mul_f32_e32 v77, 0xbfb8aa3b, v70
	v_mov_b32_e32 v70, v67
	v_mul_f32_e32 v67, 0xbfb8aa3b, v72
	v_mov_b32_e32 v72, v69
	v_exp_f32_e32 v69, v86
	v_exp_f32_e32 v75, v75
	v_exp_f32_e32 v77, v77
	v_exp_f32_e32 v67, v67
	v_add_f32_e32 v69, 1.0, v69
	v_rcp_f32_e32 v134, v69
	v_add_f32_e32 v88, 1.0, v75
	v_add_f32_e32 v92, 1.0, v77
	v_add_f32_e32 v94, 1.0, v67
	v_add_f32_e32 v95, 1.0, v73
	v_lshl_add_u64 v[86:87], v[136:137], 0, s[0:1]
	v_lshl_add_u64 v[90:91], s[16:17], 0, v[86:87]
	s_mov_b64 s[0:1], 0x48000
	s_waitcnt vmcnt(0)
	v_lshlrev_b32_e32 v75, 16, v82
	v_pk_mul_f32 v[74:75], v[74:75], v[134:135]
	v_rcp_f32_e32 v134, v79
	v_and_b32_e32 v79, 0xffff0000, v82
	v_lshlrev_b32_e32 v77, 16, v83
	v_lshlrev_b32_e32 v67, 16, v84
	v_pk_mul_f32 v[78:79], v[78:79], v[134:135]
	v_rcp_f32_e32 v134, v88
	v_add_f32_e32 v82, v74, v75
	v_and_b32_e32 v71, 0xffff0000, v84
	v_lshlrev_b32_e32 v69, 16, v85
	v_pk_mul_f32 v[76:77], v[76:77], v[134:135]
	v_rcp_f32_e32 v134, v81
	v_and_b32_e32 v81, 0xffff0000, v83
	v_and_b32_e32 v73, 0xffff0000, v85
	v_lshl_add_u64 v[88:89], s[6:7], 0, v[102:103]
	v_pk_mul_f32 v[80:81], v[80:81], v[134:135]
	v_rcp_f32_e32 v134, v92
	s_nop 0
	v_pk_mul_f32 v[74:75], v[66:67], v[134:135]
	v_rcp_f32_e32 v134, v93
	v_add_f32_e32 v66, v78, v79
	v_add_f32_e32 v67, v76, v77
	v_add_f32_e32 v76, v80, v81
	v_pk_mul_f32 v[70:71], v[70:71], v[134:135]
	v_rcp_f32_e32 v134, v94
	v_cvt_pk_bf16_f32 v66, v82, v66
	v_cvt_pk_bf16_f32 v67, v67, v76
	v_add_f32_e32 v76, v74, v75
	v_pk_mul_f32 v[74:75], v[68:69], v[134:135]
	v_rcp_f32_e32 v134, v95
	v_add_f32_e32 v68, v70, v71
	v_add_f32_e32 v69, v74, v75
	v_cvt_pk_bf16_f32 v68, v76, v68
	v_pk_mul_f32 v[70:71], v[72:73], v[134:135]
	v_add_f32_e32 v77, 1.0, v55
	v_add_f32_e32 v70, v70, v71
	v_cvt_pk_bf16_f32 v69, v69, v70
	global_store_dwordx4 v[88:89], v[66:69], off
	global_load_dwordx4 v[66:69], v[90:91], off
	v_mul_f32_e32 v70, 0xbfb8aa3b, v62
	v_mov_b32_e32 v62, v59
	v_mul_f32_e32 v59, 0xbfb8aa3b, v64
	v_mov_b32_e32 v64, v61
	v_mul_f32_e32 v61, 0xbfb8aa3b, v54
	v_mov_b32_e32 v54, v51
	v_mul_f32_e32 v51, 0xbfb8aa3b, v56
	v_mov_b32_e32 v56, v53
	v_exp_f32_e32 v53, v70
	v_exp_f32_e32 v59, v59
	v_exp_f32_e32 v61, v61
	v_exp_f32_e32 v51, v51
	v_add_f32_e32 v53, 1.0, v53
	v_rcp_f32_e32 v134, v53
	v_add_f32_e32 v72, 1.0, v59
	v_add_f32_e32 v76, 1.0, v61
	v_add_f32_e32 v78, 1.0, v51
	v_add_f32_e32 v79, 1.0, v57
	v_lshl_add_u64 v[70:71], v[136:137], 0, s[0:1]
	v_lshl_add_u64 v[74:75], s[16:17], 0, v[70:71]
	s_mov_b64 s[0:1], 0x50000
	s_waitcnt vmcnt(0)
	v_lshlrev_b32_e32 v59, 16, v66
	v_pk_mul_f32 v[58:59], v[58:59], v[134:135]
	v_rcp_f32_e32 v134, v63
	v_and_b32_e32 v63, 0xffff0000, v66
	v_lshlrev_b32_e32 v61, 16, v67
	v_lshlrev_b32_e32 v51, 16, v68
	v_pk_mul_f32 v[62:63], v[62:63], v[134:135]
	v_rcp_f32_e32 v134, v72
	v_add_f32_e32 v66, v58, v59
	v_and_b32_e32 v55, 0xffff0000, v68
	v_lshlrev_b32_e32 v53, 16, v69
	v_pk_mul_f32 v[60:61], v[60:61], v[134:135]
	v_rcp_f32_e32 v134, v65
	v_and_b32_e32 v65, 0xffff0000, v67
	v_and_b32_e32 v57, 0xffff0000, v69
	v_lshl_add_u64 v[72:73], s[6:7], 0, v[86:87]
	v_pk_mul_f32 v[64:65], v[64:65], v[134:135]
	v_rcp_f32_e32 v134, v76
	s_nop 0
	v_pk_mul_f32 v[58:59], v[50:51], v[134:135]
	v_rcp_f32_e32 v134, v77
	v_add_f32_e32 v50, v62, v63
	v_add_f32_e32 v51, v60, v61
	v_add_f32_e32 v60, v64, v65
	v_pk_mul_f32 v[54:55], v[54:55], v[134:135]
	v_rcp_f32_e32 v134, v78
	v_cvt_pk_bf16_f32 v50, v66, v50
	v_cvt_pk_bf16_f32 v51, v51, v60
	v_add_f32_e32 v60, v58, v59
	v_pk_mul_f32 v[58:59], v[52:53], v[134:135]
	v_rcp_f32_e32 v134, v79
	v_add_f32_e32 v52, v54, v55
	v_add_f32_e32 v53, v58, v59
	v_cvt_pk_bf16_f32 v52, v60, v52
	v_pk_mul_f32 v[54:55], v[56:57], v[134:135]
	v_add_f32_e32 v61, 1.0, v39
	v_add_f32_e32 v54, v54, v55
	v_cvt_pk_bf16_f32 v53, v53, v54
	global_store_dwordx4 v[72:73], v[50:53], off
	global_load_dwordx4 v[50:53], v[74:75], off
	v_mul_f32_e32 v54, 0xbfb8aa3b, v46
	v_mov_b32_e32 v46, v43
	v_mul_f32_e32 v43, 0xbfb8aa3b, v48
	v_mov_b32_e32 v48, v45
	v_mul_f32_e32 v45, 0xbfb8aa3b, v38
	v_mov_b32_e32 v38, v35
	v_mul_f32_e32 v35, 0xbfb8aa3b, v40
	v_mov_b32_e32 v40, v37
	v_exp_f32_e32 v37, v54
	v_exp_f32_e32 v43, v43
	v_exp_f32_e32 v45, v45
	v_exp_f32_e32 v35, v35
	v_add_f32_e32 v37, 1.0, v37
	v_rcp_f32_e32 v134, v37
	v_add_f32_e32 v56, 1.0, v43
	v_add_f32_e32 v60, 1.0, v45
	v_add_f32_e32 v62, 1.0, v35
	v_add_f32_e32 v63, 1.0, v41
	v_lshl_add_u64 v[54:55], v[136:137], 0, s[0:1]
	v_lshl_add_u64 v[58:59], s[16:17], 0, v[54:55]
	s_mov_b64 s[0:1], 0x58000
	s_waitcnt vmcnt(0)
	v_lshlrev_b32_e32 v43, 16, v50
	v_pk_mul_f32 v[42:43], v[42:43], v[134:135]
	v_rcp_f32_e32 v134, v47
	v_and_b32_e32 v47, 0xffff0000, v50
	v_lshlrev_b32_e32 v45, 16, v51
	v_lshlrev_b32_e32 v35, 16, v52
	v_pk_mul_f32 v[46:47], v[46:47], v[134:135]
	v_rcp_f32_e32 v134, v56
	v_add_f32_e32 v50, v42, v43
	v_and_b32_e32 v39, 0xffff0000, v52
	v_lshlrev_b32_e32 v37, 16, v53
	v_pk_mul_f32 v[44:45], v[44:45], v[134:135]
	v_rcp_f32_e32 v134, v49
	v_and_b32_e32 v49, 0xffff0000, v51
	v_and_b32_e32 v41, 0xffff0000, v53
	v_lshl_add_u64 v[56:57], s[6:7], 0, v[70:71]
	v_pk_mul_f32 v[48:49], v[48:49], v[134:135]
	v_rcp_f32_e32 v134, v60
	s_nop 0
	v_pk_mul_f32 v[42:43], v[34:35], v[134:135]
	v_rcp_f32_e32 v134, v61
	v_add_f32_e32 v34, v46, v47
	v_add_f32_e32 v35, v44, v45
	v_add_f32_e32 v44, v48, v49
	v_pk_mul_f32 v[38:39], v[38:39], v[134:135]
	v_rcp_f32_e32 v134, v62
	v_cvt_pk_bf16_f32 v34, v50, v34
	v_cvt_pk_bf16_f32 v35, v35, v44
	v_add_f32_e32 v44, v42, v43
	v_pk_mul_f32 v[42:43], v[36:37], v[134:135]
	v_rcp_f32_e32 v134, v63
	v_add_f32_e32 v36, v38, v39
	v_add_f32_e32 v37, v42, v43
	v_cvt_pk_bf16_f32 v36, v44, v36
	v_pk_mul_f32 v[38:39], v[40:41], v[134:135]
	v_add_f32_e32 v45, 1.0, v23
	v_add_f32_e32 v38, v38, v39
	v_cvt_pk_bf16_f32 v37, v37, v38
	global_store_dwordx4 v[56:57], v[34:37], off
	global_load_dwordx4 v[34:37], v[58:59], off
	v_mul_f32_e32 v38, 0xbfb8aa3b, v30
	v_mov_b32_e32 v30, v27
	v_mul_f32_e32 v27, 0xbfb8aa3b, v32
	v_mov_b32_e32 v32, v29
	v_mul_f32_e32 v29, 0xbfb8aa3b, v22
	v_mov_b32_e32 v22, v19
	v_mul_f32_e32 v19, 0xbfb8aa3b, v24
	v_mov_b32_e32 v24, v21
	v_exp_f32_e32 v21, v38
	v_exp_f32_e32 v27, v27
	v_exp_f32_e32 v29, v29
	v_exp_f32_e32 v19, v19
	v_add_f32_e32 v21, 1.0, v21
	v_rcp_f32_e32 v134, v21
	v_add_f32_e32 v40, 1.0, v27
	v_add_f32_e32 v44, 1.0, v29
	v_add_f32_e32 v46, 1.0, v19
	v_add_f32_e32 v47, 1.0, v25
	v_lshl_add_u64 v[38:39], v[136:137], 0, s[0:1]
	v_lshl_add_u64 v[42:43], s[16:17], 0, v[38:39]
	s_mov_b64 s[0:1], -1
	s_waitcnt vmcnt(0)
	v_lshlrev_b32_e32 v27, 16, v34
	v_pk_mul_f32 v[26:27], v[26:27], v[134:135]
	v_rcp_f32_e32 v134, v31
	v_and_b32_e32 v31, 0xffff0000, v34
	v_lshlrev_b32_e32 v29, 16, v35
	v_lshlrev_b32_e32 v19, 16, v36
	v_pk_mul_f32 v[30:31], v[30:31], v[134:135]
	v_rcp_f32_e32 v134, v40
	v_add_f32_e32 v34, v26, v27
	v_and_b32_e32 v23, 0xffff0000, v36
	v_lshlrev_b32_e32 v21, 16, v37
	v_pk_mul_f32 v[28:29], v[28:29], v[134:135]
	v_rcp_f32_e32 v134, v33
	v_and_b32_e32 v33, 0xffff0000, v35
	v_and_b32_e32 v25, 0xffff0000, v37
	v_lshl_add_u64 v[40:41], s[6:7], 0, v[54:55]
	v_pk_mul_f32 v[32:33], v[32:33], v[134:135]
	v_rcp_f32_e32 v134, v44
	s_nop 0
	v_pk_mul_f32 v[26:27], v[18:19], v[134:135]
	v_rcp_f32_e32 v134, v45
	v_add_f32_e32 v18, v30, v31
	v_add_f32_e32 v19, v28, v29
	v_add_f32_e32 v28, v32, v33
	v_pk_mul_f32 v[22:23], v[22:23], v[134:135]
	v_rcp_f32_e32 v134, v46
	v_cvt_pk_bf16_f32 v18, v34, v18
	v_cvt_pk_bf16_f32 v19, v19, v28
	v_add_f32_e32 v28, v26, v27
	v_pk_mul_f32 v[26:27], v[20:21], v[134:135]
	v_rcp_f32_e32 v134, v47
	v_add_f32_e32 v20, v22, v23
	v_add_f32_e32 v21, v26, v27
	v_cvt_pk_bf16_f32 v20, v28, v20
	v_pk_mul_f32 v[22:23], v[24:25], v[134:135]
	v_add_f32_e32 v25, 1.0, v7
	v_add_f32_e32 v22, v22, v23
	v_cvt_pk_bf16_f32 v21, v21, v22
	global_store_dwordx4 v[40:41], v[18:21], off
	global_load_dwordx4 v[18:21], v[42:43], off
	v_mul_f32_e32 v22, 0xbfb8aa3b, v14
	v_mov_b32_e32 v14, v11
	v_mul_f32_e32 v11, 0xbfb8aa3b, v16
	v_mov_b32_e32 v16, v13
	v_mul_f32_e32 v13, 0xbfb8aa3b, v6
	v_mov_b32_e32 v6, v3
	v_mul_f32_e32 v3, 0xbfb8aa3b, v8
	v_mov_b32_e32 v8, v5
	v_exp_f32_e32 v5, v22
	v_exp_f32_e32 v11, v11
	v_exp_f32_e32 v13, v13
	v_exp_f32_e32 v3, v3
	v_add_f32_e32 v5, 1.0, v5
	v_rcp_f32_e32 v134, v5
	v_add_f32_e32 v22, 1.0, v11
	v_add_f32_e32 v5, 1.0, v17
	v_add_f32_e32 v24, 1.0, v13
	v_add_f32_e32 v26, 1.0, v3
	s_waitcnt vmcnt(0)
	v_lshlrev_b32_e32 v11, 16, v18
	v_pk_mul_f32 v[10:11], v[10:11], v[134:135]
	v_rcp_f32_e32 v134, v15
	v_and_b32_e32 v15, 0xffff0000, v18
	v_lshlrev_b32_e32 v13, 16, v19
	v_and_b32_e32 v17, 0xffff0000, v19
	v_pk_mul_f32 v[14:15], v[14:15], v[134:135]
	v_rcp_f32_e32 v134, v22
	v_lshlrev_b32_e32 v3, 16, v20
	v_add_f32_e32 v19, v10, v11
	v_and_b32_e32 v7, 0xffff0000, v20
	v_pk_mul_f32 v[12:13], v[12:13], v[134:135]
	v_rcp_f32_e32 v134, v5
	v_add_f32_e32 v18, 1.0, v9
	v_lshlrev_b32_e32 v5, 16, v21
	v_and_b32_e32 v9, 0xffff0000, v21
	v_pk_mul_f32 v[16:17], v[16:17], v[134:135]
	v_rcp_f32_e32 v134, v24
	v_lshl_add_u64 v[22:23], s[6:7], 0, v[38:39]
	v_pk_mul_f32 v[10:11], v[2:3], v[134:135]
	v_rcp_f32_e32 v134, v25
	v_add_f32_e32 v2, v14, v15
	v_add_f32_e32 v3, v12, v13
	v_add_f32_e32 v12, v16, v17
	v_pk_mul_f32 v[6:7], v[6:7], v[134:135]
	v_rcp_f32_e32 v134, v26
	v_cvt_pk_bf16_f32 v2, v19, v2
	v_cvt_pk_bf16_f32 v3, v3, v12
	v_add_f32_e32 v12, v10, v11
	v_pk_mul_f32 v[10:11], v[4:5], v[134:135]
	v_rcp_f32_e32 v134, v18
	v_add_f32_e32 v4, v6, v7
	v_add_f32_e32 v5, v10, v11
	v_cvt_pk_bf16_f32 v4, v12, v4
	v_pk_mul_f32 v[6:7], v[8:9], v[134:135]
	s_nop 0
	v_add_f32_e32 v6, v6, v7
	v_cvt_pk_bf16_f32 v5, v5, v6
	global_store_dwordx4 v[22:23], v[2:5], off
	s_cbranch_vccnz .LBB0_415
	s_andn2_b64 vcc, exec, s[10:11]
	v_mov_b64 v[4:5], 0
	s_cbranch_vccnz .LBB0_414
	s_barrier
	s_branch .LBB0_414

.LBB0_551:
	v_lshrrev_b32_e32 v4, 1, v2
	v_and_b32_e32 v4, 24, v4
	v_and_b32_e32 v3, 15, v2
	v_lshlrev_b32_e32 v5, 1, v4
	v_lshlrev_b32_e32 v2, 2, v2
	v_lshl_or_b32 v137, s10, 6, v3
	v_lshl_or_b32 v3, v3, 6, v5
	s_lshl_b32 s2, s10, 13
	v_and_b32_e32 v2, 32, v2
	v_bitop3_b32 v5, v3, s2, v2 bitop3:0xde
	s_lshl_b32 s2, s11, 5
	s_and_b32 s2, s2, 0x60
	s_lshl_b32 s3, s2, 7
	s_add_u32 s10, s0, 0x80
	s_addc_u32 s11, s1, 0
	s_add_i32 s63, s43, 0x18000
	v_bitop3_b32 v6, v3, s3, v2 bitop3:0xde
	s_waitcnt vmcnt(2)
	s_barrier
	s_mov_b32 s3, m0
	s_mov_b32 m0, s63
	s_nop 4
	global_load_lds_dwordx4 v136, s[10:11]
	s_mov_b32 m0, s3
	s_add_u32 s10, s0, 0x20080
	s_addc_u32 s11, s1, 0
	s_add_i32 s64, s43, 0x1a000
	s_mov_b32 s3, m0
	s_mov_b32 m0, s64
	s_nop 4
	global_load_lds_dwordx4 v136, s[10:11]
	s_mov_b32 m0, s3
	s_add_u32 s10, s44, 0x80
	s_addc_u32 s11, s45, 0
	s_add_i32 s65, s43, 0x8000
	s_mov_b32 s3, m0
	s_mov_b32 m0, s65
	s_nop 4
	global_load_lds_dwordx4 v1, s[10:11]
	s_mov_b32 m0, s3
	s_add_u32 s10, s44, 0x20080
	s_addc_u32 s11, s45, 0
	s_add_i32 s66, s43, 0xa000
	s_mov_b32 s3, m0
	s_mov_b32 m0, s66
	s_nop 4
	global_load_lds_dwordx4 v1, s[10:11]
	s_mov_b32 m0, s3
	s_add_u32 s10, s0, 0x40080
	s_addc_u32 s11, s1, 0
	s_add_i32 s67, s43, 0x1c000
	s_mov_b32 s3, m0
	s_mov_b32 m0, s67
	s_nop 4
	global_load_lds_dwordx4 v136, s[10:11]
	s_mov_b32 m0, s3
	s_add_u32 s10, s0, 0x60080
	s_addc_u32 s11, s1, 0
	s_add_i32 s73, s43, 0x1e000
	s_mov_b32 s3, m0
	s_mov_b32 m0, s73
	s_nop 4
	global_load_lds_dwordx4 v136, s[10:11]
	s_mov_b32 m0, s3
	s_waitcnt vmcnt(6)
	s_add_i32 s74, s43, 0xc000
	s_cmpk_lt_u32 s5, 0x100
	v_mov_b64_e32 v[2:3], 0
	s_sext_i32_i16 s78, s4
	s_cselect_b64 s[10:11], -1, 0
	s_ashr_i32 s75, s72, 31
	v_or_b32_e32 v138, s2, v4
	v_mov_b64_e32 v[130:131], 0x16b0
	v_mov_b64_e32 v[132:133], 0x16af
	v_add_u32_e32 v139, 0, v6
	v_add_u32_e32 v140, 0, v5
	s_mov_b32 s76, 0xc3dc0000
	s_movk_i32 s77, 0xb00
	v_mov_b32_e32 v141, 0x43dc0000
	s_waitcnt vmcnt(3)
	s_waitcnt vmcnt(2) lgkmcnt(0)
	s_barrier
	s_branch .LBB0_554

.LBB0_556:
	s_ashr_i32 s27, s26, 31
	s_lshl_b64 s[14:15], s[26:27], 19
	s_add_u32 s36, s16, s14
	s_addc_u32 s37, s17, s15
	s_and_b64 s[14:15], s[4:5], exec
	s_cselect_b32 s14, s37, s45
	s_cselect_b32 s15, s36, s44
	s_ashr_i32 s25, s24, 31
	s_lshl_b64 s[34:35], s[24:25], 19
	s_add_u32 s38, s40, s34
	s_addc_u32 s39, s41, s35
	s_and_b64 s[34:35], s[4:5], exec
	s_cselect_b32 s25, s39, s1
	s_cselect_b32 s27, s38, s0
	s_add_u32 s79, s0, 0x100
	s_addc_u32 s80, s1, 0
	s_mov_b32 s81, -2
	v_add_u32_e32 v134, 0x10000, v139
	ds_read_b128 v[142:145], v134
	ds_read_b128 v[146:149], v134 offset:1024
	ds_read_b128 v[150:153], v134 offset:2048
	ds_read_b128 v[154:157], v134 offset:3072
	v_add_u32_e32 v134, 0x14000, v139
	ds_read_b128 v[158:161], v134
	ds_read_b128 v[162:165], v134 offset:1024
	ds_read_b128 v[166:169], v134 offset:2048
	ds_read_b128 v[170:173], v134 offset:3072
	s_add_u32 s0, s44, 0x100
	s_addc_u32 s1, s45, 0
	s_cmp_eq_u32 s81, 12
	s_cselect_b32 s34, s15, s0
	s_cselect_b32 s35, s14, s1
	s_cselect_b32 s52, s27, s79
	s_cselect_b32 s53, s25, s80
	s_add_u32 s50, s34, 0x80
	s_addc_u32 s51, s35, 0
	ds_read_b128 v[174:177], v140
	ds_read_b128 v[178:181], v140 offset:1024
	ds_read_b128 v[182:185], v140 offset:2048
	ds_read_b128 v[186:189], v140 offset:3072
	ds_read_b128 v[190:193], v140 offset:4096
	ds_read_b128 v[194:197], v140 offset:5120
	ds_read_b128 v[198:201], v140 offset:6144
	ds_read_b128 v[202:205], v140 offset:7168
	s_add_u32 s84, s44, 0x40080
	s_addc_u32 s85, s45, 0
	s_mov_b32 s2, m0
	s_mov_b32 m0, s74
	s_nop 4
	global_load_lds_dwordx4 v1, s[84:85]
	s_mov_b32 m0, s2
	s_add_u32 s44, s44, 0x60080
	s_addc_u32 s45, s45, 0
	s_add_i32 s2, s43, 0xe000
	s_mov_b32 s3, m0
	s_mov_b32 m0, s2
	s_nop 4
	global_load_lds_dwordx4 v1, s[44:45]
	s_mov_b32 m0, s3
	s_waitcnt vmcnt(8)
	s_waitcnt lgkmcnt(0)
	s_barrier
	s_waitcnt lgkmcnt(7)
	v_mfma_f32_16x16x32_bf16 v[122:125], v[142:145], v[174:177], 0
	v_mfma_f32_16x16x32_bf16 v[114:117], v[150:153], v[174:177], 0
	s_waitcnt lgkmcnt(5)
	v_mfma_f32_16x16x32_bf16 v[106:109], v[142:145], v[182:185], 0
	v_mfma_f32_16x16x32_bf16 v[98:101], v[150:153], v[182:185], 0
	s_waitcnt lgkmcnt(3)
	v_mfma_f32_16x16x32_bf16 v[90:93], v[142:145], v[190:193], 0
	v_mfma_f32_16x16x32_bf16 v[82:85], v[150:153], v[190:193], 0
	s_waitcnt lgkmcnt(1)
	v_mfma_f32_16x16x32_bf16 v[74:77], v[142:145], v[198:201], 0
	v_mfma_f32_16x16x32_bf16 v[66:69], v[150:153], v[198:201], 0
	v_mfma_f32_16x16x32_bf16 v[122:125], v[146:149], v[178:181], v[122:125]
	v_mfma_f32_16x16x32_bf16 v[114:117], v[154:157], v[178:181], v[114:117]
	v_mfma_f32_16x16x32_bf16 v[106:109], v[146:149], v[186:189], v[106:109]
	v_mfma_f32_16x16x32_bf16 v[98:101], v[154:157], v[186:189], v[98:101]
	v_mfma_f32_16x16x32_bf16 v[90:93], v[146:149], v[194:197], v[90:93]
	v_mfma_f32_16x16x32_bf16 v[82:85], v[154:157], v[194:197], v[82:85]
	s_waitcnt lgkmcnt(0)
	v_mfma_f32_16x16x32_bf16 v[74:77], v[146:149], v[202:205], v[74:77]
	v_mfma_f32_16x16x32_bf16 v[66:69], v[154:157], v[202:205], v[66:69]
	v_mfma_f32_16x16x32_bf16 v[126:129], v[158:161], v[174:177], 0
	v_mfma_f32_16x16x32_bf16 v[118:121], v[166:169], v[174:177], 0
	v_mfma_f32_16x16x32_bf16 v[110:113], v[158:161], v[182:185], 0
	v_mfma_f32_16x16x32_bf16 v[102:105], v[166:169], v[182:185], 0
	v_mfma_f32_16x16x32_bf16 v[94:97], v[158:161], v[190:193], 0
	v_mfma_f32_16x16x32_bf16 v[86:89], v[166:169], v[190:193], 0
	v_mfma_f32_16x16x32_bf16 v[78:81], v[158:161], v[198:201], 0
	v_mfma_f32_16x16x32_bf16 v[70:73], v[166:169], v[198:201], 0
	v_mfma_f32_16x16x32_bf16 v[126:129], v[162:165], v[178:181], v[126:129]
	v_mfma_f32_16x16x32_bf16 v[118:121], v[170:173], v[178:181], v[118:121]
	v_mfma_f32_16x16x32_bf16 v[110:113], v[162:165], v[186:189], v[110:113]
	v_mfma_f32_16x16x32_bf16 v[102:105], v[170:173], v[186:189], v[102:105]
	v_mfma_f32_16x16x32_bf16 v[94:97], v[162:165], v[194:197], v[94:97]
	v_mfma_f32_16x16x32_bf16 v[86:89], v[170:173], v[194:197], v[86:89]
	v_mfma_f32_16x16x32_bf16 v[78:81], v[162:165], v[202:205], v[78:81]
	v_mfma_f32_16x16x32_bf16 v[70:73], v[170:173], v[202:205], v[70:73]
	s_barrier
	s_add_u32 s44, s52, 0x20000
	ds_read_b128 v[174:177], v140 offset:16384
	ds_read_b128 v[178:181], v140 offset:17408
	ds_read_b128 v[182:185], v140 offset:18432
	ds_read_b128 v[186:189], v140 offset:19456
	ds_read_b128 v[190:193], v140 offset:20480
	ds_read_b128 v[194:197], v140 offset:21504
	ds_read_b128 v[198:201], v140 offset:22528
	ds_read_b128 v[202:205], v140 offset:23552
	s_mov_b32 s2, m0
	s_mov_b32 m0, s56
	s_nop 4
	global_load_lds_dwordx4 v136, s[52:53]
	s_mov_b32 m0, s2
	s_addc_u32 s45, s53, 0
	s_mov_b32 s2, m0
	s_mov_b32 m0, s57
	s_nop 4
	global_load_lds_dwordx4 v136, s[44:45]
	s_mov_b32 m0, s2
	s_add_u32 s44, s52, 0x40000
	s_addc_u32 s45, s53, 0
	s_mov_b32 s2, m0
	s_mov_b32 m0, s58
	s_nop 4
	global_load_lds_dwordx4 v136, s[44:45]
	s_mov_b32 m0, s2
	s_add_u32 s44, s52, 0x60000
	s_addc_u32 s45, s53, 0
	s_mov_b32 s2, m0
	s_mov_b32 m0, s59
	s_nop 4
	global_load_lds_dwordx4 v136, s[44:45]
	s_mov_b32 m0, s2
	s_add_u32 s44, s34, 0x20000
	s_mov_b32 s2, m0
	s_mov_b32 m0, s43
	s_nop 4
	global_load_lds_dwordx4 v1, s[34:35]
	s_mov_b32 m0, s2
	s_addc_u32 s45, s35, 0
	s_mov_b32 s2, m0
	s_mov_b32 m0, s60
	s_nop 4
	global_load_lds_dwordx4 v1, s[44:45]
	s_mov_b32 m0, s2
	s_waitcnt vmcnt(8)
	s_waitcnt lgkmcnt(0)
	s_barrier
	s_waitcnt lgkmcnt(7)
	v_mfma_f32_16x16x32_bf16 v[58:61], v[142:145], v[174:177], 0
	v_mfma_f32_16x16x32_bf16 v[50:53], v[150:153], v[174:177], 0
	s_waitcnt lgkmcnt(5)
	v_mfma_f32_16x16x32_bf16 v[42:45], v[142:145], v[182:185], 0
	v_mfma_f32_16x16x32_bf16 v[34:37], v[150:153], v[182:185], 0
	s_waitcnt lgkmcnt(3)
	v_mfma_f32_16x16x32_bf16 v[26:29], v[142:145], v[190:193], 0
	v_mfma_f32_16x16x32_bf16 v[18:21], v[150:153], v[190:193], 0
	s_waitcnt lgkmcnt(1)
	v_mfma_f32_16x16x32_bf16 v[10:13], v[142:145], v[198:201], 0
	v_mfma_f32_16x16x32_bf16 v[6:9], v[150:153], v[198:201], 0
	v_mfma_f32_16x16x32_bf16 v[58:61], v[146:149], v[178:181], v[58:61]
	v_mfma_f32_16x16x32_bf16 v[50:53], v[154:157], v[178:181], v[50:53]
	v_mfma_f32_16x16x32_bf16 v[42:45], v[146:149], v[186:189], v[42:45]
	v_mfma_f32_16x16x32_bf16 v[34:37], v[154:157], v[186:189], v[34:37]
	v_mfma_f32_16x16x32_bf16 v[26:29], v[146:149], v[194:197], v[26:29]
	v_mfma_f32_16x16x32_bf16 v[18:21], v[154:157], v[194:197], v[18:21]
	s_waitcnt lgkmcnt(0)
	v_mfma_f32_16x16x32_bf16 v[10:13], v[146:149], v[202:205], v[10:13]
	v_mfma_f32_16x16x32_bf16 v[6:9], v[154:157], v[202:205], v[6:9]
	v_mfma_f32_16x16x32_bf16 v[62:65], v[158:161], v[174:177], 0
	v_mfma_f32_16x16x32_bf16 v[54:57], v[166:169], v[174:177], 0
	v_mfma_f32_16x16x32_bf16 v[46:49], v[158:161], v[182:185], 0
	v_mfma_f32_16x16x32_bf16 v[38:41], v[166:169], v[182:185], 0
	v_mfma_f32_16x16x32_bf16 v[30:33], v[158:161], v[190:193], 0
	v_mfma_f32_16x16x32_bf16 v[22:25], v[166:169], v[190:193], 0
	v_mfma_f32_16x16x32_bf16 v[14:17], v[158:161], v[198:201], 0
	v_mfma_f32_16x16x32_bf16 v[2:5], v[166:169], v[198:201], 0
	v_mfma_f32_16x16x32_bf16 v[62:65], v[162:165], v[178:181], v[62:65]
	v_mfma_f32_16x16x32_bf16 v[54:57], v[170:173], v[178:181], v[54:57]
	v_mfma_f32_16x16x32_bf16 v[46:49], v[162:165], v[186:189], v[46:49]
	v_mfma_f32_16x16x32_bf16 v[38:41], v[170:173], v[186:189], v[38:41]
	v_mfma_f32_16x16x32_bf16 v[30:33], v[162:165], v[194:197], v[30:33]
	v_mfma_f32_16x16x32_bf16 v[22:25], v[170:173], v[194:197], v[22:25]
	v_mfma_f32_16x16x32_bf16 v[14:17], v[162:165], v[202:205], v[14:17]
	v_mfma_f32_16x16x32_bf16 v[2:5], v[170:173], v[202:205], v[2:5]
	s_barrier
	v_add_u32_e32 v134, 0x18000, v139
	ds_read_b128 v[142:145], v134
	ds_read_b128 v[146:149], v134 offset:1024
	ds_read_b128 v[150:153], v134 offset:2048
	ds_read_b128 v[154:157], v134 offset:3072
	v_add_u32_e32 v134, 0x1c000, v139
	ds_read_b128 v[158:161], v134
	ds_read_b128 v[162:165], v134 offset:1024
	ds_read_b128 v[166:169], v134 offset:2048
	ds_read_b128 v[170:173], v134 offset:3072
	ds_read_b128 v[174:177], v140 offset:32768
	ds_read_b128 v[178:181], v140 offset:33792
	ds_read_b128 v[182:185], v140 offset:34816
	ds_read_b128 v[186:189], v140 offset:35840
	ds_read_b128 v[190:193], v140 offset:36864
	ds_read_b128 v[194:197], v140 offset:37888
	ds_read_b128 v[198:201], v140 offset:38912
	ds_read_b128 v[202:205], v140 offset:39936
	s_add_u32 s44, s34, 0x40000
	s_addc_u32 s45, s35, 0
	s_mov_b32 s2, m0
	s_mov_b32 m0, s61
	s_nop 4
	global_load_lds_dwordx4 v1, s[44:45]
	s_mov_b32 m0, s2
	s_add_u32 s44, s34, 0x60000
	s_addc_u32 s45, s35, 0
	s_mov_b32 s2, m0
	s_mov_b32 m0, s62
	s_nop 4
	global_load_lds_dwordx4 v1, s[44:45]
	s_mov_b32 m0, s2
	s_waitcnt vmcnt(8)
	s_waitcnt lgkmcnt(0)
	s_barrier
	s_waitcnt lgkmcnt(7)
	v_mfma_f32_16x16x32_bf16 v[122:125], v[142:145], v[174:177], v[122:125]
	v_mfma_f32_16x16x32_bf16 v[114:117], v[150:153], v[174:177], v[114:117]
	s_waitcnt lgkmcnt(5)
	v_mfma_f32_16x16x32_bf16 v[106:109], v[142:145], v[182:185], v[106:109]
	v_mfma_f32_16x16x32_bf16 v[98:101], v[150:153], v[182:185], v[98:101]
	s_waitcnt lgkmcnt(3)
	v_mfma_f32_16x16x32_bf16 v[90:93], v[142:145], v[190:193], v[90:93]
	v_mfma_f32_16x16x32_bf16 v[82:85], v[150:153], v[190:193], v[82:85]
	s_waitcnt lgkmcnt(1)
	v_mfma_f32_16x16x32_bf16 v[74:77], v[142:145], v[198:201], v[74:77]
	v_mfma_f32_16x16x32_bf16 v[66:69], v[150:153], v[198:201], v[66:69]
	v_mfma_f32_16x16x32_bf16 v[122:125], v[146:149], v[178:181], v[122:125]
	v_mfma_f32_16x16x32_bf16 v[114:117], v[154:157], v[178:181], v[114:117]
	v_mfma_f32_16x16x32_bf16 v[106:109], v[146:149], v[186:189], v[106:109]
	v_mfma_f32_16x16x32_bf16 v[98:101], v[154:157], v[186:189], v[98:101]
	v_mfma_f32_16x16x32_bf16 v[90:93], v[146:149], v[194:197], v[90:93]
	v_mfma_f32_16x16x32_bf16 v[82:85], v[154:157], v[194:197], v[82:85]
	s_waitcnt lgkmcnt(0)
	v_mfma_f32_16x16x32_bf16 v[74:77], v[146:149], v[202:205], v[74:77]
	v_mfma_f32_16x16x32_bf16 v[66:69], v[154:157], v[202:205], v[66:69]
	v_mfma_f32_16x16x32_bf16 v[126:129], v[158:161], v[174:177], v[126:129]
	v_mfma_f32_16x16x32_bf16 v[118:121], v[166:169], v[174:177], v[118:121]
	v_mfma_f32_16x16x32_bf16 v[110:113], v[158:161], v[182:185], v[110:113]
	v_mfma_f32_16x16x32_bf16 v[102:105], v[166:169], v[182:185], v[102:105]
	v_mfma_f32_16x16x32_bf16 v[94:97], v[158:161], v[190:193], v[94:97]
	v_mfma_f32_16x16x32_bf16 v[86:89], v[166:169], v[190:193], v[86:89]
	v_mfma_f32_16x16x32_bf16 v[78:81], v[158:161], v[198:201], v[78:81]
	v_mfma_f32_16x16x32_bf16 v[70:73], v[166:169], v[198:201], v[70:73]
	v_mfma_f32_16x16x32_bf16 v[126:129], v[162:165], v[178:181], v[126:129]
	v_mfma_f32_16x16x32_bf16 v[118:121], v[170:173], v[178:181], v[118:121]
	v_mfma_f32_16x16x32_bf16 v[110:113], v[162:165], v[186:189], v[110:113]
	v_mfma_f32_16x16x32_bf16 v[102:105], v[170:173], v[186:189], v[102:105]
	v_mfma_f32_16x16x32_bf16 v[94:97], v[162:165], v[194:197], v[94:97]
	v_mfma_f32_16x16x32_bf16 v[86:89], v[170:173], v[194:197], v[86:89]
	v_mfma_f32_16x16x32_bf16 v[78:81], v[162:165], v[202:205], v[78:81]
	v_mfma_f32_16x16x32_bf16 v[70:73], v[170:173], v[202:205], v[70:73]
	s_barrier
	s_add_u32 s44, s52, 0x80
	s_addc_u32 s45, s53, 0
	ds_read_b128 v[174:177], v140 offset:49152
	ds_read_b128 v[178:181], v140 offset:50176
	ds_read_b128 v[182:185], v140 offset:51200
	ds_read_b128 v[186:189], v140 offset:52224
	ds_read_b128 v[190:193], v140 offset:53248
	ds_read_b128 v[194:197], v140 offset:54272
	ds_read_b128 v[198:201], v140 offset:55296
	ds_read_b128 v[202:205], v140 offset:56320
	s_mov_b32 s2, m0
	s_mov_b32 m0, s63
	s_nop 4
	global_load_lds_dwordx4 v136, s[44:45]
	s_mov_b32 m0, s2
	s_add_u32 s44, s52, 0x20080
	s_addc_u32 s45, s53, 0
	s_mov_b32 s2, m0
	s_mov_b32 m0, s64
	s_nop 4
	global_load_lds_dwordx4 v136, s[44:45]
	s_mov_b32 m0, s2
	s_add_u32 s44, s52, 0x40080
	s_addc_u32 s45, s53, 0
	s_mov_b32 s2, m0
	s_mov_b32 m0, s67
	s_nop 4
	global_load_lds_dwordx4 v136, s[44:45]
	s_mov_b32 m0, s2
	s_add_u32 s44, s52, 0x60080
	s_addc_u32 s45, s53, 0
	s_mov_b32 s2, m0
	s_mov_b32 m0, s73
	s_nop 4
	global_load_lds_dwordx4 v136, s[44:45]
	s_mov_b32 m0, s2
	s_add_u32 s34, s34, 0x20080
	s_mov_b32 s2, m0
	s_mov_b32 m0, s65
	s_nop 4
	global_load_lds_dwordx4 v1, s[50:51]
	s_mov_b32 m0, s2
	s_addc_u32 s35, s35, 0
	s_mov_b32 s2, m0
	s_mov_b32 m0, s66
	s_nop 4
	global_load_lds_dwordx4 v1, s[34:35]
	s_mov_b32 m0, s2
	s_waitcnt vmcnt(8)
	s_waitcnt lgkmcnt(0)
	s_barrier
	s_waitcnt lgkmcnt(7)
	v_mfma_f32_16x16x32_bf16 v[58:61], v[142:145], v[174:177], v[58:61]
	v_mfma_f32_16x16x32_bf16 v[50:53], v[150:153], v[174:177], v[50:53]
	s_waitcnt lgkmcnt(5)
	v_mfma_f32_16x16x32_bf16 v[42:45], v[142:145], v[182:185], v[42:45]
	v_mfma_f32_16x16x32_bf16 v[34:37], v[150:153], v[182:185], v[34:37]
	s_waitcnt lgkmcnt(3)
	v_mfma_f32_16x16x32_bf16 v[26:29], v[142:145], v[190:193], v[26:29]
	v_mfma_f32_16x16x32_bf16 v[18:21], v[150:153], v[190:193], v[18:21]
	s_waitcnt lgkmcnt(1)
	v_mfma_f32_16x16x32_bf16 v[10:13], v[142:145], v[198:201], v[10:13]
	v_mfma_f32_16x16x32_bf16 v[6:9], v[150:153], v[198:201], v[6:9]
	v_mfma_f32_16x16x32_bf16 v[58:61], v[146:149], v[178:181], v[58:61]
	v_mfma_f32_16x16x32_bf16 v[50:53], v[154:157], v[178:181], v[50:53]
	v_mfma_f32_16x16x32_bf16 v[42:45], v[146:149], v[186:189], v[42:45]
	v_mfma_f32_16x16x32_bf16 v[34:37], v[154:157], v[186:189], v[34:37]
	v_mfma_f32_16x16x32_bf16 v[26:29], v[146:149], v[194:197], v[26:29]
	v_mfma_f32_16x16x32_bf16 v[18:21], v[154:157], v[194:197], v[18:21]
	s_waitcnt lgkmcnt(0)
	v_mfma_f32_16x16x32_bf16 v[10:13], v[146:149], v[202:205], v[10:13]
	v_mfma_f32_16x16x32_bf16 v[6:9], v[154:157], v[202:205], v[6:9]
	v_mfma_f32_16x16x32_bf16 v[62:65], v[158:161], v[174:177], v[62:65]
	v_mfma_f32_16x16x32_bf16 v[54:57], v[166:169], v[174:177], v[54:57]
	v_mfma_f32_16x16x32_bf16 v[46:49], v[158:161], v[182:185], v[46:49]
	v_mfma_f32_16x16x32_bf16 v[38:41], v[166:169], v[182:185], v[38:41]
	v_mfma_f32_16x16x32_bf16 v[30:33], v[158:161], v[190:193], v[30:33]
	v_mfma_f32_16x16x32_bf16 v[22:25], v[166:169], v[190:193], v[22:25]
	v_mfma_f32_16x16x32_bf16 v[14:17], v[158:161], v[198:201], v[14:17]
	v_mfma_f32_16x16x32_bf16 v[2:5], v[166:169], v[198:201], v[2:5]
	v_mfma_f32_16x16x32_bf16 v[62:65], v[162:165], v[178:181], v[62:65]
	v_mfma_f32_16x16x32_bf16 v[54:57], v[170:173], v[178:181], v[54:57]
	v_mfma_f32_16x16x32_bf16 v[46:49], v[162:165], v[186:189], v[46:49]
	v_mfma_f32_16x16x32_bf16 v[38:41], v[170:173], v[186:189], v[38:41]
	v_mfma_f32_16x16x32_bf16 v[30:33], v[162:165], v[194:197], v[30:33]
	v_mfma_f32_16x16x32_bf16 v[22:25], v[170:173], v[194:197], v[22:25]
	v_mfma_f32_16x16x32_bf16 v[14:17], v[162:165], v[202:205], v[14:17]
	v_mfma_f32_16x16x32_bf16 v[2:5], v[170:173], v[202:205], v[2:5]
	s_barrier
	s_add_i32 s81, s81, 2
	s_add_u32 s79, s79, 0x100
	s_addc_u32 s80, s80, 0
	s_cmp_gt_u32 s81, 13
	s_mov_b64 s[44:45], s[0:1]

.LBB0_560:
	v_exp_f32_e64 v144, -v122
	v_exp_f32_e64 v145, -v123
	v_pk_mul_f32 v[128:129], v[124:125], v[128:129]
	v_exp_f32_e64 v124, -v124
	v_exp_f32_e64 v125, -v125
	v_pk_add_f32 v[144:145], v[144:145], 1.0 op_sel_hi:[1,0]
	v_pk_mul_f32 v[122:123], v[122:123], v[126:127]
	v_rcp_f32_e32 v126, v144
	v_rcp_f32_e32 v127, v145
	v_pk_add_f32 v[124:125], v[124:125], 1.0 op_sel_hi:[1,0]
	v_pk_mul_f32 v[112:113], v[108:109], v[112:113]
	v_rcp_f32_e32 v124, v124
	v_rcp_f32_e32 v125, v125
	v_pk_mul_f32 v[122:123], v[126:127], v[122:123]
	v_exp_f32_e64 v126, -v114
	v_exp_f32_e64 v127, -v115
	v_pk_mul_f32 v[124:125], v[124:125], v[128:129]
	v_exp_f32_e64 v128, -v116
	v_exp_f32_e64 v129, -v117
	v_pk_add_f32 v[126:127], v[126:127], 1.0 op_sel_hi:[1,0]
	v_pk_mul_f32 v[114:115], v[114:115], v[118:119]
	v_rcp_f32_e32 v126, v126
	v_rcp_f32_e32 v127, v127
	v_pk_add_f32 v[128:129], v[128:129], 1.0 op_sel_hi:[1,0]
	v_pk_mul_f32 v[116:117], v[116:117], v[120:121]
	v_rcp_f32_e32 v128, v128
	v_rcp_f32_e32 v129, v129
	v_pk_mul_f32 v[114:115], v[126:127], v[114:115]
	v_med3_f32 v119, v122, s76, v141
	v_med3_f32 v120, v123, s76, v141
	v_mov_b32_e32 v118, 0
	v_pk_mul_f32 v[116:117], v[128:129], v[116:117]
	v_med3_f32 v114, v114, s76, v141
	v_med3_f32 v115, v115, s76, v141
	v_cvt_pk_fp8_f32 v118, v119, v120
	v_mov_b32_e32 v119, 0
	v_cvt_pk_fp8_f32 v119, v114, v115
	v_med3_f32 v114, v116, s76, v141
	v_med3_f32 v115, v117, s76, v141
	v_exp_f32_e64 v116, -v106
	v_exp_f32_e64 v117, -v107
	v_exp_f32_e64 v108, -v108
	v_exp_f32_e64 v109, -v109
	v_pk_mul_f32 v[106:107], v[106:107], v[110:111]
	v_pk_add_f32 v[116:117], v[116:117], 1.0 op_sel_hi:[1,0]
	v_lshl_add_u32 v142, s42, 8, v137
	v_rcp_f32_e32 v110, v116
	v_rcp_f32_e32 v111, v117
	v_pk_add_f32 v[108:109], v[108:109], 1.0 op_sel_hi:[1,0]
	v_lshl_or_b32 v134, s78, 7, v138
	v_rcp_f32_e32 v108, v108
	v_rcp_f32_e32 v109, v109
	v_pk_mul_f32 v[106:107], v[110:111], v[106:107]
	v_exp_f32_e64 v110, -v98
	v_exp_f32_e64 v111, -v99
	v_pk_mul_f32 v[108:109], v[108:109], v[112:113]
	v_exp_f32_e64 v112, -v100
	v_exp_f32_e64 v113, -v101
	v_pk_add_f32 v[110:111], v[110:111], 1.0 op_sel_hi:[1,0]
	v_pk_mul_f32 v[98:99], v[98:99], v[102:103]
	v_rcp_f32_e32 v110, v110
	v_rcp_f32_e32 v111, v111
	v_pk_add_f32 v[112:113], v[112:113], 1.0 op_sel_hi:[1,0]
	v_med3_f32 v102, v106, s76, v141
	v_rcp_f32_e32 v112, v112
	v_rcp_f32_e32 v113, v113
	v_pk_mul_f32 v[98:99], v[110:111], v[98:99]
	v_med3_f32 v103, v107, s76, v141
	v_med3_f32 v106, v98, s76, v141
	v_med3_f32 v107, v99, s76, v141
	v_mov_b32_e32 v98, 0
	v_mov_b32_e32 v99, 0
	v_cvt_pk_fp8_f32 v98, v102, v103
	v_cvt_pk_fp8_f32 v99, v106, v107
	v_pk_mul_f32 v[100:101], v[100:101], v[104:105]
	v_med3_f32 v104, v108, s76, v141
	v_pk_mul_f32 v[100:101], v[112:113], v[100:101]
	v_med3_f32 v105, v109, s76, v141
	v_med3_f32 v100, v100, s76, v141
	v_med3_f32 v101, v101, s76, v141
	v_cvt_pk_fp8_f32 v98, v104, v105 op_sel:[0,0,1]
	v_cvt_pk_fp8_f32 v99, v100, v101 op_sel:[0,0,1]
	v_exp_f32_e64 v100, -v90
	v_exp_f32_e64 v101, -v91
	v_cvt_pk_fp8_f32 v119, v114, v115 op_sel:[0,0,1]
	v_mov_b64_e32 v[114:115], s[18:19]
	v_or_b32_e32 v102, 16, v142
	v_ashrrev_i32_e32 v135, 31, v134
	v_mad_i64_i32 v[102:103], s[0:1], v102, s77, v[114:115]
	v_lshl_add_u64 v[102:103], v[102:103], 0, v[134:135]
	global_store_dwordx2 v[102:103], v[98:99], off
	v_pk_add_f32 v[98:99], v[100:101], 1.0 op_sel_hi:[1,0]
	v_pk_mul_f32 v[96:97], v[92:93], v[96:97]
	v_exp_f32_e64 v92, -v92
	v_exp_f32_e64 v93, -v93
	v_pk_mul_f32 v[90:91], v[90:91], v[94:95]
	v_rcp_f32_e32 v94, v98
	v_rcp_f32_e32 v95, v99
	v_pk_add_f32 v[92:93], v[92:93], 1.0 op_sel_hi:[1,0]
	v_pk_mul_f32 v[80:81], v[76:77], v[80:81]
	v_rcp_f32_e32 v92, v92
	v_rcp_f32_e32 v93, v93
	v_pk_mul_f32 v[90:91], v[94:95], v[90:91]
	v_exp_f32_e64 v94, -v82
	v_exp_f32_e64 v95, -v83
	v_pk_mul_f32 v[92:93], v[92:93], v[96:97]
	v_exp_f32_e64 v96, -v84
	v_exp_f32_e64 v97, -v85
	v_pk_add_f32 v[94:95], v[94:95], 1.0 op_sel_hi:[1,0]
	v_pk_mul_f32 v[82:83], v[82:83], v[86:87]
	v_rcp_f32_e32 v94, v94
	v_rcp_f32_e32 v95, v95
	v_pk_add_f32 v[96:97], v[96:97], 1.0 op_sel_hi:[1,0]
	v_med3_f32 v86, v90, s76, v141
	v_rcp_f32_e32 v96, v96
	v_rcp_f32_e32 v97, v97
	v_pk_mul_f32 v[82:83], v[94:95], v[82:83]
	v_med3_f32 v87, v91, s76, v141
	v_med3_f32 v90, v82, s76, v141
	v_med3_f32 v91, v83, s76, v141
	v_mov_b32_e32 v82, 0
	v_mov_b32_e32 v83, 0
	v_cvt_pk_fp8_f32 v82, v86, v87
	v_cvt_pk_fp8_f32 v83, v90, v91
	v_pk_mul_f32 v[84:85], v[84:85], v[88:89]
	v_med3_f32 v88, v92, s76, v141
	v_pk_mul_f32 v[84:85], v[96:97], v[84:85]
	v_med3_f32 v89, v93, s76, v141
	v_med3_f32 v84, v84, s76, v141
	v_med3_f32 v85, v85, s76, v141
	v_cvt_pk_fp8_f32 v82, v88, v89 op_sel:[0,0,1]
	v_cvt_pk_fp8_f32 v83, v84, v85 op_sel:[0,0,1]
	v_exp_f32_e64 v84, -v74
	v_exp_f32_e64 v85, -v75
	v_or_b32_e32 v86, 32, v142
	v_mad_i64_i32 v[86:87], s[0:1], v86, s77, v[114:115]
	v_lshl_add_u64 v[86:87], v[86:87], 0, v[134:135]
	global_store_dwordx2 v[86:87], v[82:83], off
	v_pk_add_f32 v[82:83], v[84:85], 1.0 op_sel_hi:[1,0]
	v_exp_f32_e64 v76, -v76
	v_exp_f32_e64 v77, -v77
	v_pk_mul_f32 v[74:75], v[74:75], v[78:79]
	v_rcp_f32_e32 v78, v82
	v_rcp_f32_e32 v79, v83
	v_pk_add_f32 v[76:77], v[76:77], 1.0 op_sel_hi:[1,0]
	v_pk_mul_f32 v[64:65], v[60:61], v[64:65]
	v_rcp_f32_e32 v76, v76
	v_rcp_f32_e32 v77, v77
	v_pk_mul_f32 v[74:75], v[78:79], v[74:75]
	v_exp_f32_e64 v78, -v66
	v_exp_f32_e64 v79, -v67
	v_pk_mul_f32 v[76:77], v[76:77], v[80:81]
	v_exp_f32_e64 v80, -v68
	v_exp_f32_e64 v81, -v69
	v_pk_add_f32 v[78:79], v[78:79], 1.0 op_sel_hi:[1,0]
	v_pk_mul_f32 v[66:67], v[66:67], v[70:71]
	v_rcp_f32_e32 v78, v78
	v_rcp_f32_e32 v79, v79
	v_pk_add_f32 v[80:81], v[80:81], 1.0 op_sel_hi:[1,0]
	v_med3_f32 v70, v74, s76, v141
	v_rcp_f32_e32 v80, v80
	v_rcp_f32_e32 v81, v81
	v_pk_mul_f32 v[66:67], v[78:79], v[66:67]
	v_med3_f32 v71, v75, s76, v141
	v_med3_f32 v74, v66, s76, v141
	v_med3_f32 v75, v67, s76, v141
	v_mov_b32_e32 v66, 0
	v_mov_b32_e32 v67, 0
	v_cvt_pk_fp8_f32 v66, v70, v71
	v_cvt_pk_fp8_f32 v67, v74, v75
	v_pk_mul_f32 v[68:69], v[68:69], v[72:73]
	v_med3_f32 v72, v76, s76, v141
	v_pk_mul_f32 v[68:69], v[80:81], v[68:69]
	v_med3_f32 v73, v77, s76, v141
	v_med3_f32 v68, v68, s76, v141
	v_med3_f32 v69, v69, s76, v141
	v_cvt_pk_fp8_f32 v66, v72, v73 op_sel:[0,0,1]
	v_cvt_pk_fp8_f32 v67, v68, v69 op_sel:[0,0,1]
	v_exp_f32_e64 v70, -v58
	v_exp_f32_e64 v71, -v59
	v_or_b32_e32 v68, 48, v142
	v_mad_i64_i32 v[68:69], s[0:1], v68, s77, v[114:115]
	v_lshl_add_u64 v[68:69], v[68:69], 0, v[134:135]
	global_store_dwordx2 v[68:69], v[66:67], off
	v_pk_add_f32 v[66:67], v[70:71], 1.0 op_sel_hi:[1,0]
	v_exp_f32_e64 v60, -v60
	v_exp_f32_e64 v61, -v61
	v_pk_mul_f32 v[58:59], v[58:59], v[62:63]
	v_rcp_f32_e32 v62, v66
	v_rcp_f32_e32 v63, v67
	v_pk_add_f32 v[60:61], v[60:61], 1.0 op_sel_hi:[1,0]
	v_add_u32_e32 v68, 0x80, v142
	v_rcp_f32_e32 v60, v60
	v_rcp_f32_e32 v61, v61
	v_pk_mul_f32 v[58:59], v[62:63], v[58:59]
	v_exp_f32_e64 v62, -v50
	v_exp_f32_e64 v63, -v51
	v_pk_mul_f32 v[60:61], v[60:61], v[64:65]
	v_exp_f32_e64 v64, -v52
	v_exp_f32_e64 v65, -v53
	v_pk_add_f32 v[62:63], v[62:63], 1.0 op_sel_hi:[1,0]
	v_pk_mul_f32 v[50:51], v[50:51], v[54:55]
	v_rcp_f32_e32 v62, v62
	v_rcp_f32_e32 v63, v63
	v_pk_add_f32 v[64:65], v[64:65], 1.0 op_sel_hi:[1,0]
	v_med3_f32 v54, v58, s76, v141
	v_rcp_f32_e32 v64, v64
	v_rcp_f32_e32 v65, v65
	v_pk_mul_f32 v[50:51], v[62:63], v[50:51]
	v_med3_f32 v55, v59, s76, v141
	v_med3_f32 v58, v50, s76, v141
	v_med3_f32 v59, v51, s76, v141
	v_mov_b32_e32 v50, 0
	v_mov_b32_e32 v51, 0
	v_cvt_pk_fp8_f32 v50, v54, v55
	v_cvt_pk_fp8_f32 v51, v58, v59
	v_pk_mul_f32 v[52:53], v[52:53], v[56:57]
	v_med3_f32 v56, v60, s76, v141
	v_pk_mul_f32 v[52:53], v[64:65], v[52:53]
	v_med3_f32 v57, v61, s76, v141
	v_med3_f32 v52, v52, s76, v141
	v_med3_f32 v53, v53, s76, v141
	v_cvt_pk_fp8_f32 v50, v56, v57 op_sel:[0,0,1]
	v_cvt_pk_fp8_f32 v51, v52, v53 op_sel:[0,0,1]
	v_exp_f32_e64 v52, -v42
	v_exp_f32_e64 v53, -v43
	v_mad_i64_i32 v[54:55], s[0:1], v68, s77, v[114:115]
	v_lshl_add_u64 v[54:55], v[54:55], 0, v[134:135]
	global_store_dwordx2 v[54:55], v[50:51], off
	v_pk_add_f32 v[50:51], v[52:53], 1.0 op_sel_hi:[1,0]
	v_pk_mul_f32 v[48:49], v[44:45], v[48:49]
	v_exp_f32_e64 v44, -v44
	v_exp_f32_e64 v45, -v45
	v_pk_mul_f32 v[42:43], v[42:43], v[46:47]
	v_rcp_f32_e32 v46, v50
	v_rcp_f32_e32 v47, v51
	v_pk_add_f32 v[44:45], v[44:45], 1.0 op_sel_hi:[1,0]
	v_pk_mul_f32 v[32:33], v[28:29], v[32:33]
	v_rcp_f32_e32 v44, v44
	v_rcp_f32_e32 v45, v45
	v_pk_mul_f32 v[42:43], v[46:47], v[42:43]
	v_exp_f32_e64 v46, -v34
	v_exp_f32_e64 v47, -v35
	v_pk_mul_f32 v[44:45], v[44:45], v[48:49]
	v_exp_f32_e64 v48, -v36
	v_exp_f32_e64 v49, -v37
	v_pk_add_f32 v[46:47], v[46:47], 1.0 op_sel_hi:[1,0]
	v_pk_mul_f32 v[34:35], v[34:35], v[38:39]
	v_rcp_f32_e32 v46, v46
	v_rcp_f32_e32 v47, v47
	v_pk_add_f32 v[48:49], v[48:49], 1.0 op_sel_hi:[1,0]
	v_med3_f32 v38, v42, s76, v141
	v_rcp_f32_e32 v48, v48
	v_rcp_f32_e32 v49, v49
	v_pk_mul_f32 v[34:35], v[46:47], v[34:35]
	v_med3_f32 v39, v43, s76, v141
	v_med3_f32 v42, v34, s76, v141
	v_med3_f32 v43, v35, s76, v141
	v_mov_b32_e32 v34, 0
	v_mov_b32_e32 v35, 0
	v_cvt_pk_fp8_f32 v34, v38, v39
	v_cvt_pk_fp8_f32 v35, v42, v43
	v_pk_mul_f32 v[36:37], v[36:37], v[40:41]
	v_med3_f32 v40, v44, s76, v141
	v_pk_mul_f32 v[36:37], v[48:49], v[36:37]
	v_med3_f32 v41, v45, s76, v141
	v_med3_f32 v36, v36, s76, v141
	v_med3_f32 v37, v37, s76, v141
	v_cvt_pk_fp8_f32 v34, v40, v41 op_sel:[0,0,1]
	v_cvt_pk_fp8_f32 v35, v36, v37 op_sel:[0,0,1]
	v_exp_f32_e64 v36, -v26
	v_exp_f32_e64 v37, -v27
	v_add_u32_e32 v38, 0x90, v142
	v_mad_i64_i32 v[38:39], s[0:1], v38, s77, v[114:115]
	v_lshl_add_u64 v[38:39], v[38:39], 0, v[134:135]
	global_store_dwordx2 v[38:39], v[34:35], off
	v_pk_add_f32 v[34:35], v[36:37], 1.0 op_sel_hi:[1,0]
	v_exp_f32_e64 v28, -v28
	v_exp_f32_e64 v29, -v29
	v_pk_mul_f32 v[26:27], v[26:27], v[30:31]
	v_rcp_f32_e32 v30, v34
	v_rcp_f32_e32 v31, v35
	v_pk_add_f32 v[28:29], v[28:29], 1.0 op_sel_hi:[1,0]
	v_pk_mul_f32 v[16:17], v[12:13], v[16:17]
	v_rcp_f32_e32 v28, v28
	v_rcp_f32_e32 v29, v29
	v_pk_mul_f32 v[26:27], v[30:31], v[26:27]
	v_exp_f32_e64 v30, -v18
	v_exp_f32_e64 v31, -v19
	v_pk_mul_f32 v[28:29], v[28:29], v[32:33]
	v_exp_f32_e64 v32, -v20
	v_exp_f32_e64 v33, -v21
	v_pk_add_f32 v[30:31], v[30:31], 1.0 op_sel_hi:[1,0]
	v_pk_mul_f32 v[18:19], v[18:19], v[22:23]
	v_rcp_f32_e32 v30, v30
	v_rcp_f32_e32 v31, v31
	v_pk_add_f32 v[32:33], v[32:33], 1.0 op_sel_hi:[1,0]
	v_med3_f32 v22, v26, s76, v141
	v_rcp_f32_e32 v32, v32
	v_rcp_f32_e32 v33, v33
	v_pk_mul_f32 v[18:19], v[30:31], v[18:19]
	v_med3_f32 v23, v27, s76, v141
	v_med3_f32 v26, v18, s76, v141
	v_med3_f32 v27, v19, s76, v141
	v_mov_b32_e32 v18, 0
	v_mov_b32_e32 v19, 0
	v_cvt_pk_fp8_f32 v18, v22, v23
	v_cvt_pk_fp8_f32 v19, v26, v27
	v_pk_mul_f32 v[20:21], v[20:21], v[24:25]
	v_med3_f32 v24, v28, s76, v141
	v_pk_mul_f32 v[20:21], v[32:33], v[20:21]
	v_med3_f32 v25, v29, s76, v141
	v_med3_f32 v20, v20, s76, v141
	v_med3_f32 v21, v21, s76, v141
	v_cvt_pk_fp8_f32 v18, v24, v25 op_sel:[0,0,1]
	v_cvt_pk_fp8_f32 v19, v20, v21 op_sel:[0,0,1]
	v_exp_f32_e64 v20, -v10
	v_exp_f32_e64 v21, -v11
	v_add_u32_e32 v22, 0xa0, v142
	v_mad_i64_i32 v[22:23], s[0:1], v22, s77, v[114:115]
	v_lshl_add_u64 v[22:23], v[22:23], 0, v[134:135]
	global_store_dwordx2 v[22:23], v[18:19], off
	v_pk_add_f32 v[18:19], v[20:21], 1.0 op_sel_hi:[1,0]
	v_exp_f32_e64 v12, -v12
	v_exp_f32_e64 v13, -v13
	v_pk_mul_f32 v[10:11], v[10:11], v[14:15]
	v_rcp_f32_e32 v14, v18
	v_rcp_f32_e32 v15, v19
	v_pk_add_f32 v[12:13], v[12:13], 1.0 op_sel_hi:[1,0]
	v_pk_mul_f32 v[2:3], v[6:7], v[2:3]
	v_rcp_f32_e32 v12, v12
	v_rcp_f32_e32 v13, v13
	v_pk_mul_f32 v[10:11], v[14:15], v[10:11]
	v_exp_f32_e64 v14, -v6
	v_exp_f32_e64 v15, -v7
	v_pk_mul_f32 v[12:13], v[12:13], v[16:17]
	v_exp_f32_e64 v16, -v8
	v_exp_f32_e64 v17, -v9
	v_pk_add_f32 v[14:15], v[14:15], 1.0 op_sel_hi:[1,0]
	v_med3_f32 v6, v10, s76, v141
	v_rcp_f32_e32 v14, v14
	v_rcp_f32_e32 v15, v15
	v_pk_add_f32 v[16:17], v[16:17], 1.0 op_sel_hi:[1,0]
	v_med3_f32 v7, v11, s76, v141
	v_rcp_f32_e32 v16, v16
	v_rcp_f32_e32 v17, v17
	v_pk_mul_f32 v[2:3], v[14:15], v[2:3]
	v_pk_mul_f32 v[4:5], v[8:9], v[4:5]
	v_med3_f32 v10, v2, s76, v141
	v_med3_f32 v11, v3, s76, v141
	v_mov_b32_e32 v2, 0
	v_mov_b32_e32 v3, 0
	v_cvt_pk_fp8_f32 v2, v6, v7
	v_cvt_pk_fp8_f32 v3, v10, v11
	v_pk_mul_f32 v[4:5], v[16:17], v[4:5]
	v_med3_f32 v121, v124, s76, v141
	v_med3_f32 v122, v125, s76, v141
	v_med3_f32 v8, v12, s76, v141
	v_med3_f32 v9, v13, s76, v141
	v_med3_f32 v4, v4, s76, v141
	v_med3_f32 v5, v5, s76, v141
	v_cvt_pk_fp8_f32 v118, v121, v122 op_sel:[0,0,1]
	v_cvt_pk_fp8_f32 v2, v8, v9 op_sel:[0,0,1]
	v_cvt_pk_fp8_f32 v3, v4, v5 op_sel:[0,0,1]
	v_add_u32_e32 v4, 0xb0, v142
	v_mad_i64_i32 v[120:121], s[0:1], v142, s77, v[114:115]
	v_mad_i64_i32 v[4:5], s[0:1], v4, s77, v[114:115]
	v_lshl_add_u64 v[120:121], v[120:121], 0, v[134:135]
	v_lshl_add_u64 v[4:5], v[4:5], 0, v[134:135]
	s_andn2_b64 vcc, exec, s[4:5]
	s_mov_b64 s[0:1], -1
	global_store_dwordx2 v[120:121], v[118:119], off
	global_store_dwordx2 v[4:5], v[2:3], off
	s_cbranch_vccnz .LBB0_553
	s_andn2_b64 vcc, exec, s[8:9]
	v_mov_b64 v[4:5], 0
	s_cbranch_vccnz .LBB0_552
	s_barrier
	s_branch .LBB0_552

.LBB0_636:
	v_and_b32_e32 v3, 48, v2
	v_lshlrev_b32_e32 v4, 6, v2
	s_movk_i32 s3, 0x3c0
	v_lshlrev_b32_e32 v2, 2, v2
	s_and_b32 s67, s14, 3
	s_lshl_b32 s2, s15, 13
	v_and_or_b32 v3, v4, s3, v3
	v_and_b32_e32 v2, 32, v2
	s_lshl_b32 s64, s15, 6
	v_bitop3_b32 v4, v3, s2, v2 bitop3:0xde
	s_lshl_b32 s2, s67, 12
	s_add_u32 s34, s6, 0x80
	s_addc_u32 s35, s7, 0
	s_add_i32 s81, s73, 0x18000
	v_bitop3_b32 v2, v3, s2, v2 bitop3:0xde
	s_waitcnt vmcnt(2)
	s_barrier
	s_mov_b32 s2, m0
	s_mov_b32 m0, s81
	s_nop 4
	global_load_lds_dwordx4 v131, s[34:35]
	s_mov_b32 m0, s2
	s_add_u32 s34, s6, 0x2c080
	s_addc_u32 s35, s7, 0
	s_add_i32 s82, s73, 0x1a000
	s_mov_b32 s2, m0
	s_mov_b32 m0, s82
	s_nop 4
	global_load_lds_dwordx4 v131, s[34:35]
	s_mov_b32 m0, s2
	s_add_u32 s34, s10, 0x80
	s_addc_u32 s35, s11, 0
	s_add_i32 s84, s73, 0x8000
	s_mov_b32 s2, m0
	s_mov_b32 m0, s84
	s_nop 4
	global_load_lds_dwordx4 v130, s[34:35]
	s_mov_b32 m0, s2
	s_add_u32 s34, s10, 0x2c080
	s_addc_u32 s35, s11, 0
	s_add_i32 s85, s73, 0xa000
	s_mov_b32 s2, m0
	s_mov_b32 m0, s85
	s_nop 4
	global_load_lds_dwordx4 v130, s[34:35]
	s_mov_b32 m0, s2
	s_add_u32 s34, s6, 0x58080
	s_addc_u32 s35, s7, 0
	s_add_i32 s86, s73, 0x1c000
	s_mov_b32 s2, m0
	s_mov_b32 m0, s86
	s_nop 4
	global_load_lds_dwordx4 v131, s[34:35]
	s_mov_b32 m0, s2
	s_add_u32 s34, s6, 0x84080
	s_addc_u32 s35, s7, 0
	s_add_i32 s87, s73, 0x1e000
	s_mov_b32 s2, m0
	s_mov_b32 m0, s87
	s_nop 4
	global_load_lds_dwordx4 v131, s[34:35]
	s_mov_b32 m0, s2
	s_waitcnt vmcnt(6)
	s_add_i32 s88, s73, 0xc000
	s_add_u32 s89, s62, s1
	v_mov_b32_e32 v110, 0
	v_add_u32_e32 v2, 0, v2
	s_addc_u32 s90, s63, s0
	s_mov_b32 s91, -2
	v_add_u32_e32 v132, 0x10000, v2
	v_add_u32_e32 v133, 0, v4
	v_add_u32_e32 v134, 0x14000, v2
	v_add_u32_e32 v135, 0x18000, v2
	v_add_u32_e32 v136, 0x1c000, v2
	s_mov_b64 s[34:35], s[10:11]
	s_waitcnt lgkmcnt(0)
	s_barrier
	ds_read_b128 v[138:141], v132
	ds_read_b128 v[142:145], v132 offset:1024
	ds_read_b128 v[146:149], v132 offset:2048
	ds_read_b128 v[150:153], v132 offset:3072
	ds_read_b128 v[154:157], v134
	ds_read_b128 v[158:161], v134 offset:1024
	ds_read_b128 v[182:185], v134 offset:2048
	ds_read_b128 v[186:189], v134 offset:3072
	s_add_u32 s0, s34, 0x100
	s_addc_u32 s1, s35, 0
	s_cmp_eq_u32 s91, 18
	s_cselect_b32 s52, s10, s0
	s_cselect_b32 s53, s11, s1
	s_cselect_b32 s50, s6, s89
	s_cselect_b32 s51, s7, s90
	s_add_u32 s54, s52, 0x80
	s_addc_u32 s55, s53, 0
	s_add_u32 s92, s34, 0x58080
	s_addc_u32 s93, s35, 0
	s_mov_b32 m0, s88
	s_nop 4
	global_load_lds_dwordx4 v130, s[92:93]
	s_add_u32 s34, s34, 0x84080
	s_addc_u32 s35, s35, 0
	s_add_i32 s2, s73, 0xe000
	s_mov_b32 m0, s2
	s_nop 4
	global_load_lds_dwordx4 v130, s[34:35]
	ds_read_b128 v[190:193], v133
	ds_read_b128 v[194:197], v133 offset:1024
	ds_read_b128 v[198:201], v133 offset:2048
	ds_read_b128 v[202:205], v133 offset:3072
	ds_read_b128 v[206:209], v133 offset:4096
	ds_read_b128 v[210:213], v133 offset:5120
	ds_read_b128 v[214:217], v133 offset:6144
	ds_read_b128 v[218:221], v133 offset:7168
	s_waitcnt vmcnt(8)
	s_waitcnt lgkmcnt(0)
	s_barrier
	v_mfma_f32_16x16x128_f8f6f4 v[14:17], v[138:145], v[190:197], 0
	v_mfma_f32_16x16x128_f8f6f4 v[30:33], v[138:145], v[198:205], 0
	v_mfma_f32_16x16x128_f8f6f4 v[50:53], v[138:145], v[206:213], 0
	v_mfma_f32_16x16x128_f8f6f4 v[62:65], v[138:145], v[214:221], 0
	v_mfma_f32_16x16x128_f8f6f4 v[10:13], v[146:153], v[190:197], 0
	v_mfma_f32_16x16x128_f8f6f4 v[26:29], v[146:153], v[198:205], 0
	v_mfma_f32_16x16x128_f8f6f4 v[42:45], v[146:153], v[206:213], 0
	v_mfma_f32_16x16x128_f8f6f4 v[58:61], v[146:153], v[214:221], 0
	v_mfma_f32_16x16x128_f8f6f4 v[6:9], v[154:161], v[190:197], 0
	v_mfma_f32_16x16x128_f8f6f4 v[22:25], v[154:161], v[198:205], 0
	v_mfma_f32_16x16x128_f8f6f4 v[38:41], v[154:161], v[206:213], 0
	v_mfma_f32_16x16x128_f8f6f4 v[54:57], v[154:161], v[214:221], 0
	v_mfma_f32_16x16x128_f8f6f4 v[2:5], v[182:189], v[190:197], 0
	v_mfma_f32_16x16x128_f8f6f4 v[18:21], v[182:189], v[198:205], 0
	v_mfma_f32_16x16x128_f8f6f4 v[34:37], v[182:189], v[206:213], 0
	v_mfma_f32_16x16x128_f8f6f4 v[46:49], v[182:189], v[214:221], 0
	s_barrier
	ds_read_b128 v[190:193], v133 offset:16384
	ds_read_b128 v[194:197], v133 offset:17408
	ds_read_b128 v[198:201], v133 offset:18432
	ds_read_b128 v[202:205], v133 offset:19456
	ds_read_b128 v[206:209], v133 offset:20480
	ds_read_b128 v[210:213], v133 offset:21504
	ds_read_b128 v[214:217], v133 offset:22528
	ds_read_b128 v[218:221], v133 offset:23552
	s_mov_b32 m0, s74
	s_nop 4
	global_load_lds_dwordx4 v131, s[50:51]
	s_add_u32 s34, s50, 0x2c000
	s_addc_u32 s35, s51, 0
	s_mov_b32 m0, s75
	s_nop 4
	global_load_lds_dwordx4 v131, s[34:35]
	s_add_u32 s34, s50, 0x58000
	s_addc_u32 s35, s51, 0
	s_mov_b32 m0, s77
	s_nop 4
	global_load_lds_dwordx4 v131, s[34:35]
	s_add_u32 s34, s50, 0x84000
	s_addc_u32 s35, s51, 0
	s_mov_b32 m0, s78
	s_nop 4
	global_load_lds_dwordx4 v131, s[34:35]
	s_mov_b32 m0, s73
	s_nop 4
	global_load_lds_dwordx4 v130, s[52:53]
	s_add_u32 s34, s52, 0x2c000
	s_addc_u32 s35, s53, 0
	s_mov_b32 m0, s76
	s_nop 4
	global_load_lds_dwordx4 v130, s[34:35]
	s_waitcnt vmcnt(8)
	s_waitcnt lgkmcnt(0)
	s_barrier
	v_mfma_f32_16x16x128_f8f6f4 v[78:81], v[138:145], v[190:197], 0
	v_mfma_f32_16x16x128_f8f6f4 v[94:97], v[138:145], v[198:205], 0
	v_mfma_f32_16x16x128_f8f6f4 v[126:129], v[138:145], v[206:213], 0
	v_mfma_f32_16x16x128_f8f6f4 v[98:101], v[138:145], v[214:221], 0
	v_mfma_f32_16x16x128_f8f6f4 v[74:77], v[146:153], v[190:197], 0
	v_mfma_f32_16x16x128_f8f6f4 v[90:93], v[146:153], v[198:205], 0
	v_mfma_f32_16x16x128_f8f6f4 v[114:117], v[146:153], v[206:213], 0
	v_mfma_f32_16x16x128_f8f6f4 v[122:125], v[146:153], v[214:221], 0
	v_mfma_f32_16x16x128_f8f6f4 v[70:73], v[154:161], v[190:197], 0
	v_mfma_f32_16x16x128_f8f6f4 v[86:89], v[154:161], v[198:205], 0
	v_mfma_f32_16x16x128_f8f6f4 v[106:109], v[154:161], v[206:213], 0
	v_mfma_f32_16x16x128_f8f6f4 v[118:121], v[154:161], v[214:221], 0
	v_mfma_f32_16x16x128_f8f6f4 v[66:69], v[182:189], v[190:197], 0
	v_mfma_f32_16x16x128_f8f6f4 v[82:85], v[182:189], v[198:205], 0
	v_mfma_f32_16x16x128_f8f6f4 v[102:105], v[182:189], v[206:213], 0
	v_mfma_f32_16x16x128_f8f6f4 v[110:113], v[182:189], v[214:221], 0
	s_barrier
	ds_read_b128 v[138:141], v135
	ds_read_b128 v[142:145], v135 offset:1024
	ds_read_b128 v[146:149], v135 offset:2048
	ds_read_b128 v[150:153], v135 offset:3072
	ds_read_b128 v[154:157], v136
	ds_read_b128 v[158:161], v136 offset:1024
	ds_read_b128 v[182:185], v136 offset:2048
	ds_read_b128 v[186:189], v136 offset:3072
	s_add_u32 s34, s52, 0x58000
	s_addc_u32 s35, s53, 0
	s_mov_b32 m0, s79
	s_nop 4
	global_load_lds_dwordx4 v130, s[34:35]
	s_add_u32 s34, s52, 0x84000
	s_addc_u32 s35, s53, 0
	s_mov_b32 m0, s80
	s_nop 4
	global_load_lds_dwordx4 v130, s[34:35]
	ds_read_b128 v[190:193], v133 offset:32768
	ds_read_b128 v[194:197], v133 offset:33792
	ds_read_b128 v[198:201], v133 offset:34816
	ds_read_b128 v[202:205], v133 offset:35840
	ds_read_b128 v[206:209], v133 offset:36864
	ds_read_b128 v[210:213], v133 offset:37888
	ds_read_b128 v[214:217], v133 offset:38912
	ds_read_b128 v[218:221], v133 offset:39936
	s_waitcnt vmcnt(8)
	s_waitcnt lgkmcnt(0)
	s_barrier
	v_mfma_f32_16x16x128_f8f6f4 v[14:17], v[138:145], v[190:197], v[14:17]
	v_mfma_f32_16x16x128_f8f6f4 v[30:33], v[138:145], v[198:205], v[30:33]
	v_mfma_f32_16x16x128_f8f6f4 v[50:53], v[138:145], v[206:213], v[50:53]
	v_mfma_f32_16x16x128_f8f6f4 v[62:65], v[138:145], v[214:221], v[62:65]
	v_mfma_f32_16x16x128_f8f6f4 v[10:13], v[146:153], v[190:197], v[10:13]
	v_mfma_f32_16x16x128_f8f6f4 v[26:29], v[146:153], v[198:205], v[26:29]
	v_mfma_f32_16x16x128_f8f6f4 v[42:45], v[146:153], v[206:213], v[42:45]
	v_mfma_f32_16x16x128_f8f6f4 v[58:61], v[146:153], v[214:221], v[58:61]
	v_mfma_f32_16x16x128_f8f6f4 v[6:9], v[154:161], v[190:197], v[6:9]
	v_mfma_f32_16x16x128_f8f6f4 v[22:25], v[154:161], v[198:205], v[22:25]
	v_mfma_f32_16x16x128_f8f6f4 v[38:41], v[154:161], v[206:213], v[38:41]
	v_mfma_f32_16x16x128_f8f6f4 v[54:57], v[154:161], v[214:221], v[54:57]
	v_mfma_f32_16x16x128_f8f6f4 v[2:5], v[182:189], v[190:197], v[2:5]
	v_mfma_f32_16x16x128_f8f6f4 v[18:21], v[182:189], v[198:205], v[18:21]
	v_mfma_f32_16x16x128_f8f6f4 v[34:37], v[182:189], v[206:213], v[34:37]
	v_mfma_f32_16x16x128_f8f6f4 v[46:49], v[182:189], v[214:221], v[46:49]
	s_barrier
	ds_read_b128 v[190:193], v133 offset:49152
	ds_read_b128 v[194:197], v133 offset:50176
	ds_read_b128 v[198:201], v133 offset:51200
	ds_read_b128 v[202:205], v133 offset:52224
	ds_read_b128 v[206:209], v133 offset:53248
	ds_read_b128 v[210:213], v133 offset:54272
	ds_read_b128 v[214:217], v133 offset:55296
	ds_read_b128 v[218:221], v133 offset:56320
	s_add_u32 s34, s50, 0x80
	s_addc_u32 s35, s51, 0
	s_mov_b32 m0, s81
	s_nop 4
	global_load_lds_dwordx4 v131, s[34:35]
	s_add_u32 s34, s50, 0x2c080
	s_addc_u32 s35, s51, 0
	s_mov_b32 m0, s82
	s_nop 4
	global_load_lds_dwordx4 v131, s[34:35]
	s_add_u32 s34, s50, 0x58080
	s_addc_u32 s35, s51, 0
	s_mov_b32 m0, s86
	s_nop 4
	global_load_lds_dwordx4 v131, s[34:35]
	s_add_u32 s34, s50, 0x84080
	s_addc_u32 s35, s51, 0
	s_mov_b32 m0, s87
	s_nop 4
	global_load_lds_dwordx4 v131, s[34:35]
	s_mov_b32 m0, s84
	s_nop 4
	global_load_lds_dwordx4 v130, s[54:55]
	s_add_u32 s34, s52, 0x2c080
	s_addc_u32 s35, s53, 0
	s_mov_b32 m0, s85
	s_nop 4
	global_load_lds_dwordx4 v130, s[34:35]
	s_waitcnt vmcnt(8)
	s_waitcnt lgkmcnt(0)
	s_barrier
	v_mfma_f32_16x16x128_f8f6f4 v[78:81], v[138:145], v[190:197], v[78:81]
	v_mfma_f32_16x16x128_f8f6f4 v[94:97], v[138:145], v[198:205], v[94:97]
	v_mfma_f32_16x16x128_f8f6f4 v[126:129], v[138:145], v[206:213], v[126:129]
	v_mfma_f32_16x16x128_f8f6f4 v[98:101], v[138:145], v[214:221], v[98:101]
	v_mfma_f32_16x16x128_f8f6f4 v[74:77], v[146:153], v[190:197], v[74:77]
	v_mfma_f32_16x16x128_f8f6f4 v[90:93], v[146:153], v[198:205], v[90:93]
	v_mfma_f32_16x16x128_f8f6f4 v[114:117], v[146:153], v[206:213], v[114:117]
	v_mfma_f32_16x16x128_f8f6f4 v[122:125], v[146:153], v[214:221], v[122:125]
	v_mfma_f32_16x16x128_f8f6f4 v[70:73], v[154:161], v[190:197], v[70:73]
	v_mfma_f32_16x16x128_f8f6f4 v[86:89], v[154:161], v[198:205], v[86:89]
	v_mfma_f32_16x16x128_f8f6f4 v[106:109], v[154:161], v[206:213], v[106:109]
	v_mfma_f32_16x16x128_f8f6f4 v[118:121], v[154:161], v[214:221], v[118:121]
	v_mfma_f32_16x16x128_f8f6f4 v[66:69], v[182:189], v[190:197], v[66:69]
	v_mfma_f32_16x16x128_f8f6f4 v[82:85], v[182:189], v[198:205], v[82:85]
	v_mfma_f32_16x16x128_f8f6f4 v[102:105], v[182:189], v[206:213], v[102:105]
	v_mfma_f32_16x16x128_f8f6f4 v[110:113], v[182:189], v[214:221], v[110:113]
	s_add_i32 s91, s91, 2
	s_add_u32 s89, s89, 0x100
	s_addc_u32 s90, s90, 0
	s_cmp_lt_u32 s91, 20
	s_mov_b64 s[34:35], s[0:1]
	s_barrier

.LBB0_746:
	s_add_u32 s67, s68, 0x10900000
	s_addc_u32 s73, s69, 0
	s_add_u32 s82, s68, 0x20900000
	s_addc_u32 s84, s69, 0
	s_add_u32 s85, s68, 0x30a00000
	v_lshrrev_b32_e32 v4, 1, v2
	s_addc_u32 s87, s69, 0
	v_and_b32_e32 v134, 24, v4
	s_add_u32 s88, s68, 0x31200000
	v_and_b32_e32 v3, 15, v2
	v_lshlrev_b32_e32 v4, 1, v134
	v_lshlrev_b32_e32 v2, 2, v2
	s_addc_u32 s89, s69, 0
	s_and_b32 s2, s5, 3
	v_lshl_or_b32 v4, v3, 6, v4
	s_lshl_b32 s3, s14, 13
	v_and_b32_e32 v2, 32, v2
	v_bitop3_b32 v5, v4, s3, v2 bitop3:0xde
	s_lshl_b32 s3, s2, 12
	v_lshl_or_b32 v137, s14, 6, v3
	s_add_u32 s14, s0, 0x80
	s_addc_u32 s15, s1, 0
	s_add_i32 s90, s58, 0x18000
	v_bitop3_b32 v4, v4, s3, v2 bitop3:0xde
	s_waitcnt vmcnt(2)
	s_barrier
	s_mov_b32 s3, m0
	s_mov_b32 m0, s90
	s_nop 4
	global_load_lds_dwordx4 v135, s[14:15]
	s_mov_b32 m0, s3
	s_add_u32 s14, s0, 0x20080
	s_addc_u32 s15, s1, 0
	s_add_i32 s91, s58, 0x1a000
	s_mov_b32 s3, m0
	s_mov_b32 m0, s91
	s_nop 4
	global_load_lds_dwordx4 v135, s[14:15]
	s_mov_b32 m0, s3
	s_add_u32 s14, s44, 0x80
	s_addc_u32 s15, s45, 0
	s_add_i32 s92, s58, 0x8000
	s_mov_b32 s3, m0
	s_mov_b32 m0, s92
	s_nop 4
	global_load_lds_dwordx4 v1, s[14:15]
	s_mov_b32 m0, s3
	s_add_u32 s14, s44, 0x20080
	s_addc_u32 s15, s45, 0
	s_add_i32 s93, s58, 0xa000
	s_mov_b32 s3, m0
	s_mov_b32 m0, s93
	s_nop 4
	global_load_lds_dwordx4 v1, s[14:15]
	s_mov_b32 m0, s3
	s_add_u32 s14, s0, 0x40080
	s_addc_u32 s15, s1, 0
	s_add_i32 s94, s58, 0x1c000
	s_mov_b32 s3, m0
	s_mov_b32 m0, s94
	s_nop 4
	global_load_lds_dwordx4 v135, s[14:15]
	s_mov_b32 m0, s3
	s_add_u32 s14, s0, 0x60080
	s_addc_u32 s15, s1, 0
	s_add_i32 s95, s58, 0x1e000
	s_add_i32 s96, s58, 0xc000
	s_cmpk_lt_u32 s4, 0x100
	v_readlane_b32 s4, v255, 15
	s_mov_b32 s3, m0
	s_mov_b32 m0, s95
	s_nop 4
	global_load_lds_dwordx4 v135, s[14:15]
	s_mov_b32 m0, s3
	v_mov_b32_e32 v139, 0
	v_lshlrev_b32_e32 v138, 2, v134
	v_readlane_b32 s5, v255, 16
	s_waitcnt vmcnt(6)
	v_lshl_or_b32 v2, s2, 5, v134
	v_or_b32_e32 v136, 0x1000, v3
	v_lshl_add_u64 v[146:147], s[4:5], 0, v[138:139]
	v_readlane_b32 s4, v255, 17
	v_or_b32_e32 v140, 0x1010, v3
	v_or_b32_e32 v142, 0x1020, v3
	v_or_b32_e32 v144, 0x1030, v3
	v_readlane_b32 s5, v255, 18
	v_or_b32_e32 v141, 0xfffffc00, v2
	v_mov_b64_e32 v[2:3], 0
	s_cselect_b64 s[24:25], -1, 0
	s_lshl_b32 s97, s2, 6
	s_ashr_i32 s40, s72, 31
	s_ashr_i32 s41, s54, 31
	v_lshl_add_u64 v[148:149], s[4:5], 0, v[138:139]
	v_mov_b64_e32 v[150:151], 0x840
	v_mov_b64_e32 v[152:153], 0x83f
	v_add_u32_e32 v143, 0, v4
	v_add_u32_e32 v145, 0, v5
	s_movk_i32 s86, 0x1040
	s_waitcnt vmcnt(4)
	s_waitcnt vmcnt(2) lgkmcnt(0)
	s_barrier
	s_branch .LBB0_749

.LBB0_751:
	s_ashr_i32 s37, s36, 31
	s_lshl_b64 s[14:15], s[36:37], 19
	s_add_u32 s38, s16, s14
	s_addc_u32 s39, s17, s15
	s_and_b64 s[14:15], s[4:5], exec
	s_cselect_b32 s7, s39, s45
	s_cselect_b32 s9, s38, s44
	s_ashr_i32 s27, s26, 31
	s_lshl_b64 s[14:15], s[26:27], 19
	s_add_u32 s42, s55, s14
	s_addc_u32 s43, s56, s15
	s_and_b64 s[14:15], s[4:5], exec
	s_cselect_b32 s14, s43, s1
	s_cselect_b32 s15, s42, s0
	s_add_u32 s27, s0, 0x100
	s_addc_u32 s37, s1, 0
	s_mov_b32 vcc_lo, -2
	v_add_u32_e32 v138, 0x10000, v143
	ds_read_b128 v[130:133], v138
	ds_read_b128 v[154:157], v138 offset:1024
	ds_read_b128 v[158:161], v138 offset:2048
	ds_read_b128 v[162:165], v138 offset:3072
	v_add_u32_e32 v138, 0x14000, v143
	ds_read_b128 v[166:169], v138
	ds_read_b128 v[170:173], v138 offset:1024
	ds_read_b128 v[174:177], v138 offset:2048
	ds_read_b128 v[178:181], v138 offset:3072
	s_add_u32 s0, s44, 0x100
	s_addc_u32 s1, s45, 0
	s_cmp_eq_u32 vcc_lo, 12
	s_cselect_b32 s34, s9, s0
	s_cselect_b32 s35, s7, s1
	s_cselect_b32 s52, s15, s27
	s_cselect_b32 s53, s14, s37
	s_add_u32 s50, s34, 0x80
	s_addc_u32 s51, s35, 0
	ds_read_b128 v[182:185], v145
	ds_read_b128 v[186:189], v145 offset:1024
	ds_read_b128 v[190:193], v145 offset:2048
	ds_read_b128 v[194:197], v145 offset:3072
	ds_read_b128 v[198:201], v145 offset:4096
	ds_read_b128 v[202:205], v145 offset:5120
	ds_read_b128 v[206:209], v145 offset:6144
	ds_read_b128 v[210:213], v145 offset:7168
	s_add_u32 s2, s44, 0x40080
	s_addc_u32 s3, s45, 0
	s_mov_b32 s12, m0
	s_mov_b32 m0, s96
	s_nop 4
	global_load_lds_dwordx4 v1, s[2:3]
	s_mov_b32 m0, s12
	s_add_u32 s2, s44, 0x60080
	s_addc_u32 s3, s45, 0
	s_add_i32 s12, s58, 0xe000
	s_mov_b32 s13, m0
	s_mov_b32 m0, s12
	s_nop 4
	global_load_lds_dwordx4 v1, s[2:3]
	s_mov_b32 m0, s13
	s_waitcnt vmcnt(8)
	s_waitcnt lgkmcnt(0)
	s_barrier
	s_waitcnt lgkmcnt(7)
	v_mfma_f32_16x16x32_bf16 v[118:121], v[130:133], v[182:185], 0
	v_mfma_f32_16x16x32_bf16 v[114:117], v[158:161], v[182:185], 0
	s_waitcnt lgkmcnt(5)
	v_mfma_f32_16x16x32_bf16 v[102:105], v[130:133], v[190:193], 0
	v_mfma_f32_16x16x32_bf16 v[98:101], v[158:161], v[190:193], 0
	s_waitcnt lgkmcnt(3)
	v_mfma_f32_16x16x32_bf16 v[86:89], v[130:133], v[198:201], 0
	v_mfma_f32_16x16x32_bf16 v[82:85], v[158:161], v[198:201], 0
	s_waitcnt lgkmcnt(1)
	v_mfma_f32_16x16x32_bf16 v[70:73], v[130:133], v[206:209], 0
	v_mfma_f32_16x16x32_bf16 v[66:69], v[158:161], v[206:209], 0
	v_mfma_f32_16x16x32_bf16 v[118:121], v[154:157], v[186:189], v[118:121]
	v_mfma_f32_16x16x32_bf16 v[114:117], v[162:165], v[186:189], v[114:117]
	v_mfma_f32_16x16x32_bf16 v[102:105], v[154:157], v[194:197], v[102:105]
	v_mfma_f32_16x16x32_bf16 v[98:101], v[162:165], v[194:197], v[98:101]
	v_mfma_f32_16x16x32_bf16 v[86:89], v[154:157], v[202:205], v[86:89]
	v_mfma_f32_16x16x32_bf16 v[82:85], v[162:165], v[202:205], v[82:85]
	s_waitcnt lgkmcnt(0)
	v_mfma_f32_16x16x32_bf16 v[70:73], v[154:157], v[210:213], v[70:73]
	v_mfma_f32_16x16x32_bf16 v[66:69], v[162:165], v[210:213], v[66:69]
	v_mfma_f32_16x16x32_bf16 v[126:129], v[166:169], v[182:185], 0
	v_mfma_f32_16x16x32_bf16 v[122:125], v[174:177], v[182:185], 0
	v_mfma_f32_16x16x32_bf16 v[110:113], v[166:169], v[190:193], 0
	v_mfma_f32_16x16x32_bf16 v[106:109], v[174:177], v[190:193], 0
	v_mfma_f32_16x16x32_bf16 v[94:97], v[166:169], v[198:201], 0
	v_mfma_f32_16x16x32_bf16 v[90:93], v[174:177], v[198:201], 0
	v_mfma_f32_16x16x32_bf16 v[78:81], v[166:169], v[206:209], 0
	v_mfma_f32_16x16x32_bf16 v[74:77], v[174:177], v[206:209], 0
	v_mfma_f32_16x16x32_bf16 v[126:129], v[170:173], v[186:189], v[126:129]
	v_mfma_f32_16x16x32_bf16 v[122:125], v[178:181], v[186:189], v[122:125]
	v_mfma_f32_16x16x32_bf16 v[110:113], v[170:173], v[194:197], v[110:113]
	v_mfma_f32_16x16x32_bf16 v[106:109], v[178:181], v[194:197], v[106:109]
	v_mfma_f32_16x16x32_bf16 v[94:97], v[170:173], v[202:205], v[94:97]
	v_mfma_f32_16x16x32_bf16 v[90:93], v[178:181], v[202:205], v[90:93]
	v_mfma_f32_16x16x32_bf16 v[78:81], v[170:173], v[210:213], v[78:81]
	v_mfma_f32_16x16x32_bf16 v[74:77], v[178:181], v[210:213], v[74:77]
	s_barrier
	ds_read_b128 v[182:185], v145 offset:16384
	ds_read_b128 v[186:189], v145 offset:17408
	ds_read_b128 v[190:193], v145 offset:18432
	ds_read_b128 v[194:197], v145 offset:19456
	ds_read_b128 v[198:201], v145 offset:20480
	ds_read_b128 v[202:205], v145 offset:21504
	ds_read_b128 v[206:209], v145 offset:22528
	ds_read_b128 v[210:213], v145 offset:23552
	s_mov_b32 s2, m0
	s_mov_b32 m0, s60
	s_nop 4
	global_load_lds_dwordx4 v135, s[52:53]
	s_mov_b32 m0, s2
	s_add_u32 s2, s52, 0x20000
	s_addc_u32 s3, s53, 0
	s_mov_b32 s12, m0
	s_mov_b32 m0, s61
	s_nop 4
	global_load_lds_dwordx4 v135, s[2:3]
	s_mov_b32 m0, s12
	s_add_u32 s2, s52, 0x40000
	s_addc_u32 s3, s53, 0
	s_mov_b32 s12, m0
	s_mov_b32 m0, s62
	s_nop 4
	global_load_lds_dwordx4 v135, s[2:3]
	s_mov_b32 m0, s12
	s_add_u32 s2, s52, 0x60000
	s_addc_u32 s3, s53, 0
	s_mov_b32 s12, m0
	s_mov_b32 m0, s63
	s_nop 4
	global_load_lds_dwordx4 v135, s[2:3]
	s_mov_b32 m0, s12
	s_mov_b32 s2, m0
	s_mov_b32 m0, s58
	s_nop 4
	global_load_lds_dwordx4 v1, s[34:35]
	s_mov_b32 m0, s2
	s_add_u32 s2, s34, 0x20000
	s_addc_u32 s3, s35, 0
	s_mov_b32 s12, m0
	s_mov_b32 m0, s64
	s_nop 4
	global_load_lds_dwordx4 v1, s[2:3]
	s_mov_b32 m0, s12
	s_waitcnt vmcnt(8)
	s_waitcnt lgkmcnt(0)
	s_barrier
	s_waitcnt lgkmcnt(7)
	v_mfma_f32_16x16x32_bf16 v[54:57], v[130:133], v[182:185], 0
	v_mfma_f32_16x16x32_bf16 v[50:53], v[158:161], v[182:185], 0
	s_waitcnt lgkmcnt(5)
	v_mfma_f32_16x16x32_bf16 v[38:41], v[130:133], v[190:193], 0
	v_mfma_f32_16x16x32_bf16 v[34:37], v[158:161], v[190:193], 0
	s_waitcnt lgkmcnt(3)
	v_mfma_f32_16x16x32_bf16 v[22:25], v[130:133], v[198:201], 0
	v_mfma_f32_16x16x32_bf16 v[18:21], v[158:161], v[198:201], 0
	s_waitcnt lgkmcnt(1)
	v_mfma_f32_16x16x32_bf16 v[10:13], v[130:133], v[206:209], 0
	v_mfma_f32_16x16x32_bf16 v[6:9], v[158:161], v[206:209], 0
	v_mfma_f32_16x16x32_bf16 v[54:57], v[154:157], v[186:189], v[54:57]
	v_mfma_f32_16x16x32_bf16 v[50:53], v[162:165], v[186:189], v[50:53]
	v_mfma_f32_16x16x32_bf16 v[38:41], v[154:157], v[194:197], v[38:41]
	v_mfma_f32_16x16x32_bf16 v[34:37], v[162:165], v[194:197], v[34:37]
	v_mfma_f32_16x16x32_bf16 v[22:25], v[154:157], v[202:205], v[22:25]
	v_mfma_f32_16x16x32_bf16 v[18:21], v[162:165], v[202:205], v[18:21]
	s_waitcnt lgkmcnt(0)
	v_mfma_f32_16x16x32_bf16 v[10:13], v[154:157], v[210:213], v[10:13]
	v_mfma_f32_16x16x32_bf16 v[6:9], v[162:165], v[210:213], v[6:9]
	v_mfma_f32_16x16x32_bf16 v[62:65], v[166:169], v[182:185], 0
	v_mfma_f32_16x16x32_bf16 v[58:61], v[174:177], v[182:185], 0
	v_mfma_f32_16x16x32_bf16 v[46:49], v[166:169], v[190:193], 0
	v_mfma_f32_16x16x32_bf16 v[42:45], v[174:177], v[190:193], 0
	v_mfma_f32_16x16x32_bf16 v[30:33], v[166:169], v[198:201], 0
	v_mfma_f32_16x16x32_bf16 v[26:29], v[174:177], v[198:201], 0
	v_mfma_f32_16x16x32_bf16 v[14:17], v[166:169], v[206:209], 0
	v_mfma_f32_16x16x32_bf16 v[2:5], v[174:177], v[206:209], 0
	v_mfma_f32_16x16x32_bf16 v[62:65], v[170:173], v[186:189], v[62:65]
	v_mfma_f32_16x16x32_bf16 v[58:61], v[178:181], v[186:189], v[58:61]
	v_mfma_f32_16x16x32_bf16 v[46:49], v[170:173], v[194:197], v[46:49]
	v_mfma_f32_16x16x32_bf16 v[42:45], v[178:181], v[194:197], v[42:45]
	v_mfma_f32_16x16x32_bf16 v[30:33], v[170:173], v[202:205], v[30:33]
	v_mfma_f32_16x16x32_bf16 v[26:29], v[178:181], v[202:205], v[26:29]
	v_mfma_f32_16x16x32_bf16 v[14:17], v[170:173], v[210:213], v[14:17]
	v_mfma_f32_16x16x32_bf16 v[2:5], v[178:181], v[210:213], v[2:5]
	s_barrier
	v_add_u32_e32 v138, 0x18000, v143
	ds_read_b128 v[130:133], v138
	ds_read_b128 v[154:157], v138 offset:1024
	ds_read_b128 v[158:161], v138 offset:2048
	ds_read_b128 v[162:165], v138 offset:3072
	v_add_u32_e32 v138, 0x1c000, v143
	ds_read_b128 v[166:169], v138
	ds_read_b128 v[170:173], v138 offset:1024
	ds_read_b128 v[174:177], v138 offset:2048
	ds_read_b128 v[178:181], v138 offset:3072
	ds_read_b128 v[182:185], v145 offset:32768
	ds_read_b128 v[186:189], v145 offset:33792
	ds_read_b128 v[190:193], v145 offset:34816
	ds_read_b128 v[194:197], v145 offset:35840
	ds_read_b128 v[198:201], v145 offset:36864
	ds_read_b128 v[202:205], v145 offset:37888
	ds_read_b128 v[206:209], v145 offset:38912
	ds_read_b128 v[210:213], v145 offset:39936
	s_add_u32 s2, s34, 0x40000
	s_addc_u32 s3, s35, 0
	s_mov_b32 s12, m0
	s_mov_b32 m0, s65
	s_nop 4
	global_load_lds_dwordx4 v1, s[2:3]
	s_mov_b32 m0, s12
	s_add_u32 s2, s34, 0x60000
	s_addc_u32 s3, s35, 0
	s_mov_b32 s12, m0
	s_mov_b32 m0, s66
	s_nop 4
	global_load_lds_dwordx4 v1, s[2:3]
	s_mov_b32 m0, s12
	s_waitcnt vmcnt(8)
	s_waitcnt lgkmcnt(0)
	s_barrier
	s_waitcnt lgkmcnt(7)
	v_mfma_f32_16x16x32_bf16 v[118:121], v[130:133], v[182:185], v[118:121]
	v_mfma_f32_16x16x32_bf16 v[114:117], v[158:161], v[182:185], v[114:117]
	s_waitcnt lgkmcnt(5)
	v_mfma_f32_16x16x32_bf16 v[102:105], v[130:133], v[190:193], v[102:105]
	v_mfma_f32_16x16x32_bf16 v[98:101], v[158:161], v[190:193], v[98:101]
	s_waitcnt lgkmcnt(3)
	v_mfma_f32_16x16x32_bf16 v[86:89], v[130:133], v[198:201], v[86:89]
	v_mfma_f32_16x16x32_bf16 v[82:85], v[158:161], v[198:201], v[82:85]
	s_waitcnt lgkmcnt(1)
	v_mfma_f32_16x16x32_bf16 v[70:73], v[130:133], v[206:209], v[70:73]
	v_mfma_f32_16x16x32_bf16 v[66:69], v[158:161], v[206:209], v[66:69]
	v_mfma_f32_16x16x32_bf16 v[118:121], v[154:157], v[186:189], v[118:121]
	v_mfma_f32_16x16x32_bf16 v[114:117], v[162:165], v[186:189], v[114:117]
	v_mfma_f32_16x16x32_bf16 v[102:105], v[154:157], v[194:197], v[102:105]
	v_mfma_f32_16x16x32_bf16 v[98:101], v[162:165], v[194:197], v[98:101]
	v_mfma_f32_16x16x32_bf16 v[86:89], v[154:157], v[202:205], v[86:89]
	v_mfma_f32_16x16x32_bf16 v[82:85], v[162:165], v[202:205], v[82:85]
	s_waitcnt lgkmcnt(0)
	v_mfma_f32_16x16x32_bf16 v[70:73], v[154:157], v[210:213], v[70:73]
	v_mfma_f32_16x16x32_bf16 v[66:69], v[162:165], v[210:213], v[66:69]
	v_mfma_f32_16x16x32_bf16 v[126:129], v[166:169], v[182:185], v[126:129]
	v_mfma_f32_16x16x32_bf16 v[122:125], v[174:177], v[182:185], v[122:125]
	v_mfma_f32_16x16x32_bf16 v[110:113], v[166:169], v[190:193], v[110:113]
	v_mfma_f32_16x16x32_bf16 v[106:109], v[174:177], v[190:193], v[106:109]
	v_mfma_f32_16x16x32_bf16 v[94:97], v[166:169], v[198:201], v[94:97]
	v_mfma_f32_16x16x32_bf16 v[90:93], v[174:177], v[198:201], v[90:93]
	v_mfma_f32_16x16x32_bf16 v[78:81], v[166:169], v[206:209], v[78:81]
	v_mfma_f32_16x16x32_bf16 v[74:77], v[174:177], v[206:209], v[74:77]
	v_mfma_f32_16x16x32_bf16 v[126:129], v[170:173], v[186:189], v[126:129]
	v_mfma_f32_16x16x32_bf16 v[122:125], v[178:181], v[186:189], v[122:125]
	v_mfma_f32_16x16x32_bf16 v[110:113], v[170:173], v[194:197], v[110:113]
	v_mfma_f32_16x16x32_bf16 v[106:109], v[178:181], v[194:197], v[106:109]
	v_mfma_f32_16x16x32_bf16 v[94:97], v[170:173], v[202:205], v[94:97]
	v_mfma_f32_16x16x32_bf16 v[90:93], v[178:181], v[202:205], v[90:93]
	v_mfma_f32_16x16x32_bf16 v[78:81], v[170:173], v[210:213], v[78:81]
	v_mfma_f32_16x16x32_bf16 v[74:77], v[178:181], v[210:213], v[74:77]
	s_barrier
	s_add_u32 s2, s52, 0x80
	s_addc_u32 s3, s53, 0
	ds_read_b128 v[182:185], v145 offset:49152
	ds_read_b128 v[186:189], v145 offset:50176
	ds_read_b128 v[190:193], v145 offset:51200
	ds_read_b128 v[194:197], v145 offset:52224
	ds_read_b128 v[198:201], v145 offset:53248
	ds_read_b128 v[202:205], v145 offset:54272
	ds_read_b128 v[206:209], v145 offset:55296
	ds_read_b128 v[210:213], v145 offset:56320
	s_mov_b32 s12, m0
	s_mov_b32 m0, s90
	s_nop 4
	global_load_lds_dwordx4 v135, s[2:3]
	s_mov_b32 m0, s12
	s_add_u32 s2, s52, 0x20080
	s_addc_u32 s3, s53, 0
	s_mov_b32 s12, m0
	s_mov_b32 m0, s91
	s_nop 4
	global_load_lds_dwordx4 v135, s[2:3]
	s_mov_b32 m0, s12
	s_add_u32 s2, s52, 0x40080
	s_addc_u32 s3, s53, 0
	s_mov_b32 s12, m0
	s_mov_b32 m0, s94
	s_nop 4
	global_load_lds_dwordx4 v135, s[2:3]
	s_mov_b32 m0, s12
	s_add_u32 s2, s52, 0x60080
	s_addc_u32 s3, s53, 0
	s_mov_b32 s12, m0
	s_mov_b32 m0, s95
	s_nop 4
	global_load_lds_dwordx4 v135, s[2:3]
	s_mov_b32 m0, s12
	s_mov_b32 s2, m0
	s_mov_b32 m0, s92
	s_nop 4
	global_load_lds_dwordx4 v1, s[50:51]
	s_mov_b32 m0, s2
	s_add_u32 s2, s34, 0x20080
	s_addc_u32 s3, s35, 0
	s_mov_b32 s12, m0
	s_mov_b32 m0, s93
	s_nop 4
	global_load_lds_dwordx4 v1, s[2:3]
	s_mov_b32 m0, s12
	s_waitcnt vmcnt(8)
	s_waitcnt lgkmcnt(0)
	s_barrier
	s_waitcnt lgkmcnt(7)
	v_mfma_f32_16x16x32_bf16 v[54:57], v[130:133], v[182:185], v[54:57]
	v_mfma_f32_16x16x32_bf16 v[50:53], v[158:161], v[182:185], v[50:53]
	s_waitcnt lgkmcnt(5)
	v_mfma_f32_16x16x32_bf16 v[38:41], v[130:133], v[190:193], v[38:41]
	v_mfma_f32_16x16x32_bf16 v[34:37], v[158:161], v[190:193], v[34:37]
	s_waitcnt lgkmcnt(3)
	v_mfma_f32_16x16x32_bf16 v[22:25], v[130:133], v[198:201], v[22:25]
	v_mfma_f32_16x16x32_bf16 v[18:21], v[158:161], v[198:201], v[18:21]
	s_waitcnt lgkmcnt(1)
	v_mfma_f32_16x16x32_bf16 v[10:13], v[130:133], v[206:209], v[10:13]
	v_mfma_f32_16x16x32_bf16 v[6:9], v[158:161], v[206:209], v[6:9]
	v_mfma_f32_16x16x32_bf16 v[54:57], v[154:157], v[186:189], v[54:57]
	v_mfma_f32_16x16x32_bf16 v[50:53], v[162:165], v[186:189], v[50:53]
	v_mfma_f32_16x16x32_bf16 v[38:41], v[154:157], v[194:197], v[38:41]
	v_mfma_f32_16x16x32_bf16 v[34:37], v[162:165], v[194:197], v[34:37]
	v_mfma_f32_16x16x32_bf16 v[22:25], v[154:157], v[202:205], v[22:25]
	v_mfma_f32_16x16x32_bf16 v[18:21], v[162:165], v[202:205], v[18:21]
	s_waitcnt lgkmcnt(0)
	v_mfma_f32_16x16x32_bf16 v[10:13], v[154:157], v[210:213], v[10:13]
	v_mfma_f32_16x16x32_bf16 v[6:9], v[162:165], v[210:213], v[6:9]
	v_mfma_f32_16x16x32_bf16 v[62:65], v[166:169], v[182:185], v[62:65]
	v_mfma_f32_16x16x32_bf16 v[58:61], v[174:177], v[182:185], v[58:61]
	v_mfma_f32_16x16x32_bf16 v[46:49], v[166:169], v[190:193], v[46:49]
	v_mfma_f32_16x16x32_bf16 v[42:45], v[174:177], v[190:193], v[42:45]
	v_mfma_f32_16x16x32_bf16 v[30:33], v[166:169], v[198:201], v[30:33]
	v_mfma_f32_16x16x32_bf16 v[26:29], v[174:177], v[198:201], v[26:29]
	v_mfma_f32_16x16x32_bf16 v[14:17], v[166:169], v[206:209], v[14:17]
	v_mfma_f32_16x16x32_bf16 v[2:5], v[174:177], v[206:209], v[2:5]
	v_mfma_f32_16x16x32_bf16 v[62:65], v[170:173], v[186:189], v[62:65]
	v_mfma_f32_16x16x32_bf16 v[58:61], v[178:181], v[186:189], v[58:61]
	v_mfma_f32_16x16x32_bf16 v[46:49], v[170:173], v[194:197], v[46:49]
	v_mfma_f32_16x16x32_bf16 v[42:45], v[178:181], v[194:197], v[42:45]
	v_mfma_f32_16x16x32_bf16 v[30:33], v[170:173], v[202:205], v[30:33]
	v_mfma_f32_16x16x32_bf16 v[26:29], v[178:181], v[202:205], v[26:29]
	v_mfma_f32_16x16x32_bf16 v[14:17], v[170:173], v[210:213], v[14:17]
	v_mfma_f32_16x16x32_bf16 v[2:5], v[178:181], v[210:213], v[2:5]
	s_barrier
	s_add_i32 vcc_lo, vcc_lo, 2
	s_add_u32 s27, s27, 0x100
	s_addc_u32 s37, s37, 0
	s_cmp_gt_u32 vcc_lo, 13
	s_mov_b64 s[44:45], s[0:1]

.LBB0_787:
	s_andn2_b64 vcc, exec, s[4:5]
	s_mov_b64 s[0:1], -1
	s_cbranch_vccnz .LBB0_748
	s_andn2_b64 vcc, exec, s[10:11]
	v_mov_b64 v[4:5], 0
	s_cbranch_vccnz .LBB0_747
	s_barrier
	s_branch .LBB0_747

.LBB0_794:
	v_lshrrev_b32_e32 v4, 1, v2
	v_and_b32_e32 v4, 24, v4
	v_and_b32_e32 v3, 15, v2
	v_lshlrev_b32_e32 v5, 1, v4
	v_lshlrev_b32_e32 v2, 2, v2
	v_lshl_or_b32 v137, s8, 6, v3
	v_lshl_or_b32 v3, v3, 6, v5
	s_lshl_b32 s2, s8, 13
	v_and_b32_e32 v2, 32, v2
	v_bitop3_b32 v5, v3, s2, v2 bitop3:0xde
	s_lshl_b32 s2, s9, 5
	s_sext_i32_i16 s85, s4
	s_and_b32 s4, s2, 0x60
	s_lshl_b32 s2, s4, 7
	v_bitop3_b32 v6, v3, s2, v2 bitop3:0xde
	s_add_u32 s2, s0, 0x80
	s_addc_u32 s3, s1, 0
	s_add_i32 s61, s39, 0x18000
	s_waitcnt vmcnt(2)
	s_barrier
	s_mov_b32 s8, m0
	s_mov_b32 m0, s61
	s_nop 4
	global_load_lds_dwordx4 v136, s[2:3]
	s_mov_b32 m0, s8
	s_add_u32 s2, s0, 0x20080
	s_addc_u32 s3, s1, 0
	s_add_i32 s62, s39, 0x1a000
	s_mov_b32 s8, m0
	s_mov_b32 m0, s62
	s_nop 4
	global_load_lds_dwordx4 v136, s[2:3]
	s_mov_b32 m0, s8
	s_add_u32 s2, s42, 0x80
	s_addc_u32 s3, s43, 0
	s_add_i32 s63, s39, 0x8000
	s_mov_b32 s8, m0
	s_mov_b32 m0, s63
	s_nop 4
	global_load_lds_dwordx4 v1, s[2:3]
	s_mov_b32 m0, s8
	s_add_u32 s2, s42, 0x20080
	s_addc_u32 s3, s43, 0
	s_add_i32 s64, s39, 0xa000
	s_mov_b32 s8, m0
	s_mov_b32 m0, s64
	s_nop 4
	global_load_lds_dwordx4 v1, s[2:3]
	s_mov_b32 m0, s8
	s_add_u32 s2, s0, 0x40080
	s_addc_u32 s3, s1, 0
	s_add_i32 s65, s39, 0x1c000
	s_mov_b32 s8, m0
	s_mov_b32 m0, s65
	s_nop 4
	global_load_lds_dwordx4 v136, s[2:3]
	s_mov_b32 m0, s8
	s_add_u32 s2, s0, 0x60080
	s_addc_u32 s3, s1, 0
	s_add_i32 s66, s39, 0x1e000
	s_mov_b32 s8, m0
	s_mov_b32 m0, s66
	s_nop 4
	global_load_lds_dwordx4 v136, s[2:3]
	s_mov_b32 m0, s8
	s_waitcnt vmcnt(6)
	s_add_i32 s67, s39, 0xc000
	s_cmpk_lt_u32 s5, 0x100
	v_mov_b64_e32 v[2:3], 0
	s_cselect_b64 s[8:9], -1, 0
	s_ashr_i32 s73, s72, 31
	v_or_b32_e32 v138, s4, v4
	v_mov_b64_e32 v[130:131], 0x16b0
	v_mov_b64_e32 v[132:133], 0x16af
	v_add_u32_e32 v139, 0, v6
	v_add_u32_e32 v140, 0, v5
	s_mov_b32 s82, 0xc3dc0000
	s_movk_i32 s84, 0xb00
	v_mov_b32_e32 v141, 0x43dc0000
	s_waitcnt vmcnt(3)
	s_waitcnt vmcnt(2) lgkmcnt(0)
	s_barrier
	s_branch .LBB0_797

.LBB0_799:
	s_ashr_i32 s25, s24, 31
	s_lshl_b64 s[2:3], s[24:25], 19
	s_add_u32 s26, s16, s2
	s_addc_u32 s27, s17, s3
	s_and_b64 s[2:3], s[4:5], exec
	s_cselect_b32 s14, s27, s43
	s_cselect_b32 s15, s26, s42
	s_ashr_i32 s11, s10, 31
	s_lshl_b64 s[2:3], s[10:11], 19
	s_add_u32 s36, s40, s2
	s_addc_u32 s37, s41, s3
	s_and_b64 s[2:3], s[4:5], exec
	s_cselect_b32 s11, s37, s1
	s_cselect_b32 s25, s36, s0
	s_add_u32 s86, s0, 0x100
	s_addc_u32 s87, s1, 0
	s_mov_b32 s88, -2
	v_add_u32_e32 v134, 0x10000, v139
	ds_read_b128 v[142:145], v134
	ds_read_b128 v[146:149], v134 offset:1024
	ds_read_b128 v[150:153], v134 offset:2048
	ds_read_b128 v[154:157], v134 offset:3072
	v_add_u32_e32 v134, 0x14000, v139
	ds_read_b128 v[158:161], v134
	ds_read_b128 v[162:165], v134 offset:1024
	ds_read_b128 v[166:169], v134 offset:2048
	ds_read_b128 v[170:173], v134 offset:3072
	s_add_u32 s0, s42, 0x100
	s_addc_u32 s1, s43, 0
	s_cmp_eq_u32 s88, 12
	s_cselect_b32 s34, s15, s0
	s_cselect_b32 s35, s14, s1
	s_cselect_b32 s50, s25, s86
	s_cselect_b32 s51, s11, s87
	s_add_u32 s44, s34, 0x80
	s_addc_u32 s45, s35, 0
	ds_read_b128 v[174:177], v140
	ds_read_b128 v[178:181], v140 offset:1024
	ds_read_b128 v[182:185], v140 offset:2048
	ds_read_b128 v[186:189], v140 offset:3072
	ds_read_b128 v[190:193], v140 offset:4096
	ds_read_b128 v[194:197], v140 offset:5120
	ds_read_b128 v[198:201], v140 offset:6144
	ds_read_b128 v[202:205], v140 offset:7168
	s_add_u32 s2, s42, 0x40080
	s_addc_u32 s3, s43, 0
	s_mov_b32 s12, m0
	s_mov_b32 m0, s67
	s_nop 4
	global_load_lds_dwordx4 v1, s[2:3]
	s_mov_b32 m0, s12
	s_add_u32 s2, s42, 0x60080
	s_addc_u32 s3, s43, 0
	s_add_i32 s12, s39, 0xe000
	s_mov_b32 s13, m0
	s_mov_b32 m0, s12
	s_nop 4
	global_load_lds_dwordx4 v1, s[2:3]
	s_mov_b32 m0, s13
	s_waitcnt vmcnt(8)
	s_waitcnt lgkmcnt(0)
	s_barrier
	s_waitcnt lgkmcnt(7)
	v_mfma_f32_16x16x32_bf16 v[122:125], v[142:145], v[174:177], 0
	v_mfma_f32_16x16x32_bf16 v[114:117], v[150:153], v[174:177], 0
	s_waitcnt lgkmcnt(5)
	v_mfma_f32_16x16x32_bf16 v[106:109], v[142:145], v[182:185], 0
	v_mfma_f32_16x16x32_bf16 v[98:101], v[150:153], v[182:185], 0
	s_waitcnt lgkmcnt(3)
	v_mfma_f32_16x16x32_bf16 v[90:93], v[142:145], v[190:193], 0
	v_mfma_f32_16x16x32_bf16 v[82:85], v[150:153], v[190:193], 0
	s_waitcnt lgkmcnt(1)
	v_mfma_f32_16x16x32_bf16 v[74:77], v[142:145], v[198:201], 0
	v_mfma_f32_16x16x32_bf16 v[66:69], v[150:153], v[198:201], 0
	v_mfma_f32_16x16x32_bf16 v[122:125], v[146:149], v[178:181], v[122:125]
	v_mfma_f32_16x16x32_bf16 v[114:117], v[154:157], v[178:181], v[114:117]
	v_mfma_f32_16x16x32_bf16 v[106:109], v[146:149], v[186:189], v[106:109]
	v_mfma_f32_16x16x32_bf16 v[98:101], v[154:157], v[186:189], v[98:101]
	v_mfma_f32_16x16x32_bf16 v[90:93], v[146:149], v[194:197], v[90:93]
	v_mfma_f32_16x16x32_bf16 v[82:85], v[154:157], v[194:197], v[82:85]
	s_waitcnt lgkmcnt(0)
	v_mfma_f32_16x16x32_bf16 v[74:77], v[146:149], v[202:205], v[74:77]
	v_mfma_f32_16x16x32_bf16 v[66:69], v[154:157], v[202:205], v[66:69]
	v_mfma_f32_16x16x32_bf16 v[126:129], v[158:161], v[174:177], 0
	v_mfma_f32_16x16x32_bf16 v[118:121], v[166:169], v[174:177], 0
	v_mfma_f32_16x16x32_bf16 v[110:113], v[158:161], v[182:185], 0
	v_mfma_f32_16x16x32_bf16 v[102:105], v[166:169], v[182:185], 0
	v_mfma_f32_16x16x32_bf16 v[94:97], v[158:161], v[190:193], 0
	v_mfma_f32_16x16x32_bf16 v[86:89], v[166:169], v[190:193], 0
	v_mfma_f32_16x16x32_bf16 v[78:81], v[158:161], v[198:201], 0
	v_mfma_f32_16x16x32_bf16 v[70:73], v[166:169], v[198:201], 0
	v_mfma_f32_16x16x32_bf16 v[126:129], v[162:165], v[178:181], v[126:129]
	v_mfma_f32_16x16x32_bf16 v[118:121], v[170:173], v[178:181], v[118:121]
	v_mfma_f32_16x16x32_bf16 v[110:113], v[162:165], v[186:189], v[110:113]
	v_mfma_f32_16x16x32_bf16 v[102:105], v[170:173], v[186:189], v[102:105]
	v_mfma_f32_16x16x32_bf16 v[94:97], v[162:165], v[194:197], v[94:97]
	v_mfma_f32_16x16x32_bf16 v[86:89], v[170:173], v[194:197], v[86:89]
	v_mfma_f32_16x16x32_bf16 v[78:81], v[162:165], v[202:205], v[78:81]
	v_mfma_f32_16x16x32_bf16 v[70:73], v[170:173], v[202:205], v[70:73]
	s_barrier
	ds_read_b128 v[174:177], v140 offset:16384
	ds_read_b128 v[178:181], v140 offset:17408
	ds_read_b128 v[182:185], v140 offset:18432
	ds_read_b128 v[186:189], v140 offset:19456
	ds_read_b128 v[190:193], v140 offset:20480
	ds_read_b128 v[194:197], v140 offset:21504
	ds_read_b128 v[198:201], v140 offset:22528
	ds_read_b128 v[202:205], v140 offset:23552
	s_mov_b32 s2, m0
	s_mov_b32 m0, s54
	s_nop 4
	global_load_lds_dwordx4 v136, s[50:51]
	s_mov_b32 m0, s2
	s_add_u32 s2, s50, 0x20000
	s_addc_u32 s3, s51, 0
	s_mov_b32 s12, m0
	s_mov_b32 m0, s55
	s_nop 4
	global_load_lds_dwordx4 v136, s[2:3]
	s_mov_b32 m0, s12
	s_add_u32 s2, s50, 0x40000
	s_addc_u32 s3, s51, 0
	s_mov_b32 s12, m0
	s_mov_b32 m0, s56
	s_nop 4
	global_load_lds_dwordx4 v136, s[2:3]
	s_mov_b32 m0, s12
	s_add_u32 s2, s50, 0x60000
	s_addc_u32 s3, s51, 0
	s_mov_b32 s12, m0
	s_mov_b32 m0, s57
	s_nop 4
	global_load_lds_dwordx4 v136, s[2:3]
	s_mov_b32 m0, s12
	s_mov_b32 s2, m0
	s_mov_b32 m0, s39
	s_nop 4
	global_load_lds_dwordx4 v1, s[34:35]
	s_mov_b32 m0, s2
	s_add_u32 s2, s34, 0x20000
	s_addc_u32 s3, s35, 0
	s_mov_b32 s12, m0
	s_mov_b32 m0, s58
	s_nop 4
	global_load_lds_dwordx4 v1, s[2:3]
	s_mov_b32 m0, s12
	s_waitcnt vmcnt(8)
	s_waitcnt lgkmcnt(0)
	s_barrier
	s_waitcnt lgkmcnt(7)
	v_mfma_f32_16x16x32_bf16 v[58:61], v[142:145], v[174:177], 0
	v_mfma_f32_16x16x32_bf16 v[50:53], v[150:153], v[174:177], 0
	s_waitcnt lgkmcnt(5)
	v_mfma_f32_16x16x32_bf16 v[42:45], v[142:145], v[182:185], 0
	v_mfma_f32_16x16x32_bf16 v[34:37], v[150:153], v[182:185], 0
	s_waitcnt lgkmcnt(3)
	v_mfma_f32_16x16x32_bf16 v[26:29], v[142:145], v[190:193], 0
	v_mfma_f32_16x16x32_bf16 v[18:21], v[150:153], v[190:193], 0
	s_waitcnt lgkmcnt(1)
	v_mfma_f32_16x16x32_bf16 v[10:13], v[142:145], v[198:201], 0
	v_mfma_f32_16x16x32_bf16 v[6:9], v[150:153], v[198:201], 0
	v_mfma_f32_16x16x32_bf16 v[58:61], v[146:149], v[178:181], v[58:61]
	v_mfma_f32_16x16x32_bf16 v[50:53], v[154:157], v[178:181], v[50:53]
	v_mfma_f32_16x16x32_bf16 v[42:45], v[146:149], v[186:189], v[42:45]
	v_mfma_f32_16x16x32_bf16 v[34:37], v[154:157], v[186:189], v[34:37]
	v_mfma_f32_16x16x32_bf16 v[26:29], v[146:149], v[194:197], v[26:29]
	v_mfma_f32_16x16x32_bf16 v[18:21], v[154:157], v[194:197], v[18:21]
	s_waitcnt lgkmcnt(0)
	v_mfma_f32_16x16x32_bf16 v[10:13], v[146:149], v[202:205], v[10:13]
	v_mfma_f32_16x16x32_bf16 v[6:9], v[154:157], v[202:205], v[6:9]
	v_mfma_f32_16x16x32_bf16 v[62:65], v[158:161], v[174:177], 0
	v_mfma_f32_16x16x32_bf16 v[54:57], v[166:169], v[174:177], 0
	v_mfma_f32_16x16x32_bf16 v[46:49], v[158:161], v[182:185], 0
	v_mfma_f32_16x16x32_bf16 v[38:41], v[166:169], v[182:185], 0
	v_mfma_f32_16x16x32_bf16 v[30:33], v[158:161], v[190:193], 0
	v_mfma_f32_16x16x32_bf16 v[22:25], v[166:169], v[190:193], 0
	v_mfma_f32_16x16x32_bf16 v[14:17], v[158:161], v[198:201], 0
	v_mfma_f32_16x16x32_bf16 v[2:5], v[166:169], v[198:201], 0
	v_mfma_f32_16x16x32_bf16 v[62:65], v[162:165], v[178:181], v[62:65]
	v_mfma_f32_16x16x32_bf16 v[54:57], v[170:173], v[178:181], v[54:57]
	v_mfma_f32_16x16x32_bf16 v[46:49], v[162:165], v[186:189], v[46:49]
	v_mfma_f32_16x16x32_bf16 v[38:41], v[170:173], v[186:189], v[38:41]
	v_mfma_f32_16x16x32_bf16 v[30:33], v[162:165], v[194:197], v[30:33]
	v_mfma_f32_16x16x32_bf16 v[22:25], v[170:173], v[194:197], v[22:25]
	v_mfma_f32_16x16x32_bf16 v[14:17], v[162:165], v[202:205], v[14:17]
	v_mfma_f32_16x16x32_bf16 v[2:5], v[170:173], v[202:205], v[2:5]
	s_barrier
	v_add_u32_e32 v134, 0x18000, v139
	ds_read_b128 v[142:145], v134
	ds_read_b128 v[146:149], v134 offset:1024
	ds_read_b128 v[150:153], v134 offset:2048
	ds_read_b128 v[154:157], v134 offset:3072
	v_add_u32_e32 v134, 0x1c000, v139
	ds_read_b128 v[158:161], v134
	ds_read_b128 v[162:165], v134 offset:1024
	ds_read_b128 v[166:169], v134 offset:2048
	ds_read_b128 v[170:173], v134 offset:3072
	ds_read_b128 v[174:177], v140 offset:32768
	ds_read_b128 v[178:181], v140 offset:33792
	ds_read_b128 v[182:185], v140 offset:34816
	ds_read_b128 v[186:189], v140 offset:35840
	ds_read_b128 v[190:193], v140 offset:36864
	ds_read_b128 v[194:197], v140 offset:37888
	ds_read_b128 v[198:201], v140 offset:38912
	ds_read_b128 v[202:205], v140 offset:39936
	s_add_u32 s2, s34, 0x40000
	s_addc_u32 s3, s35, 0
	s_mov_b32 s12, m0
	s_mov_b32 m0, s59
	s_nop 4
	global_load_lds_dwordx4 v1, s[2:3]
	s_mov_b32 m0, s12
	s_add_u32 s2, s34, 0x60000
	s_addc_u32 s3, s35, 0
	s_mov_b32 s12, m0
	s_mov_b32 m0, s60
	s_nop 4
	global_load_lds_dwordx4 v1, s[2:3]
	s_mov_b32 m0, s12
	s_waitcnt vmcnt(8)
	s_waitcnt lgkmcnt(0)
	s_barrier
	s_waitcnt lgkmcnt(7)
	v_mfma_f32_16x16x32_bf16 v[122:125], v[142:145], v[174:177], v[122:125]
	v_mfma_f32_16x16x32_bf16 v[114:117], v[150:153], v[174:177], v[114:117]
	s_waitcnt lgkmcnt(5)
	v_mfma_f32_16x16x32_bf16 v[106:109], v[142:145], v[182:185], v[106:109]
	v_mfma_f32_16x16x32_bf16 v[98:101], v[150:153], v[182:185], v[98:101]
	s_waitcnt lgkmcnt(3)
	v_mfma_f32_16x16x32_bf16 v[90:93], v[142:145], v[190:193], v[90:93]
	v_mfma_f32_16x16x32_bf16 v[82:85], v[150:153], v[190:193], v[82:85]
	s_waitcnt lgkmcnt(1)
	v_mfma_f32_16x16x32_bf16 v[74:77], v[142:145], v[198:201], v[74:77]
	v_mfma_f32_16x16x32_bf16 v[66:69], v[150:153], v[198:201], v[66:69]
	v_mfma_f32_16x16x32_bf16 v[122:125], v[146:149], v[178:181], v[122:125]
	v_mfma_f32_16x16x32_bf16 v[114:117], v[154:157], v[178:181], v[114:117]
	v_mfma_f32_16x16x32_bf16 v[106:109], v[146:149], v[186:189], v[106:109]
	v_mfma_f32_16x16x32_bf16 v[98:101], v[154:157], v[186:189], v[98:101]
	v_mfma_f32_16x16x32_bf16 v[90:93], v[146:149], v[194:197], v[90:93]
	v_mfma_f32_16x16x32_bf16 v[82:85], v[154:157], v[194:197], v[82:85]
	s_waitcnt lgkmcnt(0)
	v_mfma_f32_16x16x32_bf16 v[74:77], v[146:149], v[202:205], v[74:77]
	v_mfma_f32_16x16x32_bf16 v[66:69], v[154:157], v[202:205], v[66:69]
	v_mfma_f32_16x16x32_bf16 v[126:129], v[158:161], v[174:177], v[126:129]
	v_mfma_f32_16x16x32_bf16 v[118:121], v[166:169], v[174:177], v[118:121]
	v_mfma_f32_16x16x32_bf16 v[110:113], v[158:161], v[182:185], v[110:113]
	v_mfma_f32_16x16x32_bf16 v[102:105], v[166:169], v[182:185], v[102:105]
	v_mfma_f32_16x16x32_bf16 v[94:97], v[158:161], v[190:193], v[94:97]
	v_mfma_f32_16x16x32_bf16 v[86:89], v[166:169], v[190:193], v[86:89]
	v_mfma_f32_16x16x32_bf16 v[78:81], v[158:161], v[198:201], v[78:81]
	v_mfma_f32_16x16x32_bf16 v[70:73], v[166:169], v[198:201], v[70:73]
	v_mfma_f32_16x16x32_bf16 v[126:129], v[162:165], v[178:181], v[126:129]
	v_mfma_f32_16x16x32_bf16 v[118:121], v[170:173], v[178:181], v[118:121]
	v_mfma_f32_16x16x32_bf16 v[110:113], v[162:165], v[186:189], v[110:113]
	v_mfma_f32_16x16x32_bf16 v[102:105], v[170:173], v[186:189], v[102:105]
	v_mfma_f32_16x16x32_bf16 v[94:97], v[162:165], v[194:197], v[94:97]
	v_mfma_f32_16x16x32_bf16 v[86:89], v[170:173], v[194:197], v[86:89]
	v_mfma_f32_16x16x32_bf16 v[78:81], v[162:165], v[202:205], v[78:81]
	v_mfma_f32_16x16x32_bf16 v[70:73], v[170:173], v[202:205], v[70:73]
	s_barrier
	s_add_u32 s2, s50, 0x80
	s_addc_u32 s3, s51, 0
	ds_read_b128 v[174:177], v140 offset:49152
	ds_read_b128 v[178:181], v140 offset:50176
	ds_read_b128 v[182:185], v140 offset:51200
	ds_read_b128 v[186:189], v140 offset:52224
	ds_read_b128 v[190:193], v140 offset:53248
	ds_read_b128 v[194:197], v140 offset:54272
	ds_read_b128 v[198:201], v140 offset:55296
	ds_read_b128 v[202:205], v140 offset:56320
	s_mov_b32 s12, m0
	s_mov_b32 m0, s61
	s_nop 4
	global_load_lds_dwordx4 v136, s[2:3]
	s_mov_b32 m0, s12
	s_add_u32 s2, s50, 0x20080
	s_addc_u32 s3, s51, 0
	s_mov_b32 s12, m0
	s_mov_b32 m0, s62
	s_nop 4
	global_load_lds_dwordx4 v136, s[2:3]
	s_mov_b32 m0, s12
	s_add_u32 s2, s50, 0x40080
	s_addc_u32 s3, s51, 0
	s_mov_b32 s12, m0
	s_mov_b32 m0, s65
	s_nop 4
	global_load_lds_dwordx4 v136, s[2:3]
	s_mov_b32 m0, s12
	s_add_u32 s2, s50, 0x60080
	s_addc_u32 s3, s51, 0
	s_mov_b32 s12, m0
	s_mov_b32 m0, s66
	s_nop 4
	global_load_lds_dwordx4 v136, s[2:3]
	s_mov_b32 m0, s12
	s_mov_b32 s2, m0
	s_mov_b32 m0, s63
	s_nop 4
	global_load_lds_dwordx4 v1, s[44:45]
	s_mov_b32 m0, s2
	s_add_u32 s2, s34, 0x20080
	s_addc_u32 s3, s35, 0
	s_mov_b32 s12, m0
	s_mov_b32 m0, s64
	s_nop 4
	global_load_lds_dwordx4 v1, s[2:3]
	s_mov_b32 m0, s12
	s_waitcnt vmcnt(8)
	s_waitcnt lgkmcnt(0)
	s_barrier
	s_waitcnt lgkmcnt(7)
	v_mfma_f32_16x16x32_bf16 v[58:61], v[142:145], v[174:177], v[58:61]
	v_mfma_f32_16x16x32_bf16 v[50:53], v[150:153], v[174:177], v[50:53]
	s_waitcnt lgkmcnt(5)
	v_mfma_f32_16x16x32_bf16 v[42:45], v[142:145], v[182:185], v[42:45]
	v_mfma_f32_16x16x32_bf16 v[34:37], v[150:153], v[182:185], v[34:37]
	s_waitcnt lgkmcnt(3)
	v_mfma_f32_16x16x32_bf16 v[26:29], v[142:145], v[190:193], v[26:29]
	v_mfma_f32_16x16x32_bf16 v[18:21], v[150:153], v[190:193], v[18:21]
	s_waitcnt lgkmcnt(1)
	v_mfma_f32_16x16x32_bf16 v[10:13], v[142:145], v[198:201], v[10:13]
	v_mfma_f32_16x16x32_bf16 v[6:9], v[150:153], v[198:201], v[6:9]
	v_mfma_f32_16x16x32_bf16 v[58:61], v[146:149], v[178:181], v[58:61]
	v_mfma_f32_16x16x32_bf16 v[50:53], v[154:157], v[178:181], v[50:53]
	v_mfma_f32_16x16x32_bf16 v[42:45], v[146:149], v[186:189], v[42:45]
	v_mfma_f32_16x16x32_bf16 v[34:37], v[154:157], v[186:189], v[34:37]
	v_mfma_f32_16x16x32_bf16 v[26:29], v[146:149], v[194:197], v[26:29]
	v_mfma_f32_16x16x32_bf16 v[18:21], v[154:157], v[194:197], v[18:21]
	s_waitcnt lgkmcnt(0)
	v_mfma_f32_16x16x32_bf16 v[10:13], v[146:149], v[202:205], v[10:13]
	v_mfma_f32_16x16x32_bf16 v[6:9], v[154:157], v[202:205], v[6:9]
	v_mfma_f32_16x16x32_bf16 v[62:65], v[158:161], v[174:177], v[62:65]
	v_mfma_f32_16x16x32_bf16 v[54:57], v[166:169], v[174:177], v[54:57]
	v_mfma_f32_16x16x32_bf16 v[46:49], v[158:161], v[182:185], v[46:49]
	v_mfma_f32_16x16x32_bf16 v[38:41], v[166:169], v[182:185], v[38:41]
	v_mfma_f32_16x16x32_bf16 v[30:33], v[158:161], v[190:193], v[30:33]
	v_mfma_f32_16x16x32_bf16 v[22:25], v[166:169], v[190:193], v[22:25]
	v_mfma_f32_16x16x32_bf16 v[14:17], v[158:161], v[198:201], v[14:17]
	v_mfma_f32_16x16x32_bf16 v[2:5], v[166:169], v[198:201], v[2:5]
	v_mfma_f32_16x16x32_bf16 v[62:65], v[162:165], v[178:181], v[62:65]
	v_mfma_f32_16x16x32_bf16 v[54:57], v[170:173], v[178:181], v[54:57]
	v_mfma_f32_16x16x32_bf16 v[46:49], v[162:165], v[186:189], v[46:49]
	v_mfma_f32_16x16x32_bf16 v[38:41], v[170:173], v[186:189], v[38:41]
	v_mfma_f32_16x16x32_bf16 v[30:33], v[162:165], v[194:197], v[30:33]
	v_mfma_f32_16x16x32_bf16 v[22:25], v[170:173], v[194:197], v[22:25]
	v_mfma_f32_16x16x32_bf16 v[14:17], v[162:165], v[202:205], v[14:17]
	v_mfma_f32_16x16x32_bf16 v[2:5], v[170:173], v[202:205], v[2:5]
	s_barrier
	s_add_i32 s88, s88, 2
	s_add_u32 s86, s86, 0x100
	s_addc_u32 s87, s87, 0
	s_cmp_gt_u32 s88, 13
	s_mov_b64 s[42:43], s[0:1]

.LBB0_803:
	v_exp_f32_e64 v144, -v122
	v_exp_f32_e64 v145, -v123
	v_pk_mul_f32 v[128:129], v[124:125], v[128:129]
	v_exp_f32_e64 v124, -v124
	v_exp_f32_e64 v125, -v125
	v_pk_add_f32 v[144:145], v[144:145], 1.0 op_sel_hi:[1,0]
	v_pk_mul_f32 v[122:123], v[122:123], v[126:127]
	v_rcp_f32_e32 v126, v144
	v_rcp_f32_e32 v127, v145
	v_pk_add_f32 v[124:125], v[124:125], 1.0 op_sel_hi:[1,0]
	v_pk_mul_f32 v[112:113], v[108:109], v[112:113]
	v_rcp_f32_e32 v124, v124
	v_rcp_f32_e32 v125, v125
	v_pk_mul_f32 v[122:123], v[126:127], v[122:123]
	v_exp_f32_e64 v126, -v114
	v_exp_f32_e64 v127, -v115
	v_pk_mul_f32 v[124:125], v[124:125], v[128:129]
	v_exp_f32_e64 v128, -v116
	v_exp_f32_e64 v129, -v117
	v_pk_add_f32 v[126:127], v[126:127], 1.0 op_sel_hi:[1,0]
	v_pk_mul_f32 v[114:115], v[114:115], v[118:119]
	v_rcp_f32_e32 v126, v126
	v_rcp_f32_e32 v127, v127
	v_pk_add_f32 v[128:129], v[128:129], 1.0 op_sel_hi:[1,0]
	v_pk_mul_f32 v[116:117], v[116:117], v[120:121]
	v_rcp_f32_e32 v128, v128
	v_rcp_f32_e32 v129, v129
	v_pk_mul_f32 v[114:115], v[126:127], v[114:115]
	v_med3_f32 v119, v122, s82, v141
	v_med3_f32 v120, v123, s82, v141
	v_mov_b32_e32 v118, 0
	v_pk_mul_f32 v[116:117], v[128:129], v[116:117]
	v_med3_f32 v114, v114, s82, v141
	v_med3_f32 v115, v115, s82, v141
	v_cvt_pk_fp8_f32 v118, v119, v120
	v_mov_b32_e32 v119, 0
	v_cvt_pk_fp8_f32 v119, v114, v115
	v_med3_f32 v114, v116, s82, v141
	v_med3_f32 v115, v117, s82, v141
	v_exp_f32_e64 v116, -v106
	v_exp_f32_e64 v117, -v107
	v_exp_f32_e64 v108, -v108
	v_exp_f32_e64 v109, -v109
	v_pk_mul_f32 v[106:107], v[106:107], v[110:111]
	v_pk_add_f32 v[116:117], v[116:117], 1.0 op_sel_hi:[1,0]
	v_lshl_add_u32 v142, s38, 8, v137
	v_rcp_f32_e32 v110, v116
	v_rcp_f32_e32 v111, v117
	v_pk_add_f32 v[108:109], v[108:109], 1.0 op_sel_hi:[1,0]
	v_lshl_or_b32 v134, s85, 7, v138
	v_rcp_f32_e32 v108, v108
	v_rcp_f32_e32 v109, v109
	v_pk_mul_f32 v[106:107], v[110:111], v[106:107]
	v_exp_f32_e64 v110, -v98
	v_exp_f32_e64 v111, -v99
	v_pk_mul_f32 v[108:109], v[108:109], v[112:113]
	v_exp_f32_e64 v112, -v100
	v_exp_f32_e64 v113, -v101
	v_pk_add_f32 v[110:111], v[110:111], 1.0 op_sel_hi:[1,0]
	v_pk_mul_f32 v[98:99], v[98:99], v[102:103]
	v_rcp_f32_e32 v110, v110
	v_rcp_f32_e32 v111, v111
	v_pk_add_f32 v[112:113], v[112:113], 1.0 op_sel_hi:[1,0]
	v_med3_f32 v102, v106, s82, v141
	v_rcp_f32_e32 v112, v112
	v_rcp_f32_e32 v113, v113
	v_pk_mul_f32 v[98:99], v[110:111], v[98:99]
	v_med3_f32 v103, v107, s82, v141
	v_med3_f32 v106, v98, s82, v141
	v_med3_f32 v107, v99, s82, v141
	v_mov_b32_e32 v98, 0
	v_mov_b32_e32 v99, 0
	v_cvt_pk_fp8_f32 v98, v102, v103
	v_cvt_pk_fp8_f32 v99, v106, v107
	v_pk_mul_f32 v[100:101], v[100:101], v[104:105]
	v_med3_f32 v104, v108, s82, v141
	v_pk_mul_f32 v[100:101], v[112:113], v[100:101]
	v_med3_f32 v105, v109, s82, v141
	v_med3_f32 v100, v100, s82, v141
	v_med3_f32 v101, v101, s82, v141
	v_cvt_pk_fp8_f32 v98, v104, v105 op_sel:[0,0,1]
	v_cvt_pk_fp8_f32 v99, v100, v101 op_sel:[0,0,1]
	v_exp_f32_e64 v100, -v90
	v_exp_f32_e64 v101, -v91
	v_cvt_pk_fp8_f32 v119, v114, v115 op_sel:[0,0,1]
	v_mov_b64_e32 v[114:115], s[18:19]
	v_or_b32_e32 v102, 16, v142
	v_ashrrev_i32_e32 v135, 31, v134
	v_mad_i64_i32 v[102:103], s[0:1], v102, s84, v[114:115]
	v_lshl_add_u64 v[102:103], v[102:103], 0, v[134:135]
	global_store_dwordx2 v[102:103], v[98:99], off
	v_pk_add_f32 v[98:99], v[100:101], 1.0 op_sel_hi:[1,0]
	v_pk_mul_f32 v[96:97], v[92:93], v[96:97]
	v_exp_f32_e64 v92, -v92
	v_exp_f32_e64 v93, -v93
	v_pk_mul_f32 v[90:91], v[90:91], v[94:95]
	v_rcp_f32_e32 v94, v98
	v_rcp_f32_e32 v95, v99
	v_pk_add_f32 v[92:93], v[92:93], 1.0 op_sel_hi:[1,0]
	v_pk_mul_f32 v[80:81], v[76:77], v[80:81]
	v_rcp_f32_e32 v92, v92
	v_rcp_f32_e32 v93, v93
	v_pk_mul_f32 v[90:91], v[94:95], v[90:91]
	v_exp_f32_e64 v94, -v82
	v_exp_f32_e64 v95, -v83
	v_pk_mul_f32 v[92:93], v[92:93], v[96:97]
	v_exp_f32_e64 v96, -v84
	v_exp_f32_e64 v97, -v85
	v_pk_add_f32 v[94:95], v[94:95], 1.0 op_sel_hi:[1,0]
	v_pk_mul_f32 v[82:83], v[82:83], v[86:87]
	v_rcp_f32_e32 v94, v94
	v_rcp_f32_e32 v95, v95
	v_pk_add_f32 v[96:97], v[96:97], 1.0 op_sel_hi:[1,0]
	v_med3_f32 v86, v90, s82, v141
	v_rcp_f32_e32 v96, v96
	v_rcp_f32_e32 v97, v97
	v_pk_mul_f32 v[82:83], v[94:95], v[82:83]
	v_med3_f32 v87, v91, s82, v141
	v_med3_f32 v90, v82, s82, v141
	v_med3_f32 v91, v83, s82, v141
	v_mov_b32_e32 v82, 0
	v_mov_b32_e32 v83, 0
	v_cvt_pk_fp8_f32 v82, v86, v87
	v_cvt_pk_fp8_f32 v83, v90, v91
	v_pk_mul_f32 v[84:85], v[84:85], v[88:89]
	v_med3_f32 v88, v92, s82, v141
	v_pk_mul_f32 v[84:85], v[96:97], v[84:85]
	v_med3_f32 v89, v93, s82, v141
	v_med3_f32 v84, v84, s82, v141
	v_med3_f32 v85, v85, s82, v141
	v_cvt_pk_fp8_f32 v82, v88, v89 op_sel:[0,0,1]
	v_cvt_pk_fp8_f32 v83, v84, v85 op_sel:[0,0,1]
	v_exp_f32_e64 v84, -v74
	v_exp_f32_e64 v85, -v75
	v_or_b32_e32 v86, 32, v142
	v_mad_i64_i32 v[86:87], s[0:1], v86, s84, v[114:115]
	v_lshl_add_u64 v[86:87], v[86:87], 0, v[134:135]
	global_store_dwordx2 v[86:87], v[82:83], off
	v_pk_add_f32 v[82:83], v[84:85], 1.0 op_sel_hi:[1,0]
	v_exp_f32_e64 v76, -v76
	v_exp_f32_e64 v77, -v77
	v_pk_mul_f32 v[74:75], v[74:75], v[78:79]
	v_rcp_f32_e32 v78, v82
	v_rcp_f32_e32 v79, v83
	v_pk_add_f32 v[76:77], v[76:77], 1.0 op_sel_hi:[1,0]
	v_pk_mul_f32 v[64:65], v[60:61], v[64:65]
	v_rcp_f32_e32 v76, v76
	v_rcp_f32_e32 v77, v77
	v_pk_mul_f32 v[74:75], v[78:79], v[74:75]
	v_exp_f32_e64 v78, -v66
	v_exp_f32_e64 v79, -v67
	v_pk_mul_f32 v[76:77], v[76:77], v[80:81]
	v_exp_f32_e64 v80, -v68
	v_exp_f32_e64 v81, -v69
	v_pk_add_f32 v[78:79], v[78:79], 1.0 op_sel_hi:[1,0]
	v_pk_mul_f32 v[66:67], v[66:67], v[70:71]
	v_rcp_f32_e32 v78, v78
	v_rcp_f32_e32 v79, v79
	v_pk_add_f32 v[80:81], v[80:81], 1.0 op_sel_hi:[1,0]
	v_med3_f32 v70, v74, s82, v141
	v_rcp_f32_e32 v80, v80
	v_rcp_f32_e32 v81, v81
	v_pk_mul_f32 v[66:67], v[78:79], v[66:67]
	v_med3_f32 v71, v75, s82, v141
	v_med3_f32 v74, v66, s82, v141
	v_med3_f32 v75, v67, s82, v141
	v_mov_b32_e32 v66, 0
	v_mov_b32_e32 v67, 0
	v_cvt_pk_fp8_f32 v66, v70, v71
	v_cvt_pk_fp8_f32 v67, v74, v75
	v_pk_mul_f32 v[68:69], v[68:69], v[72:73]
	v_med3_f32 v72, v76, s82, v141
	v_pk_mul_f32 v[68:69], v[80:81], v[68:69]
	v_med3_f32 v73, v77, s82, v141
	v_med3_f32 v68, v68, s82, v141
	v_med3_f32 v69, v69, s82, v141
	v_cvt_pk_fp8_f32 v66, v72, v73 op_sel:[0,0,1]
	v_cvt_pk_fp8_f32 v67, v68, v69 op_sel:[0,0,1]
	v_exp_f32_e64 v70, -v58
	v_exp_f32_e64 v71, -v59
	v_or_b32_e32 v68, 48, v142
	v_mad_i64_i32 v[68:69], s[0:1], v68, s84, v[114:115]
	v_lshl_add_u64 v[68:69], v[68:69], 0, v[134:135]
	global_store_dwordx2 v[68:69], v[66:67], off
	v_pk_add_f32 v[66:67], v[70:71], 1.0 op_sel_hi:[1,0]
	v_exp_f32_e64 v60, -v60
	v_exp_f32_e64 v61, -v61
	v_pk_mul_f32 v[58:59], v[58:59], v[62:63]
	v_rcp_f32_e32 v62, v66
	v_rcp_f32_e32 v63, v67
	v_pk_add_f32 v[60:61], v[60:61], 1.0 op_sel_hi:[1,0]
	v_add_u32_e32 v68, 0x80, v142
	v_rcp_f32_e32 v60, v60
	v_rcp_f32_e32 v61, v61
	v_pk_mul_f32 v[58:59], v[62:63], v[58:59]
	v_exp_f32_e64 v62, -v50
	v_exp_f32_e64 v63, -v51
	v_pk_mul_f32 v[60:61], v[60:61], v[64:65]
	v_exp_f32_e64 v64, -v52
	v_exp_f32_e64 v65, -v53
	v_pk_add_f32 v[62:63], v[62:63], 1.0 op_sel_hi:[1,0]
	v_pk_mul_f32 v[50:51], v[50:51], v[54:55]
	v_rcp_f32_e32 v62, v62
	v_rcp_f32_e32 v63, v63
	v_pk_add_f32 v[64:65], v[64:65], 1.0 op_sel_hi:[1,0]
	v_med3_f32 v54, v58, s82, v141
	v_rcp_f32_e32 v64, v64
	v_rcp_f32_e32 v65, v65
	v_pk_mul_f32 v[50:51], v[62:63], v[50:51]
	v_med3_f32 v55, v59, s82, v141
	v_med3_f32 v58, v50, s82, v141
	v_med3_f32 v59, v51, s82, v141
	v_mov_b32_e32 v50, 0
	v_mov_b32_e32 v51, 0
	v_cvt_pk_fp8_f32 v50, v54, v55
	v_cvt_pk_fp8_f32 v51, v58, v59
	v_pk_mul_f32 v[52:53], v[52:53], v[56:57]
	v_med3_f32 v56, v60, s82, v141
	v_pk_mul_f32 v[52:53], v[64:65], v[52:53]
	v_med3_f32 v57, v61, s82, v141
	v_med3_f32 v52, v52, s82, v141
	v_med3_f32 v53, v53, s82, v141
	v_cvt_pk_fp8_f32 v50, v56, v57 op_sel:[0,0,1]
	v_cvt_pk_fp8_f32 v51, v52, v53 op_sel:[0,0,1]
	v_exp_f32_e64 v52, -v42
	v_exp_f32_e64 v53, -v43
	v_mad_i64_i32 v[54:55], s[0:1], v68, s84, v[114:115]
	v_lshl_add_u64 v[54:55], v[54:55], 0, v[134:135]
	global_store_dwordx2 v[54:55], v[50:51], off
	v_pk_add_f32 v[50:51], v[52:53], 1.0 op_sel_hi:[1,0]
	v_pk_mul_f32 v[48:49], v[44:45], v[48:49]
	v_exp_f32_e64 v44, -v44
	v_exp_f32_e64 v45, -v45
	v_pk_mul_f32 v[42:43], v[42:43], v[46:47]
	v_rcp_f32_e32 v46, v50
	v_rcp_f32_e32 v47, v51
	v_pk_add_f32 v[44:45], v[44:45], 1.0 op_sel_hi:[1,0]
	v_pk_mul_f32 v[32:33], v[28:29], v[32:33]
	v_rcp_f32_e32 v44, v44
	v_rcp_f32_e32 v45, v45
	v_pk_mul_f32 v[42:43], v[46:47], v[42:43]
	v_exp_f32_e64 v46, -v34
	v_exp_f32_e64 v47, -v35
	v_pk_mul_f32 v[44:45], v[44:45], v[48:49]
	v_exp_f32_e64 v48, -v36
	v_exp_f32_e64 v49, -v37
	v_pk_add_f32 v[46:47], v[46:47], 1.0 op_sel_hi:[1,0]
	v_pk_mul_f32 v[34:35], v[34:35], v[38:39]
	v_rcp_f32_e32 v46, v46
	v_rcp_f32_e32 v47, v47
	v_pk_add_f32 v[48:49], v[48:49], 1.0 op_sel_hi:[1,0]
	v_med3_f32 v38, v42, s82, v141
	v_rcp_f32_e32 v48, v48
	v_rcp_f32_e32 v49, v49
	v_pk_mul_f32 v[34:35], v[46:47], v[34:35]
	v_med3_f32 v39, v43, s82, v141
	v_med3_f32 v42, v34, s82, v141
	v_med3_f32 v43, v35, s82, v141
	v_mov_b32_e32 v34, 0
	v_mov_b32_e32 v35, 0
	v_cvt_pk_fp8_f32 v34, v38, v39
	v_cvt_pk_fp8_f32 v35, v42, v43
	v_pk_mul_f32 v[36:37], v[36:37], v[40:41]
	v_med3_f32 v40, v44, s82, v141
	v_pk_mul_f32 v[36:37], v[48:49], v[36:37]
	v_med3_f32 v41, v45, s82, v141
	v_med3_f32 v36, v36, s82, v141
	v_med3_f32 v37, v37, s82, v141
	v_cvt_pk_fp8_f32 v34, v40, v41 op_sel:[0,0,1]
	v_cvt_pk_fp8_f32 v35, v36, v37 op_sel:[0,0,1]
	v_exp_f32_e64 v36, -v26
	v_exp_f32_e64 v37, -v27
	v_add_u32_e32 v38, 0x90, v142
	v_mad_i64_i32 v[38:39], s[0:1], v38, s84, v[114:115]
	v_lshl_add_u64 v[38:39], v[38:39], 0, v[134:135]
	global_store_dwordx2 v[38:39], v[34:35], off
	v_pk_add_f32 v[34:35], v[36:37], 1.0 op_sel_hi:[1,0]
	v_exp_f32_e64 v28, -v28
	v_exp_f32_e64 v29, -v29
	v_pk_mul_f32 v[26:27], v[26:27], v[30:31]
	v_rcp_f32_e32 v30, v34
	v_rcp_f32_e32 v31, v35
	v_pk_add_f32 v[28:29], v[28:29], 1.0 op_sel_hi:[1,0]
	v_pk_mul_f32 v[16:17], v[12:13], v[16:17]
	v_rcp_f32_e32 v28, v28
	v_rcp_f32_e32 v29, v29
	v_pk_mul_f32 v[26:27], v[30:31], v[26:27]
	v_exp_f32_e64 v30, -v18
	v_exp_f32_e64 v31, -v19
	v_pk_mul_f32 v[28:29], v[28:29], v[32:33]
	v_exp_f32_e64 v32, -v20
	v_exp_f32_e64 v33, -v21
	v_pk_add_f32 v[30:31], v[30:31], 1.0 op_sel_hi:[1,0]
	v_pk_mul_f32 v[18:19], v[18:19], v[22:23]
	v_rcp_f32_e32 v30, v30
	v_rcp_f32_e32 v31, v31
	v_pk_add_f32 v[32:33], v[32:33], 1.0 op_sel_hi:[1,0]
	v_med3_f32 v22, v26, s82, v141
	v_rcp_f32_e32 v32, v32
	v_rcp_f32_e32 v33, v33
	v_pk_mul_f32 v[18:19], v[30:31], v[18:19]
	v_med3_f32 v23, v27, s82, v141
	v_med3_f32 v26, v18, s82, v141
	v_med3_f32 v27, v19, s82, v141
	v_mov_b32_e32 v18, 0
	v_mov_b32_e32 v19, 0
	v_cvt_pk_fp8_f32 v18, v22, v23
	v_cvt_pk_fp8_f32 v19, v26, v27
	v_pk_mul_f32 v[20:21], v[20:21], v[24:25]
	v_med3_f32 v24, v28, s82, v141
	v_pk_mul_f32 v[20:21], v[32:33], v[20:21]
	v_med3_f32 v25, v29, s82, v141
	v_med3_f32 v20, v20, s82, v141
	v_med3_f32 v21, v21, s82, v141
	v_cvt_pk_fp8_f32 v18, v24, v25 op_sel:[0,0,1]
	v_cvt_pk_fp8_f32 v19, v20, v21 op_sel:[0,0,1]
	v_exp_f32_e64 v20, -v10
	v_exp_f32_e64 v21, -v11
	v_add_u32_e32 v22, 0xa0, v142
	v_mad_i64_i32 v[22:23], s[0:1], v22, s84, v[114:115]
	v_lshl_add_u64 v[22:23], v[22:23], 0, v[134:135]
	global_store_dwordx2 v[22:23], v[18:19], off
	v_pk_add_f32 v[18:19], v[20:21], 1.0 op_sel_hi:[1,0]
	v_exp_f32_e64 v12, -v12
	v_exp_f32_e64 v13, -v13
	v_pk_mul_f32 v[10:11], v[10:11], v[14:15]
	v_rcp_f32_e32 v14, v18
	v_rcp_f32_e32 v15, v19
	v_pk_add_f32 v[12:13], v[12:13], 1.0 op_sel_hi:[1,0]
	v_pk_mul_f32 v[2:3], v[6:7], v[2:3]
	v_rcp_f32_e32 v12, v12
	v_rcp_f32_e32 v13, v13
	v_pk_mul_f32 v[10:11], v[14:15], v[10:11]
	v_exp_f32_e64 v14, -v6
	v_exp_f32_e64 v15, -v7
	v_pk_mul_f32 v[12:13], v[12:13], v[16:17]
	v_exp_f32_e64 v16, -v8
	v_exp_f32_e64 v17, -v9
	v_pk_add_f32 v[14:15], v[14:15], 1.0 op_sel_hi:[1,0]
	v_med3_f32 v6, v10, s82, v141
	v_rcp_f32_e32 v14, v14
	v_rcp_f32_e32 v15, v15
	v_pk_add_f32 v[16:17], v[16:17], 1.0 op_sel_hi:[1,0]
	v_med3_f32 v7, v11, s82, v141
	v_rcp_f32_e32 v16, v16
	v_rcp_f32_e32 v17, v17
	v_pk_mul_f32 v[2:3], v[14:15], v[2:3]
	v_pk_mul_f32 v[4:5], v[8:9], v[4:5]
	v_med3_f32 v10, v2, s82, v141
	v_med3_f32 v11, v3, s82, v141
	v_mov_b32_e32 v2, 0
	v_mov_b32_e32 v3, 0
	v_cvt_pk_fp8_f32 v2, v6, v7
	v_cvt_pk_fp8_f32 v3, v10, v11
	v_pk_mul_f32 v[4:5], v[16:17], v[4:5]
	v_med3_f32 v121, v124, s82, v141
	v_med3_f32 v122, v125, s82, v141
	v_med3_f32 v8, v12, s82, v141
	v_med3_f32 v9, v13, s82, v141
	v_med3_f32 v4, v4, s82, v141
	v_med3_f32 v5, v5, s82, v141
	v_cvt_pk_fp8_f32 v118, v121, v122 op_sel:[0,0,1]
	v_cvt_pk_fp8_f32 v2, v8, v9 op_sel:[0,0,1]
	v_cvt_pk_fp8_f32 v3, v4, v5 op_sel:[0,0,1]
	v_add_u32_e32 v4, 0xb0, v142
	v_mad_i64_i32 v[120:121], s[0:1], v142, s84, v[114:115]
	v_mad_i64_i32 v[4:5], s[0:1], v4, s84, v[114:115]
	v_lshl_add_u64 v[120:121], v[120:121], 0, v[134:135]
	v_lshl_add_u64 v[4:5], v[4:5], 0, v[134:135]
	s_andn2_b64 vcc, exec, s[4:5]
	s_mov_b64 s[0:1], -1
	global_store_dwordx2 v[120:121], v[118:119], off
	global_store_dwordx2 v[4:5], v[2:3], off
	s_cbranch_vccnz .LBB0_796
	s_andn2_b64 vcc, exec, s[6:7]
	v_mov_b64 v[4:5], 0
	s_cbranch_vccnz .LBB0_795
	s_barrier
	s_branch .LBB0_795

.LBB0_874:
	v_and_b32_e32 v3, 48, v2
	v_lshlrev_b32_e32 v4, 6, v2
	s_movk_i32 s13, 0x3c0
	v_lshlrev_b32_e32 v2, 2, v2
	s_and_b32 s65, s14, 3
	s_lshl_b32 s12, s15, 13
	v_and_or_b32 v3, v4, s13, v3
	v_and_b32_e32 v2, 32, v2
	s_lshl_b32 s62, s15, 6
	v_bitop3_b32 v4, v3, s12, v2 bitop3:0xde
	s_lshl_b32 s12, s65, 12
	s_add_u32 s34, s4, 0x80
	s_addc_u32 s35, s5, 0
	s_add_i32 s88, s66, 0x18000
	v_bitop3_b32 v2, v3, s12, v2 bitop3:0xde
	s_waitcnt vmcnt(2)
	s_barrier
	s_mov_b32 s12, m0
	s_mov_b32 m0, s88
	s_nop 4
	global_load_lds_dwordx4 v131, s[34:35]
	s_mov_b32 m0, s12
	s_add_u32 s34, s4, 0x2c080
	s_addc_u32 s35, s5, 0
	s_add_i32 s89, s66, 0x1a000
	s_mov_b32 s12, m0
	s_mov_b32 m0, s89
	s_nop 4
	global_load_lds_dwordx4 v131, s[34:35]
	s_mov_b32 m0, s12
	s_add_u32 s34, s8, 0x80
	s_addc_u32 s35, s9, 0
	s_add_i32 s90, s66, 0x8000
	s_mov_b32 s12, m0
	s_mov_b32 m0, s90
	s_nop 4
	global_load_lds_dwordx4 v130, s[34:35]
	s_mov_b32 m0, s12
	s_add_u32 s34, s8, 0x2c080
	s_addc_u32 s35, s9, 0
	s_add_i32 s91, s66, 0xa000
	s_mov_b32 s12, m0
	s_mov_b32 m0, s91
	s_nop 4
	global_load_lds_dwordx4 v130, s[34:35]
	s_mov_b32 m0, s12
	s_add_u32 s34, s4, 0x58080
	s_addc_u32 s35, s5, 0
	s_add_i32 s92, s66, 0x1c000
	s_mov_b32 s12, m0
	s_mov_b32 m0, s92
	s_nop 4
	global_load_lds_dwordx4 v131, s[34:35]
	s_mov_b32 m0, s12
	s_add_u32 s34, s4, 0x84080
	s_addc_u32 s35, s5, 0
	s_add_i32 s93, s66, 0x1e000
	s_mov_b32 s12, m0
	s_mov_b32 m0, s93
	s_nop 4
	global_load_lds_dwordx4 v131, s[34:35]
	s_mov_b32 m0, s12
	s_waitcnt vmcnt(6)
	s_add_i32 s94, s66, 0xc000
	s_add_u32 s95, s60, s1
	v_mov_b32_e32 v110, 0
	v_add_u32_e32 v2, 0, v2
	s_addc_u32 s96, s61, s0
	s_mov_b32 s97, -2
	v_add_u32_e32 v132, 0x10000, v2
	v_add_u32_e32 v133, 0, v4
	v_add_u32_e32 v134, 0x14000, v2
	v_add_u32_e32 v135, 0x18000, v2
	v_add_u32_e32 v136, 0x1c000, v2
	s_mov_b64 s[34:35], s[8:9]
	s_waitcnt lgkmcnt(0)
	s_barrier
	ds_read_b128 v[138:141], v132
	ds_read_b128 v[142:145], v132 offset:1024
	ds_read_b128 v[146:149], v132 offset:2048
	ds_read_b128 v[150:153], v132 offset:3072
	ds_read_b128 v[154:157], v134
	ds_read_b128 v[158:161], v134 offset:1024
	ds_read_b128 v[182:185], v134 offset:2048
	ds_read_b128 v[186:189], v134 offset:3072
	s_add_u32 s0, s34, 0x100
	s_addc_u32 s1, s35, 0
	s_cmp_eq_u32 s97, 18
	s_cselect_b32 s50, s8, s0
	s_cselect_b32 s51, s9, s1
	s_cselect_b32 s44, s4, s95
	s_cselect_b32 s45, s5, s96
	s_add_u32 s52, s50, 0x80
	s_addc_u32 s53, s51, 0
	s_add_u32 s12, s34, 0x58080
	s_addc_u32 s13, s35, 0
	s_mov_b32 m0, s94
	s_nop 4
	global_load_lds_dwordx4 v130, s[12:13]
	s_add_u32 s12, s34, 0x84080
	s_addc_u32 s13, s35, 0
	s_add_i32 s34, s66, 0xe000
	s_mov_b32 m0, s34
	s_nop 4
	global_load_lds_dwordx4 v130, s[12:13]
	ds_read_b128 v[190:193], v133
	ds_read_b128 v[194:197], v133 offset:1024
	ds_read_b128 v[198:201], v133 offset:2048
	ds_read_b128 v[202:205], v133 offset:3072
	ds_read_b128 v[206:209], v133 offset:4096
	ds_read_b128 v[210:213], v133 offset:5120
	ds_read_b128 v[214:217], v133 offset:6144
	ds_read_b128 v[218:221], v133 offset:7168
	s_waitcnt vmcnt(8)
	s_waitcnt lgkmcnt(0)
	s_barrier
	v_mfma_f32_16x16x128_f8f6f4 v[14:17], v[138:145], v[190:197], 0
	v_mfma_f32_16x16x128_f8f6f4 v[30:33], v[138:145], v[198:205], 0
	v_mfma_f32_16x16x128_f8f6f4 v[50:53], v[138:145], v[206:213], 0
	v_mfma_f32_16x16x128_f8f6f4 v[62:65], v[138:145], v[214:221], 0
	v_mfma_f32_16x16x128_f8f6f4 v[10:13], v[146:153], v[190:197], 0
	v_mfma_f32_16x16x128_f8f6f4 v[26:29], v[146:153], v[198:205], 0
	v_mfma_f32_16x16x128_f8f6f4 v[42:45], v[146:153], v[206:213], 0
	v_mfma_f32_16x16x128_f8f6f4 v[58:61], v[146:153], v[214:221], 0
	v_mfma_f32_16x16x128_f8f6f4 v[6:9], v[154:161], v[190:197], 0
	v_mfma_f32_16x16x128_f8f6f4 v[22:25], v[154:161], v[198:205], 0
	v_mfma_f32_16x16x128_f8f6f4 v[38:41], v[154:161], v[206:213], 0
	v_mfma_f32_16x16x128_f8f6f4 v[54:57], v[154:161], v[214:221], 0
	v_mfma_f32_16x16x128_f8f6f4 v[2:5], v[182:189], v[190:197], 0
	v_mfma_f32_16x16x128_f8f6f4 v[18:21], v[182:189], v[198:205], 0
	v_mfma_f32_16x16x128_f8f6f4 v[34:37], v[182:189], v[206:213], 0
	v_mfma_f32_16x16x128_f8f6f4 v[46:49], v[182:189], v[214:221], 0
	s_barrier
	ds_read_b128 v[190:193], v133 offset:16384
	ds_read_b128 v[194:197], v133 offset:17408
	ds_read_b128 v[198:201], v133 offset:18432
	ds_read_b128 v[202:205], v133 offset:19456
	ds_read_b128 v[206:209], v133 offset:20480
	ds_read_b128 v[210:213], v133 offset:21504
	ds_read_b128 v[214:217], v133 offset:22528
	ds_read_b128 v[218:221], v133 offset:23552
	s_mov_b32 m0, s67
	s_nop 4
	global_load_lds_dwordx4 v131, s[44:45]
	s_add_u32 s12, s44, 0x2c000
	s_addc_u32 s13, s45, 0
	s_mov_b32 m0, s73
	s_nop 4
	global_load_lds_dwordx4 v131, s[12:13]
	s_add_u32 s12, s44, 0x58000
	s_addc_u32 s13, s45, 0
	s_mov_b32 m0, s84
	s_nop 4
	global_load_lds_dwordx4 v131, s[12:13]
	s_add_u32 s12, s44, 0x84000
	s_addc_u32 s13, s45, 0
	s_mov_b32 m0, s85
	s_nop 4
	global_load_lds_dwordx4 v131, s[12:13]
	s_mov_b32 m0, s66
	s_nop 4
	global_load_lds_dwordx4 v130, s[50:51]
	s_add_u32 s12, s50, 0x2c000
	s_addc_u32 s13, s51, 0
	s_mov_b32 m0, s82
	s_nop 4
	global_load_lds_dwordx4 v130, s[12:13]
	s_waitcnt vmcnt(8)
	s_waitcnt lgkmcnt(0)
	s_barrier
	v_mfma_f32_16x16x128_f8f6f4 v[78:81], v[138:145], v[190:197], 0
	v_mfma_f32_16x16x128_f8f6f4 v[94:97], v[138:145], v[198:205], 0
	v_mfma_f32_16x16x128_f8f6f4 v[126:129], v[138:145], v[206:213], 0
	v_mfma_f32_16x16x128_f8f6f4 v[98:101], v[138:145], v[214:221], 0
	v_mfma_f32_16x16x128_f8f6f4 v[74:77], v[146:153], v[190:197], 0
	v_mfma_f32_16x16x128_f8f6f4 v[90:93], v[146:153], v[198:205], 0
	v_mfma_f32_16x16x128_f8f6f4 v[114:117], v[146:153], v[206:213], 0
	v_mfma_f32_16x16x128_f8f6f4 v[122:125], v[146:153], v[214:221], 0
	v_mfma_f32_16x16x128_f8f6f4 v[70:73], v[154:161], v[190:197], 0
	v_mfma_f32_16x16x128_f8f6f4 v[86:89], v[154:161], v[198:205], 0
	v_mfma_f32_16x16x128_f8f6f4 v[106:109], v[154:161], v[206:213], 0
	v_mfma_f32_16x16x128_f8f6f4 v[118:121], v[154:161], v[214:221], 0
	v_mfma_f32_16x16x128_f8f6f4 v[66:69], v[182:189], v[190:197], 0
	v_mfma_f32_16x16x128_f8f6f4 v[82:85], v[182:189], v[198:205], 0
	v_mfma_f32_16x16x128_f8f6f4 v[102:105], v[182:189], v[206:213], 0
	v_mfma_f32_16x16x128_f8f6f4 v[110:113], v[182:189], v[214:221], 0
	s_barrier
	ds_read_b128 v[138:141], v135
	ds_read_b128 v[142:145], v135 offset:1024
	ds_read_b128 v[146:149], v135 offset:2048
	ds_read_b128 v[150:153], v135 offset:3072
	ds_read_b128 v[154:157], v136
	ds_read_b128 v[158:161], v136 offset:1024
	ds_read_b128 v[182:185], v136 offset:2048
	ds_read_b128 v[186:189], v136 offset:3072
	s_add_u32 s12, s50, 0x58000
	s_addc_u32 s13, s51, 0
	s_mov_b32 m0, s86
	s_nop 4
	global_load_lds_dwordx4 v130, s[12:13]
	s_add_u32 s12, s50, 0x84000
	s_addc_u32 s13, s51, 0
	s_mov_b32 m0, s87
	s_nop 4
	global_load_lds_dwordx4 v130, s[12:13]
	ds_read_b128 v[190:193], v133 offset:32768
	ds_read_b128 v[194:197], v133 offset:33792
	ds_read_b128 v[198:201], v133 offset:34816
	ds_read_b128 v[202:205], v133 offset:35840
	ds_read_b128 v[206:209], v133 offset:36864
	ds_read_b128 v[210:213], v133 offset:37888
	ds_read_b128 v[214:217], v133 offset:38912
	ds_read_b128 v[218:221], v133 offset:39936
	s_waitcnt vmcnt(8)
	s_waitcnt lgkmcnt(0)
	s_barrier
	v_mfma_f32_16x16x128_f8f6f4 v[14:17], v[138:145], v[190:197], v[14:17]
	v_mfma_f32_16x16x128_f8f6f4 v[30:33], v[138:145], v[198:205], v[30:33]
	v_mfma_f32_16x16x128_f8f6f4 v[50:53], v[138:145], v[206:213], v[50:53]
	v_mfma_f32_16x16x128_f8f6f4 v[62:65], v[138:145], v[214:221], v[62:65]
	v_mfma_f32_16x16x128_f8f6f4 v[10:13], v[146:153], v[190:197], v[10:13]
	v_mfma_f32_16x16x128_f8f6f4 v[26:29], v[146:153], v[198:205], v[26:29]
	v_mfma_f32_16x16x128_f8f6f4 v[42:45], v[146:153], v[206:213], v[42:45]
	v_mfma_f32_16x16x128_f8f6f4 v[58:61], v[146:153], v[214:221], v[58:61]
	v_mfma_f32_16x16x128_f8f6f4 v[6:9], v[154:161], v[190:197], v[6:9]
	v_mfma_f32_16x16x128_f8f6f4 v[22:25], v[154:161], v[198:205], v[22:25]
	v_mfma_f32_16x16x128_f8f6f4 v[38:41], v[154:161], v[206:213], v[38:41]
	v_mfma_f32_16x16x128_f8f6f4 v[54:57], v[154:161], v[214:221], v[54:57]
	v_mfma_f32_16x16x128_f8f6f4 v[2:5], v[182:189], v[190:197], v[2:5]
	v_mfma_f32_16x16x128_f8f6f4 v[18:21], v[182:189], v[198:205], v[18:21]
	v_mfma_f32_16x16x128_f8f6f4 v[34:37], v[182:189], v[206:213], v[34:37]
	v_mfma_f32_16x16x128_f8f6f4 v[46:49], v[182:189], v[214:221], v[46:49]
	s_barrier
	ds_read_b128 v[190:193], v133 offset:49152
	ds_read_b128 v[194:197], v133 offset:50176
	ds_read_b128 v[198:201], v133 offset:51200
	ds_read_b128 v[202:205], v133 offset:52224
	ds_read_b128 v[206:209], v133 offset:53248
	ds_read_b128 v[210:213], v133 offset:54272
	ds_read_b128 v[214:217], v133 offset:55296
	ds_read_b128 v[218:221], v133 offset:56320
	s_add_u32 s12, s44, 0x80
	s_addc_u32 s13, s45, 0
	s_mov_b32 m0, s88
	s_nop 4
	global_load_lds_dwordx4 v131, s[12:13]
	s_add_u32 s12, s44, 0x2c080
	s_addc_u32 s13, s45, 0
	s_mov_b32 m0, s89
	s_nop 4
	global_load_lds_dwordx4 v131, s[12:13]
	s_add_u32 s12, s44, 0x58080
	s_addc_u32 s13, s45, 0
	s_mov_b32 m0, s92
	s_nop 4
	global_load_lds_dwordx4 v131, s[12:13]
	s_add_u32 s12, s44, 0x84080
	s_addc_u32 s13, s45, 0
	s_mov_b32 m0, s93
	s_nop 4
	global_load_lds_dwordx4 v131, s[12:13]
	s_mov_b32 m0, s90
	s_nop 4
	global_load_lds_dwordx4 v130, s[52:53]
	s_add_u32 s12, s50, 0x2c080
	s_addc_u32 s13, s51, 0
	s_mov_b32 m0, s91
	s_nop 4
	global_load_lds_dwordx4 v130, s[12:13]
	s_waitcnt vmcnt(8)
	s_waitcnt lgkmcnt(0)
	s_barrier
	v_mfma_f32_16x16x128_f8f6f4 v[78:81], v[138:145], v[190:197], v[78:81]
	v_mfma_f32_16x16x128_f8f6f4 v[94:97], v[138:145], v[198:205], v[94:97]
	v_mfma_f32_16x16x128_f8f6f4 v[126:129], v[138:145], v[206:213], v[126:129]
	v_mfma_f32_16x16x128_f8f6f4 v[98:101], v[138:145], v[214:221], v[98:101]
	v_mfma_f32_16x16x128_f8f6f4 v[74:77], v[146:153], v[190:197], v[74:77]
	v_mfma_f32_16x16x128_f8f6f4 v[90:93], v[146:153], v[198:205], v[90:93]
	v_mfma_f32_16x16x128_f8f6f4 v[114:117], v[146:153], v[206:213], v[114:117]
	v_mfma_f32_16x16x128_f8f6f4 v[122:125], v[146:153], v[214:221], v[122:125]
	v_mfma_f32_16x16x128_f8f6f4 v[70:73], v[154:161], v[190:197], v[70:73]
	v_mfma_f32_16x16x128_f8f6f4 v[86:89], v[154:161], v[198:205], v[86:89]
	v_mfma_f32_16x16x128_f8f6f4 v[106:109], v[154:161], v[206:213], v[106:109]
	v_mfma_f32_16x16x128_f8f6f4 v[118:121], v[154:161], v[214:221], v[118:121]
	v_mfma_f32_16x16x128_f8f6f4 v[66:69], v[182:189], v[190:197], v[66:69]
	v_mfma_f32_16x16x128_f8f6f4 v[82:85], v[182:189], v[198:205], v[82:85]
	v_mfma_f32_16x16x128_f8f6f4 v[102:105], v[182:189], v[206:213], v[102:105]
	v_mfma_f32_16x16x128_f8f6f4 v[110:113], v[182:189], v[214:221], v[110:113]
	s_add_i32 s97, s97, 2
	s_add_u32 s95, s95, 0x100
	s_addc_u32 s96, s96, 0
	s_cmp_lt_u32 s97, 20
	s_mov_b64 s[34:35], s[0:1]
	s_barrier

.LBB0_982:
	v_lshrrev_b32_e32 v4, 1, v2
	v_and_b32_e32 v4, 24, v4
	v_and_b32_e32 v3, 15, v2
	v_lshlrev_b32_e32 v5, 1, v4
	v_lshlrev_b32_e32 v2, 2, v2
	s_sext_i32_i8 s39, s2
	s_and_b32 s2, s8, 3
	v_lshl_or_b32 v5, v3, 6, v5
	s_lshl_b32 s8, s9, 13
	v_and_b32_e32 v2, 32, v2
	v_bitop3_b32 v6, v5, s8, v2 bitop3:0xde
	s_lshl_b32 s8, s2, 12
	v_bitop3_b32 v5, v5, s8, v2 bitop3:0xde
	s_add_u32 s8, s0, 0x80
	v_lshl_or_b32 v145, s9, 6, v3
	s_addc_u32 s9, s1, 0
	s_add_i32 s63, s54, 0x18000
	s_waitcnt vmcnt(2)
	s_barrier
	s_mov_b32 s10, m0
	s_mov_b32 m0, s63
	s_nop 4
	global_load_lds_dwordx4 v144, s[8:9]
	s_mov_b32 m0, s10
	s_add_u32 s8, s0, 0x20080
	s_addc_u32 s9, s1, 0
	s_add_i32 s64, s54, 0x1a000
	s_mov_b32 s10, m0
	s_mov_b32 m0, s64
	s_nop 4
	global_load_lds_dwordx4 v144, s[8:9]
	s_mov_b32 m0, s10
	s_add_u32 s8, s40, 0x80
	s_addc_u32 s9, s41, 0
	s_add_i32 s65, s54, 0x8000
	s_mov_b32 s10, m0
	s_mov_b32 m0, s65
	s_nop 4
	global_load_lds_dwordx4 v1, s[8:9]
	s_mov_b32 m0, s10
	s_add_u32 s8, s40, 0x20080
	s_addc_u32 s9, s41, 0
	s_add_i32 s66, s54, 0xa000
	s_mov_b32 s10, m0
	s_mov_b32 m0, s66
	s_nop 4
	global_load_lds_dwordx4 v1, s[8:9]
	s_mov_b32 m0, s10
	s_add_u32 s8, s0, 0x40080
	s_addc_u32 s9, s1, 0
	s_add_i32 s67, s54, 0x1c000
	s_mov_b32 s10, m0
	s_mov_b32 m0, s67
	s_nop 4
	global_load_lds_dwordx4 v144, s[8:9]
	s_mov_b32 m0, s10
	s_add_u32 s8, s0, 0x60080
	s_addc_u32 s9, s1, 0
	s_add_i32 s73, s54, 0x1e000
	s_add_i32 s82, s54, 0xc000
	s_cmpk_lt_u32 s3, 0x100
	s_mov_b32 s10, m0
	s_mov_b32 m0, s73
	s_nop 4
	global_load_lds_dwordx4 v144, s[8:9]
	s_mov_b32 m0, s10
	s_cselect_b64 s[8:9], -1, 0
	s_lshl_b32 s84, s2, 6
	v_readlane_b32 s2, v255, 15
	v_mov_b32_e32 v131, 0
	v_lshlrev_b32_e32 v130, 2, v4
	v_readlane_b32 s3, v255, 16
	s_waitcnt vmcnt(6)
	v_or_b32_e32 v146, 0x1000, v3
	v_or_b32_e32 v147, 0x1010, v3
	v_lshl_add_u64 v[132:133], s[2:3], 0, v[130:131]
	v_readlane_b32 s2, v255, 17
	v_or_b32_e32 v148, 0x1020, v3
	v_or_b32_e32 v149, 0x1030, v3
	v_readlane_b32 s3, v255, 18
	v_mov_b64_e32 v[2:3], 0
	s_ashr_i32 s85, s72, 31
	v_lshl_add_u64 v[134:135], s[2:3], 0, v[130:131]
	v_mov_b64_e32 v[136:137], 0x420
	v_mov_b64_e32 v[138:139], 0x41f
	v_add_u32_e32 v150, 0, v5
	v_add_u32_e32 v151, 0, v6
	v_lshlrev_b32_e32 v140, 1, v4
	s_waitcnt vmcnt(3)
	s_waitcnt vmcnt(2) lgkmcnt(0)
	s_barrier
	s_branch .LBB0_985

.LBB0_987:
	s_ashr_i32 s25, s24, 31
	s_lshl_b64 s[12:13], s[24:25], 19
	s_add_u32 s26, s16, s12
	s_addc_u32 s27, s17, s13
	s_and_b64 s[12:13], s[2:3], exec
	s_cselect_b32 s14, s27, s41
	s_cselect_b32 s15, s26, s40
	s_ashr_i32 s11, s10, 31
	s_lshl_b64 s[12:13], s[10:11], 19
	s_add_u32 s36, s50, s12
	s_addc_u32 s37, s51, s13
	s_and_b64 s[12:13], s[2:3], exec
	s_cselect_b32 s11, s37, s1
	s_cselect_b32 s25, s36, s0
	s_add_u32 s86, s0, 0x100
	s_addc_u32 s87, s1, 0
	s_mov_b32 s88, -2
	v_add_u32_e32 v130, 0x10000, v150
	ds_read_b128 v[152:155], v130
	ds_read_b128 v[156:159], v130 offset:1024
	ds_read_b128 v[160:163], v130 offset:2048
	ds_read_b128 v[164:167], v130 offset:3072
	v_add_u32_e32 v130, 0x14000, v150
	ds_read_b128 v[168:171], v130
	ds_read_b128 v[172:175], v130 offset:1024
	ds_read_b128 v[176:179], v130 offset:2048
	ds_read_b128 v[180:183], v130 offset:3072
	s_add_u32 s0, s40, 0x100
	s_addc_u32 s1, s41, 0
	s_cmp_eq_u32 s88, 12
	s_cselect_b32 s34, s15, s0
	s_cselect_b32 s35, s14, s1
	s_cselect_b32 s44, s25, s86
	s_cselect_b32 s45, s11, s87
	s_add_u32 s42, s34, 0x80
	s_addc_u32 s43, s35, 0
	ds_read_b128 v[184:187], v151
	ds_read_b128 v[188:191], v151 offset:1024
	ds_read_b128 v[192:195], v151 offset:2048
	ds_read_b128 v[196:199], v151 offset:3072
	ds_read_b128 v[200:203], v151 offset:4096
	ds_read_b128 v[204:207], v151 offset:5120
	ds_read_b128 v[208:211], v151 offset:6144
	ds_read_b128 v[212:215], v151 offset:7168
	s_add_u32 s12, s40, 0x40080
	s_addc_u32 s13, s41, 0
	s_mov_b32 s89, m0
	s_mov_b32 m0, s82
	s_nop 4
	global_load_lds_dwordx4 v1, s[12:13]
	s_mov_b32 m0, s89
	s_add_u32 s12, s40, 0x60080
	s_addc_u32 s13, s41, 0
	s_add_i32 s40, s54, 0xe000
	s_mov_b32 s41, m0
	s_mov_b32 m0, s40
	s_nop 4
	global_load_lds_dwordx4 v1, s[12:13]
	s_mov_b32 m0, s41
	s_waitcnt vmcnt(8)
	s_waitcnt lgkmcnt(0)
	s_barrier
	s_waitcnt lgkmcnt(7)
	v_mfma_f32_16x16x32_bf16 v[122:125], v[152:155], v[184:187], 0
	v_mfma_f32_16x16x32_bf16 v[114:117], v[160:163], v[184:187], 0
	s_waitcnt lgkmcnt(5)
	v_mfma_f32_16x16x32_bf16 v[106:109], v[152:155], v[192:195], 0
	v_mfma_f32_16x16x32_bf16 v[98:101], v[160:163], v[192:195], 0
	s_waitcnt lgkmcnt(3)
	v_mfma_f32_16x16x32_bf16 v[90:93], v[152:155], v[200:203], 0
	v_mfma_f32_16x16x32_bf16 v[82:85], v[160:163], v[200:203], 0
	s_waitcnt lgkmcnt(1)
	v_mfma_f32_16x16x32_bf16 v[74:77], v[152:155], v[208:211], 0
	v_mfma_f32_16x16x32_bf16 v[66:69], v[160:163], v[208:211], 0
	v_mfma_f32_16x16x32_bf16 v[122:125], v[156:159], v[188:191], v[122:125]
	v_mfma_f32_16x16x32_bf16 v[114:117], v[164:167], v[188:191], v[114:117]
	v_mfma_f32_16x16x32_bf16 v[106:109], v[156:159], v[196:199], v[106:109]
	v_mfma_f32_16x16x32_bf16 v[98:101], v[164:167], v[196:199], v[98:101]
	v_mfma_f32_16x16x32_bf16 v[90:93], v[156:159], v[204:207], v[90:93]
	v_mfma_f32_16x16x32_bf16 v[82:85], v[164:167], v[204:207], v[82:85]
	s_waitcnt lgkmcnt(0)
	v_mfma_f32_16x16x32_bf16 v[74:77], v[156:159], v[212:215], v[74:77]
	v_mfma_f32_16x16x32_bf16 v[66:69], v[164:167], v[212:215], v[66:69]
	v_mfma_f32_16x16x32_bf16 v[126:129], v[168:171], v[184:187], 0
	v_mfma_f32_16x16x32_bf16 v[118:121], v[176:179], v[184:187], 0
	v_mfma_f32_16x16x32_bf16 v[110:113], v[168:171], v[192:195], 0
	v_mfma_f32_16x16x32_bf16 v[102:105], v[176:179], v[192:195], 0
	v_mfma_f32_16x16x32_bf16 v[94:97], v[168:171], v[200:203], 0
	v_mfma_f32_16x16x32_bf16 v[86:89], v[176:179], v[200:203], 0
	v_mfma_f32_16x16x32_bf16 v[78:81], v[168:171], v[208:211], 0
	v_mfma_f32_16x16x32_bf16 v[70:73], v[176:179], v[208:211], 0
	v_mfma_f32_16x16x32_bf16 v[126:129], v[172:175], v[188:191], v[126:129]
	v_mfma_f32_16x16x32_bf16 v[118:121], v[180:183], v[188:191], v[118:121]
	v_mfma_f32_16x16x32_bf16 v[110:113], v[172:175], v[196:199], v[110:113]
	v_mfma_f32_16x16x32_bf16 v[102:105], v[180:183], v[196:199], v[102:105]
	v_mfma_f32_16x16x32_bf16 v[94:97], v[172:175], v[204:207], v[94:97]
	v_mfma_f32_16x16x32_bf16 v[86:89], v[180:183], v[204:207], v[86:89]
	v_mfma_f32_16x16x32_bf16 v[78:81], v[172:175], v[212:215], v[78:81]
	v_mfma_f32_16x16x32_bf16 v[70:73], v[180:183], v[212:215], v[70:73]
	s_barrier
	ds_read_b128 v[184:187], v151 offset:16384
	ds_read_b128 v[188:191], v151 offset:17408
	ds_read_b128 v[192:195], v151 offset:18432
	ds_read_b128 v[196:199], v151 offset:19456
	ds_read_b128 v[200:203], v151 offset:20480
	ds_read_b128 v[204:207], v151 offset:21504
	ds_read_b128 v[208:211], v151 offset:22528
	ds_read_b128 v[212:215], v151 offset:23552
	s_mov_b32 s12, m0
	s_mov_b32 m0, s56
	s_nop 4
	global_load_lds_dwordx4 v144, s[44:45]
	s_mov_b32 m0, s12
	s_add_u32 s12, s44, 0x20000
	s_addc_u32 s13, s45, 0
	s_mov_b32 s40, m0
	s_mov_b32 m0, s57
	s_nop 4
	global_load_lds_dwordx4 v144, s[12:13]
	s_mov_b32 m0, s40
	s_add_u32 s12, s44, 0x40000
	s_addc_u32 s13, s45, 0
	s_mov_b32 s40, m0
	s_mov_b32 m0, s58
	s_nop 4
	global_load_lds_dwordx4 v144, s[12:13]
	s_mov_b32 m0, s40
	s_add_u32 s12, s44, 0x60000
	s_addc_u32 s13, s45, 0
	s_mov_b32 s40, m0
	s_mov_b32 m0, s59
	s_nop 4
	global_load_lds_dwordx4 v144, s[12:13]
	s_mov_b32 m0, s40
	s_mov_b32 s12, m0
	s_mov_b32 m0, s54
	s_nop 4
	global_load_lds_dwordx4 v1, s[34:35]
	s_mov_b32 m0, s12
	s_add_u32 s12, s34, 0x20000
	s_addc_u32 s13, s35, 0
	s_mov_b32 s40, m0
	s_mov_b32 m0, s60
	s_nop 4
	global_load_lds_dwordx4 v1, s[12:13]
	s_mov_b32 m0, s40
	s_waitcnt vmcnt(8)
	s_waitcnt lgkmcnt(0)
	s_barrier
	s_waitcnt lgkmcnt(7)
	v_mfma_f32_16x16x32_bf16 v[58:61], v[152:155], v[184:187], 0
	v_mfma_f32_16x16x32_bf16 v[50:53], v[160:163], v[184:187], 0
	s_waitcnt lgkmcnt(5)
	v_mfma_f32_16x16x32_bf16 v[42:45], v[152:155], v[192:195], 0
	v_mfma_f32_16x16x32_bf16 v[34:37], v[160:163], v[192:195], 0
	s_waitcnt lgkmcnt(3)
	v_mfma_f32_16x16x32_bf16 v[26:29], v[152:155], v[200:203], 0
	v_mfma_f32_16x16x32_bf16 v[18:21], v[160:163], v[200:203], 0
	s_waitcnt lgkmcnt(1)
	v_mfma_f32_16x16x32_bf16 v[10:13], v[152:155], v[208:211], 0
	v_mfma_f32_16x16x32_bf16 v[6:9], v[160:163], v[208:211], 0
	v_mfma_f32_16x16x32_bf16 v[58:61], v[156:159], v[188:191], v[58:61]
	v_mfma_f32_16x16x32_bf16 v[50:53], v[164:167], v[188:191], v[50:53]
	v_mfma_f32_16x16x32_bf16 v[42:45], v[156:159], v[196:199], v[42:45]
	v_mfma_f32_16x16x32_bf16 v[34:37], v[164:167], v[196:199], v[34:37]
	v_mfma_f32_16x16x32_bf16 v[26:29], v[156:159], v[204:207], v[26:29]
	v_mfma_f32_16x16x32_bf16 v[18:21], v[164:167], v[204:207], v[18:21]
	s_waitcnt lgkmcnt(0)
	v_mfma_f32_16x16x32_bf16 v[10:13], v[156:159], v[212:215], v[10:13]
	v_mfma_f32_16x16x32_bf16 v[6:9], v[164:167], v[212:215], v[6:9]
	v_mfma_f32_16x16x32_bf16 v[62:65], v[168:171], v[184:187], 0
	v_mfma_f32_16x16x32_bf16 v[54:57], v[176:179], v[184:187], 0
	v_mfma_f32_16x16x32_bf16 v[46:49], v[168:171], v[192:195], 0
	v_mfma_f32_16x16x32_bf16 v[38:41], v[176:179], v[192:195], 0
	v_mfma_f32_16x16x32_bf16 v[30:33], v[168:171], v[200:203], 0
	v_mfma_f32_16x16x32_bf16 v[22:25], v[176:179], v[200:203], 0
	v_mfma_f32_16x16x32_bf16 v[14:17], v[168:171], v[208:211], 0
	v_mfma_f32_16x16x32_bf16 v[2:5], v[176:179], v[208:211], 0
	v_mfma_f32_16x16x32_bf16 v[62:65], v[172:175], v[188:191], v[62:65]
	v_mfma_f32_16x16x32_bf16 v[54:57], v[180:183], v[188:191], v[54:57]
	v_mfma_f32_16x16x32_bf16 v[46:49], v[172:175], v[196:199], v[46:49]
	v_mfma_f32_16x16x32_bf16 v[38:41], v[180:183], v[196:199], v[38:41]
	v_mfma_f32_16x16x32_bf16 v[30:33], v[172:175], v[204:207], v[30:33]
	v_mfma_f32_16x16x32_bf16 v[22:25], v[180:183], v[204:207], v[22:25]
	v_mfma_f32_16x16x32_bf16 v[14:17], v[172:175], v[212:215], v[14:17]
	v_mfma_f32_16x16x32_bf16 v[2:5], v[180:183], v[212:215], v[2:5]
	s_barrier
	v_add_u32_e32 v130, 0x18000, v150
	ds_read_b128 v[152:155], v130
	ds_read_b128 v[156:159], v130 offset:1024
	ds_read_b128 v[160:163], v130 offset:2048
	ds_read_b128 v[164:167], v130 offset:3072
	v_add_u32_e32 v130, 0x1c000, v150
	ds_read_b128 v[168:171], v130
	ds_read_b128 v[172:175], v130 offset:1024
	ds_read_b128 v[176:179], v130 offset:2048
	ds_read_b128 v[180:183], v130 offset:3072
	ds_read_b128 v[184:187], v151 offset:32768
	ds_read_b128 v[188:191], v151 offset:33792
	ds_read_b128 v[192:195], v151 offset:34816
	ds_read_b128 v[196:199], v151 offset:35840
	ds_read_b128 v[200:203], v151 offset:36864
	ds_read_b128 v[204:207], v151 offset:37888
	ds_read_b128 v[208:211], v151 offset:38912
	ds_read_b128 v[212:215], v151 offset:39936
	s_add_u32 s12, s34, 0x40000
	s_addc_u32 s13, s35, 0
	s_mov_b32 s40, m0
	s_mov_b32 m0, s61
	s_nop 4
	global_load_lds_dwordx4 v1, s[12:13]
	s_mov_b32 m0, s40
	s_add_u32 s12, s34, 0x60000
	s_addc_u32 s13, s35, 0
	s_mov_b32 s40, m0
	s_mov_b32 m0, s62
	s_nop 4
	global_load_lds_dwordx4 v1, s[12:13]
	s_mov_b32 m0, s40
	s_waitcnt vmcnt(8)
	s_waitcnt lgkmcnt(0)
	s_barrier
	s_waitcnt lgkmcnt(7)
	v_mfma_f32_16x16x32_bf16 v[122:125], v[152:155], v[184:187], v[122:125]
	v_mfma_f32_16x16x32_bf16 v[114:117], v[160:163], v[184:187], v[114:117]
	s_waitcnt lgkmcnt(5)
	v_mfma_f32_16x16x32_bf16 v[106:109], v[152:155], v[192:195], v[106:109]
	v_mfma_f32_16x16x32_bf16 v[98:101], v[160:163], v[192:195], v[98:101]
	s_waitcnt lgkmcnt(3)
	v_mfma_f32_16x16x32_bf16 v[90:93], v[152:155], v[200:203], v[90:93]
	v_mfma_f32_16x16x32_bf16 v[82:85], v[160:163], v[200:203], v[82:85]
	s_waitcnt lgkmcnt(1)
	v_mfma_f32_16x16x32_bf16 v[74:77], v[152:155], v[208:211], v[74:77]
	v_mfma_f32_16x16x32_bf16 v[66:69], v[160:163], v[208:211], v[66:69]
	v_mfma_f32_16x16x32_bf16 v[122:125], v[156:159], v[188:191], v[122:125]
	v_mfma_f32_16x16x32_bf16 v[114:117], v[164:167], v[188:191], v[114:117]
	v_mfma_f32_16x16x32_bf16 v[106:109], v[156:159], v[196:199], v[106:109]
	v_mfma_f32_16x16x32_bf16 v[98:101], v[164:167], v[196:199], v[98:101]
	v_mfma_f32_16x16x32_bf16 v[90:93], v[156:159], v[204:207], v[90:93]
	v_mfma_f32_16x16x32_bf16 v[82:85], v[164:167], v[204:207], v[82:85]
	s_waitcnt lgkmcnt(0)
	v_mfma_f32_16x16x32_bf16 v[74:77], v[156:159], v[212:215], v[74:77]
	v_mfma_f32_16x16x32_bf16 v[66:69], v[164:167], v[212:215], v[66:69]
	v_mfma_f32_16x16x32_bf16 v[126:129], v[168:171], v[184:187], v[126:129]
	v_mfma_f32_16x16x32_bf16 v[118:121], v[176:179], v[184:187], v[118:121]
	v_mfma_f32_16x16x32_bf16 v[110:113], v[168:171], v[192:195], v[110:113]
	v_mfma_f32_16x16x32_bf16 v[102:105], v[176:179], v[192:195], v[102:105]
	v_mfma_f32_16x16x32_bf16 v[94:97], v[168:171], v[200:203], v[94:97]
	v_mfma_f32_16x16x32_bf16 v[86:89], v[176:179], v[200:203], v[86:89]
	v_mfma_f32_16x16x32_bf16 v[78:81], v[168:171], v[208:211], v[78:81]
	v_mfma_f32_16x16x32_bf16 v[70:73], v[176:179], v[208:211], v[70:73]
	v_mfma_f32_16x16x32_bf16 v[126:129], v[172:175], v[188:191], v[126:129]
	v_mfma_f32_16x16x32_bf16 v[118:121], v[180:183], v[188:191], v[118:121]
	v_mfma_f32_16x16x32_bf16 v[110:113], v[172:175], v[196:199], v[110:113]
	v_mfma_f32_16x16x32_bf16 v[102:105], v[180:183], v[196:199], v[102:105]
	v_mfma_f32_16x16x32_bf16 v[94:97], v[172:175], v[204:207], v[94:97]
	v_mfma_f32_16x16x32_bf16 v[86:89], v[180:183], v[204:207], v[86:89]
	v_mfma_f32_16x16x32_bf16 v[78:81], v[172:175], v[212:215], v[78:81]
	v_mfma_f32_16x16x32_bf16 v[70:73], v[180:183], v[212:215], v[70:73]
	s_barrier
	s_add_u32 s12, s44, 0x80
	s_addc_u32 s13, s45, 0
	ds_read_b128 v[184:187], v151 offset:49152
	ds_read_b128 v[188:191], v151 offset:50176
	ds_read_b128 v[192:195], v151 offset:51200
	ds_read_b128 v[196:199], v151 offset:52224
	ds_read_b128 v[200:203], v151 offset:53248
	ds_read_b128 v[204:207], v151 offset:54272
	ds_read_b128 v[208:211], v151 offset:55296
	ds_read_b128 v[212:215], v151 offset:56320
	s_mov_b32 s40, m0
	s_mov_b32 m0, s63
	s_nop 4
	global_load_lds_dwordx4 v144, s[12:13]
	s_mov_b32 m0, s40
	s_add_u32 s12, s44, 0x20080
	s_addc_u32 s13, s45, 0
	s_mov_b32 s40, m0
	s_mov_b32 m0, s64
	s_nop 4
	global_load_lds_dwordx4 v144, s[12:13]
	s_mov_b32 m0, s40
	s_add_u32 s12, s44, 0x40080
	s_addc_u32 s13, s45, 0
	s_mov_b32 s40, m0
	s_mov_b32 m0, s67
	s_nop 4
	global_load_lds_dwordx4 v144, s[12:13]
	s_mov_b32 m0, s40
	s_add_u32 s12, s44, 0x60080
	s_addc_u32 s13, s45, 0
	s_mov_b32 s40, m0
	s_mov_b32 m0, s73
	s_nop 4
	global_load_lds_dwordx4 v144, s[12:13]
	s_mov_b32 m0, s40
	s_mov_b32 s12, m0
	s_mov_b32 m0, s65
	s_nop 4
	global_load_lds_dwordx4 v1, s[42:43]
	s_mov_b32 m0, s12
	s_add_u32 s12, s34, 0x20080
	s_addc_u32 s13, s35, 0
	s_mov_b32 s34, m0
	s_mov_b32 m0, s66
	s_nop 4
	global_load_lds_dwordx4 v1, s[12:13]
	s_mov_b32 m0, s34
	s_waitcnt vmcnt(8)
	s_waitcnt lgkmcnt(0)
	s_barrier
	s_waitcnt lgkmcnt(7)
	v_mfma_f32_16x16x32_bf16 v[58:61], v[152:155], v[184:187], v[58:61]
	v_mfma_f32_16x16x32_bf16 v[50:53], v[160:163], v[184:187], v[50:53]
	s_waitcnt lgkmcnt(5)
	v_mfma_f32_16x16x32_bf16 v[42:45], v[152:155], v[192:195], v[42:45]
	v_mfma_f32_16x16x32_bf16 v[34:37], v[160:163], v[192:195], v[34:37]
	s_waitcnt lgkmcnt(3)
	v_mfma_f32_16x16x32_bf16 v[26:29], v[152:155], v[200:203], v[26:29]
	v_mfma_f32_16x16x32_bf16 v[18:21], v[160:163], v[200:203], v[18:21]
	s_waitcnt lgkmcnt(1)
	v_mfma_f32_16x16x32_bf16 v[10:13], v[152:155], v[208:211], v[10:13]
	v_mfma_f32_16x16x32_bf16 v[6:9], v[160:163], v[208:211], v[6:9]
	v_mfma_f32_16x16x32_bf16 v[58:61], v[156:159], v[188:191], v[58:61]
	v_mfma_f32_16x16x32_bf16 v[50:53], v[164:167], v[188:191], v[50:53]
	v_mfma_f32_16x16x32_bf16 v[42:45], v[156:159], v[196:199], v[42:45]
	v_mfma_f32_16x16x32_bf16 v[34:37], v[164:167], v[196:199], v[34:37]
	v_mfma_f32_16x16x32_bf16 v[26:29], v[156:159], v[204:207], v[26:29]
	v_mfma_f32_16x16x32_bf16 v[18:21], v[164:167], v[204:207], v[18:21]
	s_waitcnt lgkmcnt(0)
	v_mfma_f32_16x16x32_bf16 v[10:13], v[156:159], v[212:215], v[10:13]
	v_mfma_f32_16x16x32_bf16 v[6:9], v[164:167], v[212:215], v[6:9]
	v_mfma_f32_16x16x32_bf16 v[62:65], v[168:171], v[184:187], v[62:65]
	v_mfma_f32_16x16x32_bf16 v[54:57], v[176:179], v[184:187], v[54:57]
	v_mfma_f32_16x16x32_bf16 v[46:49], v[168:171], v[192:195], v[46:49]
	v_mfma_f32_16x16x32_bf16 v[38:41], v[176:179], v[192:195], v[38:41]
	v_mfma_f32_16x16x32_bf16 v[30:33], v[168:171], v[200:203], v[30:33]
	v_mfma_f32_16x16x32_bf16 v[22:25], v[176:179], v[200:203], v[22:25]
	v_mfma_f32_16x16x32_bf16 v[14:17], v[168:171], v[208:211], v[14:17]
	v_mfma_f32_16x16x32_bf16 v[2:5], v[176:179], v[208:211], v[2:5]
	v_mfma_f32_16x16x32_bf16 v[62:65], v[172:175], v[188:191], v[62:65]
	v_mfma_f32_16x16x32_bf16 v[54:57], v[180:183], v[188:191], v[54:57]
	v_mfma_f32_16x16x32_bf16 v[46:49], v[172:175], v[196:199], v[46:49]
	v_mfma_f32_16x16x32_bf16 v[38:41], v[180:183], v[196:199], v[38:41]
	v_mfma_f32_16x16x32_bf16 v[30:33], v[172:175], v[204:207], v[30:33]
	v_mfma_f32_16x16x32_bf16 v[22:25], v[180:183], v[204:207], v[22:25]
	v_mfma_f32_16x16x32_bf16 v[14:17], v[172:175], v[212:215], v[14:17]
	v_mfma_f32_16x16x32_bf16 v[2:5], v[180:183], v[212:215], v[2:5]
	s_barrier
	s_add_i32 s88, s88, 2
	s_add_u32 s86, s86, 0x100
	s_addc_u32 s87, s87, 0
	s_cmp_gt_u32 s88, 13
	s_mov_b64 s[40:41], s[0:1]

.LBB0_991:
	v_lshl_add_u32 v142, s38, 8, v145
	v_and_b32_e32 v130, 0x7cf, v142
	v_cmp_gt_i32_e32 vcc, s55, v142
	v_mov_b32_e32 v170, v126
	v_mov_b32_e32 v171, v122
	v_cndmask_b32_e32 v130, v146, v130, vcc
	v_lshlrev_b32_e32 v130, 7, v130
	v_lshl_add_u64 v[160:161], v[132:133], 0, v[130:131]
	v_lshl_add_u64 v[164:165], v[134:135], 0, v[130:131]
	global_load_dwordx4 v[152:155], v[160:161], off
	global_load_dwordx4 v[156:159], v[164:165], off
	s_nop 0
	global_load_dwordx4 v[160:163], v[160:161], off offset:16
	s_nop 0
	global_load_dwordx4 v[164:167], v[164:165], off offset:16
	v_mov_b32_e32 v168, v122
	v_mov_b32_e32 v169, v126
	v_mov_b32_e32 v126, v123
	v_mov_b32_e32 v122, v127
	v_mov_b32_e32 v172, v124
	v_mov_b32_e32 v173, v128
	v_mov_b32_e32 v174, v128
	v_mov_b32_e32 v175, v124
	v_mov_b32_e32 v176, v114
	v_mov_b32_e32 v177, v118
	v_mov_b32_e32 v178, v118
	v_mov_b32_e32 v179, v114
	v_mov_b32_e32 v118, v115
	v_mov_b32_e32 v114, v119
	v_mov_b32_e32 v180, v116
	v_mov_b32_e32 v181, v120
	v_mov_b32_e32 v128, v125
	v_mov_b32_e32 v124, v129
	v_mov_b32_e32 v182, v120
	v_mov_b32_e32 v183, v116
	s_lshl_b32 s0, s39, 8
	s_or_b32 s0, s0, s84
	v_ashrrev_i32_e32 v143, 31, v142
	s_ashr_i32 s1, s0, 31
	s_lshl_b64 s[38:39], s[0:1], 1
	v_mov_b32_e32 v141, v131
	s_movk_i32 s0, 0x7df
	s_waitcnt vmcnt(3)
	v_mov_b32_e32 v184, v152
	s_waitcnt vmcnt(2)
	v_mov_b32_e32 v185, v156
	v_mov_b32_e32 v156, v153
	v_mov_b32_e32 v152, v154
	v_mov_b32_e32 v153, v158
	v_mov_b32_e32 v158, v155
	s_waitcnt vmcnt(1)
	v_mov_b32_e32 v154, v160
	s_waitcnt vmcnt(0)
	v_mov_b32_e32 v155, v164
	v_mov_b32_e32 v164, v161
	v_mov_b32_e32 v160, v162
	v_mov_b32_e32 v161, v166
	v_pk_mul_f32 v[170:171], v[170:171], v[184:185]
	v_pk_mul_f32 v[126:127], v[126:127], v[156:157]
	v_pk_mul_f32 v[122:123], v[122:123], v[156:157]
	v_pk_mul_f32 v[156:157], v[172:173], v[152:153]
	v_pk_mul_f32 v[152:153], v[174:175], v[152:153]
	v_pk_mul_f32 v[118:119], v[118:119], v[164:165]
	v_pk_mul_f32 v[114:115], v[114:115], v[164:165]
	v_pk_mul_f32 v[164:165], v[180:181], v[160:161]
	v_add_f32_e32 v120, v170, v171
	v_pk_mul_f32 v[168:169], v[168:169], v[184:185]
	v_pk_mul_f32 v[128:129], v[128:129], v[158:159]
	v_pk_mul_f32 v[124:125], v[124:125], v[158:159]
	v_pk_mul_f32 v[158:159], v[176:177], v[154:155]
	v_pk_mul_f32 v[154:155], v[178:179], v[154:155]
	v_sub_f32_e32 v126, v126, v127
	v_add_f32_e32 v127, v152, v153
	v_add_f32_e32 v114, v114, v115
	v_sub_f32_e32 v115, v164, v165
	v_mul_f32_e32 v152, 0x3e38aa3b, v120
	v_mov_b32_e32 v120, v117
	v_mov_b32_e32 v166, v163
	v_sub_f32_e32 v116, v168, v169
	v_sub_f32_e32 v128, v128, v129
	v_add_f32_e32 v129, v154, v155
	v_mul_f32_e32 v154, 0x3e38aa3b, v114
	v_mul_f32_e32 v155, 0x3e38aa3b, v115
	v_pk_mul_f32 v[114:115], v[120:121], v[166:167]
	v_mul_f32_e32 v130, 0x3e38aa3b, v116
	v_sub_f32_e32 v114, v114, v115
	v_mov_b32_e32 v116, v121
	v_mul_f32_e32 v120, 0x3e38aa3b, v114
	v_pk_mul_f32 v[114:115], v[116:117], v[166:167]
	v_pk_mul_f32 v[160:161], v[182:183], v[160:161]
	v_add_f32_e32 v114, v114, v115
	v_mul_f32_e32 v121, 0x3e38aa3b, v114
	v_lshlrev_b64 v[114:115], 11, v[142:143]
	v_lshl_add_u64 v[114:115], s[18:19], 0, v[114:115]
	v_sub_f32_e32 v118, v118, v119
	v_add_f32_e32 v119, v160, v161
	v_lshl_add_u64 v[114:115], v[114:115], 0, s[38:39]
	v_add_f32_e32 v122, v122, v123
	v_sub_f32_e32 v123, v156, v157
	v_add_f32_e32 v124, v124, v125
	v_sub_f32_e32 v125, v158, v159
	v_mul_f32_e32 v126, 0x3e38aa3b, v126
	v_mul_f32_e32 v153, 0x3e38aa3b, v118
	v_mul_f32_e32 v156, 0x3e38aa3b, v119
	v_lshl_add_u64 v[118:119], v[114:115], 0, v[140:141]
	v_cvt_pk_bf16_f32 v114, v130, v126
	v_mul_f32_e32 v122, 0x3e38aa3b, v122
	v_mul_f32_e32 v123, 0x3e38aa3b, v123
	v_mul_f32_e32 v128, 0x3e38aa3b, v128
	v_mul_f32_e32 v125, 0x3e38aa3b, v125
	v_cvt_pk_bf16_f32 v115, v123, v128
	v_cvt_pk_bf16_f32 v116, v125, v153
	v_cvt_pk_bf16_f32 v117, v155, v120
	global_store_dwordx4 v[118:119], v[114:117], off
	v_mul_f32_e32 v127, 0x3e38aa3b, v127
	v_mul_f32_e32 v124, 0x3e38aa3b, v124
	v_cvt_pk_bf16_f32 v114, v152, v122
	v_or_b32_e32 v152, 16, v142
	v_mul_f32_e32 v129, 0x3e38aa3b, v129
	v_cvt_pk_bf16_f32 v115, v127, v124
	v_cvt_pk_bf16_f32 v116, v129, v154
	v_cvt_pk_bf16_f32 v117, v156, v121
	global_store_dwordx4 v[118:119], v[114:117], off offset:64
	v_cmp_gt_i32_e32 vcc, s55, v152
	v_mov_b32_e32 v154, v106
	v_bitop3_b32 v114, v142, s0, 16 bitop3:0xc8
	v_cndmask_b32_e32 v114, v147, v114, vcc
	v_lshlrev_b32_e32 v130, 7, v114
	v_lshl_add_u64 v[122:123], v[132:133], 0, v[130:131]
	v_lshl_add_u64 v[126:127], v[134:135], 0, v[130:131]
	global_load_dwordx4 v[114:117], v[122:123], off
	global_load_dwordx4 v[118:121], v[126:127], off
	s_nop 0
	global_load_dwordx4 v[122:125], v[122:123], off offset:16
	s_nop 0
	global_load_dwordx4 v[126:129], v[126:127], off offset:16
	v_mov_b32_e32 v155, v110
	v_mov_b32_e32 v156, v110
	v_mov_b32_e32 v157, v106
	v_mov_b32_e32 v110, v107
	v_mov_b32_e32 v106, v111
	v_mov_b32_e32 v158, v108
	v_mov_b32_e32 v159, v112
	v_mov_b32_e32 v160, v112
	v_mov_b32_e32 v161, v108
	v_mov_b32_e32 v112, v109
	v_mov_b32_e32 v108, v113
	v_mov_b32_e32 v163, v102
	v_mov_b32_e32 v164, v102
	v_mov_b32_e32 v165, v98
	v_mov_b32_e32 v162, v98
	v_ashrrev_i32_e32 v153, 31, v152
	s_movk_i32 s0, 0x7ef
	s_waitcnt vmcnt(3)
	v_mov_b32_e32 v166, v114
	s_waitcnt vmcnt(2)
	v_mov_b32_e32 v167, v118
	v_mov_b32_e32 v118, v115
	v_mov_b32_e32 v114, v116
	v_mov_b32_e32 v115, v120
	v_mov_b32_e32 v120, v117
	v_pk_mul_f32 v[154:155], v[154:155], v[166:167]
	v_pk_mul_f32 v[110:111], v[110:111], v[118:119]
	v_pk_mul_f32 v[106:107], v[106:107], v[118:119]
	v_pk_mul_f32 v[118:119], v[158:159], v[114:115]
	s_waitcnt vmcnt(1)
	v_mov_b32_e32 v116, v122
	s_waitcnt vmcnt(0)
	v_mov_b32_e32 v117, v126
	v_pk_mul_f32 v[114:115], v[160:161], v[114:115]
	v_pk_mul_f32 v[112:113], v[112:113], v[120:121]
	v_sub_f32_e32 v102, v154, v155
	v_add_f32_e32 v106, v106, v107
	v_sub_f32_e32 v107, v118, v119
	v_sub_f32_e32 v110, v110, v111
	v_add_f32_e32 v111, v114, v115
	v_sub_f32_e32 v112, v112, v113
	v_mul_f32_e32 v113, 0x3e38aa3b, v102
	v_mul_f32_e32 v115, 0x3e38aa3b, v106
	v_mul_f32_e32 v118, 0x3e38aa3b, v107
	v_pk_mul_f32 v[106:107], v[164:165], v[116:117]
	v_mov_b32_e32 v102, v99
	v_mov_b32_e32 v126, v123
	v_add_f32_e32 v98, v106, v107
	v_pk_mul_f32 v[106:107], v[102:103], v[126:127]
	v_pk_mul_f32 v[108:109], v[108:109], v[120:121]
	v_pk_mul_f32 v[120:121], v[162:163], v[116:117]
	v_mul_f32_e32 v116, 0x3e38aa3b, v98
	v_sub_f32_e32 v98, v106, v107
	v_mul_f32_e32 v106, 0x3e38aa3b, v98
	v_mov_b32_e32 v98, v103
	v_pk_mul_f32 v[98:99], v[98:99], v[126:127]
	v_mov_b32_e32 v102, v124
	v_add_f32_e32 v98, v98, v99
	v_mul_f32_e32 v107, 0x3e38aa3b, v98
	v_mov_b32_e32 v98, v100
	v_mov_b32_e32 v99, v104
	v_mov_b32_e32 v103, v128
	v_pk_mul_f32 v[98:99], v[98:99], v[102:103]
	v_mov_b32_e32 v128, v125
	v_sub_f32_e32 v98, v98, v99
	v_mul_f32_e32 v117, 0x3e38aa3b, v98
	v_mov_b32_e32 v98, v104
	v_mov_b32_e32 v99, v100
	v_pk_mul_f32 v[98:99], v[98:99], v[102:103]
	v_mov_b32_e32 v104, v101
	v_add_f32_e32 v98, v98, v99
	v_mul_f32_e32 v119, 0x3e38aa3b, v98
	v_pk_mul_f32 v[98:99], v[104:105], v[128:129]
	v_mov_b32_e32 v100, v105
	v_sub_f32_e32 v98, v98, v99
	v_mul_f32_e32 v104, 0x3e38aa3b, v98
	v_pk_mul_f32 v[98:99], v[100:101], v[128:129]
	v_pk_mul_f32 v[156:157], v[156:157], v[166:167]
	v_add_f32_e32 v98, v98, v99
	v_mul_f32_e32 v105, 0x3e38aa3b, v98
	v_lshlrev_b64 v[98:99], 11, v[152:153]
	v_lshl_add_u64 v[98:99], s[18:19], 0, v[98:99]
	v_add_f32_e32 v122, v156, v157
	v_lshl_add_u64 v[98:99], v[98:99], 0, s[38:39]
	v_add_f32_e32 v108, v108, v109
	v_sub_f32_e32 v109, v120, v121
	v_mul_f32_e32 v114, 0x3e38aa3b, v122
	v_mul_f32_e32 v110, 0x3e38aa3b, v110
	v_lshl_add_u64 v[102:103], v[98:99], 0, v[140:141]
	v_cvt_pk_bf16_f32 v98, v113, v110
	v_mul_f32_e32 v112, 0x3e38aa3b, v112
	v_mul_f32_e32 v109, 0x3e38aa3b, v109
	v_cvt_pk_bf16_f32 v99, v118, v112
	v_cvt_pk_bf16_f32 v100, v109, v106
	v_cvt_pk_bf16_f32 v101, v117, v104
	global_store_dwordx4 v[102:103], v[98:101], off
	v_mul_f32_e32 v111, 0x3e38aa3b, v111
	v_mul_f32_e32 v108, 0x3e38aa3b, v108
	v_cvt_pk_bf16_f32 v98, v114, v115
	v_or_b32_e32 v114, 32, v142
	v_cvt_pk_bf16_f32 v99, v111, v108
	v_cvt_pk_bf16_f32 v100, v116, v107
	v_cvt_pk_bf16_f32 v101, v119, v105
	global_store_dwordx4 v[102:103], v[98:101], off offset:64
	v_cmp_gt_i32_e32 vcc, s55, v114
	v_mov_b32_e32 v116, v90
	v_bitop3_b32 v98, v142, s0, 32 bitop3:0xc8
	v_cndmask_b32_e32 v98, v148, v98, vcc
	v_lshlrev_b32_e32 v130, 7, v98
	v_lshl_add_u64 v[106:107], v[132:133], 0, v[130:131]
	v_lshl_add_u64 v[110:111], v[134:135], 0, v[130:131]
	global_load_dwordx4 v[98:101], v[106:107], off
	global_load_dwordx4 v[102:105], v[110:111], off
	s_nop 0
	global_load_dwordx4 v[106:109], v[106:107], off offset:16
	s_nop 0
	global_load_dwordx4 v[110:113], v[110:111], off offset:16
	v_mov_b32_e32 v117, v94
	v_mov_b32_e32 v118, v94
	v_mov_b32_e32 v119, v90
	v_mov_b32_e32 v94, v91
	v_mov_b32_e32 v90, v95
	v_mov_b32_e32 v120, v92
	v_mov_b32_e32 v121, v96
	v_ashrrev_i32_e32 v115, 31, v114
	s_movk_i32 s0, 0x7ff
	s_waitcnt vmcnt(3)
	v_mov_b32_e32 v122, v98
	s_waitcnt vmcnt(2)
	v_mov_b32_e32 v123, v102
	v_mov_b32_e32 v102, v99
	v_mov_b32_e32 v98, v100
	v_mov_b32_e32 v99, v104
	v_pk_mul_f32 v[94:95], v[94:95], v[102:103]
	v_pk_mul_f32 v[90:91], v[90:91], v[102:103]
	v_pk_mul_f32 v[102:103], v[120:121], v[98:99]
	v_add_f32_e32 v90, v90, v91
	v_sub_f32_e32 v91, v102, v103
	v_pk_mul_f32 v[116:117], v[116:117], v[122:123]
	v_pk_mul_f32 v[118:119], v[118:119], v[122:123]
	v_mul_f32_e32 v102, 0x3e38aa3b, v90
	v_mul_f32_e32 v103, 0x3e38aa3b, v91
	v_mov_b32_e32 v90, v96
	v_mov_b32_e32 v91, v92
	v_sub_f32_e32 v100, v116, v117
	v_add_f32_e32 v104, v118, v119
	v_pk_mul_f32 v[90:91], v[90:91], v[98:99]
	v_sub_f32_e32 v94, v94, v95
	v_mul_f32_e32 v95, 0x3e38aa3b, v100
	v_mul_f32_e32 v100, 0x3e38aa3b, v104
	v_add_f32_e32 v90, v90, v91
	v_mov_b32_e32 v96, v93
	v_mov_b32_e32 v104, v101
	v_mul_f32_e32 v98, 0x3e38aa3b, v90
	v_pk_mul_f32 v[90:91], v[96:97], v[104:105]
	v_mov_b32_e32 v92, v97
	v_sub_f32_e32 v90, v90, v91
	v_mul_f32_e32 v96, 0x3e38aa3b, v90
	v_pk_mul_f32 v[90:91], v[92:93], v[104:105]
	s_waitcnt vmcnt(1)
	v_mov_b32_e32 v92, v106
	v_add_f32_e32 v90, v90, v91
	v_mul_f32_e32 v97, 0x3e38aa3b, v90
	v_mov_b32_e32 v90, v82
	v_mov_b32_e32 v91, v86
	s_waitcnt vmcnt(0)
	v_mov_b32_e32 v93, v110
	v_pk_mul_f32 v[90:91], v[90:91], v[92:93]
	v_mov_b32_e32 v110, v107
	v_sub_f32_e32 v90, v90, v91
	v_mul_f32_e32 v99, 0x3e38aa3b, v90
	v_mov_b32_e32 v90, v86
	v_mov_b32_e32 v91, v82
	v_pk_mul_f32 v[90:91], v[90:91], v[92:93]
	v_mov_b32_e32 v86, v83
	v_add_f32_e32 v82, v90, v91
	v_pk_mul_f32 v[90:91], v[86:87], v[110:111]
	v_mul_f32_e32 v92, 0x3e38aa3b, v82
	v_sub_f32_e32 v82, v90, v91
	v_mul_f32_e32 v90, 0x3e38aa3b, v82
	v_mov_b32_e32 v82, v87
	v_pk_mul_f32 v[82:83], v[82:83], v[110:111]
	v_mov_b32_e32 v86, v108
	v_add_f32_e32 v82, v82, v83
	v_mul_f32_e32 v91, 0x3e38aa3b, v82
	v_mov_b32_e32 v82, v84
	v_mov_b32_e32 v83, v88
	v_mov_b32_e32 v87, v112
	v_pk_mul_f32 v[82:83], v[82:83], v[86:87]
	v_mov_b32_e32 v112, v109
	v_sub_f32_e32 v82, v82, v83
	v_mul_f32_e32 v93, 0x3e38aa3b, v82
	v_mov_b32_e32 v82, v88
	v_mov_b32_e32 v83, v84
	v_pk_mul_f32 v[82:83], v[82:83], v[86:87]
	v_mov_b32_e32 v88, v85
	v_add_f32_e32 v82, v82, v83
	v_mul_f32_e32 v101, 0x3e38aa3b, v82
	v_pk_mul_f32 v[82:83], v[88:89], v[112:113]
	v_mov_b32_e32 v84, v89
	v_sub_f32_e32 v82, v82, v83
	v_mul_f32_e32 v88, 0x3e38aa3b, v82
	v_pk_mul_f32 v[82:83], v[84:85], v[112:113]
	v_mul_f32_e32 v94, 0x3e38aa3b, v94
	v_add_f32_e32 v82, v82, v83
	v_mul_f32_e32 v89, 0x3e38aa3b, v82
	v_lshlrev_b64 v[82:83], 11, v[114:115]
	v_lshl_add_u64 v[82:83], s[18:19], 0, v[82:83]
	v_lshl_add_u64 v[82:83], v[82:83], 0, s[38:39]
	v_lshl_add_u64 v[86:87], v[82:83], 0, v[140:141]
	v_cvt_pk_bf16_f32 v82, v95, v94
	v_cvt_pk_bf16_f32 v83, v103, v96
	v_cvt_pk_bf16_f32 v84, v99, v90
	v_cvt_pk_bf16_f32 v85, v93, v88
	global_store_dwordx4 v[86:87], v[82:85], off
	s_nop 1
	v_cvt_pk_bf16_f32 v82, v100, v102
	v_cvt_pk_bf16_f32 v83, v98, v97
	v_or_b32_e32 v98, 48, v142
	v_cvt_pk_bf16_f32 v84, v92, v91
	v_cvt_pk_bf16_f32 v85, v101, v89
	global_store_dwordx4 v[86:87], v[82:85], off offset:64
	v_cmp_gt_i32_e32 vcc, s55, v98
	v_mov_b32_e32 v100, v74
	v_bitop3_b32 v82, v142, s0, 48 bitop3:0xc8
	v_cndmask_b32_e32 v82, v149, v82, vcc
	v_lshlrev_b32_e32 v130, 7, v82
	v_lshl_add_u64 v[90:91], v[132:133], 0, v[130:131]
	v_lshl_add_u64 v[94:95], v[134:135], 0, v[130:131]
	global_load_dwordx4 v[82:85], v[90:91], off
	global_load_dwordx4 v[86:89], v[94:95], off
	s_nop 0
	global_load_dwordx4 v[90:93], v[90:91], off offset:16
	s_nop 0
	global_load_dwordx4 v[94:97], v[94:95], off offset:16
	v_mov_b32_e32 v101, v78
	v_ashrrev_i32_e32 v99, 31, v98
	s_mov_b32 s0, 0xff80
	v_cmp_gt_i32_e32 vcc, s0, v142
	s_mov_b32 s0, 0xff70
	s_waitcnt vmcnt(3)
	v_mov_b32_e32 v102, v82
	s_waitcnt vmcnt(2)
	v_mov_b32_e32 v103, v86
	v_pk_mul_f32 v[100:101], v[100:101], v[102:103]
	v_mov_b32_e32 v86, v83
	v_sub_f32_e32 v82, v100, v101
	v_mov_b32_e32 v100, v78
	v_mov_b32_e32 v101, v74
	v_pk_mul_f32 v[100:101], v[100:101], v[102:103]
	v_mov_b32_e32 v78, v75
	v_mul_f32_e32 v104, 0x3e38aa3b, v82
	v_add_f32_e32 v74, v100, v101
	v_pk_mul_f32 v[82:83], v[78:79], v[86:87]
	v_mul_f32_e32 v100, 0x3e38aa3b, v74
	v_sub_f32_e32 v74, v82, v83
	v_mul_f32_e32 v82, 0x3e38aa3b, v74
	v_mov_b32_e32 v74, v79
	v_pk_mul_f32 v[74:75], v[74:75], v[86:87]
	v_mov_b32_e32 v78, v84
	v_add_f32_e32 v74, v74, v75
	v_mul_f32_e32 v83, 0x3e38aa3b, v74
	v_mov_b32_e32 v74, v76
	v_mov_b32_e32 v75, v80
	v_mov_b32_e32 v79, v88
	v_pk_mul_f32 v[74:75], v[74:75], v[78:79]
	v_mov_b32_e32 v88, v85
	v_sub_f32_e32 v74, v74, v75
	v_mul_f32_e32 v84, 0x3e38aa3b, v74
	v_mov_b32_e32 v74, v80
	v_mov_b32_e32 v75, v76
	v_pk_mul_f32 v[74:75], v[74:75], v[78:79]
	v_mov_b32_e32 v80, v77
	v_add_f32_e32 v74, v74, v75
	v_mul_f32_e32 v78, 0x3e38aa3b, v74
	v_pk_mul_f32 v[74:75], v[80:81], v[88:89]
	v_mov_b32_e32 v76, v81
	v_sub_f32_e32 v74, v74, v75
	v_mul_f32_e32 v79, 0x3e38aa3b, v74
	v_pk_mul_f32 v[74:75], v[76:77], v[88:89]
	s_waitcnt vmcnt(1)
	v_mov_b32_e32 v76, v90
	v_add_f32_e32 v74, v74, v75
	v_mul_f32_e32 v80, 0x3e38aa3b, v74
	v_mov_b32_e32 v74, v66
	v_mov_b32_e32 v75, v70
	s_waitcnt vmcnt(0)
	v_mov_b32_e32 v77, v94
	v_pk_mul_f32 v[74:75], v[74:75], v[76:77]
	v_mov_b32_e32 v94, v91
	v_sub_f32_e32 v74, v74, v75
	v_mul_f32_e32 v81, 0x3e38aa3b, v74
	v_mov_b32_e32 v74, v70
	v_mov_b32_e32 v75, v66
	v_pk_mul_f32 v[74:75], v[74:75], v[76:77]
	v_mov_b32_e32 v70, v67
	v_add_f32_e32 v66, v74, v75
	v_pk_mul_f32 v[74:75], v[70:71], v[94:95]
	v_mul_f32_e32 v76, 0x3e38aa3b, v66
	v_sub_f32_e32 v66, v74, v75
	v_mul_f32_e32 v74, 0x3e38aa3b, v66
	v_mov_b32_e32 v66, v71
	v_pk_mul_f32 v[66:67], v[66:67], v[94:95]
	v_mov_b32_e32 v70, v92
	v_add_f32_e32 v66, v66, v67
	v_mul_f32_e32 v75, 0x3e38aa3b, v66
	v_mov_b32_e32 v66, v68
	v_mov_b32_e32 v67, v72
	v_mov_b32_e32 v71, v96
	v_pk_mul_f32 v[66:67], v[66:67], v[70:71]
	v_mov_b32_e32 v96, v93
	v_sub_f32_e32 v66, v66, v67
	v_mul_f32_e32 v77, 0x3e38aa3b, v66
	v_mov_b32_e32 v66, v72
	v_mov_b32_e32 v67, v68
	v_pk_mul_f32 v[66:67], v[66:67], v[70:71]
	v_mov_b32_e32 v72, v69
	v_add_f32_e32 v66, v66, v67
	v_mul_f32_e32 v85, 0x3e38aa3b, v66
	v_pk_mul_f32 v[66:67], v[72:73], v[96:97]
	v_mov_b32_e32 v68, v73
	v_sub_f32_e32 v66, v66, v67
	v_mul_f32_e32 v72, 0x3e38aa3b, v66
	v_pk_mul_f32 v[66:67], v[68:69], v[96:97]
	s_nop 0
	v_add_f32_e32 v66, v66, v67
	v_mul_f32_e32 v73, 0x3e38aa3b, v66
	v_lshlrev_b64 v[66:67], 11, v[98:99]
	v_lshl_add_u64 v[66:67], s[18:19], 0, v[66:67]
	v_lshl_add_u64 v[66:67], v[66:67], 0, s[38:39]
	v_lshl_add_u64 v[70:71], v[66:67], 0, v[140:141]
	v_cvt_pk_bf16_f32 v66, v104, v82
	v_cvt_pk_bf16_f32 v67, v84, v79
	v_cvt_pk_bf16_f32 v68, v81, v74
	v_cvt_pk_bf16_f32 v69, v77, v72
	global_store_dwordx4 v[70:71], v[66:69], off
	v_add_u32_e32 v82, 0x80, v142
	v_mov_b32_e32 v84, v58
	v_cvt_pk_bf16_f32 v66, v100, v83
	v_cvt_pk_bf16_f32 v67, v78, v80
	v_cvt_pk_bf16_f32 v68, v76, v75
	v_cvt_pk_bf16_f32 v69, v85, v73
	global_store_dwordx4 v[70:71], v[66:69], off offset:64
	v_mov_b32_e32 v85, v62
	v_ashrrev_i32_e32 v83, 31, v82
	v_and_b32_e32 v66, 0x7cf, v82
	v_cndmask_b32_e32 v66, v146, v66, vcc
	v_lshlrev_b32_e32 v130, 7, v66
	v_lshl_add_u64 v[74:75], v[132:133], 0, v[130:131]
	v_lshl_add_u64 v[78:79], v[134:135], 0, v[130:131]
	global_load_dwordx4 v[66:69], v[74:75], off
	global_load_dwordx4 v[70:73], v[78:79], off
	s_nop 0
	global_load_dwordx4 v[74:77], v[74:75], off offset:16
	s_nop 0
	global_load_dwordx4 v[78:81], v[78:79], off offset:16
	v_cmp_gt_i32_e32 vcc, s0, v142
	s_mov_b32 s0, 0xff60
	s_waitcnt vmcnt(3)
	v_mov_b32_e32 v86, v66
	s_waitcnt vmcnt(2)
	v_mov_b32_e32 v87, v70
	v_pk_mul_f32 v[84:85], v[84:85], v[86:87]
	v_mov_b32_e32 v70, v67
	v_sub_f32_e32 v66, v84, v85
	v_mov_b32_e32 v84, v62
	v_mov_b32_e32 v85, v58
	v_pk_mul_f32 v[84:85], v[84:85], v[86:87]
	v_mov_b32_e32 v62, v59
	v_mul_f32_e32 v88, 0x3e38aa3b, v66
	v_add_f32_e32 v58, v84, v85
	v_pk_mul_f32 v[66:67], v[62:63], v[70:71]
	v_mul_f32_e32 v84, 0x3e38aa3b, v58
	v_sub_f32_e32 v58, v66, v67
	v_mul_f32_e32 v66, 0x3e38aa3b, v58
	v_mov_b32_e32 v58, v63
	v_pk_mul_f32 v[58:59], v[58:59], v[70:71]
	v_mov_b32_e32 v62, v68
	v_add_f32_e32 v58, v58, v59
	v_mul_f32_e32 v67, 0x3e38aa3b, v58
	v_mov_b32_e32 v58, v60
	v_mov_b32_e32 v59, v64
	v_mov_b32_e32 v63, v72
	v_pk_mul_f32 v[58:59], v[58:59], v[62:63]
	v_mov_b32_e32 v72, v69
	v_sub_f32_e32 v58, v58, v59
	v_mul_f32_e32 v68, 0x3e38aa3b, v58
	v_mov_b32_e32 v58, v64
	v_mov_b32_e32 v59, v60
	v_pk_mul_f32 v[58:59], v[58:59], v[62:63]
	v_mov_b32_e32 v64, v61
	v_add_f32_e32 v58, v58, v59
	v_mul_f32_e32 v62, 0x3e38aa3b, v58
	v_pk_mul_f32 v[58:59], v[64:65], v[72:73]
	v_mov_b32_e32 v60, v65
	v_sub_f32_e32 v58, v58, v59
	v_mul_f32_e32 v63, 0x3e38aa3b, v58
	v_pk_mul_f32 v[58:59], v[60:61], v[72:73]
	s_waitcnt vmcnt(1)
	v_mov_b32_e32 v60, v74
	v_add_f32_e32 v58, v58, v59
	v_mul_f32_e32 v64, 0x3e38aa3b, v58
	v_mov_b32_e32 v58, v50
	v_mov_b32_e32 v59, v54
	s_waitcnt vmcnt(0)
	v_mov_b32_e32 v61, v78
	v_pk_mul_f32 v[58:59], v[58:59], v[60:61]
	v_mov_b32_e32 v78, v75
	v_sub_f32_e32 v58, v58, v59
	v_mul_f32_e32 v65, 0x3e38aa3b, v58
	v_mov_b32_e32 v58, v54
	v_mov_b32_e32 v59, v50
	v_pk_mul_f32 v[58:59], v[58:59], v[60:61]
	v_mov_b32_e32 v54, v51
	v_add_f32_e32 v50, v58, v59
	v_pk_mul_f32 v[58:59], v[54:55], v[78:79]
	v_mul_f32_e32 v60, 0x3e38aa3b, v50
	v_sub_f32_e32 v50, v58, v59
	v_mul_f32_e32 v58, 0x3e38aa3b, v50
	v_mov_b32_e32 v50, v55
	v_pk_mul_f32 v[50:51], v[50:51], v[78:79]
	v_mov_b32_e32 v54, v76
	v_add_f32_e32 v50, v50, v51
	v_mul_f32_e32 v59, 0x3e38aa3b, v50
	v_mov_b32_e32 v50, v52
	v_mov_b32_e32 v51, v56
	v_mov_b32_e32 v55, v80
	v_pk_mul_f32 v[50:51], v[50:51], v[54:55]
	v_mov_b32_e32 v80, v77
	v_sub_f32_e32 v50, v50, v51
	v_mul_f32_e32 v61, 0x3e38aa3b, v50
	v_mov_b32_e32 v50, v56
	v_mov_b32_e32 v51, v52
	v_pk_mul_f32 v[50:51], v[50:51], v[54:55]
	v_mov_b32_e32 v56, v53
	v_add_f32_e32 v50, v50, v51
	v_mul_f32_e32 v69, 0x3e38aa3b, v50
	v_pk_mul_f32 v[50:51], v[56:57], v[80:81]
	v_mov_b32_e32 v52, v57
	v_sub_f32_e32 v50, v50, v51
	v_mul_f32_e32 v56, 0x3e38aa3b, v50
	v_pk_mul_f32 v[50:51], v[52:53], v[80:81]
	s_nop 0
	v_add_f32_e32 v50, v50, v51
	v_mul_f32_e32 v57, 0x3e38aa3b, v50
	v_lshlrev_b64 v[50:51], 11, v[82:83]
	v_lshl_add_u64 v[50:51], s[18:19], 0, v[50:51]
	v_lshl_add_u64 v[50:51], v[50:51], 0, s[38:39]
	v_lshl_add_u64 v[54:55], v[50:51], 0, v[140:141]
	v_cvt_pk_bf16_f32 v50, v88, v66
	v_cvt_pk_bf16_f32 v51, v68, v63
	v_cvt_pk_bf16_f32 v52, v65, v58
	v_cvt_pk_bf16_f32 v53, v61, v56
	global_store_dwordx4 v[54:55], v[50:53], off
	v_add_u32_e32 v66, 0x90, v142
	v_mov_b32_e32 v68, v42
	v_cvt_pk_bf16_f32 v50, v84, v67
	v_cvt_pk_bf16_f32 v51, v62, v64
	v_cvt_pk_bf16_f32 v52, v60, v59
	v_cvt_pk_bf16_f32 v53, v69, v57
	global_store_dwordx4 v[54:55], v[50:53], off offset:64
	v_mov_b32_e32 v69, v46
	v_ashrrev_i32_e32 v67, 31, v66
	v_and_b32_e32 v50, 0x7df, v66
	v_cndmask_b32_e32 v50, v147, v50, vcc
	v_lshlrev_b32_e32 v130, 7, v50
	v_lshl_add_u64 v[58:59], v[132:133], 0, v[130:131]
	v_lshl_add_u64 v[62:63], v[134:135], 0, v[130:131]
	global_load_dwordx4 v[50:53], v[58:59], off
	global_load_dwordx4 v[54:57], v[62:63], off
	s_nop 0
	global_load_dwordx4 v[58:61], v[58:59], off offset:16
	s_nop 0
	global_load_dwordx4 v[62:65], v[62:63], off offset:16
	v_cmp_gt_i32_e32 vcc, s0, v142
	s_mov_b32 s0, 0xff50
	s_waitcnt vmcnt(3)
	v_mov_b32_e32 v70, v50
	s_waitcnt vmcnt(2)
	v_mov_b32_e32 v71, v54
	v_pk_mul_f32 v[68:69], v[68:69], v[70:71]
	v_mov_b32_e32 v54, v51
	v_sub_f32_e32 v50, v68, v69
	v_mov_b32_e32 v68, v46
	v_mov_b32_e32 v69, v42
	v_pk_mul_f32 v[68:69], v[68:69], v[70:71]
	v_mov_b32_e32 v46, v43
	v_mul_f32_e32 v72, 0x3e38aa3b, v50
	v_add_f32_e32 v42, v68, v69
	v_pk_mul_f32 v[50:51], v[46:47], v[54:55]
	v_mul_f32_e32 v68, 0x3e38aa3b, v42
	v_sub_f32_e32 v42, v50, v51
	v_mul_f32_e32 v50, 0x3e38aa3b, v42
	v_mov_b32_e32 v42, v47
	v_pk_mul_f32 v[42:43], v[42:43], v[54:55]
	v_mov_b32_e32 v46, v52
	v_add_f32_e32 v42, v42, v43
	v_mul_f32_e32 v51, 0x3e38aa3b, v42
	v_mov_b32_e32 v42, v44
	v_mov_b32_e32 v43, v48
	v_mov_b32_e32 v47, v56
	v_pk_mul_f32 v[42:43], v[42:43], v[46:47]
	v_mov_b32_e32 v56, v53
	v_sub_f32_e32 v42, v42, v43
	v_mul_f32_e32 v52, 0x3e38aa3b, v42
	v_mov_b32_e32 v42, v48
	v_mov_b32_e32 v43, v44
	v_pk_mul_f32 v[42:43], v[42:43], v[46:47]
	v_mov_b32_e32 v48, v45
	v_add_f32_e32 v42, v42, v43
	v_mul_f32_e32 v46, 0x3e38aa3b, v42
	v_pk_mul_f32 v[42:43], v[48:49], v[56:57]
	v_mov_b32_e32 v44, v49
	v_sub_f32_e32 v42, v42, v43
	v_mul_f32_e32 v47, 0x3e38aa3b, v42
	v_pk_mul_f32 v[42:43], v[44:45], v[56:57]
	s_waitcnt vmcnt(1)
	v_mov_b32_e32 v44, v58
	v_add_f32_e32 v42, v42, v43
	v_mul_f32_e32 v48, 0x3e38aa3b, v42
	v_mov_b32_e32 v42, v34
	v_mov_b32_e32 v43, v38
	s_waitcnt vmcnt(0)
	v_mov_b32_e32 v45, v62
	v_pk_mul_f32 v[42:43], v[42:43], v[44:45]
	v_mov_b32_e32 v62, v59
	v_sub_f32_e32 v42, v42, v43
	v_mul_f32_e32 v49, 0x3e38aa3b, v42
	v_mov_b32_e32 v42, v38
	v_mov_b32_e32 v43, v34
	v_pk_mul_f32 v[42:43], v[42:43], v[44:45]
	v_mov_b32_e32 v38, v35
	v_add_f32_e32 v34, v42, v43
	v_pk_mul_f32 v[42:43], v[38:39], v[62:63]
	v_mul_f32_e32 v44, 0x3e38aa3b, v34
	v_sub_f32_e32 v34, v42, v43
	v_mul_f32_e32 v42, 0x3e38aa3b, v34
	v_mov_b32_e32 v34, v39
	v_pk_mul_f32 v[34:35], v[34:35], v[62:63]
	v_mov_b32_e32 v38, v60
	v_add_f32_e32 v34, v34, v35
	v_mul_f32_e32 v43, 0x3e38aa3b, v34
	v_mov_b32_e32 v34, v36
	v_mov_b32_e32 v35, v40
	v_mov_b32_e32 v39, v64
	v_pk_mul_f32 v[34:35], v[34:35], v[38:39]
	v_mov_b32_e32 v64, v61
	v_sub_f32_e32 v34, v34, v35
	v_mul_f32_e32 v45, 0x3e38aa3b, v34
	v_mov_b32_e32 v34, v40
	v_mov_b32_e32 v35, v36
	v_pk_mul_f32 v[34:35], v[34:35], v[38:39]
	v_mov_b32_e32 v40, v37
	v_add_f32_e32 v34, v34, v35
	v_mul_f32_e32 v53, 0x3e38aa3b, v34
	v_pk_mul_f32 v[34:35], v[40:41], v[64:65]
	v_mov_b32_e32 v36, v41
	v_sub_f32_e32 v34, v34, v35
	v_mul_f32_e32 v40, 0x3e38aa3b, v34
	v_pk_mul_f32 v[34:35], v[36:37], v[64:65]
	s_nop 0
	v_add_f32_e32 v34, v34, v35
	v_mul_f32_e32 v41, 0x3e38aa3b, v34
	v_lshlrev_b64 v[34:35], 11, v[66:67]
	v_lshl_add_u64 v[34:35], s[18:19], 0, v[34:35]
	v_lshl_add_u64 v[34:35], v[34:35], 0, s[38:39]
	v_lshl_add_u64 v[38:39], v[34:35], 0, v[140:141]
	v_cvt_pk_bf16_f32 v34, v72, v50
	v_cvt_pk_bf16_f32 v35, v52, v47
	v_cvt_pk_bf16_f32 v36, v49, v42
	v_cvt_pk_bf16_f32 v37, v45, v40
	global_store_dwordx4 v[38:39], v[34:37], off
	v_add_u32_e32 v50, 0xa0, v142
	v_mov_b32_e32 v52, v26
	v_cvt_pk_bf16_f32 v34, v68, v51
	v_cvt_pk_bf16_f32 v35, v46, v48
	v_cvt_pk_bf16_f32 v36, v44, v43
	v_cvt_pk_bf16_f32 v37, v53, v41
	global_store_dwordx4 v[38:39], v[34:37], off offset:64
	v_mov_b32_e32 v53, v30
	v_ashrrev_i32_e32 v51, 31, v50
	v_and_b32_e32 v34, 0x7ef, v50
	v_cndmask_b32_e32 v34, v148, v34, vcc
	v_lshlrev_b32_e32 v130, 7, v34
	v_lshl_add_u64 v[42:43], v[132:133], 0, v[130:131]
	v_lshl_add_u64 v[46:47], v[134:135], 0, v[130:131]
	global_load_dwordx4 v[34:37], v[42:43], off
	global_load_dwordx4 v[38:41], v[46:47], off
	s_nop 0
	global_load_dwordx4 v[42:45], v[42:43], off offset:16
	s_nop 0
	global_load_dwordx4 v[46:49], v[46:47], off offset:16
	v_cmp_gt_i32_e32 vcc, s0, v142
	s_mov_b64 s[0:1], -1
	s_waitcnt vmcnt(3)
	v_mov_b32_e32 v54, v34
	s_waitcnt vmcnt(2)
	v_mov_b32_e32 v55, v38
	v_pk_mul_f32 v[52:53], v[52:53], v[54:55]
	v_mov_b32_e32 v38, v35
	v_sub_f32_e32 v34, v52, v53
	v_mov_b32_e32 v52, v30
	v_mov_b32_e32 v53, v26
	v_pk_mul_f32 v[52:53], v[52:53], v[54:55]
	v_mov_b32_e32 v30, v27
	v_mul_f32_e32 v56, 0x3e38aa3b, v34
	v_add_f32_e32 v26, v52, v53
	v_pk_mul_f32 v[34:35], v[30:31], v[38:39]
	v_mul_f32_e32 v52, 0x3e38aa3b, v26
	v_sub_f32_e32 v26, v34, v35
	v_mul_f32_e32 v34, 0x3e38aa3b, v26
	v_mov_b32_e32 v26, v31
	v_pk_mul_f32 v[26:27], v[26:27], v[38:39]
	v_mov_b32_e32 v30, v36
	v_add_f32_e32 v26, v26, v27
	v_mul_f32_e32 v35, 0x3e38aa3b, v26
	v_mov_b32_e32 v26, v28
	v_mov_b32_e32 v27, v32
	v_mov_b32_e32 v31, v40
	v_pk_mul_f32 v[26:27], v[26:27], v[30:31]
	v_mov_b32_e32 v40, v37
	v_sub_f32_e32 v26, v26, v27
	v_mul_f32_e32 v36, 0x3e38aa3b, v26
	v_mov_b32_e32 v26, v32
	v_mov_b32_e32 v27, v28
	v_pk_mul_f32 v[26:27], v[26:27], v[30:31]
	v_mov_b32_e32 v32, v29
	v_add_f32_e32 v26, v26, v27
	v_mul_f32_e32 v30, 0x3e38aa3b, v26
	v_pk_mul_f32 v[26:27], v[32:33], v[40:41]
	v_mov_b32_e32 v28, v33
	v_sub_f32_e32 v26, v26, v27
	v_mul_f32_e32 v31, 0x3e38aa3b, v26
	v_pk_mul_f32 v[26:27], v[28:29], v[40:41]
	s_waitcnt vmcnt(1)
	v_mov_b32_e32 v28, v42
	v_add_f32_e32 v26, v26, v27
	v_mul_f32_e32 v32, 0x3e38aa3b, v26
	v_mov_b32_e32 v26, v18
	v_mov_b32_e32 v27, v22
	s_waitcnt vmcnt(0)
	v_mov_b32_e32 v29, v46
	v_pk_mul_f32 v[26:27], v[26:27], v[28:29]
	v_mov_b32_e32 v46, v43
	v_sub_f32_e32 v26, v26, v27
	v_mul_f32_e32 v33, 0x3e38aa3b, v26
	v_mov_b32_e32 v26, v22
	v_mov_b32_e32 v27, v18
	v_pk_mul_f32 v[26:27], v[26:27], v[28:29]
	v_mov_b32_e32 v22, v19
	v_add_f32_e32 v18, v26, v27
	v_pk_mul_f32 v[26:27], v[22:23], v[46:47]
	v_mul_f32_e32 v28, 0x3e38aa3b, v18
	v_sub_f32_e32 v18, v26, v27
	v_mul_f32_e32 v26, 0x3e38aa3b, v18
	v_mov_b32_e32 v18, v23
	v_pk_mul_f32 v[18:19], v[18:19], v[46:47]
	v_mov_b32_e32 v22, v44
	v_add_f32_e32 v18, v18, v19
	v_mul_f32_e32 v27, 0x3e38aa3b, v18
	v_mov_b32_e32 v18, v20
	v_mov_b32_e32 v19, v24
	v_mov_b32_e32 v23, v48
	v_pk_mul_f32 v[18:19], v[18:19], v[22:23]
	v_mov_b32_e32 v48, v45
	v_sub_f32_e32 v18, v18, v19
	v_mul_f32_e32 v29, 0x3e38aa3b, v18
	v_mov_b32_e32 v18, v24
	v_mov_b32_e32 v19, v20
	v_pk_mul_f32 v[18:19], v[18:19], v[22:23]
	v_mov_b32_e32 v24, v21
	v_add_f32_e32 v18, v18, v19
	v_mul_f32_e32 v37, 0x3e38aa3b, v18
	v_pk_mul_f32 v[18:19], v[24:25], v[48:49]
	v_mov_b32_e32 v20, v25
	v_sub_f32_e32 v18, v18, v19
	v_mul_f32_e32 v24, 0x3e38aa3b, v18
	v_pk_mul_f32 v[18:19], v[20:21], v[48:49]
	s_nop 0
	v_add_f32_e32 v18, v18, v19
	v_mul_f32_e32 v25, 0x3e38aa3b, v18
	v_lshlrev_b64 v[18:19], 11, v[50:51]
	v_lshl_add_u64 v[18:19], s[18:19], 0, v[18:19]
	v_lshl_add_u64 v[18:19], v[18:19], 0, s[38:39]
	v_lshl_add_u64 v[22:23], v[18:19], 0, v[140:141]
	v_cvt_pk_bf16_f32 v18, v56, v34
	v_cvt_pk_bf16_f32 v19, v36, v31
	v_cvt_pk_bf16_f32 v20, v33, v26
	v_cvt_pk_bf16_f32 v21, v29, v24
	global_store_dwordx4 v[22:23], v[18:21], off
	v_add_u32_e32 v34, 0xb0, v142
	v_mov_b32_e32 v36, v10
	v_cvt_pk_bf16_f32 v18, v52, v35
	v_cvt_pk_bf16_f32 v19, v30, v32
	v_cvt_pk_bf16_f32 v20, v28, v27
	v_cvt_pk_bf16_f32 v21, v37, v25
	global_store_dwordx4 v[22:23], v[18:21], off offset:64
	v_mov_b32_e32 v37, v14
	v_ashrrev_i32_e32 v35, 31, v34
	v_and_b32_e32 v18, 0x7ff, v34
	v_cndmask_b32_e32 v18, v149, v18, vcc
	v_lshlrev_b32_e32 v130, 7, v18
	v_lshl_add_u64 v[26:27], v[132:133], 0, v[130:131]
	v_lshl_add_u64 v[30:31], v[134:135], 0, v[130:131]
	global_load_dwordx4 v[18:21], v[26:27], off
	global_load_dwordx4 v[22:25], v[30:31], off
	s_nop 0
	global_load_dwordx4 v[26:29], v[26:27], off offset:16
	s_nop 0
	global_load_dwordx4 v[30:33], v[30:31], off offset:16
	s_andn2_b64 vcc, exec, s[2:3]
	s_waitcnt vmcnt(3)
	v_mov_b32_e32 v38, v18
	s_waitcnt vmcnt(2)
	v_mov_b32_e32 v39, v22
	v_pk_mul_f32 v[36:37], v[36:37], v[38:39]
	v_mov_b32_e32 v22, v19
	v_sub_f32_e32 v18, v36, v37
	v_mov_b32_e32 v36, v14
	v_mov_b32_e32 v37, v10
	v_pk_mul_f32 v[36:37], v[36:37], v[38:39]
	v_mov_b32_e32 v14, v11
	v_mul_f32_e32 v40, 0x3e38aa3b, v18
	v_add_f32_e32 v10, v36, v37
	v_pk_mul_f32 v[18:19], v[14:15], v[22:23]
	v_mul_f32_e32 v36, 0x3e38aa3b, v10
	v_sub_f32_e32 v10, v18, v19
	v_mul_f32_e32 v18, 0x3e38aa3b, v10
	v_mov_b32_e32 v10, v15
	v_pk_mul_f32 v[10:11], v[10:11], v[22:23]
	v_mov_b32_e32 v14, v20
	v_add_f32_e32 v10, v10, v11
	v_mul_f32_e32 v19, 0x3e38aa3b, v10
	v_mov_b32_e32 v10, v12
	v_mov_b32_e32 v11, v16
	v_mov_b32_e32 v15, v24
	v_pk_mul_f32 v[10:11], v[10:11], v[14:15]
	v_mov_b32_e32 v24, v21
	v_sub_f32_e32 v10, v10, v11
	v_mul_f32_e32 v20, 0x3e38aa3b, v10
	v_mov_b32_e32 v10, v16
	v_mov_b32_e32 v11, v12
	v_pk_mul_f32 v[10:11], v[10:11], v[14:15]
	v_mov_b32_e32 v16, v13
	v_add_f32_e32 v10, v10, v11
	v_mul_f32_e32 v14, 0x3e38aa3b, v10
	v_pk_mul_f32 v[10:11], v[16:17], v[24:25]
	v_mov_b32_e32 v12, v17
	v_sub_f32_e32 v10, v10, v11
	v_mul_f32_e32 v15, 0x3e38aa3b, v10
	v_pk_mul_f32 v[10:11], v[12:13], v[24:25]
	s_waitcnt vmcnt(1)
	v_mov_b32_e32 v12, v26
	v_add_f32_e32 v10, v10, v11
	v_mul_f32_e32 v16, 0x3e38aa3b, v10
	v_mov_b32_e32 v10, v6
	v_mov_b32_e32 v11, v2
	s_waitcnt vmcnt(0)
	v_mov_b32_e32 v13, v30
	v_pk_mul_f32 v[10:11], v[10:11], v[12:13]
	v_mov_b32_e32 v30, v27
	v_sub_f32_e32 v10, v10, v11
	v_mul_f32_e32 v17, 0x3e38aa3b, v10
	v_mov_b32_e32 v10, v2
	v_mov_b32_e32 v11, v6
	v_pk_mul_f32 v[10:11], v[10:11], v[12:13]
	v_mov_b32_e32 v6, v3
	v_add_f32_e32 v2, v10, v11
	v_mul_f32_e32 v12, 0x3e38aa3b, v2
	v_mov_b32_e32 v2, v7
	v_pk_mul_f32 v[10:11], v[2:3], v[30:31]
	s_nop 0
	v_sub_f32_e32 v2, v10, v11
	v_mul_f32_e32 v10, 0x3e38aa3b, v2
	v_pk_mul_f32 v[2:3], v[6:7], v[30:31]
	v_mov_b32_e32 v6, v28
	v_add_f32_e32 v2, v2, v3
	v_mul_f32_e32 v11, 0x3e38aa3b, v2
	v_mov_b32_e32 v2, v8
	v_mov_b32_e32 v3, v4
	v_mov_b32_e32 v7, v32
	v_pk_mul_f32 v[2:3], v[2:3], v[6:7]
	v_mov_b32_e32 v32, v29
	v_sub_f32_e32 v2, v2, v3
	v_mul_f32_e32 v13, 0x3e38aa3b, v2
	v_mov_b32_e32 v2, v4
	v_mov_b32_e32 v3, v8
	v_pk_mul_f32 v[2:3], v[2:3], v[6:7]
	v_mov_b32_e32 v4, v9
	v_add_f32_e32 v2, v2, v3
	v_mul_f32_e32 v21, 0x3e38aa3b, v2
	v_pk_mul_f32 v[2:3], v[4:5], v[32:33]
	v_mov_b32_e32 v8, v5
	v_sub_f32_e32 v2, v2, v3
	v_mul_f32_e32 v22, 0x3e38aa3b, v2
	v_pk_mul_f32 v[2:3], v[8:9], v[32:33]
	s_nop 0
	v_add_f32_e32 v2, v2, v3
	v_mul_f32_e32 v8, 0x3e38aa3b, v2
	v_lshlrev_b64 v[2:3], 11, v[34:35]
	v_lshl_add_u64 v[2:3], s[18:19], 0, v[2:3]
	v_lshl_add_u64 v[2:3], v[2:3], 0, s[38:39]
	v_lshl_add_u64 v[6:7], v[2:3], 0, v[140:141]
	v_cvt_pk_bf16_f32 v2, v40, v18
	v_cvt_pk_bf16_f32 v3, v20, v15
	v_cvt_pk_bf16_f32 v4, v17, v10
	v_cvt_pk_bf16_f32 v5, v13, v22
	global_store_dwordx4 v[6:7], v[2:5], off
	s_nop 1
	v_cvt_pk_bf16_f32 v2, v36, v19
	v_cvt_pk_bf16_f32 v3, v14, v16
	v_cvt_pk_bf16_f32 v4, v12, v11
	v_cvt_pk_bf16_f32 v5, v21, v8
	global_store_dwordx4 v[6:7], v[2:5], off offset:64
	s_cbranch_vccnz .LBB0_984
	s_andn2_b64 vcc, exec, s[6:7]
	v_mov_b64 v[4:5], 0
	s_cbranch_vccnz .LBB0_983
	s_barrier
	s_branch .LBB0_983

.LBB0_1316:
	v_and_b32_e32 v3, 48, v2
	v_lshlrev_b32_e32 v4, 6, v2
	v_lshlrev_b32_e32 v2, 2, v2
	s_and_b32 s45, s15, 3
	s_lshl_b32 s12, s14, 13
	v_and_or_b32 v3, v4, s51, v3
	v_and_b32_e32 v2, 32, v2
	s_lshl_b32 s78, s14, 6
	v_bitop3_b32 v4, v3, s12, v2 bitop3:0xde
	s_lshl_b32 s12, s45, 12
	v_bitop3_b32 v2, v3, s12, v2 bitop3:0xde
	s_add_u32 s12, s4, 0x80
	s_addc_u32 s13, s5, 0
	s_add_i32 s80, s66, 0x18000
	s_waitcnt vmcnt(2)
	s_barrier
	s_mov_b32 s34, m0
	s_mov_b32 m0, s80
	s_nop 4
	global_load_lds_dwordx4 v131, s[12:13]
	s_mov_b32 m0, s34
	s_add_u32 s12, s4, 0x20080
	s_addc_u32 s13, s5, 0
	s_add_i32 s81, s66, 0x1a000
	s_mov_b32 s34, m0
	s_mov_b32 m0, s81
	s_nop 4
	global_load_lds_dwordx4 v131, s[12:13]
	s_mov_b32 m0, s34
	s_add_u32 s12, s8, 0x80
	s_addc_u32 s13, s9, 0
	s_add_i32 s82, s66, 0x8000
	s_mov_b32 s34, m0
	s_mov_b32 m0, s82
	s_nop 4
	global_load_lds_dwordx4 v130, s[12:13]
	s_mov_b32 m0, s34
	s_add_u32 s12, s8, 0x20080
	s_addc_u32 s13, s9, 0
	s_add_i32 s84, s66, 0xa000
	s_mov_b32 s34, m0
	s_mov_b32 m0, s84
	s_nop 4
	global_load_lds_dwordx4 v130, s[12:13]
	s_mov_b32 m0, s34
	s_add_u32 s12, s4, 0x40080
	s_addc_u32 s13, s5, 0
	s_add_i32 s85, s66, 0x1c000
	s_mov_b32 s34, m0
	s_mov_b32 m0, s85
	s_nop 4
	global_load_lds_dwordx4 v131, s[12:13]
	s_mov_b32 m0, s34
	s_add_u32 s12, s4, 0x60080
	s_addc_u32 s13, s5, 0
	s_add_i32 s86, s66, 0x1e000
	s_mov_b32 s34, m0
	s_mov_b32 m0, s86
	s_nop 4
	global_load_lds_dwordx4 v131, s[12:13]
	s_mov_b32 m0, s34
	s_waitcnt vmcnt(6)
	s_add_i32 s87, s66, 0xc000
	s_add_u32 s88, s70, s0
	v_mov_b32_e32 v106, 0
	v_add_u32_e32 v2, 0, v2
	s_addc_u32 s89, s71, s1
	s_mov_b32 s90, -2
	s_mov_b64 s[46:47], 0x15c40080
	v_add_u32_e32 v132, 0x10000, v2
	v_add_u32_e32 v133, 0x14000, v2
	v_add_u32_e32 v134, 0, v4
	v_add_u32_e32 v135, 0x18000, v2
	v_add_u32_e32 v136, 0x1c000, v2
	s_barrier
	ds_read_b128 v[138:141], v132
	ds_read_b128 v[142:145], v132 offset:1024
	ds_read_b128 v[146:149], v132 offset:2048
	ds_read_b128 v[150:153], v132 offset:3072
	ds_read_b128 v[154:157], v133
	ds_read_b128 v[158:161], v133 offset:1024
	ds_read_b128 v[166:169], v133 offset:2048
	ds_read_b128 v[170:173], v133 offset:3072
	s_add_u32 s0, s46, 0xea3c0080
	s_addc_u32 s1, s47, -1
	s_cmp_lg_u32 s90, 12
	s_cselect_b32 s13, s0, 0
	s_cselect_b32 s12, s1, 0
	s_add_u32 s0, s8, s13
	s_addc_u32 s1, s9, s12
	s_add_u32 s34, s0, 0x80
	s_addc_u32 s35, s1, 0
	s_add_u32 s48, s4, s13
	s_addc_u32 s49, s5, s12
	ds_read_b128 v[174:177], v134
	ds_read_b128 v[184:187], v134 offset:1024
	ds_read_b128 v[188:191], v134 offset:2048
	ds_read_b128 v[192:195], v134 offset:3072
	ds_read_b128 v[196:199], v134 offset:4096
	ds_read_b128 v[200:203], v134 offset:5120
	ds_read_b128 v[204:207], v134 offset:6144
	ds_read_b128 v[208:211], v134 offset:7168
	s_add_u32 s12, s88, s46
	s_addc_u32 s13, s89, s47
	s_mov_b32 s91, m0
	s_mov_b32 m0, s87
	s_nop 4
	global_load_lds_dwordx4 v130, s[12:13]
	s_mov_b32 m0, s91
	s_add_u32 s12, s12, 0x20000
	s_addc_u32 s13, s13, 0
	s_add_i32 s91, s66, 0xe000
	s_mov_b32 s92, m0
	s_mov_b32 m0, s91
	s_nop 4
	global_load_lds_dwordx4 v130, s[12:13]
	s_mov_b32 m0, s92
	s_waitcnt vmcnt(8)
	s_waitcnt lgkmcnt(0)
	s_barrier
	s_waitcnt lgkmcnt(7)
	v_mfma_f32_16x16x32_bf16 v[2:5], v[138:141], v[174:177], 0
	v_mfma_f32_16x16x32_bf16 v[6:9], v[146:149], v[174:177], 0
	s_waitcnt lgkmcnt(5)
	v_mfma_f32_16x16x32_bf16 v[30:33], v[138:141], v[188:191], 0
	v_mfma_f32_16x16x32_bf16 v[34:37], v[146:149], v[188:191], 0
	s_waitcnt lgkmcnt(3)
	v_mfma_f32_16x16x32_bf16 v[54:57], v[138:141], v[196:199], 0
	v_mfma_f32_16x16x32_bf16 v[50:53], v[146:149], v[196:199], 0
	s_waitcnt lgkmcnt(1)
	v_mfma_f32_16x16x32_bf16 v[70:73], v[138:141], v[204:207], 0
	v_mfma_f32_16x16x32_bf16 v[66:69], v[146:149], v[204:207], 0
	v_mfma_f32_16x16x32_bf16 v[2:5], v[142:145], v[184:187], v[2:5]
	v_mfma_f32_16x16x32_bf16 v[6:9], v[150:153], v[184:187], v[6:9]
	v_mfma_f32_16x16x32_bf16 v[30:33], v[142:145], v[192:195], v[30:33]
	v_mfma_f32_16x16x32_bf16 v[34:37], v[150:153], v[192:195], v[34:37]
	v_mfma_f32_16x16x32_bf16 v[54:57], v[142:145], v[200:203], v[54:57]
	v_mfma_f32_16x16x32_bf16 v[50:53], v[150:153], v[200:203], v[50:53]
	s_waitcnt lgkmcnt(0)
	v_mfma_f32_16x16x32_bf16 v[70:73], v[142:145], v[208:211], v[70:73]
	v_mfma_f32_16x16x32_bf16 v[66:69], v[150:153], v[208:211], v[66:69]
	v_mfma_f32_16x16x32_bf16 v[10:13], v[154:157], v[174:177], 0
	v_mfma_f32_16x16x32_bf16 v[14:17], v[166:169], v[174:177], 0
	v_mfma_f32_16x16x32_bf16 v[22:25], v[154:157], v[188:191], 0
	v_mfma_f32_16x16x32_bf16 v[18:21], v[166:169], v[188:191], 0
	v_mfma_f32_16x16x32_bf16 v[38:41], v[154:157], v[196:199], 0
	v_mfma_f32_16x16x32_bf16 v[26:29], v[166:169], v[196:199], 0
	v_mfma_f32_16x16x32_bf16 v[46:49], v[154:157], v[204:207], 0
	v_mfma_f32_16x16x32_bf16 v[42:45], v[166:169], v[204:207], 0
	v_mfma_f32_16x16x32_bf16 v[10:13], v[158:161], v[184:187], v[10:13]
	v_mfma_f32_16x16x32_bf16 v[14:17], v[170:173], v[184:187], v[14:17]
	v_mfma_f32_16x16x32_bf16 v[22:25], v[158:161], v[192:195], v[22:25]
	v_mfma_f32_16x16x32_bf16 v[18:21], v[170:173], v[192:195], v[18:21]
	v_mfma_f32_16x16x32_bf16 v[38:41], v[158:161], v[200:203], v[38:41]
	v_mfma_f32_16x16x32_bf16 v[26:29], v[170:173], v[200:203], v[26:29]
	v_mfma_f32_16x16x32_bf16 v[46:49], v[158:161], v[208:211], v[46:49]
	v_mfma_f32_16x16x32_bf16 v[42:45], v[170:173], v[208:211], v[42:45]
	s_barrier
	ds_read_b128 v[174:177], v134 offset:16384
	ds_read_b128 v[184:187], v134 offset:17408
	ds_read_b128 v[188:191], v134 offset:18432
	ds_read_b128 v[192:195], v134 offset:19456
	ds_read_b128 v[196:199], v134 offset:20480
	ds_read_b128 v[200:203], v134 offset:21504
	ds_read_b128 v[204:207], v134 offset:22528
	ds_read_b128 v[208:211], v134 offset:23552
	s_mov_b32 s12, m0
	s_mov_b32 m0, s67
	s_nop 4
	global_load_lds_dwordx4 v131, s[48:49]
	s_mov_b32 m0, s12
	s_add_u32 s12, s48, 0x20000
	s_addc_u32 s13, s49, 0
	s_mov_b32 s91, m0
	s_mov_b32 m0, s73
	s_nop 4
	global_load_lds_dwordx4 v131, s[12:13]
	s_mov_b32 m0, s91
	s_add_u32 s12, s48, 0x40000
	s_addc_u32 s13, s49, 0
	s_mov_b32 s91, m0
	s_mov_b32 m0, s74
	s_nop 4
	global_load_lds_dwordx4 v131, s[12:13]
	s_mov_b32 m0, s91
	s_add_u32 s12, s48, 0x60000
	s_addc_u32 s13, s49, 0
	s_mov_b32 s91, m0
	s_mov_b32 m0, s75
	s_nop 4
	global_load_lds_dwordx4 v131, s[12:13]
	s_mov_b32 m0, s91
	s_mov_b32 s12, m0
	s_mov_b32 m0, s66
	s_nop 4
	global_load_lds_dwordx4 v130, s[0:1]
	s_mov_b32 m0, s12
	s_add_u32 s12, s0, 0x20000
	s_addc_u32 s13, s1, 0
	s_mov_b32 s91, m0
	s_mov_b32 m0, s76
	s_nop 4
	global_load_lds_dwordx4 v130, s[12:13]
	s_mov_b32 m0, s91
	s_waitcnt vmcnt(8)
	s_waitcnt lgkmcnt(0)
	s_barrier
	s_waitcnt lgkmcnt(7)
	v_mfma_f32_16x16x32_bf16 v[82:85], v[138:141], v[174:177], 0
	v_mfma_f32_16x16x32_bf16 v[74:77], v[146:149], v[174:177], 0
	s_waitcnt lgkmcnt(5)
	v_mfma_f32_16x16x32_bf16 v[98:101], v[138:141], v[188:191], 0
	v_mfma_f32_16x16x32_bf16 v[90:93], v[146:149], v[188:191], 0
	s_waitcnt lgkmcnt(3)
	v_mfma_f32_16x16x32_bf16 v[118:121], v[138:141], v[196:199], 0
	v_mfma_f32_16x16x32_bf16 v[114:117], v[146:149], v[196:199], 0
	s_waitcnt lgkmcnt(1)
	v_mfma_f32_16x16x32_bf16 v[126:129], v[138:141], v[204:207], 0
	v_mfma_f32_16x16x32_bf16 v[122:125], v[146:149], v[204:207], 0
	v_mfma_f32_16x16x32_bf16 v[82:85], v[142:145], v[184:187], v[82:85]
	v_mfma_f32_16x16x32_bf16 v[74:77], v[150:153], v[184:187], v[74:77]
	v_mfma_f32_16x16x32_bf16 v[98:101], v[142:145], v[192:195], v[98:101]
	v_mfma_f32_16x16x32_bf16 v[90:93], v[150:153], v[192:195], v[90:93]
	v_mfma_f32_16x16x32_bf16 v[118:121], v[142:145], v[200:203], v[118:121]
	v_mfma_f32_16x16x32_bf16 v[114:117], v[150:153], v[200:203], v[114:117]
	s_waitcnt lgkmcnt(0)
	v_mfma_f32_16x16x32_bf16 v[126:129], v[142:145], v[208:211], v[126:129]
	v_mfma_f32_16x16x32_bf16 v[122:125], v[150:153], v[208:211], v[122:125]
	v_mfma_f32_16x16x32_bf16 v[62:65], v[154:157], v[174:177], 0
	v_mfma_f32_16x16x32_bf16 v[58:61], v[166:169], v[174:177], 0
	v_mfma_f32_16x16x32_bf16 v[86:89], v[154:157], v[188:191], 0
	v_mfma_f32_16x16x32_bf16 v[78:81], v[166:169], v[188:191], 0
	v_mfma_f32_16x16x32_bf16 v[102:105], v[154:157], v[196:199], 0
	v_mfma_f32_16x16x32_bf16 v[94:97], v[166:169], v[196:199], 0
	v_mfma_f32_16x16x32_bf16 v[110:113], v[154:157], v[204:207], 0
	v_mfma_f32_16x16x32_bf16 v[106:109], v[166:169], v[204:207], 0
	v_mfma_f32_16x16x32_bf16 v[62:65], v[158:161], v[184:187], v[62:65]
	v_mfma_f32_16x16x32_bf16 v[58:61], v[170:173], v[184:187], v[58:61]
	v_mfma_f32_16x16x32_bf16 v[86:89], v[158:161], v[192:195], v[86:89]
	v_mfma_f32_16x16x32_bf16 v[78:81], v[170:173], v[192:195], v[78:81]
	v_mfma_f32_16x16x32_bf16 v[102:105], v[158:161], v[200:203], v[102:105]
	v_mfma_f32_16x16x32_bf16 v[94:97], v[170:173], v[200:203], v[94:97]
	v_mfma_f32_16x16x32_bf16 v[110:113], v[158:161], v[208:211], v[110:113]
	v_mfma_f32_16x16x32_bf16 v[106:109], v[170:173], v[208:211], v[106:109]
	s_barrier
	ds_read_b128 v[138:141], v135
	ds_read_b128 v[142:145], v135 offset:1024
	ds_read_b128 v[146:149], v135 offset:2048
	ds_read_b128 v[150:153], v135 offset:3072
	ds_read_b128 v[154:157], v136
	ds_read_b128 v[158:161], v136 offset:1024
	ds_read_b128 v[166:169], v136 offset:2048
	ds_read_b128 v[170:173], v136 offset:3072
	ds_read_b128 v[174:177], v134 offset:32768
	ds_read_b128 v[184:187], v134 offset:33792
	ds_read_b128 v[188:191], v134 offset:34816
	ds_read_b128 v[192:195], v134 offset:35840
	ds_read_b128 v[196:199], v134 offset:36864
	ds_read_b128 v[200:203], v134 offset:37888
	ds_read_b128 v[204:207], v134 offset:38912
	ds_read_b128 v[208:211], v134 offset:39936
	s_add_u32 s12, s0, 0x40000
	s_addc_u32 s13, s1, 0
	s_mov_b32 s91, m0
	s_mov_b32 m0, s77
	s_nop 4
	global_load_lds_dwordx4 v130, s[12:13]
	s_mov_b32 m0, s91
	s_add_u32 s12, s0, 0x60000
	s_addc_u32 s13, s1, 0
	s_mov_b32 s91, m0
	s_mov_b32 m0, s79
	s_nop 4
	global_load_lds_dwordx4 v130, s[12:13]
	s_mov_b32 m0, s91
	s_waitcnt vmcnt(8)
	s_waitcnt lgkmcnt(0)
	s_barrier
	s_waitcnt lgkmcnt(7)
	v_mfma_f32_16x16x32_bf16 v[2:5], v[138:141], v[174:177], v[2:5]
	v_mfma_f32_16x16x32_bf16 v[6:9], v[146:149], v[174:177], v[6:9]
	s_waitcnt lgkmcnt(5)
	v_mfma_f32_16x16x32_bf16 v[30:33], v[138:141], v[188:191], v[30:33]
	v_mfma_f32_16x16x32_bf16 v[34:37], v[146:149], v[188:191], v[34:37]
	s_waitcnt lgkmcnt(3)
	v_mfma_f32_16x16x32_bf16 v[54:57], v[138:141], v[196:199], v[54:57]
	v_mfma_f32_16x16x32_bf16 v[50:53], v[146:149], v[196:199], v[50:53]
	s_waitcnt lgkmcnt(1)
	v_mfma_f32_16x16x32_bf16 v[70:73], v[138:141], v[204:207], v[70:73]
	v_mfma_f32_16x16x32_bf16 v[66:69], v[146:149], v[204:207], v[66:69]
	v_mfma_f32_16x16x32_bf16 v[2:5], v[142:145], v[184:187], v[2:5]
	v_mfma_f32_16x16x32_bf16 v[6:9], v[150:153], v[184:187], v[6:9]
	v_mfma_f32_16x16x32_bf16 v[30:33], v[142:145], v[192:195], v[30:33]
	v_mfma_f32_16x16x32_bf16 v[34:37], v[150:153], v[192:195], v[34:37]
	v_mfma_f32_16x16x32_bf16 v[54:57], v[142:145], v[200:203], v[54:57]
	v_mfma_f32_16x16x32_bf16 v[50:53], v[150:153], v[200:203], v[50:53]
	s_waitcnt lgkmcnt(0)
	v_mfma_f32_16x16x32_bf16 v[70:73], v[142:145], v[208:211], v[70:73]
	v_mfma_f32_16x16x32_bf16 v[66:69], v[150:153], v[208:211], v[66:69]
	v_mfma_f32_16x16x32_bf16 v[10:13], v[154:157], v[174:177], v[10:13]
	v_mfma_f32_16x16x32_bf16 v[14:17], v[166:169], v[174:177], v[14:17]
	v_mfma_f32_16x16x32_bf16 v[22:25], v[154:157], v[188:191], v[22:25]
	v_mfma_f32_16x16x32_bf16 v[18:21], v[166:169], v[188:191], v[18:21]
	v_mfma_f32_16x16x32_bf16 v[38:41], v[154:157], v[196:199], v[38:41]
	v_mfma_f32_16x16x32_bf16 v[26:29], v[166:169], v[196:199], v[26:29]
	v_mfma_f32_16x16x32_bf16 v[46:49], v[154:157], v[204:207], v[46:49]
	v_mfma_f32_16x16x32_bf16 v[42:45], v[166:169], v[204:207], v[42:45]
	v_mfma_f32_16x16x32_bf16 v[10:13], v[158:161], v[184:187], v[10:13]
	v_mfma_f32_16x16x32_bf16 v[14:17], v[170:173], v[184:187], v[14:17]
	v_mfma_f32_16x16x32_bf16 v[22:25], v[158:161], v[192:195], v[22:25]
	v_mfma_f32_16x16x32_bf16 v[18:21], v[170:173], v[192:195], v[18:21]
	v_mfma_f32_16x16x32_bf16 v[38:41], v[158:161], v[200:203], v[38:41]
	v_mfma_f32_16x16x32_bf16 v[26:29], v[170:173], v[200:203], v[26:29]
	v_mfma_f32_16x16x32_bf16 v[46:49], v[158:161], v[208:211], v[46:49]
	v_mfma_f32_16x16x32_bf16 v[42:45], v[170:173], v[208:211], v[42:45]
	s_barrier
	s_add_u32 s12, s48, 0x80
	s_addc_u32 s13, s49, 0
	ds_read_b128 v[174:177], v134 offset:49152
	ds_read_b128 v[184:187], v134 offset:50176
	ds_read_b128 v[188:191], v134 offset:51200
	ds_read_b128 v[192:195], v134 offset:52224
	ds_read_b128 v[196:199], v134 offset:53248
	ds_read_b128 v[200:203], v134 offset:54272
	ds_read_b128 v[204:207], v134 offset:55296
	ds_read_b128 v[208:211], v134 offset:56320
	s_mov_b32 s91, m0
	s_mov_b32 m0, s80
	s_nop 4
	global_load_lds_dwordx4 v131, s[12:13]
	s_mov_b32 m0, s91
	s_add_u32 s12, s48, 0x20080
	s_addc_u32 s13, s49, 0
	s_mov_b32 s91, m0
	s_mov_b32 m0, s81
	s_nop 4
	global_load_lds_dwordx4 v131, s[12:13]
	s_mov_b32 m0, s91
	s_add_u32 s12, s48, 0x40080
	s_addc_u32 s13, s49, 0
	s_mov_b32 s91, m0
	s_mov_b32 m0, s85
	s_nop 4
	global_load_lds_dwordx4 v131, s[12:13]
	s_mov_b32 m0, s91
	s_add_u32 s12, s48, 0x60080
	s_addc_u32 s13, s49, 0
	s_mov_b32 s48, m0
	s_mov_b32 m0, s86
	s_nop 4
	global_load_lds_dwordx4 v131, s[12:13]
	s_mov_b32 m0, s48
	s_mov_b32 s12, m0
	s_mov_b32 m0, s82
	s_nop 4
	global_load_lds_dwordx4 v130, s[34:35]
	s_mov_b32 m0, s12
	s_add_u32 s0, s0, 0x20080
	s_addc_u32 s1, s1, 0
	s_mov_b32 s12, m0
	s_mov_b32 m0, s84
	s_nop 4
	global_load_lds_dwordx4 v130, s[0:1]
	s_mov_b32 m0, s12
	s_waitcnt vmcnt(8)
	s_waitcnt lgkmcnt(0)
	s_barrier
	s_waitcnt lgkmcnt(7)
	v_mfma_f32_16x16x32_bf16 v[82:85], v[138:141], v[174:177], v[82:85]
	v_mfma_f32_16x16x32_bf16 v[74:77], v[146:149], v[174:177], v[74:77]
	s_waitcnt lgkmcnt(5)
	v_mfma_f32_16x16x32_bf16 v[98:101], v[138:141], v[188:191], v[98:101]
	v_mfma_f32_16x16x32_bf16 v[90:93], v[146:149], v[188:191], v[90:93]
	s_waitcnt lgkmcnt(3)
	v_mfma_f32_16x16x32_bf16 v[118:121], v[138:141], v[196:199], v[118:121]
	v_mfma_f32_16x16x32_bf16 v[114:117], v[146:149], v[196:199], v[114:117]
	s_waitcnt lgkmcnt(1)
	v_mfma_f32_16x16x32_bf16 v[126:129], v[138:141], v[204:207], v[126:129]
	v_mfma_f32_16x16x32_bf16 v[122:125], v[146:149], v[204:207], v[122:125]
	v_mfma_f32_16x16x32_bf16 v[82:85], v[142:145], v[184:187], v[82:85]
	v_mfma_f32_16x16x32_bf16 v[74:77], v[150:153], v[184:187], v[74:77]
	v_mfma_f32_16x16x32_bf16 v[98:101], v[142:145], v[192:195], v[98:101]
	v_mfma_f32_16x16x32_bf16 v[90:93], v[150:153], v[192:195], v[90:93]
	v_mfma_f32_16x16x32_bf16 v[118:121], v[142:145], v[200:203], v[118:121]
	v_mfma_f32_16x16x32_bf16 v[114:117], v[150:153], v[200:203], v[114:117]
	s_waitcnt lgkmcnt(0)
	v_mfma_f32_16x16x32_bf16 v[126:129], v[142:145], v[208:211], v[126:129]
	v_mfma_f32_16x16x32_bf16 v[122:125], v[150:153], v[208:211], v[122:125]
	v_mfma_f32_16x16x32_bf16 v[62:65], v[154:157], v[174:177], v[62:65]
	v_mfma_f32_16x16x32_bf16 v[58:61], v[166:169], v[174:177], v[58:61]
	v_mfma_f32_16x16x32_bf16 v[86:89], v[154:157], v[188:191], v[86:89]
	v_mfma_f32_16x16x32_bf16 v[78:81], v[166:169], v[188:191], v[78:81]
	v_mfma_f32_16x16x32_bf16 v[102:105], v[154:157], v[196:199], v[102:105]
	v_mfma_f32_16x16x32_bf16 v[94:97], v[166:169], v[196:199], v[94:97]
	v_mfma_f32_16x16x32_bf16 v[110:113], v[154:157], v[204:207], v[110:113]
	v_mfma_f32_16x16x32_bf16 v[106:109], v[166:169], v[204:207], v[106:109]
	v_mfma_f32_16x16x32_bf16 v[62:65], v[158:161], v[184:187], v[62:65]
	v_mfma_f32_16x16x32_bf16 v[58:61], v[170:173], v[184:187], v[58:61]
	v_mfma_f32_16x16x32_bf16 v[86:89], v[158:161], v[192:195], v[86:89]
	v_mfma_f32_16x16x32_bf16 v[78:81], v[170:173], v[192:195], v[78:81]
	v_mfma_f32_16x16x32_bf16 v[102:105], v[158:161], v[200:203], v[102:105]
	v_mfma_f32_16x16x32_bf16 v[94:97], v[170:173], v[200:203], v[94:97]
	v_mfma_f32_16x16x32_bf16 v[110:113], v[158:161], v[208:211], v[110:113]
	v_mfma_f32_16x16x32_bf16 v[106:109], v[170:173], v[208:211], v[106:109]
	s_barrier
	s_add_i32 s90, s90, 2
	s_add_u32 s46, s46, 0x100
	s_addc_u32 s47, s47, 0
	s_cmp_lt_u32 s90, 14

.LBB0_1418:
	v_lshrrev_b32_e32 v4, 1, v2
	v_and_b32_e32 v4, 24, v4
	v_and_b32_e32 v3, 15, v2
	v_lshlrev_b32_e32 v5, 1, v4
	v_lshlrev_b32_e32 v2, 2, v2
	s_sext_i32_i16 s63, s2
	v_lshl_or_b32 v137, s8, 6, v3
	v_lshl_or_b32 v3, v3, 6, v5
	s_lshl_b32 s2, s8, 13
	v_and_b32_e32 v2, 32, v2
	v_bitop3_b32 v5, v3, s2, v2 bitop3:0xde
	s_lshl_b32 s2, s9, 5
	s_and_b32 s2, s2, 0x60
	s_lshl_b32 s8, s2, 7
	v_bitop3_b32 v6, v3, s8, v2 bitop3:0xde
	s_add_u32 s8, s0, 0x80
	s_addc_u32 s9, s1, 0
	s_add_i32 s53, s27, 0x18000
	s_waitcnt vmcnt(2)
	s_barrier
	s_mov_b32 s10, m0
	s_mov_b32 m0, s53
	s_nop 4
	global_load_lds_dwordx4 v136, s[8:9]
	s_mov_b32 m0, s10
	s_add_u32 s8, s0, 0x20080
	s_addc_u32 s9, s1, 0
	s_add_i32 s54, s27, 0x1a000
	s_mov_b32 s10, m0
	s_mov_b32 m0, s54
	s_nop 4
	global_load_lds_dwordx4 v136, s[8:9]
	s_mov_b32 m0, s10
	s_add_u32 s8, s36, 0x80
	s_addc_u32 s9, s37, 0
	s_add_i32 s55, s27, 0x8000
	s_mov_b32 s10, m0
	s_mov_b32 m0, s55
	s_nop 4
	global_load_lds_dwordx4 v1, s[8:9]
	s_mov_b32 m0, s10
	s_add_u32 s8, s36, 0x20080
	s_addc_u32 s9, s37, 0
	s_add_i32 s56, s27, 0xa000
	s_mov_b32 s10, m0
	s_mov_b32 m0, s56
	s_nop 4
	global_load_lds_dwordx4 v1, s[8:9]
	s_mov_b32 m0, s10
	s_add_u32 s8, s0, 0x40080
	s_addc_u32 s9, s1, 0
	s_add_i32 s57, s27, 0x1c000
	s_mov_b32 s10, m0
	s_mov_b32 m0, s57
	s_nop 4
	global_load_lds_dwordx4 v136, s[8:9]
	s_mov_b32 m0, s10
	s_add_u32 s8, s0, 0x60080
	s_addc_u32 s9, s1, 0
	s_add_i32 s58, s27, 0x1e000
	s_mov_b32 s10, m0
	s_mov_b32 m0, s58
	s_nop 4
	global_load_lds_dwordx4 v136, s[8:9]
	s_mov_b32 m0, s10
	s_waitcnt vmcnt(6)
	s_add_i32 s59, s27, 0xc000
	s_cmpk_lt_u32 s3, 0x100
	v_mov_b64_e32 v[2:3], 0
	s_cselect_b64 s[8:9], -1, 0
	s_ashr_i32 s60, s72, 31
	v_or_b32_e32 v138, s2, v4
	v_mov_b64_e32 v[130:131], 0x16b0
	v_mov_b64_e32 v[132:133], 0x16af
	v_add_u32_e32 v139, 0, v6
	v_add_u32_e32 v140, 0, v5
	s_mov_b32 s61, 0xc3dc0000
	s_movk_i32 s62, 0xb00
	v_mov_b32_e32 v141, 0x43dc0000
	s_barrier
	s_branch .LBB0_1421

.LBB0_1423:
	s_ashr_i32 s21, s20, 31
	s_lshl_b64 s[12:13], s[20:21], 19
	s_add_u32 s22, s16, s12
	s_addc_u32 s23, s17, s13
	s_and_b64 s[12:13], s[2:3], exec
	s_cselect_b32 s14, s23, s37
	s_cselect_b32 s15, s22, s36
	s_ashr_i32 s11, s10, 31
	s_lshl_b64 s[12:13], s[10:11], 19
	s_add_u32 s24, s42, s12
	s_addc_u32 s25, s43, s13
	s_and_b64 s[12:13], s[2:3], exec
	s_cselect_b32 s11, s25, s1
	s_cselect_b32 s21, s24, s0
	s_add_u32 s64, s0, 0x100
	s_addc_u32 s65, s1, 0
	s_mov_b32 s66, -2
	v_add_u32_e32 v134, 0x10000, v139
	ds_read_b128 v[142:145], v134
	ds_read_b128 v[146:149], v134 offset:1024
	ds_read_b128 v[150:153], v134 offset:2048
	ds_read_b128 v[154:157], v134 offset:3072
	v_add_u32_e32 v134, 0x14000, v139
	ds_read_b128 v[158:161], v134
	ds_read_b128 v[162:165], v134 offset:1024
	ds_read_b128 v[166:169], v134 offset:2048
	ds_read_b128 v[170:173], v134 offset:3072
	s_add_u32 s0, s36, 0x100
	s_addc_u32 s1, s37, 0
	s_cmp_eq_u32 s66, 12
	s_cselect_b32 s34, s15, s0
	s_cselect_b32 s35, s14, s1
	s_cselect_b32 s40, s21, s64
	s_cselect_b32 s41, s11, s65
	s_add_u32 s38, s34, 0x80
	s_addc_u32 s39, s35, 0
	ds_read_b128 v[174:177], v140
	ds_read_b128 v[178:181], v140 offset:1024
	ds_read_b128 v[182:185], v140 offset:2048
	ds_read_b128 v[186:189], v140 offset:3072
	ds_read_b128 v[190:193], v140 offset:4096
	ds_read_b128 v[194:197], v140 offset:5120
	ds_read_b128 v[198:201], v140 offset:6144
	ds_read_b128 v[202:205], v140 offset:7168
	s_add_u32 s12, s36, 0x40080
	s_addc_u32 s13, s37, 0
	s_mov_b32 s67, m0
	s_mov_b32 m0, s59
	s_nop 4
	global_load_lds_dwordx4 v1, s[12:13]
	s_mov_b32 m0, s67
	s_add_u32 s12, s36, 0x60080
	s_addc_u32 s13, s37, 0
	s_add_i32 s36, s27, 0xe000
	s_mov_b32 s37, m0
	s_mov_b32 m0, s36
	s_nop 4
	global_load_lds_dwordx4 v1, s[12:13]
	s_mov_b32 m0, s37
	s_waitcnt vmcnt(8)
	s_waitcnt lgkmcnt(0)
	s_barrier
	s_waitcnt lgkmcnt(7)
	v_mfma_f32_16x16x32_bf16 v[122:125], v[142:145], v[174:177], 0
	v_mfma_f32_16x16x32_bf16 v[114:117], v[150:153], v[174:177], 0
	s_waitcnt lgkmcnt(5)
	v_mfma_f32_16x16x32_bf16 v[106:109], v[142:145], v[182:185], 0
	v_mfma_f32_16x16x32_bf16 v[98:101], v[150:153], v[182:185], 0
	s_waitcnt lgkmcnt(3)
	v_mfma_f32_16x16x32_bf16 v[90:93], v[142:145], v[190:193], 0
	v_mfma_f32_16x16x32_bf16 v[82:85], v[150:153], v[190:193], 0
	s_waitcnt lgkmcnt(1)
	v_mfma_f32_16x16x32_bf16 v[74:77], v[142:145], v[198:201], 0
	v_mfma_f32_16x16x32_bf16 v[66:69], v[150:153], v[198:201], 0
	v_mfma_f32_16x16x32_bf16 v[122:125], v[146:149], v[178:181], v[122:125]
	v_mfma_f32_16x16x32_bf16 v[114:117], v[154:157], v[178:181], v[114:117]
	v_mfma_f32_16x16x32_bf16 v[106:109], v[146:149], v[186:189], v[106:109]
	v_mfma_f32_16x16x32_bf16 v[98:101], v[154:157], v[186:189], v[98:101]
	v_mfma_f32_16x16x32_bf16 v[90:93], v[146:149], v[194:197], v[90:93]
	v_mfma_f32_16x16x32_bf16 v[82:85], v[154:157], v[194:197], v[82:85]
	s_waitcnt lgkmcnt(0)
	v_mfma_f32_16x16x32_bf16 v[74:77], v[146:149], v[202:205], v[74:77]
	v_mfma_f32_16x16x32_bf16 v[66:69], v[154:157], v[202:205], v[66:69]
	v_mfma_f32_16x16x32_bf16 v[126:129], v[158:161], v[174:177], 0
	v_mfma_f32_16x16x32_bf16 v[118:121], v[166:169], v[174:177], 0
	v_mfma_f32_16x16x32_bf16 v[110:113], v[158:161], v[182:185], 0
	v_mfma_f32_16x16x32_bf16 v[102:105], v[166:169], v[182:185], 0
	v_mfma_f32_16x16x32_bf16 v[94:97], v[158:161], v[190:193], 0
	v_mfma_f32_16x16x32_bf16 v[86:89], v[166:169], v[190:193], 0
	v_mfma_f32_16x16x32_bf16 v[78:81], v[158:161], v[198:201], 0
	v_mfma_f32_16x16x32_bf16 v[70:73], v[166:169], v[198:201], 0
	v_mfma_f32_16x16x32_bf16 v[126:129], v[162:165], v[178:181], v[126:129]
	v_mfma_f32_16x16x32_bf16 v[118:121], v[170:173], v[178:181], v[118:121]
	v_mfma_f32_16x16x32_bf16 v[110:113], v[162:165], v[186:189], v[110:113]
	v_mfma_f32_16x16x32_bf16 v[102:105], v[170:173], v[186:189], v[102:105]
	v_mfma_f32_16x16x32_bf16 v[94:97], v[162:165], v[194:197], v[94:97]
	v_mfma_f32_16x16x32_bf16 v[86:89], v[170:173], v[194:197], v[86:89]
	v_mfma_f32_16x16x32_bf16 v[78:81], v[162:165], v[202:205], v[78:81]
	v_mfma_f32_16x16x32_bf16 v[70:73], v[170:173], v[202:205], v[70:73]
	s_barrier
	ds_read_b128 v[174:177], v140 offset:16384
	ds_read_b128 v[178:181], v140 offset:17408
	ds_read_b128 v[182:185], v140 offset:18432
	ds_read_b128 v[186:189], v140 offset:19456
	ds_read_b128 v[190:193], v140 offset:20480
	ds_read_b128 v[194:197], v140 offset:21504
	ds_read_b128 v[198:201], v140 offset:22528
	ds_read_b128 v[202:205], v140 offset:23552
	s_mov_b32 s12, m0
	s_mov_b32 m0, s46
	s_nop 4
	global_load_lds_dwordx4 v136, s[40:41]
	s_mov_b32 m0, s12
	s_add_u32 s12, s40, 0x20000
	s_addc_u32 s13, s41, 0
	s_mov_b32 s36, m0
	s_mov_b32 m0, s47
	s_nop 4
	global_load_lds_dwordx4 v136, s[12:13]
	s_mov_b32 m0, s36
	s_add_u32 s12, s40, 0x40000
	s_addc_u32 s13, s41, 0
	s_mov_b32 s36, m0
	s_mov_b32 m0, s48
	s_nop 4
	global_load_lds_dwordx4 v136, s[12:13]
	s_mov_b32 m0, s36
	s_add_u32 s12, s40, 0x60000
	s_addc_u32 s13, s41, 0
	s_mov_b32 s36, m0
	s_mov_b32 m0, s49
	s_nop 4
	global_load_lds_dwordx4 v136, s[12:13]
	s_mov_b32 m0, s36
	s_mov_b32 s12, m0
	s_mov_b32 m0, s27
	s_nop 4
	global_load_lds_dwordx4 v1, s[34:35]
	s_mov_b32 m0, s12
	s_add_u32 s12, s34, 0x20000
	s_addc_u32 s13, s35, 0
	s_mov_b32 s36, m0
	s_mov_b32 m0, s50
	s_nop 4
	global_load_lds_dwordx4 v1, s[12:13]
	s_mov_b32 m0, s36
	s_waitcnt vmcnt(8)
	s_waitcnt lgkmcnt(0)
	s_barrier
	s_waitcnt lgkmcnt(7)
	v_mfma_f32_16x16x32_bf16 v[58:61], v[142:145], v[174:177], 0
	v_mfma_f32_16x16x32_bf16 v[50:53], v[150:153], v[174:177], 0
	s_waitcnt lgkmcnt(5)
	v_mfma_f32_16x16x32_bf16 v[42:45], v[142:145], v[182:185], 0
	v_mfma_f32_16x16x32_bf16 v[34:37], v[150:153], v[182:185], 0
	s_waitcnt lgkmcnt(3)
	v_mfma_f32_16x16x32_bf16 v[26:29], v[142:145], v[190:193], 0
	v_mfma_f32_16x16x32_bf16 v[18:21], v[150:153], v[190:193], 0
	s_waitcnt lgkmcnt(1)
	v_mfma_f32_16x16x32_bf16 v[10:13], v[142:145], v[198:201], 0
	v_mfma_f32_16x16x32_bf16 v[6:9], v[150:153], v[198:201], 0
	v_mfma_f32_16x16x32_bf16 v[58:61], v[146:149], v[178:181], v[58:61]
	v_mfma_f32_16x16x32_bf16 v[50:53], v[154:157], v[178:181], v[50:53]
	v_mfma_f32_16x16x32_bf16 v[42:45], v[146:149], v[186:189], v[42:45]
	v_mfma_f32_16x16x32_bf16 v[34:37], v[154:157], v[186:189], v[34:37]
	v_mfma_f32_16x16x32_bf16 v[26:29], v[146:149], v[194:197], v[26:29]
	v_mfma_f32_16x16x32_bf16 v[18:21], v[154:157], v[194:197], v[18:21]
	s_waitcnt lgkmcnt(0)
	v_mfma_f32_16x16x32_bf16 v[10:13], v[146:149], v[202:205], v[10:13]
	v_mfma_f32_16x16x32_bf16 v[6:9], v[154:157], v[202:205], v[6:9]
	v_mfma_f32_16x16x32_bf16 v[62:65], v[158:161], v[174:177], 0
	v_mfma_f32_16x16x32_bf16 v[54:57], v[166:169], v[174:177], 0
	v_mfma_f32_16x16x32_bf16 v[46:49], v[158:161], v[182:185], 0
	v_mfma_f32_16x16x32_bf16 v[38:41], v[166:169], v[182:185], 0
	v_mfma_f32_16x16x32_bf16 v[30:33], v[158:161], v[190:193], 0
	v_mfma_f32_16x16x32_bf16 v[22:25], v[166:169], v[190:193], 0
	v_mfma_f32_16x16x32_bf16 v[14:17], v[158:161], v[198:201], 0
	v_mfma_f32_16x16x32_bf16 v[2:5], v[166:169], v[198:201], 0
	v_mfma_f32_16x16x32_bf16 v[62:65], v[162:165], v[178:181], v[62:65]
	v_mfma_f32_16x16x32_bf16 v[54:57], v[170:173], v[178:181], v[54:57]
	v_mfma_f32_16x16x32_bf16 v[46:49], v[162:165], v[186:189], v[46:49]
	v_mfma_f32_16x16x32_bf16 v[38:41], v[170:173], v[186:189], v[38:41]
	v_mfma_f32_16x16x32_bf16 v[30:33], v[162:165], v[194:197], v[30:33]
	v_mfma_f32_16x16x32_bf16 v[22:25], v[170:173], v[194:197], v[22:25]
	v_mfma_f32_16x16x32_bf16 v[14:17], v[162:165], v[202:205], v[14:17]
	v_mfma_f32_16x16x32_bf16 v[2:5], v[170:173], v[202:205], v[2:5]
	s_barrier
	v_add_u32_e32 v134, 0x18000, v139
	ds_read_b128 v[142:145], v134
	ds_read_b128 v[146:149], v134 offset:1024
	ds_read_b128 v[150:153], v134 offset:2048
	ds_read_b128 v[154:157], v134 offset:3072
	v_add_u32_e32 v134, 0x1c000, v139
	ds_read_b128 v[158:161], v134
	ds_read_b128 v[162:165], v134 offset:1024
	ds_read_b128 v[166:169], v134 offset:2048
	ds_read_b128 v[170:173], v134 offset:3072
	ds_read_b128 v[174:177], v140 offset:32768
	ds_read_b128 v[178:181], v140 offset:33792
	ds_read_b128 v[182:185], v140 offset:34816
	ds_read_b128 v[186:189], v140 offset:35840
	ds_read_b128 v[190:193], v140 offset:36864
	ds_read_b128 v[194:197], v140 offset:37888
	ds_read_b128 v[198:201], v140 offset:38912
	ds_read_b128 v[202:205], v140 offset:39936
	s_add_u32 s12, s34, 0x40000
	s_addc_u32 s13, s35, 0
	s_mov_b32 s36, m0
	s_mov_b32 m0, s51
	s_nop 4
	global_load_lds_dwordx4 v1, s[12:13]
	s_mov_b32 m0, s36
	s_add_u32 s12, s34, 0x60000
	s_addc_u32 s13, s35, 0
	s_mov_b32 s36, m0
	s_mov_b32 m0, s52
	s_nop 4
	global_load_lds_dwordx4 v1, s[12:13]
	s_mov_b32 m0, s36
	s_waitcnt vmcnt(8)
	s_waitcnt lgkmcnt(0)
	s_barrier
	s_waitcnt lgkmcnt(7)
	v_mfma_f32_16x16x32_bf16 v[122:125], v[142:145], v[174:177], v[122:125]
	v_mfma_f32_16x16x32_bf16 v[114:117], v[150:153], v[174:177], v[114:117]
	s_waitcnt lgkmcnt(5)
	v_mfma_f32_16x16x32_bf16 v[106:109], v[142:145], v[182:185], v[106:109]
	v_mfma_f32_16x16x32_bf16 v[98:101], v[150:153], v[182:185], v[98:101]
	s_waitcnt lgkmcnt(3)
	v_mfma_f32_16x16x32_bf16 v[90:93], v[142:145], v[190:193], v[90:93]
	v_mfma_f32_16x16x32_bf16 v[82:85], v[150:153], v[190:193], v[82:85]
	s_waitcnt lgkmcnt(1)
	v_mfma_f32_16x16x32_bf16 v[74:77], v[142:145], v[198:201], v[74:77]
	v_mfma_f32_16x16x32_bf16 v[66:69], v[150:153], v[198:201], v[66:69]
	v_mfma_f32_16x16x32_bf16 v[122:125], v[146:149], v[178:181], v[122:125]
	v_mfma_f32_16x16x32_bf16 v[114:117], v[154:157], v[178:181], v[114:117]
	v_mfma_f32_16x16x32_bf16 v[106:109], v[146:149], v[186:189], v[106:109]
	v_mfma_f32_16x16x32_bf16 v[98:101], v[154:157], v[186:189], v[98:101]
	v_mfma_f32_16x16x32_bf16 v[90:93], v[146:149], v[194:197], v[90:93]
	v_mfma_f32_16x16x32_bf16 v[82:85], v[154:157], v[194:197], v[82:85]
	s_waitcnt lgkmcnt(0)
	v_mfma_f32_16x16x32_bf16 v[74:77], v[146:149], v[202:205], v[74:77]
	v_mfma_f32_16x16x32_bf16 v[66:69], v[154:157], v[202:205], v[66:69]
	v_mfma_f32_16x16x32_bf16 v[126:129], v[158:161], v[174:177], v[126:129]
	v_mfma_f32_16x16x32_bf16 v[118:121], v[166:169], v[174:177], v[118:121]
	v_mfma_f32_16x16x32_bf16 v[110:113], v[158:161], v[182:185], v[110:113]
	v_mfma_f32_16x16x32_bf16 v[102:105], v[166:169], v[182:185], v[102:105]
	v_mfma_f32_16x16x32_bf16 v[94:97], v[158:161], v[190:193], v[94:97]
	v_mfma_f32_16x16x32_bf16 v[86:89], v[166:169], v[190:193], v[86:89]
	v_mfma_f32_16x16x32_bf16 v[78:81], v[158:161], v[198:201], v[78:81]
	v_mfma_f32_16x16x32_bf16 v[70:73], v[166:169], v[198:201], v[70:73]
	v_mfma_f32_16x16x32_bf16 v[126:129], v[162:165], v[178:181], v[126:129]
	v_mfma_f32_16x16x32_bf16 v[118:121], v[170:173], v[178:181], v[118:121]
	v_mfma_f32_16x16x32_bf16 v[110:113], v[162:165], v[186:189], v[110:113]
	v_mfma_f32_16x16x32_bf16 v[102:105], v[170:173], v[186:189], v[102:105]
	v_mfma_f32_16x16x32_bf16 v[94:97], v[162:165], v[194:197], v[94:97]
	v_mfma_f32_16x16x32_bf16 v[86:89], v[170:173], v[194:197], v[86:89]
	v_mfma_f32_16x16x32_bf16 v[78:81], v[162:165], v[202:205], v[78:81]
	v_mfma_f32_16x16x32_bf16 v[70:73], v[170:173], v[202:205], v[70:73]
	s_barrier
	s_add_u32 s12, s40, 0x80
	s_addc_u32 s13, s41, 0
	ds_read_b128 v[174:177], v140 offset:49152
	ds_read_b128 v[178:181], v140 offset:50176
	ds_read_b128 v[182:185], v140 offset:51200
	ds_read_b128 v[186:189], v140 offset:52224
	ds_read_b128 v[190:193], v140 offset:53248
	ds_read_b128 v[194:197], v140 offset:54272
	ds_read_b128 v[198:201], v140 offset:55296
	ds_read_b128 v[202:205], v140 offset:56320
	s_mov_b32 s36, m0
	s_mov_b32 m0, s53
	s_nop 4
	global_load_lds_dwordx4 v136, s[12:13]
	s_mov_b32 m0, s36
	s_add_u32 s12, s40, 0x20080
	s_addc_u32 s13, s41, 0
	s_mov_b32 s36, m0
	s_mov_b32 m0, s54
	s_nop 4
	global_load_lds_dwordx4 v136, s[12:13]
	s_mov_b32 m0, s36
	s_add_u32 s12, s40, 0x40080
	s_addc_u32 s13, s41, 0
	s_mov_b32 s36, m0
	s_mov_b32 m0, s57
	s_nop 4
	global_load_lds_dwordx4 v136, s[12:13]
	s_mov_b32 m0, s36
	s_add_u32 s12, s40, 0x60080
	s_addc_u32 s13, s41, 0
	s_mov_b32 s36, m0
	s_mov_b32 m0, s58
	s_nop 4
	global_load_lds_dwordx4 v136, s[12:13]
	s_mov_b32 m0, s36
	s_mov_b32 s12, m0
	s_mov_b32 m0, s55
	s_nop 4
	global_load_lds_dwordx4 v1, s[38:39]
	s_mov_b32 m0, s12
	s_add_u32 s12, s34, 0x20080
	s_addc_u32 s13, s35, 0
	s_mov_b32 s34, m0
	s_mov_b32 m0, s56
	s_nop 4
	global_load_lds_dwordx4 v1, s[12:13]
	s_mov_b32 m0, s34
	s_waitcnt vmcnt(8)
	s_waitcnt lgkmcnt(0)
	s_barrier
	s_waitcnt lgkmcnt(7)
	v_mfma_f32_16x16x32_bf16 v[58:61], v[142:145], v[174:177], v[58:61]
	v_mfma_f32_16x16x32_bf16 v[50:53], v[150:153], v[174:177], v[50:53]
	s_waitcnt lgkmcnt(5)
	v_mfma_f32_16x16x32_bf16 v[42:45], v[142:145], v[182:185], v[42:45]
	v_mfma_f32_16x16x32_bf16 v[34:37], v[150:153], v[182:185], v[34:37]
	s_waitcnt lgkmcnt(3)
	v_mfma_f32_16x16x32_bf16 v[26:29], v[142:145], v[190:193], v[26:29]
	v_mfma_f32_16x16x32_bf16 v[18:21], v[150:153], v[190:193], v[18:21]
	s_waitcnt lgkmcnt(1)
	v_mfma_f32_16x16x32_bf16 v[10:13], v[142:145], v[198:201], v[10:13]
	v_mfma_f32_16x16x32_bf16 v[6:9], v[150:153], v[198:201], v[6:9]
	v_mfma_f32_16x16x32_bf16 v[58:61], v[146:149], v[178:181], v[58:61]
	v_mfma_f32_16x16x32_bf16 v[50:53], v[154:157], v[178:181], v[50:53]
	v_mfma_f32_16x16x32_bf16 v[42:45], v[146:149], v[186:189], v[42:45]
	v_mfma_f32_16x16x32_bf16 v[34:37], v[154:157], v[186:189], v[34:37]
	v_mfma_f32_16x16x32_bf16 v[26:29], v[146:149], v[194:197], v[26:29]
	v_mfma_f32_16x16x32_bf16 v[18:21], v[154:157], v[194:197], v[18:21]
	s_waitcnt lgkmcnt(0)
	v_mfma_f32_16x16x32_bf16 v[10:13], v[146:149], v[202:205], v[10:13]
	v_mfma_f32_16x16x32_bf16 v[6:9], v[154:157], v[202:205], v[6:9]
	v_mfma_f32_16x16x32_bf16 v[62:65], v[158:161], v[174:177], v[62:65]
	v_mfma_f32_16x16x32_bf16 v[54:57], v[166:169], v[174:177], v[54:57]
	v_mfma_f32_16x16x32_bf16 v[46:49], v[158:161], v[182:185], v[46:49]
	v_mfma_f32_16x16x32_bf16 v[38:41], v[166:169], v[182:185], v[38:41]
	v_mfma_f32_16x16x32_bf16 v[30:33], v[158:161], v[190:193], v[30:33]
	v_mfma_f32_16x16x32_bf16 v[22:25], v[166:169], v[190:193], v[22:25]
	v_mfma_f32_16x16x32_bf16 v[14:17], v[158:161], v[198:201], v[14:17]
	v_mfma_f32_16x16x32_bf16 v[2:5], v[166:169], v[198:201], v[2:5]
	v_mfma_f32_16x16x32_bf16 v[62:65], v[162:165], v[178:181], v[62:65]
	v_mfma_f32_16x16x32_bf16 v[54:57], v[170:173], v[178:181], v[54:57]
	v_mfma_f32_16x16x32_bf16 v[46:49], v[162:165], v[186:189], v[46:49]
	v_mfma_f32_16x16x32_bf16 v[38:41], v[170:173], v[186:189], v[38:41]
	v_mfma_f32_16x16x32_bf16 v[30:33], v[162:165], v[194:197], v[30:33]
	v_mfma_f32_16x16x32_bf16 v[22:25], v[170:173], v[194:197], v[22:25]
	v_mfma_f32_16x16x32_bf16 v[14:17], v[162:165], v[202:205], v[14:17]
	v_mfma_f32_16x16x32_bf16 v[2:5], v[170:173], v[202:205], v[2:5]
	s_barrier
	s_add_i32 s66, s66, 2
	s_add_u32 s64, s64, 0x100
	s_addc_u32 s65, s65, 0
	s_cmp_gt_u32 s66, 13
	s_mov_b64 s[36:37], s[0:1]

.LBB0_1427:
	v_exp_f32_e64 v144, -v122
	v_exp_f32_e64 v145, -v123
	v_pk_mul_f32 v[128:129], v[124:125], v[128:129]
	v_exp_f32_e64 v124, -v124
	v_exp_f32_e64 v125, -v125
	v_pk_add_f32 v[144:145], v[144:145], 1.0 op_sel_hi:[1,0]
	v_pk_mul_f32 v[122:123], v[122:123], v[126:127]
	v_rcp_f32_e32 v126, v144
	v_rcp_f32_e32 v127, v145
	v_pk_add_f32 v[124:125], v[124:125], 1.0 op_sel_hi:[1,0]
	v_pk_mul_f32 v[112:113], v[108:109], v[112:113]
	v_rcp_f32_e32 v124, v124
	v_rcp_f32_e32 v125, v125
	v_pk_mul_f32 v[122:123], v[126:127], v[122:123]
	v_exp_f32_e64 v126, -v114
	v_exp_f32_e64 v127, -v115
	v_pk_mul_f32 v[124:125], v[124:125], v[128:129]
	v_exp_f32_e64 v128, -v116
	v_exp_f32_e64 v129, -v117
	v_pk_add_f32 v[126:127], v[126:127], 1.0 op_sel_hi:[1,0]
	v_pk_mul_f32 v[114:115], v[114:115], v[118:119]
	v_rcp_f32_e32 v126, v126
	v_rcp_f32_e32 v127, v127
	v_pk_add_f32 v[128:129], v[128:129], 1.0 op_sel_hi:[1,0]
	v_pk_mul_f32 v[116:117], v[116:117], v[120:121]
	v_rcp_f32_e32 v128, v128
	v_rcp_f32_e32 v129, v129
	v_pk_mul_f32 v[114:115], v[126:127], v[114:115]
	v_med3_f32 v119, v122, s61, v141
	v_med3_f32 v120, v123, s61, v141
	v_mov_b32_e32 v118, 0
	v_pk_mul_f32 v[116:117], v[128:129], v[116:117]
	v_med3_f32 v114, v114, s61, v141
	v_med3_f32 v115, v115, s61, v141
	v_cvt_pk_fp8_f32 v118, v119, v120
	v_mov_b32_e32 v119, 0
	v_cvt_pk_fp8_f32 v119, v114, v115
	v_med3_f32 v114, v116, s61, v141
	v_med3_f32 v115, v117, s61, v141
	v_exp_f32_e64 v116, -v106
	v_exp_f32_e64 v117, -v107
	v_exp_f32_e64 v108, -v108
	v_exp_f32_e64 v109, -v109
	v_pk_mul_f32 v[106:107], v[106:107], v[110:111]
	v_pk_add_f32 v[116:117], v[116:117], 1.0 op_sel_hi:[1,0]
	v_lshl_add_u32 v142, s26, 8, v137
	v_rcp_f32_e32 v110, v116
	v_rcp_f32_e32 v111, v117
	v_pk_add_f32 v[108:109], v[108:109], 1.0 op_sel_hi:[1,0]
	v_lshl_or_b32 v134, s63, 7, v138
	v_rcp_f32_e32 v108, v108
	v_rcp_f32_e32 v109, v109
	v_pk_mul_f32 v[106:107], v[110:111], v[106:107]
	v_exp_f32_e64 v110, -v98
	v_exp_f32_e64 v111, -v99
	v_pk_mul_f32 v[108:109], v[108:109], v[112:113]
	v_exp_f32_e64 v112, -v100
	v_exp_f32_e64 v113, -v101
	v_pk_add_f32 v[110:111], v[110:111], 1.0 op_sel_hi:[1,0]
	v_pk_mul_f32 v[98:99], v[98:99], v[102:103]
	v_rcp_f32_e32 v110, v110
	v_rcp_f32_e32 v111, v111
	v_pk_add_f32 v[112:113], v[112:113], 1.0 op_sel_hi:[1,0]
	v_med3_f32 v102, v106, s61, v141
	v_rcp_f32_e32 v112, v112
	v_rcp_f32_e32 v113, v113
	v_pk_mul_f32 v[98:99], v[110:111], v[98:99]
	v_med3_f32 v103, v107, s61, v141
	v_med3_f32 v106, v98, s61, v141
	v_med3_f32 v107, v99, s61, v141
	v_mov_b32_e32 v98, 0
	v_mov_b32_e32 v99, 0
	v_cvt_pk_fp8_f32 v98, v102, v103
	v_cvt_pk_fp8_f32 v99, v106, v107
	v_pk_mul_f32 v[100:101], v[100:101], v[104:105]
	v_med3_f32 v104, v108, s61, v141
	v_pk_mul_f32 v[100:101], v[112:113], v[100:101]
	v_med3_f32 v105, v109, s61, v141
	v_med3_f32 v100, v100, s61, v141
	v_med3_f32 v101, v101, s61, v141
	v_cvt_pk_fp8_f32 v98, v104, v105 op_sel:[0,0,1]
	v_cvt_pk_fp8_f32 v99, v100, v101 op_sel:[0,0,1]
	v_exp_f32_e64 v100, -v90
	v_exp_f32_e64 v101, -v91
	v_cvt_pk_fp8_f32 v119, v114, v115 op_sel:[0,0,1]
	v_mov_b64_e32 v[114:115], s[18:19]
	v_or_b32_e32 v102, 16, v142
	v_ashrrev_i32_e32 v135, 31, v134
	v_mad_i64_i32 v[102:103], s[0:1], v102, s62, v[114:115]
	v_lshl_add_u64 v[102:103], v[102:103], 0, v[134:135]
	global_store_dwordx2 v[102:103], v[98:99], off
	v_pk_add_f32 v[98:99], v[100:101], 1.0 op_sel_hi:[1,0]
	v_pk_mul_f32 v[96:97], v[92:93], v[96:97]
	v_exp_f32_e64 v92, -v92
	v_exp_f32_e64 v93, -v93
	v_pk_mul_f32 v[90:91], v[90:91], v[94:95]
	v_rcp_f32_e32 v94, v98
	v_rcp_f32_e32 v95, v99
	v_pk_add_f32 v[92:93], v[92:93], 1.0 op_sel_hi:[1,0]
	v_pk_mul_f32 v[80:81], v[76:77], v[80:81]
	v_rcp_f32_e32 v92, v92
	v_rcp_f32_e32 v93, v93
	v_pk_mul_f32 v[90:91], v[94:95], v[90:91]
	v_exp_f32_e64 v94, -v82
	v_exp_f32_e64 v95, -v83
	v_pk_mul_f32 v[92:93], v[92:93], v[96:97]
	v_exp_f32_e64 v96, -v84
	v_exp_f32_e64 v97, -v85
	v_pk_add_f32 v[94:95], v[94:95], 1.0 op_sel_hi:[1,0]
	v_pk_mul_f32 v[82:83], v[82:83], v[86:87]
	v_rcp_f32_e32 v94, v94
	v_rcp_f32_e32 v95, v95
	v_pk_add_f32 v[96:97], v[96:97], 1.0 op_sel_hi:[1,0]
	v_med3_f32 v86, v90, s61, v141
	v_rcp_f32_e32 v96, v96
	v_rcp_f32_e32 v97, v97
	v_pk_mul_f32 v[82:83], v[94:95], v[82:83]
	v_med3_f32 v87, v91, s61, v141
	v_med3_f32 v90, v82, s61, v141
	v_med3_f32 v91, v83, s61, v141
	v_mov_b32_e32 v82, 0
	v_mov_b32_e32 v83, 0
	v_cvt_pk_fp8_f32 v82, v86, v87
	v_cvt_pk_fp8_f32 v83, v90, v91
	v_pk_mul_f32 v[84:85], v[84:85], v[88:89]
	v_med3_f32 v88, v92, s61, v141
	v_pk_mul_f32 v[84:85], v[96:97], v[84:85]
	v_med3_f32 v89, v93, s61, v141
	v_med3_f32 v84, v84, s61, v141
	v_med3_f32 v85, v85, s61, v141
	v_cvt_pk_fp8_f32 v82, v88, v89 op_sel:[0,0,1]
	v_cvt_pk_fp8_f32 v83, v84, v85 op_sel:[0,0,1]
	v_exp_f32_e64 v84, -v74
	v_exp_f32_e64 v85, -v75
	v_or_b32_e32 v86, 32, v142
	v_mad_i64_i32 v[86:87], s[0:1], v86, s62, v[114:115]
	v_lshl_add_u64 v[86:87], v[86:87], 0, v[134:135]
	global_store_dwordx2 v[86:87], v[82:83], off
	v_pk_add_f32 v[82:83], v[84:85], 1.0 op_sel_hi:[1,0]
	v_exp_f32_e64 v76, -v76
	v_exp_f32_e64 v77, -v77
	v_pk_mul_f32 v[74:75], v[74:75], v[78:79]
	v_rcp_f32_e32 v78, v82
	v_rcp_f32_e32 v79, v83
	v_pk_add_f32 v[76:77], v[76:77], 1.0 op_sel_hi:[1,0]
	v_pk_mul_f32 v[64:65], v[60:61], v[64:65]
	v_rcp_f32_e32 v76, v76
	v_rcp_f32_e32 v77, v77
	v_pk_mul_f32 v[74:75], v[78:79], v[74:75]
	v_exp_f32_e64 v78, -v66
	v_exp_f32_e64 v79, -v67
	v_pk_mul_f32 v[76:77], v[76:77], v[80:81]
	v_exp_f32_e64 v80, -v68
	v_exp_f32_e64 v81, -v69
	v_pk_add_f32 v[78:79], v[78:79], 1.0 op_sel_hi:[1,0]
	v_pk_mul_f32 v[66:67], v[66:67], v[70:71]
	v_rcp_f32_e32 v78, v78
	v_rcp_f32_e32 v79, v79
	v_pk_add_f32 v[80:81], v[80:81], 1.0 op_sel_hi:[1,0]
	v_med3_f32 v70, v74, s61, v141
	v_rcp_f32_e32 v80, v80
	v_rcp_f32_e32 v81, v81
	v_pk_mul_f32 v[66:67], v[78:79], v[66:67]
	v_med3_f32 v71, v75, s61, v141
	v_med3_f32 v74, v66, s61, v141
	v_med3_f32 v75, v67, s61, v141
	v_mov_b32_e32 v66, 0
	v_mov_b32_e32 v67, 0
	v_cvt_pk_fp8_f32 v66, v70, v71
	v_cvt_pk_fp8_f32 v67, v74, v75
	v_pk_mul_f32 v[68:69], v[68:69], v[72:73]
	v_med3_f32 v72, v76, s61, v141
	v_pk_mul_f32 v[68:69], v[80:81], v[68:69]
	v_med3_f32 v73, v77, s61, v141
	v_med3_f32 v68, v68, s61, v141
	v_med3_f32 v69, v69, s61, v141
	v_cvt_pk_fp8_f32 v66, v72, v73 op_sel:[0,0,1]
	v_cvt_pk_fp8_f32 v67, v68, v69 op_sel:[0,0,1]
	v_exp_f32_e64 v70, -v58
	v_exp_f32_e64 v71, -v59
	v_or_b32_e32 v68, 48, v142
	v_mad_i64_i32 v[68:69], s[0:1], v68, s62, v[114:115]
	v_lshl_add_u64 v[68:69], v[68:69], 0, v[134:135]
	global_store_dwordx2 v[68:69], v[66:67], off
	v_pk_add_f32 v[66:67], v[70:71], 1.0 op_sel_hi:[1,0]
	v_exp_f32_e64 v60, -v60
	v_exp_f32_e64 v61, -v61
	v_pk_mul_f32 v[58:59], v[58:59], v[62:63]
	v_rcp_f32_e32 v62, v66
	v_rcp_f32_e32 v63, v67
	v_pk_add_f32 v[60:61], v[60:61], 1.0 op_sel_hi:[1,0]
	v_add_u32_e32 v68, 0x80, v142
	v_rcp_f32_e32 v60, v60
	v_rcp_f32_e32 v61, v61
	v_pk_mul_f32 v[58:59], v[62:63], v[58:59]
	v_exp_f32_e64 v62, -v50
	v_exp_f32_e64 v63, -v51
	v_pk_mul_f32 v[60:61], v[60:61], v[64:65]
	v_exp_f32_e64 v64, -v52
	v_exp_f32_e64 v65, -v53
	v_pk_add_f32 v[62:63], v[62:63], 1.0 op_sel_hi:[1,0]
	v_pk_mul_f32 v[50:51], v[50:51], v[54:55]
	v_rcp_f32_e32 v62, v62
	v_rcp_f32_e32 v63, v63
	v_pk_add_f32 v[64:65], v[64:65], 1.0 op_sel_hi:[1,0]
	v_med3_f32 v54, v58, s61, v141
	v_rcp_f32_e32 v64, v64
	v_rcp_f32_e32 v65, v65
	v_pk_mul_f32 v[50:51], v[62:63], v[50:51]
	v_med3_f32 v55, v59, s61, v141
	v_med3_f32 v58, v50, s61, v141
	v_med3_f32 v59, v51, s61, v141
	v_mov_b32_e32 v50, 0
	v_mov_b32_e32 v51, 0
	v_cvt_pk_fp8_f32 v50, v54, v55
	v_cvt_pk_fp8_f32 v51, v58, v59
	v_pk_mul_f32 v[52:53], v[52:53], v[56:57]
	v_med3_f32 v56, v60, s61, v141
	v_pk_mul_f32 v[52:53], v[64:65], v[52:53]
	v_med3_f32 v57, v61, s61, v141
	v_med3_f32 v52, v52, s61, v141
	v_med3_f32 v53, v53, s61, v141
	v_cvt_pk_fp8_f32 v50, v56, v57 op_sel:[0,0,1]
	v_cvt_pk_fp8_f32 v51, v52, v53 op_sel:[0,0,1]
	v_exp_f32_e64 v52, -v42
	v_exp_f32_e64 v53, -v43
	v_mad_i64_i32 v[54:55], s[0:1], v68, s62, v[114:115]
	v_lshl_add_u64 v[54:55], v[54:55], 0, v[134:135]
	global_store_dwordx2 v[54:55], v[50:51], off
	v_pk_add_f32 v[50:51], v[52:53], 1.0 op_sel_hi:[1,0]
	v_pk_mul_f32 v[48:49], v[44:45], v[48:49]
	v_exp_f32_e64 v44, -v44
	v_exp_f32_e64 v45, -v45
	v_pk_mul_f32 v[42:43], v[42:43], v[46:47]
	v_rcp_f32_e32 v46, v50
	v_rcp_f32_e32 v47, v51
	v_pk_add_f32 v[44:45], v[44:45], 1.0 op_sel_hi:[1,0]
	v_pk_mul_f32 v[32:33], v[28:29], v[32:33]
	v_rcp_f32_e32 v44, v44
	v_rcp_f32_e32 v45, v45
	v_pk_mul_f32 v[42:43], v[46:47], v[42:43]
	v_exp_f32_e64 v46, -v34
	v_exp_f32_e64 v47, -v35
	v_pk_mul_f32 v[44:45], v[44:45], v[48:49]
	v_exp_f32_e64 v48, -v36
	v_exp_f32_e64 v49, -v37
	v_pk_add_f32 v[46:47], v[46:47], 1.0 op_sel_hi:[1,0]
	v_pk_mul_f32 v[34:35], v[34:35], v[38:39]
	v_rcp_f32_e32 v46, v46
	v_rcp_f32_e32 v47, v47
	v_pk_add_f32 v[48:49], v[48:49], 1.0 op_sel_hi:[1,0]
	v_med3_f32 v38, v42, s61, v141
	v_rcp_f32_e32 v48, v48
	v_rcp_f32_e32 v49, v49
	v_pk_mul_f32 v[34:35], v[46:47], v[34:35]
	v_med3_f32 v39, v43, s61, v141
	v_med3_f32 v42, v34, s61, v141
	v_med3_f32 v43, v35, s61, v141
	v_mov_b32_e32 v34, 0
	v_mov_b32_e32 v35, 0
	v_cvt_pk_fp8_f32 v34, v38, v39
	v_cvt_pk_fp8_f32 v35, v42, v43
	v_pk_mul_f32 v[36:37], v[36:37], v[40:41]
	v_med3_f32 v40, v44, s61, v141
	v_pk_mul_f32 v[36:37], v[48:49], v[36:37]
	v_med3_f32 v41, v45, s61, v141
	v_med3_f32 v36, v36, s61, v141
	v_med3_f32 v37, v37, s61, v141
	v_cvt_pk_fp8_f32 v34, v40, v41 op_sel:[0,0,1]
	v_cvt_pk_fp8_f32 v35, v36, v37 op_sel:[0,0,1]
	v_exp_f32_e64 v36, -v26
	v_exp_f32_e64 v37, -v27
	v_add_u32_e32 v38, 0x90, v142
	v_mad_i64_i32 v[38:39], s[0:1], v38, s62, v[114:115]
	v_lshl_add_u64 v[38:39], v[38:39], 0, v[134:135]
	global_store_dwordx2 v[38:39], v[34:35], off
	v_pk_add_f32 v[34:35], v[36:37], 1.0 op_sel_hi:[1,0]
	v_exp_f32_e64 v28, -v28
	v_exp_f32_e64 v29, -v29
	v_pk_mul_f32 v[26:27], v[26:27], v[30:31]
	v_rcp_f32_e32 v30, v34
	v_rcp_f32_e32 v31, v35
	v_pk_add_f32 v[28:29], v[28:29], 1.0 op_sel_hi:[1,0]
	v_pk_mul_f32 v[16:17], v[12:13], v[16:17]
	v_rcp_f32_e32 v28, v28
	v_rcp_f32_e32 v29, v29
	v_pk_mul_f32 v[26:27], v[30:31], v[26:27]
	v_exp_f32_e64 v30, -v18
	v_exp_f32_e64 v31, -v19
	v_pk_mul_f32 v[28:29], v[28:29], v[32:33]
	v_exp_f32_e64 v32, -v20
	v_exp_f32_e64 v33, -v21
	v_pk_add_f32 v[30:31], v[30:31], 1.0 op_sel_hi:[1,0]
	v_pk_mul_f32 v[18:19], v[18:19], v[22:23]
	v_rcp_f32_e32 v30, v30
	v_rcp_f32_e32 v31, v31
	v_pk_add_f32 v[32:33], v[32:33], 1.0 op_sel_hi:[1,0]
	v_med3_f32 v22, v26, s61, v141
	v_rcp_f32_e32 v32, v32
	v_rcp_f32_e32 v33, v33
	v_pk_mul_f32 v[18:19], v[30:31], v[18:19]
	v_med3_f32 v23, v27, s61, v141
	v_med3_f32 v26, v18, s61, v141
	v_med3_f32 v27, v19, s61, v141
	v_mov_b32_e32 v18, 0
	v_mov_b32_e32 v19, 0
	v_cvt_pk_fp8_f32 v18, v22, v23
	v_cvt_pk_fp8_f32 v19, v26, v27
	v_pk_mul_f32 v[20:21], v[20:21], v[24:25]
	v_med3_f32 v24, v28, s61, v141
	v_pk_mul_f32 v[20:21], v[32:33], v[20:21]
	v_med3_f32 v25, v29, s61, v141
	v_med3_f32 v20, v20, s61, v141
	v_med3_f32 v21, v21, s61, v141
	v_cvt_pk_fp8_f32 v18, v24, v25 op_sel:[0,0,1]
	v_cvt_pk_fp8_f32 v19, v20, v21 op_sel:[0,0,1]
	v_exp_f32_e64 v20, -v10
	v_exp_f32_e64 v21, -v11
	v_add_u32_e32 v22, 0xa0, v142
	v_mad_i64_i32 v[22:23], s[0:1], v22, s62, v[114:115]
	v_lshl_add_u64 v[22:23], v[22:23], 0, v[134:135]
	global_store_dwordx2 v[22:23], v[18:19], off
	v_pk_add_f32 v[18:19], v[20:21], 1.0 op_sel_hi:[1,0]
	v_exp_f32_e64 v12, -v12
	v_exp_f32_e64 v13, -v13
	v_pk_mul_f32 v[10:11], v[10:11], v[14:15]
	v_rcp_f32_e32 v14, v18
	v_rcp_f32_e32 v15, v19
	v_pk_add_f32 v[12:13], v[12:13], 1.0 op_sel_hi:[1,0]
	v_pk_mul_f32 v[2:3], v[6:7], v[2:3]
	v_rcp_f32_e32 v12, v12
	v_rcp_f32_e32 v13, v13
	v_pk_mul_f32 v[10:11], v[14:15], v[10:11]
	v_exp_f32_e64 v14, -v6
	v_exp_f32_e64 v15, -v7
	v_pk_mul_f32 v[12:13], v[12:13], v[16:17]
	v_exp_f32_e64 v16, -v8
	v_exp_f32_e64 v17, -v9
	v_pk_add_f32 v[14:15], v[14:15], 1.0 op_sel_hi:[1,0]
	v_med3_f32 v6, v10, s61, v141
	v_rcp_f32_e32 v14, v14
	v_rcp_f32_e32 v15, v15
	v_pk_add_f32 v[16:17], v[16:17], 1.0 op_sel_hi:[1,0]
	v_med3_f32 v7, v11, s61, v141
	v_rcp_f32_e32 v16, v16
	v_rcp_f32_e32 v17, v17
	v_pk_mul_f32 v[2:3], v[14:15], v[2:3]
	v_pk_mul_f32 v[4:5], v[8:9], v[4:5]
	v_med3_f32 v10, v2, s61, v141
	v_med3_f32 v11, v3, s61, v141
	v_mov_b32_e32 v2, 0
	v_mov_b32_e32 v3, 0
	v_cvt_pk_fp8_f32 v2, v6, v7
	v_cvt_pk_fp8_f32 v3, v10, v11
	v_pk_mul_f32 v[4:5], v[16:17], v[4:5]
	v_med3_f32 v121, v124, s61, v141
	v_med3_f32 v122, v125, s61, v141
	v_med3_f32 v8, v12, s61, v141
	v_med3_f32 v9, v13, s61, v141
	v_med3_f32 v4, v4, s61, v141
	v_med3_f32 v5, v5, s61, v141
	v_cvt_pk_fp8_f32 v118, v121, v122 op_sel:[0,0,1]
	v_cvt_pk_fp8_f32 v2, v8, v9 op_sel:[0,0,1]
	v_cvt_pk_fp8_f32 v3, v4, v5 op_sel:[0,0,1]
	v_add_u32_e32 v4, 0xb0, v142
	v_mad_i64_i32 v[120:121], s[0:1], v142, s62, v[114:115]
	v_mad_i64_i32 v[4:5], s[0:1], v4, s62, v[114:115]
	v_lshl_add_u64 v[120:121], v[120:121], 0, v[134:135]
	v_lshl_add_u64 v[4:5], v[4:5], 0, v[134:135]
	s_andn2_b64 vcc, exec, s[2:3]
	s_mov_b64 s[0:1], -1
	global_store_dwordx2 v[120:121], v[118:119], off
	global_store_dwordx2 v[4:5], v[2:3], off
	s_cbranch_vccnz .LBB0_1420
	s_andn2_b64 vcc, exec, s[6:7]
	v_mov_b64 v[4:5], 0
	s_cbranch_vccnz .LBB0_1419
	s_barrier
	s_branch .LBB0_1419

.LBB0_1492:
	v_and_b32_e32 v3, 48, v2
	v_lshlrev_b32_e32 v4, 6, v2
	v_lshlrev_b32_e32 v2, 2, v2
	s_and_b32 s65, s63, 3
	s_lshl_b32 s36, s64, 13
	v_and_or_b32 v3, v4, s45, v3
	v_and_b32_e32 v2, 32, v2
	s_lshl_b32 s60, s64, 6
	v_bitop3_b32 v4, v3, s36, v2 bitop3:0xde
	s_lshl_b32 s36, s65, 12
	v_bitop3_b32 v2, v3, s36, v2 bitop3:0xde
	s_add_u32 s36, s2, 0x80
	s_addc_u32 s37, s3, 0
	s_add_i32 s78, s66, 0x18000
	s_waitcnt vmcnt(2)
	s_barrier
	s_mov_b32 s38, m0
	s_mov_b32 m0, s78
	s_nop 4
	global_load_lds_dwordx4 v131, s[36:37]
	s_mov_b32 m0, s38
	s_add_u32 s36, s2, 0x2c080
	s_addc_u32 s37, s3, 0
	s_add_i32 s79, s66, 0x1a000
	s_mov_b32 s38, m0
	s_mov_b32 m0, s79
	s_nop 4
	global_load_lds_dwordx4 v131, s[36:37]
	s_mov_b32 m0, s38
	s_add_u32 s36, s6, 0x80
	s_addc_u32 s37, s7, 0
	s_add_i32 s80, s66, 0x8000
	s_mov_b32 s38, m0
	s_mov_b32 m0, s80
	s_nop 4
	global_load_lds_dwordx4 v130, s[36:37]
	s_mov_b32 m0, s38
	s_add_u32 s36, s6, 0x2c080
	s_addc_u32 s37, s7, 0
	s_add_i32 s81, s66, 0xa000
	s_mov_b32 s38, m0
	s_mov_b32 m0, s81
	s_nop 4
	global_load_lds_dwordx4 v130, s[36:37]
	s_mov_b32 m0, s38
	s_add_u32 s36, s2, 0x58080
	s_addc_u32 s37, s3, 0
	s_add_i32 s82, s66, 0x1c000
	s_mov_b32 s38, m0
	s_mov_b32 m0, s82
	s_nop 4
	global_load_lds_dwordx4 v131, s[36:37]
	s_mov_b32 m0, s38
	s_add_u32 s36, s2, 0x84080
	s_addc_u32 s37, s3, 0
	s_add_i32 s83, s66, 0x1e000
	s_mov_b32 s38, m0
	s_mov_b32 m0, s83
	s_nop 4
	global_load_lds_dwordx4 v131, s[36:37]
	s_mov_b32 m0, s38
	s_waitcnt vmcnt(6)
	s_add_i32 s84, s66, 0xc000
	s_add_u32 s85, s58, s35
	v_mov_b32_e32 v34, 0
	v_add_u32_e32 v2, 0, v2
	s_addc_u32 s86, s59, s34
	s_mov_b32 s87, -2
	v_add_u32_e32 v132, 0x10000, v2
	v_add_u32_e32 v133, 0, v4
	s_waitcnt vmcnt(32)
	v_add_u32_e32 v134, 0x14000, v2
	v_add_u32_e32 v135, 0x18000, v2
	v_add_u32_e32 v136, 0x1c000, v2
	s_mov_b64 s[36:37], s[6:7]
	v_mov_b32_e32 v170, v34
	v_mov_b32_e32 v171, v34
	v_mov_b32_e32 v172, v34
	v_mov_b32_e32 v173, v34
	s_barrier
	ds_read_b128 v[138:141], v132
	ds_read_b128 v[142:145], v132 offset:1024
	ds_read_b128 v[146:149], v132 offset:2048
	ds_read_b128 v[150:153], v132 offset:3072
	ds_read_b128 v[154:157], v134
	ds_read_b128 v[158:161], v134 offset:1024
	ds_read_b128 v[162:165], v134 offset:2048
	ds_read_b128 v[166:169], v134 offset:3072
	s_add_u32 s34, s36, 0x100
	s_addc_u32 s35, s37, 0
	s_cmp_eq_u32 s87, 18
	s_cselect_b32 s40, s6, s34
	s_cselect_b32 s41, s7, s35
	s_cselect_b32 s38, s2, s85
	s_cselect_b32 s39, s3, s86
	s_add_u32 s42, s40, 0x80
	s_addc_u32 s43, s41, 0
	s_add_u32 s88, s36, 0x58080
	s_addc_u32 s89, s37, 0
	s_mov_b32 m0, s84
	s_nop 4
	global_load_lds_dwordx4 v130, s[88:89]
	s_add_u32 s36, s36, 0x84080
	s_addc_u32 s37, s37, 0
	s_add_i32 s88, s66, 0xe000
	s_mov_b32 m0, s88
	s_nop 4
	global_load_lds_dwordx4 v130, s[36:37]
	ds_read_b128 v[176:179], v133
	ds_read_b128 v[180:183], v133 offset:1024
	ds_read_b128 v[186:189], v133 offset:2048
	ds_read_b128 v[190:193], v133 offset:3072
	ds_read_b128 v[194:197], v133 offset:4096
	ds_read_b128 v[198:201], v133 offset:5120
	ds_read_b128 v[202:205], v133 offset:6144
	ds_read_b128 v[206:209], v133 offset:7168
	s_waitcnt vmcnt(8)
	s_waitcnt lgkmcnt(0)
	s_barrier
	v_mfma_f32_16x16x128_f8f6f4 v[126:129], v[138:145], v[176:183], 0
	v_mfma_f32_16x16x128_f8f6f4 v[118:121], v[138:145], v[186:193], 0
	v_mfma_f32_16x16x128_f8f6f4 v[102:105], v[138:145], v[194:201], 0
	v_mfma_f32_16x16x128_f8f6f4 v[86:89], v[138:145], v[202:209], 0
	v_mfma_f32_16x16x128_f8f6f4 v[122:125], v[146:153], v[176:183], 0
	v_mfma_f32_16x16x128_f8f6f4 v[114:117], v[146:153], v[186:193], 0
	v_mfma_f32_16x16x128_f8f6f4 v[98:101], v[146:153], v[194:201], 0
	v_mfma_f32_16x16x128_f8f6f4 v[82:85], v[146:153], v[202:209], 0
	v_mfma_f32_16x16x128_f8f6f4 v[110:113], v[154:161], v[176:183], 0
	v_mfma_f32_16x16x128_f8f6f4 v[94:97], v[154:161], v[186:193], 0
	v_mfma_f32_16x16x128_f8f6f4 v[78:81], v[154:161], v[194:201], 0
	v_mfma_f32_16x16x128_f8f6f4 v[62:65], v[154:161], v[202:209], 0
	v_mfma_f32_16x16x128_f8f6f4 v[106:109], v[162:169], v[176:183], 0
	v_mfma_f32_16x16x128_f8f6f4 v[90:93], v[162:169], v[186:193], 0
	v_mfma_f32_16x16x128_f8f6f4 v[74:77], v[162:169], v[194:201], 0
	v_mfma_f32_16x16x128_f8f6f4 v[42:45], v[162:169], v[202:209], 0
	s_barrier
	ds_read_b128 v[176:179], v133 offset:16384
	ds_read_b128 v[180:183], v133 offset:17408
	ds_read_b128 v[186:189], v133 offset:18432
	ds_read_b128 v[190:193], v133 offset:19456
	ds_read_b128 v[194:197], v133 offset:20480
	ds_read_b128 v[198:201], v133 offset:21504
	ds_read_b128 v[202:205], v133 offset:22528
	ds_read_b128 v[206:209], v133 offset:23552
	s_nop 4
	s_mov_b32 m0, s67
	s_nop 4
	global_load_lds_dwordx4 v131, s[38:39]
	s_add_u32 s36, s38, 0x2c000
	s_addc_u32 s37, s39, 0
	s_mov_b32 m0, s72
	s_nop 4
	global_load_lds_dwordx4 v131, s[36:37]
	s_add_u32 s36, s38, 0x58000
	s_addc_u32 s37, s39, 0
	s_mov_b32 m0, s74
	s_nop 4
	global_load_lds_dwordx4 v131, s[36:37]
	s_add_u32 s36, s38, 0x84000
	s_addc_u32 s37, s39, 0
	s_mov_b32 m0, s75
	s_nop 4
	global_load_lds_dwordx4 v131, s[36:37]
	s_nop 2
	s_mov_b32 m0, s66
	s_nop 4
	global_load_lds_dwordx4 v130, s[40:41]
	s_add_u32 s36, s40, 0x2c000
	s_addc_u32 s37, s41, 0
	s_mov_b32 m0, s73
	s_nop 4
	global_load_lds_dwordx4 v130, s[36:37]
	s_waitcnt vmcnt(8)
	s_waitcnt lgkmcnt(0)
	s_barrier
	v_mfma_f32_16x16x128_f8f6f4 v[70:73], v[138:145], v[176:183], 0
	v_mfma_f32_16x16x128_f8f6f4 v[50:53], v[138:145], v[186:193], 0
	v_mfma_f32_16x16x128_f8f6f4 v[22:25], v[138:145], v[194:201], 0
	v_mfma_f32_16x16x128_f8f6f4 v[54:57], v[138:145], v[202:209], 0
	v_mfma_f32_16x16x128_f8f6f4 v[66:69], v[146:153], v[176:183], 0
	v_mfma_f32_16x16x128_f8f6f4 v[38:41], v[146:153], v[186:193], 0
	v_mfma_f32_16x16x128_f8f6f4 v[18:21], v[146:153], v[194:201], 0
	v_mfma_f32_16x16x128_f8f6f4 v[46:49], v[146:153], v[202:209], 0
	v_mfma_f32_16x16x128_f8f6f4 v[30:33], v[154:161], v[176:183], 0
	v_mfma_f32_16x16x128_f8f6f4 v[14:17], v[154:161], v[186:193], 0
	v_mfma_f32_16x16x128_f8f6f4 v[6:9], v[154:161], v[194:201], 0
	v_mfma_f32_16x16x128_f8f6f4 v[170:173], v[154:161], v[202:209], 0
	v_mfma_f32_16x16x128_f8f6f4 v[26:29], v[162:169], v[176:183], 0
	v_mfma_f32_16x16x128_f8f6f4 v[10:13], v[162:169], v[186:193], 0
	v_mfma_f32_16x16x128_f8f6f4 v[2:5], v[162:169], v[194:201], 0
	v_mfma_f32_16x16x128_f8f6f4 v[34:37], v[162:169], v[202:209], 0
	s_barrier
	ds_read_b128 v[138:141], v135
	ds_read_b128 v[142:145], v135 offset:1024
	ds_read_b128 v[146:149], v135 offset:2048
	ds_read_b128 v[150:153], v135 offset:3072
	ds_read_b128 v[154:157], v136
	ds_read_b128 v[158:161], v136 offset:1024
	ds_read_b128 v[162:165], v136 offset:2048
	ds_read_b128 v[166:169], v136 offset:3072
	s_nop 3
	s_add_u32 s36, s40, 0x58000
	s_addc_u32 s37, s41, 0
	s_mov_b32 m0, s76
	s_nop 4
	global_load_lds_dwordx4 v130, s[36:37]
	s_add_u32 s36, s40, 0x84000
	s_addc_u32 s37, s41, 0
	s_mov_b32 m0, s77
	s_nop 4
	global_load_lds_dwordx4 v130, s[36:37]
	ds_read_b128 v[176:179], v133 offset:32768
	ds_read_b128 v[180:183], v133 offset:33792
	ds_read_b128 v[186:189], v133 offset:34816
	ds_read_b128 v[190:193], v133 offset:35840
	ds_read_b128 v[194:197], v133 offset:36864
	ds_read_b128 v[198:201], v133 offset:37888
	ds_read_b128 v[202:205], v133 offset:38912
	ds_read_b128 v[206:209], v133 offset:39936
	s_waitcnt vmcnt(8)
	s_waitcnt lgkmcnt(0)
	s_barrier
	v_mfma_f32_16x16x128_f8f6f4 v[126:129], v[138:145], v[176:183], v[126:129]
	v_mfma_f32_16x16x128_f8f6f4 v[118:121], v[138:145], v[186:193], v[118:121]
	v_mfma_f32_16x16x128_f8f6f4 v[102:105], v[138:145], v[194:201], v[102:105]
	v_mfma_f32_16x16x128_f8f6f4 v[86:89], v[138:145], v[202:209], v[86:89]
	v_mfma_f32_16x16x128_f8f6f4 v[122:125], v[146:153], v[176:183], v[122:125]
	v_mfma_f32_16x16x128_f8f6f4 v[114:117], v[146:153], v[186:193], v[114:117]
	v_mfma_f32_16x16x128_f8f6f4 v[98:101], v[146:153], v[194:201], v[98:101]
	v_mfma_f32_16x16x128_f8f6f4 v[82:85], v[146:153], v[202:209], v[82:85]
	v_mfma_f32_16x16x128_f8f6f4 v[110:113], v[154:161], v[176:183], v[110:113]
	v_mfma_f32_16x16x128_f8f6f4 v[94:97], v[154:161], v[186:193], v[94:97]
	v_mfma_f32_16x16x128_f8f6f4 v[78:81], v[154:161], v[194:201], v[78:81]
	v_mfma_f32_16x16x128_f8f6f4 v[62:65], v[154:161], v[202:209], v[62:65]
	v_mfma_f32_16x16x128_f8f6f4 v[106:109], v[162:169], v[176:183], v[106:109]
	v_mfma_f32_16x16x128_f8f6f4 v[90:93], v[162:169], v[186:193], v[90:93]
	v_mfma_f32_16x16x128_f8f6f4 v[74:77], v[162:169], v[194:201], v[74:77]
	v_mfma_f32_16x16x128_f8f6f4 v[42:45], v[162:169], v[202:209], v[42:45]
	s_barrier
	ds_read_b128 v[176:179], v133 offset:49152
	ds_read_b128 v[180:183], v133 offset:50176
	ds_read_b128 v[186:189], v133 offset:51200
	ds_read_b128 v[190:193], v133 offset:52224
	ds_read_b128 v[194:197], v133 offset:53248
	ds_read_b128 v[198:201], v133 offset:54272
	ds_read_b128 v[202:205], v133 offset:55296
	ds_read_b128 v[206:209], v133 offset:56320
	s_add_u32 s36, s38, 0x80
	s_addc_u32 s37, s39, 0
	s_mov_b32 m0, s78
	s_nop 4
	global_load_lds_dwordx4 v131, s[36:37]
	s_add_u32 s36, s38, 0x2c080
	s_addc_u32 s37, s39, 0
	s_mov_b32 m0, s79
	s_nop 4
	global_load_lds_dwordx4 v131, s[36:37]
	s_add_u32 s36, s38, 0x58080
	s_addc_u32 s37, s39, 0
	s_mov_b32 m0, s82
	s_nop 4
	global_load_lds_dwordx4 v131, s[36:37]
	s_add_u32 s36, s38, 0x84080
	s_addc_u32 s37, s39, 0
	s_mov_b32 m0, s83
	s_nop 4
	global_load_lds_dwordx4 v131, s[36:37]
	s_mov_b32 m0, s80
	s_nop 4
	global_load_lds_dwordx4 v130, s[42:43]
	s_add_u32 s36, s40, 0x2c080
	s_addc_u32 s37, s41, 0
	s_mov_b32 m0, s81
	s_nop 4
	global_load_lds_dwordx4 v130, s[36:37]
	s_waitcnt vmcnt(8)
	s_waitcnt lgkmcnt(0)
	s_barrier
	v_mfma_f32_16x16x128_f8f6f4 v[70:73], v[138:145], v[176:183], v[70:73]
	v_mfma_f32_16x16x128_f8f6f4 v[50:53], v[138:145], v[186:193], v[50:53]
	v_mfma_f32_16x16x128_f8f6f4 v[22:25], v[138:145], v[194:201], v[22:25]
	v_mfma_f32_16x16x128_f8f6f4 v[54:57], v[138:145], v[202:209], v[54:57]
	v_mfma_f32_16x16x128_f8f6f4 v[66:69], v[146:153], v[176:183], v[66:69]
	v_mfma_f32_16x16x128_f8f6f4 v[38:41], v[146:153], v[186:193], v[38:41]
	v_mfma_f32_16x16x128_f8f6f4 v[18:21], v[146:153], v[194:201], v[18:21]
	v_mfma_f32_16x16x128_f8f6f4 v[46:49], v[146:153], v[202:209], v[46:49]
	v_mfma_f32_16x16x128_f8f6f4 v[30:33], v[154:161], v[176:183], v[30:33]
	v_mfma_f32_16x16x128_f8f6f4 v[14:17], v[154:161], v[186:193], v[14:17]
	v_mfma_f32_16x16x128_f8f6f4 v[6:9], v[154:161], v[194:201], v[6:9]
	v_mfma_f32_16x16x128_f8f6f4 v[170:173], v[154:161], v[202:209], v[170:173]
	v_mfma_f32_16x16x128_f8f6f4 v[26:29], v[162:169], v[176:183], v[26:29]
	v_mfma_f32_16x16x128_f8f6f4 v[10:13], v[162:169], v[186:193], v[10:13]
	v_mfma_f32_16x16x128_f8f6f4 v[2:5], v[162:169], v[194:201], v[2:5]
	v_mfma_f32_16x16x128_f8f6f4 v[34:37], v[162:169], v[202:209], v[34:37]
	s_add_i32 s87, s87, 2
	s_add_u32 s85, s85, 0x100
	s_addc_u32 s86, s86, 0
	s_cmp_lt_u32 s87, 20
	s_mov_b64 s[36:37], s[34:35]
	s_barrier
